# v40 + redundant s_waitcnt lgkmcnt(0) at the head of each MFMA segment removed (already waited before the barrier)
# baseline (speedup 1.0000x reference)
; #define PG8_STAGE(bufoff, gbase, voff) do { _Pragma("unroll") for (int _i = 0; _i < 2; ++_i) \
;         __builtin_amdgcn_global_load_lds((const unsigned*)((const char*)(gbase) + (voff)[_i]), (LAS unsigned*)(lds + (bufoff) + ldsw + _i * 8192), 16, 0, 0); } while (0)
; #define PG8_LDA(dst, b, h) do { _Pragma("unroll") for (int m = 0; m < 4; ++m) _Pragma("unroll") for (int k = 0; k < 2; ++k) dst[m][k] = *(const LAS bf16x8*)(lds + PG8_SA(b, h) + aoff + m * 2048 + k * 1024); } while (0)
; #define PG8_LDB(dst, b, h) do { _Pragma("unroll") for (int n = 0; n < 2; ++n) _Pragma("unroll") for (int k = 0; k < 2; ++k) dst[n][k] = *(const LAS bf16x8*)(lds + PG8_SB(b, h) + boff + n * 2048 + k * 1024); } while (0)
; #define PG8_MMA(ai, bj, At, Bt) do { __builtin_amdgcn_s_setprio(1); _Pragma("unroll") for (int m = 0; m < 4; ++m) _Pragma("unroll") for (int n = 0; n < 2; ++n) _Pragma("unroll") for (int k = 0; k < 2; ++k) \
;         acc[ai][bj][m][n] = __builtin_amdgcn_mfma_f32_16x16x32_bf16(Bt[n][k], At[m][k], acc[ai][bj][m][n], 0, 0, 0); __builtin_amdgcn_s_setprio(0); } while (0)
; #define PG8_WAIT_V(n) asm volatile("s_waitcnt vmcnt(" #n ")" ::: "memory")
; #define PG8_BAR __builtin_amdgcn_s_barrier()
; template <class Epi>
; __device__ __forceinline__ void gemm_phase(LAS unsigned char* lds, const Gemm g, const StaticOrder& S, const Epi& E) {
;     ...
;         const bool has_next = S.next(ui + 1, nxt);
;         const char* nA = has_next ? PG8_UA(nxt) : cA; const char* nB = has_next ? PG8_UB(nxt) : cB;
;         for (int t = 0; t < nt; t += 2) {
;             const bool last = (t == nt - 2);
;             const char* a1 = cA + (size_t)(t + 1) * kstep;
;             const char* a2 = last ? nA : cA + (size_t)(t + 2) * kstep; const char* b2 = last ? nB : cB + (size_t)(t + 2) * kstep;
;             const char* a3 = a2 + kstep; const char* b3 = b2 + kstep;
;             PG8_LDB(B0, 0, 0); PG8_LDB(B1, 0, 1); PG8_SCHED; PG8_LDA(At, 0, 0); PG8_STAGE(PG8_SA(1, 1), a1 + hstepA, voffA);
;             PG8_WAIT_V(8); PG8_WAIT_L(0); PG8_BAR; PG8_MMA(0, 0, At, B0); PG8_MMA(0, 1, At, B1); PG8_BAR; PG8_SCHED;
;             PG8_LDA(At, 0, 1); PG8_STAGE(PG8_SB(0, 0), b2, voffB); PG8_STAGE(PG8_SB(0, 1), b2 + hstepB, voffB); PG8_STAGE(PG8_SA(0, 0), a2, voffA);
;             PG8_WAIT_V(8); PG8_WAIT_L(0); PG8_BAR; PG8_MMA(1, 0, At, B0); PG8_MMA(1, 1, At, B1); PG8_BAR; PG8_SCHED;
.LBB0_414:
	s_add_u32 s14, s26, 0xfff80080
	s_addc_u32 s15, s27, -1
	s_add_i32 s33, 0, 0x10000
	s_cmp_eq_u32 s21, 28
	s_cselect_b32 s29, s0, s15
	s_cselect_b32 s28, s1, s14
	s_cselect_b32 s15, s3, s19
	s_cselect_b32 s14, s7, s9
	s_add_i32 s52, 0, 0x14000
	v_add_u32_e32 v150, s33, v1
	v_add_u32_e32 v159, s52, v1
	ds_read_b128 v[138:141], v150
	ds_read_b128 v[142:145], v150 offset:1024
	ds_read_b128 v[146:149], v150 offset:2048
	ds_read_b128 v[150:153], v150 offset:3072
	ds_read_b128 v[154:157], v159
	ds_read_b128 v[160:163], v159 offset:1024
	ds_read_b128 v[164:167], v159 offset:2048
	ds_read_b128 v[168:171], v159 offset:3072
	v_lshl_add_u64 v[184:185], s[26:27], 0, v[134:135]
	s_add_i32 m0, s35, 0xc000
	ds_read_b128 v[172:175], v158
	ds_read_b128 v[176:179], v158 offset:1024
	ds_read_b128 v[188:191], v158 offset:2048
	ds_read_b128 v[192:195], v158 offset:3072
	ds_read_b128 v[196:199], v158 offset:4096
	ds_read_b128 v[200:203], v158 offset:5120
	ds_read_b128 v[204:207], v158 offset:6144
	ds_read_b128 v[208:211], v158 offset:7168
	global_load_lds_dwordx4 v[184:185], off
	v_lshl_add_u64 v[184:185], s[26:27], 0, v[136:137]
	s_add_i32 m0, s35, 0xe000
	s_nop 0
	global_load_lds_dwordx4 v[184:185], off
	s_waitcnt vmcnt(8)
	s_waitcnt lgkmcnt(0)
	s_barrier
	s_setprio 1
	v_mfma_f32_16x16x32_bf16 v[126:129], v[138:141], v[172:175], v[126:129]
	v_mfma_f32_16x16x32_bf16 v[122:125], v[146:149], v[172:175], v[122:125]
	v_mfma_f32_16x16x32_bf16 v[110:113], v[138:141], v[188:191], v[110:113]
	v_mfma_f32_16x16x32_bf16 v[106:109], v[146:149], v[188:191], v[106:109]
	v_mfma_f32_16x16x32_bf16 v[94:97], v[138:141], v[196:199], v[94:97]
	v_mfma_f32_16x16x32_bf16 v[90:93], v[146:149], v[196:199], v[90:93]
	v_mfma_f32_16x16x32_bf16 v[78:81], v[138:141], v[204:207], v[78:81]
	v_mfma_f32_16x16x32_bf16 v[74:77], v[146:149], v[204:207], v[74:77]
	v_mfma_f32_16x16x32_bf16 v[126:129], v[142:145], v[176:179], v[126:129]
	v_mfma_f32_16x16x32_bf16 v[122:125], v[150:153], v[176:179], v[122:125]
	v_mfma_f32_16x16x32_bf16 v[110:113], v[142:145], v[192:195], v[110:113]
	v_mfma_f32_16x16x32_bf16 v[106:109], v[150:153], v[192:195], v[106:109]
	v_mfma_f32_16x16x32_bf16 v[94:97], v[142:145], v[200:203], v[94:97]
	v_mfma_f32_16x16x32_bf16 v[90:93], v[150:153], v[200:203], v[90:93]
	v_mfma_f32_16x16x32_bf16 v[78:81], v[142:145], v[208:211], v[78:81]
	v_mfma_f32_16x16x32_bf16 v[74:77], v[150:153], v[208:211], v[74:77]
	v_mfma_f32_16x16x32_bf16 v[118:121], v[154:157], v[172:175], v[118:121]
	v_mfma_f32_16x16x32_bf16 v[114:117], v[164:167], v[172:175], v[114:117]
	v_mfma_f32_16x16x32_bf16 v[102:105], v[154:157], v[188:191], v[102:105]
	v_mfma_f32_16x16x32_bf16 v[98:101], v[164:167], v[188:191], v[98:101]
	v_mfma_f32_16x16x32_bf16 v[86:89], v[154:157], v[196:199], v[86:89]
	v_mfma_f32_16x16x32_bf16 v[82:85], v[164:167], v[196:199], v[82:85]
	v_mfma_f32_16x16x32_bf16 v[70:73], v[154:157], v[204:207], v[70:73]
	v_mfma_f32_16x16x32_bf16 v[66:69], v[164:167], v[204:207], v[66:69]
	v_mfma_f32_16x16x32_bf16 v[118:121], v[160:163], v[176:179], v[118:121]
	v_mfma_f32_16x16x32_bf16 v[114:117], v[168:171], v[176:179], v[114:117]
	v_mfma_f32_16x16x32_bf16 v[102:105], v[160:163], v[192:195], v[102:105]
	v_mfma_f32_16x16x32_bf16 v[98:101], v[168:171], v[192:195], v[98:101]
	v_mfma_f32_16x16x32_bf16 v[86:89], v[160:163], v[200:203], v[86:89]
	v_mfma_f32_16x16x32_bf16 v[82:85], v[168:171], v[200:203], v[82:85]
	v_mfma_f32_16x16x32_bf16 v[70:73], v[160:163], v[208:211], v[70:73]
	v_mfma_f32_16x16x32_bf16 v[66:69], v[168:171], v[208:211], v[66:69]
	s_setprio 0
	s_barrier
	s_add_i32 s33, s33, s34
	v_lshl_add_u64 v[184:185], s[14:15], 0, v[130:131]
	s_mov_b32 m0, s33
	ds_read_b128 v[172:175], v158 offset:16384
	ds_read_b128 v[176:179], v158 offset:17408
	ds_read_b128 v[188:191], v158 offset:18432
	ds_read_b128 v[192:195], v158 offset:19456
	ds_read_b128 v[196:199], v158 offset:20480
	ds_read_b128 v[200:203], v158 offset:21504
	ds_read_b128 v[204:207], v158 offset:22528
	ds_read_b128 v[208:211], v158 offset:23552
	global_load_lds_dwordx4 v[184:185], off
	s_add_i32 m0, s33, 0x2000
	s_add_u32 s40, s14, 0x80000
	v_lshl_add_u64 v[212:213], s[14:15], 0, v[132:133]
	s_addc_u32 s41, s15, 0
	s_add_i32 s33, s52, s34
	global_load_lds_dwordx4 v[212:213], off
	v_lshl_add_u64 v[214:215], s[40:41], 0, v[130:131]
	s_mov_b32 m0, s33
	v_lshl_add_u64 v[216:217], s[28:29], 0, v[132:133]
	global_load_lds_dwordx4 v[214:215], off
	v_lshl_add_u64 v[214:215], s[40:41], 0, v[132:133]
	s_add_i32 m0, s33, 0x2000
	s_nop 0
	global_load_lds_dwordx4 v[214:215], off
	v_lshl_add_u64 v[214:215], s[28:29], 0, v[130:131]
	s_mov_b32 m0, s35
	s_nop 0
	global_load_lds_dwordx4 v[214:215], off
	s_mov_b32 m0, s42
	s_nop 0
	global_load_lds_dwordx4 v[216:217], off
	s_waitcnt vmcnt(8)
	s_waitcnt lgkmcnt(0)
	s_barrier
; #define PG8_STAGE(bufoff, gbase, voff) do { _Pragma("unroll") for (int _i = 0; _i < 2; ++_i) \
;         __builtin_amdgcn_global_load_lds((const unsigned*)((const char*)(gbase) + (voff)[_i]), (LAS unsigned*)(lds + (bufoff) + ldsw + _i * 8192), 16, 0, 0); } while (0)
; #define PG8_LDA(dst, b, h) do { _Pragma("unroll") for (int m = 0; m < 4; ++m) _Pragma("unroll") for (int k = 0; k < 2; ++k) dst[m][k] = *(const LAS bf16x8*)(lds + PG8_SA(b, h) + aoff + m * 2048 + k * 1024); } while (0)
; #define PG8_LDB(dst, b, h) do { _Pragma("unroll") for (int n = 0; n < 2; ++n) _Pragma("unroll") for (int k = 0; k < 2; ++k) dst[n][k] = *(const LAS bf16x8*)(lds + PG8_SB(b, h) + boff + n * 2048 + k * 1024); } while (0)
; #define PG8_MMA(ai, bj, At, Bt) do { __builtin_amdgcn_s_setprio(1); _Pragma("unroll") for (int m = 0; m < 4; ++m) _Pragma("unroll") for (int n = 0; n < 2; ++n) _Pragma("unroll") for (int k = 0; k < 2; ++k) \
;         acc[ai][bj][m][n] = __builtin_amdgcn_mfma_f32_16x16x32_bf16(Bt[n][k], At[m][k], acc[ai][bj][m][n], 0, 0, 0); __builtin_amdgcn_s_setprio(0); } while (0)
; #define PG8_WAIT_V(n) asm volatile("s_waitcnt vmcnt(" #n ")" ::: "memory")
; #define PG8_WAIT_L(n) asm volatile("s_waitcnt lgkmcnt(" #n ")" ::: "memory")
; #define PG8_BAR __builtin_amdgcn_s_barrier()
; #define PG8_SCHED __builtin_amdgcn_sched_barrier(0)
; template <class Epi>
; __device__ __forceinline__ void gemm_phase(LAS unsigned char* lds, const Gemm g, const StaticOrder& S, const Epi& E) {
;     ...
;             PG8_LDA(At, 0, 1); PG8_STAGE(PG8_SB(0, 0), b2, voffB); PG8_STAGE(PG8_SB(0, 1), b2 + hstepB, voffB); PG8_STAGE(PG8_SA(0, 0), a2, voffA);
;             PG8_WAIT_V(8); PG8_WAIT_L(0); PG8_BAR; PG8_MMA(1, 0, At, B0); PG8_MMA(1, 1, At, B1); PG8_BAR; PG8_SCHED;
;             PG8_LDB(B0, 1, 0); PG8_LDB(B1, 1, 1); PG8_SCHED; PG8_LDA(At, 1, 0); PG8_STAGE(PG8_SA(0, 1), a2 + hstepA, voffA);
;             PG8_WAIT_V(8); PG8_WAIT_L(0); PG8_BAR; PG8_MMA(0, 0, At, B0); PG8_MMA(0, 1, At, B1); PG8_BAR; PG8_SCHED;
;             PG8_LDA(At, 1, 1); PG8_STAGE(PG8_SB(1, 0), b3, voffB); PG8_STAGE(PG8_SB(1, 1), b3 + hstepB, voffB); PG8_STAGE(PG8_SA(1, 0), a3, voffA);
	s_setprio 1
	v_mfma_f32_16x16x32_bf16 v[62:65], v[138:141], v[172:175], v[62:65]
	v_mfma_f32_16x16x32_bf16 v[58:61], v[146:149], v[172:175], v[58:61]
	v_mfma_f32_16x16x32_bf16 v[46:49], v[138:141], v[188:191], v[46:49]
	v_mfma_f32_16x16x32_bf16 v[42:45], v[146:149], v[188:191], v[42:45]
	v_mfma_f32_16x16x32_bf16 v[30:33], v[138:141], v[196:199], v[30:33]
	v_mfma_f32_16x16x32_bf16 v[26:29], v[146:149], v[196:199], v[26:29]
	v_mfma_f32_16x16x32_bf16 v[14:17], v[138:141], v[204:207], v[14:17]
	v_mfma_f32_16x16x32_bf16 v[10:13], v[146:149], v[204:207], v[10:13]
	v_mfma_f32_16x16x32_bf16 v[62:65], v[142:145], v[176:179], v[62:65]
	v_mfma_f32_16x16x32_bf16 v[58:61], v[150:153], v[176:179], v[58:61]
	v_mfma_f32_16x16x32_bf16 v[46:49], v[142:145], v[192:195], v[46:49]
	v_mfma_f32_16x16x32_bf16 v[42:45], v[150:153], v[192:195], v[42:45]
	v_mfma_f32_16x16x32_bf16 v[30:33], v[142:145], v[200:203], v[30:33]
	v_mfma_f32_16x16x32_bf16 v[26:29], v[150:153], v[200:203], v[26:29]
	v_mfma_f32_16x16x32_bf16 v[14:17], v[142:145], v[208:211], v[14:17]
	v_mfma_f32_16x16x32_bf16 v[10:13], v[150:153], v[208:211], v[10:13]
	v_mfma_f32_16x16x32_bf16 v[54:57], v[154:157], v[172:175], v[54:57]
	v_mfma_f32_16x16x32_bf16 v[50:53], v[164:167], v[172:175], v[50:53]
	v_mfma_f32_16x16x32_bf16 v[38:41], v[154:157], v[188:191], v[38:41]
	v_mfma_f32_16x16x32_bf16 v[34:37], v[164:167], v[188:191], v[34:37]
	v_mfma_f32_16x16x32_bf16 v[22:25], v[154:157], v[196:199], v[22:25]
	v_mfma_f32_16x16x32_bf16 v[18:21], v[164:167], v[196:199], v[18:21]
	v_mfma_f32_16x16x32_bf16 v[6:9], v[154:157], v[204:207], v[6:9]
	v_mfma_f32_16x16x32_bf16 v[2:5], v[164:167], v[204:207], v[2:5]
	v_mfma_f32_16x16x32_bf16 v[54:57], v[160:163], v[176:179], v[54:57]
	v_mfma_f32_16x16x32_bf16 v[50:53], v[168:171], v[176:179], v[50:53]
	v_mfma_f32_16x16x32_bf16 v[38:41], v[160:163], v[192:195], v[38:41]
	v_mfma_f32_16x16x32_bf16 v[34:37], v[168:171], v[192:195], v[34:37]
	v_mfma_f32_16x16x32_bf16 v[22:25], v[160:163], v[200:203], v[22:25]
	v_mfma_f32_16x16x32_bf16 v[18:21], v[168:171], v[200:203], v[18:21]
	v_mfma_f32_16x16x32_bf16 v[6:9], v[160:163], v[208:211], v[6:9]
	v_mfma_f32_16x16x32_bf16 v[2:5], v[168:171], v[208:211], v[2:5]
	s_setprio 0
	s_barrier
	s_add_i32 s33, 0, 0x18000
	s_add_i32 s40, 0, 0x1c000
	v_add_u32_e32 v150, s33, v1
	v_add_u32_e32 v159, s40, v1
	ds_read_b128 v[138:141], v150
	ds_read_b128 v[142:145], v150 offset:1024
	ds_read_b128 v[146:149], v150 offset:2048
	ds_read_b128 v[150:153], v150 offset:3072
	ds_read_b128 v[154:157], v159
	ds_read_b128 v[160:163], v159 offset:1024
	ds_read_b128 v[164:167], v159 offset:2048
	ds_read_b128 v[168:171], v159 offset:3072
	s_add_u32 s28, s28, 0x80000
	s_addc_u32 s29, s29, 0
	s_mov_b32 m0, s45
	v_lshl_add_u64 v[218:219], s[28:29], 0, v[130:131]
	ds_read_b128 v[172:175], v158 offset:32768
	ds_read_b128 v[176:179], v158 offset:33792
	ds_read_b128 v[188:191], v158 offset:34816
	ds_read_b128 v[192:195], v158 offset:35840
	ds_read_b128 v[196:199], v158 offset:36864
	ds_read_b128 v[200:203], v158 offset:37888
	ds_read_b128 v[204:207], v158 offset:38912
	ds_read_b128 v[208:211], v158 offset:39936
	global_load_lds_dwordx4 v[218:219], off
	v_lshl_add_u64 v[218:219], s[28:29], 0, v[132:133]
	s_mov_b32 m0, s68
	s_nop 0
	global_load_lds_dwordx4 v[218:219], off
	s_waitcnt vmcnt(8)
	s_waitcnt lgkmcnt(0)
	s_barrier
	s_setprio 1
	v_mfma_f32_16x16x32_bf16 v[126:129], v[138:141], v[172:175], v[126:129]
	v_mfma_f32_16x16x32_bf16 v[122:125], v[146:149], v[172:175], v[122:125]
	v_mfma_f32_16x16x32_bf16 v[110:113], v[138:141], v[188:191], v[110:113]
	v_mfma_f32_16x16x32_bf16 v[106:109], v[146:149], v[188:191], v[106:109]
	v_mfma_f32_16x16x32_bf16 v[94:97], v[138:141], v[196:199], v[94:97]
	v_mfma_f32_16x16x32_bf16 v[90:93], v[146:149], v[196:199], v[90:93]
	v_mfma_f32_16x16x32_bf16 v[78:81], v[138:141], v[204:207], v[78:81]
	v_mfma_f32_16x16x32_bf16 v[74:77], v[146:149], v[204:207], v[74:77]
	v_mfma_f32_16x16x32_bf16 v[126:129], v[142:145], v[176:179], v[126:129]
	v_mfma_f32_16x16x32_bf16 v[122:125], v[150:153], v[176:179], v[122:125]
	v_mfma_f32_16x16x32_bf16 v[110:113], v[142:145], v[192:195], v[110:113]
	v_mfma_f32_16x16x32_bf16 v[106:109], v[150:153], v[192:195], v[106:109]
	v_mfma_f32_16x16x32_bf16 v[94:97], v[142:145], v[200:203], v[94:97]
	v_mfma_f32_16x16x32_bf16 v[90:93], v[150:153], v[200:203], v[90:93]
	v_mfma_f32_16x16x32_bf16 v[78:81], v[142:145], v[208:211], v[78:81]
	v_mfma_f32_16x16x32_bf16 v[74:77], v[150:153], v[208:211], v[74:77]
	v_mfma_f32_16x16x32_bf16 v[118:121], v[154:157], v[172:175], v[118:121]
	v_mfma_f32_16x16x32_bf16 v[114:117], v[164:167], v[172:175], v[114:117]
	v_mfma_f32_16x16x32_bf16 v[102:105], v[154:157], v[188:191], v[102:105]
	v_mfma_f32_16x16x32_bf16 v[98:101], v[164:167], v[188:191], v[98:101]
	v_mfma_f32_16x16x32_bf16 v[86:89], v[154:157], v[196:199], v[86:89]
	v_mfma_f32_16x16x32_bf16 v[82:85], v[164:167], v[196:199], v[82:85]
	v_mfma_f32_16x16x32_bf16 v[70:73], v[154:157], v[204:207], v[70:73]
	v_mfma_f32_16x16x32_bf16 v[66:69], v[164:167], v[204:207], v[66:69]
	v_mfma_f32_16x16x32_bf16 v[118:121], v[160:163], v[176:179], v[118:121]
	v_mfma_f32_16x16x32_bf16 v[114:117], v[168:171], v[176:179], v[114:117]
	v_mfma_f32_16x16x32_bf16 v[102:105], v[160:163], v[192:195], v[102:105]
	v_mfma_f32_16x16x32_bf16 v[98:101], v[168:171], v[192:195], v[98:101]
	v_mfma_f32_16x16x32_bf16 v[86:89], v[160:163], v[200:203], v[86:89]
	v_mfma_f32_16x16x32_bf16 v[82:85], v[168:171], v[200:203], v[82:85]
	v_mfma_f32_16x16x32_bf16 v[70:73], v[160:163], v[208:211], v[70:73]
	v_mfma_f32_16x16x32_bf16 v[66:69], v[168:171], v[208:211], v[66:69]
	s_setprio 0
	s_barrier
; #define PG8_STAGE(bufoff, gbase, voff) do { _Pragma("unroll") for (int _i = 0; _i < 2; ++_i) \
;         __builtin_amdgcn_global_load_lds((const unsigned*)((const char*)(gbase) + (voff)[_i]), (LAS unsigned*)(lds + (bufoff) + ldsw + _i * 8192), 16, 0, 0); } while (0)
; #define PG8_LDA(dst, b, h) do { _Pragma("unroll") for (int m = 0; m < 4; ++m) _Pragma("unroll") for (int k = 0; k < 2; ++k) dst[m][k] = *(const LAS bf16x8*)(lds + PG8_SA(b, h) + aoff + m * 2048 + k * 1024); } while (0)
; #define PG8_MMA(ai, bj, At, Bt) do { __builtin_amdgcn_s_setprio(1); _Pragma("unroll") for (int m = 0; m < 4; ++m) _Pragma("unroll") for (int n = 0; n < 2; ++n) _Pragma("unroll") for (int k = 0; k < 2; ++k) \
;         acc[ai][bj][m][n] = __builtin_amdgcn_mfma_f32_16x16x32_bf16(Bt[n][k], At[m][k], acc[ai][bj][m][n], 0, 0, 0); __builtin_amdgcn_s_setprio(0); } while (0)
; #define PG8_WAIT_V(n) asm volatile("s_waitcnt vmcnt(" #n ")" ::: "memory")
; #define PG8_WAIT_L(n) asm volatile("s_waitcnt lgkmcnt(" #n ")" ::: "memory")
; #define PG8_BAR __builtin_amdgcn_s_barrier()
; #define PG8_SCHED __builtin_amdgcn_sched_barrier(0)
; template <class Epi>
; __device__ __forceinline__ void gemm_phase(LAS unsigned char* lds, const Gemm g, const StaticOrder& S, const Epi& E) {
;     ...
;             PG8_LDA(At, 1, 1); PG8_STAGE(PG8_SB(1, 0), b3, voffB); PG8_STAGE(PG8_SB(1, 1), b3 + hstepB, voffB); PG8_STAGE(PG8_SA(1, 0), a3, voffA);
;             PG8_WAIT_V(8); PG8_WAIT_L(0); PG8_BAR; PG8_MMA(1, 0, At, B0); PG8_MMA(1, 1, At, B1); PG8_BAR; PG8_SCHED;
;         }
	s_add_i32 s28, s33, s34
	v_lshl_add_u64 v[184:185], v[184:185], 0, s[84:85]
	s_mov_b32 m0, s28
	ds_read_b128 v[172:175], v158 offset:49152
	ds_read_b128 v[176:179], v158 offset:50176
	ds_read_b128 v[188:191], v158 offset:51200
	ds_read_b128 v[192:195], v158 offset:52224
	ds_read_b128 v[196:199], v158 offset:53248
	ds_read_b128 v[200:203], v158 offset:54272
	ds_read_b128 v[204:207], v158 offset:55296
	ds_read_b128 v[208:211], v158 offset:56320
	global_load_lds_dwordx4 v[184:185], off
	s_add_i32 m0, s28, 0x2000
	s_add_u32 s14, s14, 0x80080
	v_lshl_add_u64 v[184:185], v[212:213], 0, s[84:85]
	s_addc_u32 s15, s15, 0
	s_add_i32 s28, s40, s34
	global_load_lds_dwordx4 v[184:185], off
	v_lshl_add_u64 v[184:185], s[14:15], 0, v[130:131]
	s_mov_b32 m0, s28
	s_nop 0
	global_load_lds_dwordx4 v[184:185], off
	v_lshl_add_u64 v[184:185], s[14:15], 0, v[132:133]
	s_add_i32 m0, s28, 0x2000
	s_nop 0
	global_load_lds_dwordx4 v[184:185], off
	v_lshl_add_u64 v[184:185], v[214:215], 0, s[84:85]
	s_mov_b32 m0, s87
	s_nop 0
	global_load_lds_dwordx4 v[184:185], off
	v_lshl_add_u64 v[184:185], v[216:217], 0, s[84:85]
	s_mov_b32 m0, s91
	s_nop 0
	global_load_lds_dwordx4 v[184:185], off
	s_waitcnt vmcnt(8)
	s_waitcnt lgkmcnt(0)
	s_barrier
	s_setprio 1
	v_mfma_f32_16x16x32_bf16 v[62:65], v[138:141], v[172:175], v[62:65]
	v_mfma_f32_16x16x32_bf16 v[58:61], v[146:149], v[172:175], v[58:61]
	v_mfma_f32_16x16x32_bf16 v[46:49], v[138:141], v[188:191], v[46:49]
	v_mfma_f32_16x16x32_bf16 v[42:45], v[146:149], v[188:191], v[42:45]
	v_mfma_f32_16x16x32_bf16 v[30:33], v[138:141], v[196:199], v[30:33]
	v_mfma_f32_16x16x32_bf16 v[26:29], v[146:149], v[196:199], v[26:29]
	v_mfma_f32_16x16x32_bf16 v[14:17], v[138:141], v[204:207], v[14:17]
	v_mfma_f32_16x16x32_bf16 v[10:13], v[146:149], v[204:207], v[10:13]
	v_mfma_f32_16x16x32_bf16 v[62:65], v[142:145], v[176:179], v[62:65]
	v_mfma_f32_16x16x32_bf16 v[58:61], v[150:153], v[176:179], v[58:61]
	v_mfma_f32_16x16x32_bf16 v[46:49], v[142:145], v[192:195], v[46:49]
	v_mfma_f32_16x16x32_bf16 v[42:45], v[150:153], v[192:195], v[42:45]
	v_mfma_f32_16x16x32_bf16 v[30:33], v[142:145], v[200:203], v[30:33]
	v_mfma_f32_16x16x32_bf16 v[26:29], v[150:153], v[200:203], v[26:29]
	v_mfma_f32_16x16x32_bf16 v[14:17], v[142:145], v[208:211], v[14:17]
	v_mfma_f32_16x16x32_bf16 v[10:13], v[150:153], v[208:211], v[10:13]
	v_mfma_f32_16x16x32_bf16 v[54:57], v[154:157], v[172:175], v[54:57]
	v_mfma_f32_16x16x32_bf16 v[50:53], v[164:167], v[172:175], v[50:53]
	v_mfma_f32_16x16x32_bf16 v[38:41], v[154:157], v[188:191], v[38:41]
	v_mfma_f32_16x16x32_bf16 v[34:37], v[164:167], v[188:191], v[34:37]
	v_mfma_f32_16x16x32_bf16 v[22:25], v[154:157], v[196:199], v[22:25]
	v_mfma_f32_16x16x32_bf16 v[18:21], v[164:167], v[196:199], v[18:21]
	v_mfma_f32_16x16x32_bf16 v[6:9], v[154:157], v[204:207], v[6:9]
	v_mfma_f32_16x16x32_bf16 v[2:5], v[164:167], v[204:207], v[2:5]
	v_mfma_f32_16x16x32_bf16 v[54:57], v[160:163], v[176:179], v[54:57]
	v_mfma_f32_16x16x32_bf16 v[50:53], v[168:171], v[176:179], v[50:53]
	v_mfma_f32_16x16x32_bf16 v[38:41], v[160:163], v[192:195], v[38:41]
	v_mfma_f32_16x16x32_bf16 v[34:37], v[168:171], v[192:195], v[34:37]
	v_mfma_f32_16x16x32_bf16 v[22:25], v[160:163], v[200:203], v[22:25]
	v_mfma_f32_16x16x32_bf16 v[18:21], v[168:171], v[200:203], v[18:21]
	v_mfma_f32_16x16x32_bf16 v[6:9], v[160:163], v[208:211], v[6:9]
	v_mfma_f32_16x16x32_bf16 v[2:5], v[168:171], v[208:211], v[2:5]
	s_setprio 0
	s_barrier
	s_add_i32 s21, s21, 2
	s_add_u32 s26, s26, 0x100
	s_addc_u32 s27, s27, 0
	s_add_u32 s9, s9, 0x100
	s_addc_u32 s19, s19, 0
	s_cmp_gt_u32 s21, 29
	s_cbranch_scc0 .LBB0_414
	s_and_b64 vcc, exec, s[16:17]
	s_cbranch_vccz .LBB0_417
	s_barrier

; #define PG8_STAGE(bufoff, gbase, voff) do { _Pragma("unroll") for (int _i = 0; _i < 2; ++_i) \
;         __builtin_amdgcn_global_load_lds((const unsigned*)((const char*)(gbase) + (voff)[_i]), (LAS unsigned*)(lds + (bufoff) + ldsw + _i * 8192), 16, 0, 0); } while (0)
; #define PG8_LDA(dst, b, h) do { _Pragma("unroll") for (int m = 0; m < 4; ++m) _Pragma("unroll") for (int k = 0; k < 2; ++k) dst[m][k] = *(const LAS bf16x8*)(lds + PG8_SA(b, h) + aoff + m * 2048 + k * 1024); } while (0)
; #define PG8_LDB(dst, b, h) do { _Pragma("unroll") for (int n = 0; n < 2; ++n) _Pragma("unroll") for (int k = 0; k < 2; ++k) dst[n][k] = *(const LAS bf16x8*)(lds + PG8_SB(b, h) + boff + n * 2048 + k * 1024); } while (0)
; #define PG8_MMA(ai, bj, At, Bt) do { __builtin_amdgcn_s_setprio(1); _Pragma("unroll") for (int m = 0; m < 4; ++m) _Pragma("unroll") for (int n = 0; n < 2; ++n) _Pragma("unroll") for (int k = 0; k < 2; ++k) \
;         acc[ai][bj][m][n] = __builtin_amdgcn_mfma_f32_16x16x32_bf16(Bt[n][k], At[m][k], acc[ai][bj][m][n], 0, 0, 0); __builtin_amdgcn_s_setprio(0); } while (0)
; #define PG8_WAIT_V(n) asm volatile("s_waitcnt vmcnt(" #n ")" ::: "memory")
; template <class Epi>
; __device__ __forceinline__ void gemm_phase(LAS unsigned char* lds, const Gemm g, const StaticOrder& S, const Epi& E) {
;     ...
;             const char* a1 = cA + (size_t)(t + 1) * kstep;
;             const char* a2 = last ? nA : cA + (size_t)(t + 2) * kstep; const char* b2 = last ? nB : cB + (size_t)(t + 2) * kstep;
;             const char* a3 = a2 + kstep; const char* b3 = b2 + kstep;
;             PG8_LDB(B0, 0, 0); PG8_LDB(B1, 0, 1); PG8_SCHED; PG8_LDA(At, 0, 0); PG8_STAGE(PG8_SA(1, 1), a1 + hstepA, voffA);
;             PG8_WAIT_V(8); PG8_WAIT_L(0); PG8_BAR; PG8_MMA(0, 0, At, B0); PG8_MMA(0, 1, At, B1); PG8_BAR; PG8_SCHED;
;             PG8_LDA(At, 0, 1); PG8_STAGE(PG8_SB(0, 0), b2, voffB); PG8_STAGE(PG8_SB(0, 1), b2 + hstepB, voffB); PG8_STAGE(PG8_SA(0, 0), a2, voffA);
;             PG8_WAIT_V(8); PG8_WAIT_L(0); PG8_BAR; PG8_MMA(1, 0, At, B0); PG8_MMA(1, 1, At, B1); PG8_BAR; PG8_SCHED;
;     ...
; #pragma unroll
;         for (int a = 0; a < 2; ++a)
; #pragma unroll
;             for (int b = 0; b < 2; ++b)
; #pragma unroll
;                 for (int m = 0; m < 4; ++m)
; #pragma unroll
;                     for (int n = 0; n < 2; ++n) acc[a][b][m][n] = (f32x4){0.f, 0.f, 0.f, 0.f};
.LBB0_682:
	s_ashr_i32 s21, s20, 31
	s_lshl_b64 s[26:27], s[20:21], 17
	v_readlane_b32 s40, v254, 33
	v_readlane_b32 s41, v254, 34
	s_add_u32 s26, s40, s26
	s_addc_u32 s27, s41, s27
	s_and_b64 s[6:7], s[6:7], exec
	s_cselect_b32 s7, s27, s35
	s_cselect_b32 s6, s26, s34
	s_add_i32 s33, 0, 0x10000
	s_add_i32 s21, 0, 0x14000
	v_add_u32_e32 v147, s33, v1
	v_add_u32_e32 v181, s21, v1
	ds_read_b128 v[2:5], v147
	ds_read_b128 v[6:9], v147 offset:1024
	ds_read_b128 v[10:13], v147 offset:2048
	ds_read_b128 v[14:17], v147 offset:3072
	ds_read_b128 v[18:21], v181
	ds_read_b128 v[22:25], v181 offset:1024
	ds_read_b128 v[26:29], v181 offset:2048
	ds_read_b128 v[30:33], v181 offset:3072
	s_add_u32 s52, s30, 0x80080
	s_addc_u32 s53, s31, 0
	s_add_i32 s41, s14, 0xc000
	v_lshl_add_u64 v[66:67], s[52:53], 0, v[130:131]
	s_mov_b32 m0, s41
	s_add_i32 s1, s14, 0xe000
	ds_read_b128 v[34:37], v146
	ds_read_b128 v[38:41], v146 offset:1024
	ds_read_b128 v[42:45], v146 offset:2048
	ds_read_b128 v[46:49], v146 offset:3072
	ds_read_b128 v[50:53], v146 offset:4096
	ds_read_b128 v[54:57], v146 offset:5120
	ds_read_b128 v[58:61], v146 offset:6144
	ds_read_b128 v[62:65], v146 offset:7168
	global_load_lds_dwordx4 v[66:67], off
	v_lshl_add_u64 v[66:67], s[52:53], 0, v[134:135]
	s_mov_b32 m0, s1
	s_nop 0
	global_load_lds_dwordx4 v[66:67], off
	s_waitcnt vmcnt(8)
	s_waitcnt lgkmcnt(0)
	s_barrier
	s_setprio 1
	v_mfma_f32_16x16x32_bf16 v[66:69], v[2:5], v[34:37], 0
	v_mfma_f32_16x16x32_bf16 v[70:73], v[10:13], v[34:37], 0
	v_mfma_f32_16x16x32_bf16 v[74:77], v[2:5], v[42:45], 0
	v_mfma_f32_16x16x32_bf16 v[78:81], v[10:13], v[42:45], 0
	v_mfma_f32_16x16x32_bf16 v[82:85], v[2:5], v[50:53], 0
	v_mfma_f32_16x16x32_bf16 v[86:89], v[10:13], v[50:53], 0
	v_mfma_f32_16x16x32_bf16 v[90:93], v[2:5], v[58:61], 0
	v_mfma_f32_16x16x32_bf16 v[94:97], v[10:13], v[58:61], 0
	v_mfma_f32_16x16x32_bf16 v[66:69], v[6:9], v[38:41], v[66:69]
	v_mfma_f32_16x16x32_bf16 v[70:73], v[14:17], v[38:41], v[70:73]
	v_mfma_f32_16x16x32_bf16 v[74:77], v[6:9], v[46:49], v[74:77]
	v_mfma_f32_16x16x32_bf16 v[78:81], v[14:17], v[46:49], v[78:81]
	v_mfma_f32_16x16x32_bf16 v[82:85], v[6:9], v[54:57], v[82:85]
	v_mfma_f32_16x16x32_bf16 v[86:89], v[14:17], v[54:57], v[86:89]
	v_mfma_f32_16x16x32_bf16 v[90:93], v[6:9], v[62:65], v[90:93]
	v_mfma_f32_16x16x32_bf16 v[94:97], v[14:17], v[62:65], v[94:97]
	v_mfma_f32_16x16x32_bf16 v[98:101], v[18:21], v[34:37], 0
	v_mfma_f32_16x16x32_bf16 v[34:37], v[26:29], v[34:37], 0
	v_mfma_f32_16x16x32_bf16 v[98:101], v[22:25], v[38:41], v[98:101]
	v_mfma_f32_16x16x32_bf16 v[34:37], v[30:33], v[38:41], v[34:37]
	v_mfma_f32_16x16x32_bf16 v[38:41], v[18:21], v[42:45], 0
	v_mfma_f32_16x16x32_bf16 v[42:45], v[26:29], v[42:45], 0
	v_mfma_f32_16x16x32_bf16 v[38:41], v[22:25], v[46:49], v[38:41]
	v_mfma_f32_16x16x32_bf16 v[42:45], v[30:33], v[46:49], v[42:45]
	v_mfma_f32_16x16x32_bf16 v[46:49], v[18:21], v[50:53], 0
	v_mfma_f32_16x16x32_bf16 v[50:53], v[26:29], v[50:53], 0
	v_mfma_f32_16x16x32_bf16 v[46:49], v[22:25], v[54:57], v[46:49]
	v_mfma_f32_16x16x32_bf16 v[50:53], v[30:33], v[54:57], v[50:53]
	v_mfma_f32_16x16x32_bf16 v[54:57], v[18:21], v[58:61], 0
	v_mfma_f32_16x16x32_bf16 v[58:61], v[26:29], v[58:61], 0
	v_mfma_f32_16x16x32_bf16 v[54:57], v[22:25], v[62:65], v[54:57]
	v_mfma_f32_16x16x32_bf16 v[58:61], v[30:33], v[62:65], v[58:61]
	s_setprio 0
	s_barrier
	s_add_i32 s33, s33, s11
	v_lshl_add_u64 v[184:185], s[34:35], 0, v[132:133]
	s_mov_b64 s[62:63], 0x100
	s_add_i32 s3, s33, 0x2000
	v_lshl_add_u64 v[138:139], v[184:185], 0, s[62:63]
	s_mov_b32 m0, s33
	v_lshl_add_u64 v[212:213], s[34:35], 0, v[136:137]
	s_add_u32 s52, s34, 0x10100
	ds_read_b128 v[62:65], v146 offset:16384
	ds_read_b128 v[102:105], v146 offset:17408
	ds_read_b128 v[106:109], v146 offset:18432
	ds_read_b128 v[110:113], v146 offset:19456
	ds_read_b128 v[114:117], v146 offset:20480
	ds_read_b128 v[118:121], v146 offset:21504
	ds_read_b128 v[122:125], v146 offset:22528
	ds_read_b128 v[126:129], v146 offset:23552
	global_load_lds_dwordx4 v[138:139], off
	v_lshl_add_u64 v[138:139], v[212:213], 0, s[62:63]
	s_mov_b32 m0, s3
	s_addc_u32 s53, s35, 0
	s_add_i32 s21, s21, s11
	global_load_lds_dwordx4 v[138:139], off
	v_lshl_add_u64 v[138:139], s[52:53], 0, v[132:133]
	s_mov_b32 m0, s21
	s_add_i32 s23, s21, 0x2000
	global_load_lds_dwordx4 v[138:139], off
	v_lshl_add_u64 v[138:139], s[52:53], 0, v[136:137]
	s_mov_b32 m0, s23
	v_lshl_add_u64 v[214:215], s[30:31], 0, v[130:131]
	global_load_lds_dwordx4 v[138:139], off
	v_lshl_add_u64 v[138:139], v[214:215], 0, s[62:63]
	s_mov_b32 m0, s14
	v_lshl_add_u64 v[216:217], s[30:31], 0, v[134:135]
	global_load_lds_dwordx4 v[138:139], off
	v_lshl_add_u64 v[138:139], v[216:217], 0, s[62:63]
	s_mov_b32 m0, s15
	s_nop 0
	global_load_lds_dwordx4 v[138:139], off
	s_waitcnt vmcnt(8)
	s_waitcnt lgkmcnt(0)
	s_barrier
; #define PG8_STAGE(bufoff, gbase, voff) do { _Pragma("unroll") for (int _i = 0; _i < 2; ++_i) \
;         __builtin_amdgcn_global_load_lds((const unsigned*)((const char*)(gbase) + (voff)[_i]), (LAS unsigned*)(lds + (bufoff) + ldsw + _i * 8192), 16, 0, 0); } while (0)
; #define PG8_LDA(dst, b, h) do { _Pragma("unroll") for (int m = 0; m < 4; ++m) _Pragma("unroll") for (int k = 0; k < 2; ++k) dst[m][k] = *(const LAS bf16x8*)(lds + PG8_SA(b, h) + aoff + m * 2048 + k * 1024); } while (0)
; #define PG8_LDB(dst, b, h) do { _Pragma("unroll") for (int n = 0; n < 2; ++n) _Pragma("unroll") for (int k = 0; k < 2; ++k) dst[n][k] = *(const LAS bf16x8*)(lds + PG8_SB(b, h) + boff + n * 2048 + k * 1024); } while (0)
; #define PG8_MMA(ai, bj, At, Bt) do { __builtin_amdgcn_s_setprio(1); _Pragma("unroll") for (int m = 0; m < 4; ++m) _Pragma("unroll") for (int n = 0; n < 2; ++n) _Pragma("unroll") for (int k = 0; k < 2; ++k) \
;         acc[ai][bj][m][n] = __builtin_amdgcn_mfma_f32_16x16x32_bf16(Bt[n][k], At[m][k], acc[ai][bj][m][n], 0, 0, 0); __builtin_amdgcn_s_setprio(0); } while (0)
; #define PG8_WAIT_V(n) asm volatile("s_waitcnt vmcnt(" #n ")" ::: "memory")
; #define PG8_WAIT_L(n) asm volatile("s_waitcnt lgkmcnt(" #n ")" ::: "memory")
; #define PG8_BAR __builtin_amdgcn_s_barrier()
; template <class Epi>
; __device__ __forceinline__ void gemm_phase(LAS unsigned char* lds, const Gemm g, const StaticOrder& S, const Epi& E) {
;     ...
;             PG8_LDA(At, 0, 1); PG8_STAGE(PG8_SB(0, 0), b2, voffB); PG8_STAGE(PG8_SB(0, 1), b2 + hstepB, voffB); PG8_STAGE(PG8_SA(0, 0), a2, voffA);
;             PG8_WAIT_V(8); PG8_WAIT_L(0); PG8_BAR; PG8_MMA(1, 0, At, B0); PG8_MMA(1, 1, At, B1); PG8_BAR; PG8_SCHED;
;             PG8_LDB(B0, 1, 0); PG8_LDB(B1, 1, 1); PG8_SCHED; PG8_LDA(At, 1, 0); PG8_STAGE(PG8_SA(0, 1), a2 + hstepA, voffA);
;             PG8_WAIT_V(8); PG8_WAIT_L(0); PG8_BAR; PG8_MMA(0, 0, At, B0); PG8_MMA(0, 1, At, B1); PG8_BAR; PG8_SCHED;
;             PG8_LDA(At, 1, 1); PG8_STAGE(PG8_SB(1, 0), b3, voffB); PG8_STAGE(PG8_SB(1, 1), b3 + hstepB, voffB); PG8_STAGE(PG8_SA(1, 0), a3, voffA);
;     ...
; #pragma unroll
;         for (int a = 0; a < 2; ++a)
; #pragma unroll
;             for (int b = 0; b < 2; ++b)
; #pragma unroll
;                 for (int m = 0; m < 4; ++m)
; #pragma unroll
;                     for (int n = 0; n < 2; ++n) acc[a][b][m][n] = (f32x4){0.f, 0.f, 0.f, 0.f};
	s_setprio 1
	v_mfma_f32_16x16x32_bf16 v[138:141], v[2:5], v[62:65], 0
	v_mfma_f32_16x16x32_bf16 v[148:151], v[2:5], v[106:109], 0
	v_mfma_f32_16x16x32_bf16 v[156:159], v[2:5], v[114:117], 0
	v_mfma_f32_16x16x32_bf16 v[2:5], v[2:5], v[122:125], 0
	v_mfma_f32_16x16x32_bf16 v[138:141], v[6:9], v[102:105], v[138:141]
	v_mfma_f32_16x16x32_bf16 v[148:151], v[6:9], v[110:113], v[148:151]
	v_mfma_f32_16x16x32_bf16 v[156:159], v[6:9], v[118:121], v[156:159]
	v_mfma_f32_16x16x32_bf16 v[2:5], v[6:9], v[126:129], v[2:5]
	v_mfma_f32_16x16x32_bf16 v[6:9], v[10:13], v[122:125], 0
	v_mfma_f32_16x16x32_bf16 v[142:145], v[10:13], v[62:65], 0
	v_mfma_f32_16x16x32_bf16 v[152:155], v[10:13], v[106:109], 0
	v_mfma_f32_16x16x32_bf16 v[160:163], v[10:13], v[114:117], 0
	v_mfma_f32_16x16x32_bf16 v[6:9], v[14:17], v[126:129], v[6:9]
	v_mfma_f32_16x16x32_bf16 v[142:145], v[14:17], v[102:105], v[142:145]
	v_mfma_f32_16x16x32_bf16 v[152:155], v[14:17], v[110:113], v[152:155]
	v_mfma_f32_16x16x32_bf16 v[160:163], v[14:17], v[118:121], v[160:163]
	v_mfma_f32_16x16x32_bf16 v[10:13], v[18:21], v[62:65], 0
	v_mfma_f32_16x16x32_bf16 v[14:17], v[26:29], v[62:65], 0
	v_mfma_f32_16x16x32_bf16 v[10:13], v[22:25], v[102:105], v[10:13]
	v_mfma_f32_16x16x32_bf16 v[14:17], v[30:33], v[102:105], v[14:17]
	v_mfma_f32_16x16x32_bf16 v[62:65], v[18:21], v[106:109], 0
	v_mfma_f32_16x16x32_bf16 v[102:105], v[26:29], v[106:109], 0
	v_mfma_f32_16x16x32_bf16 v[106:109], v[18:21], v[114:117], 0
	v_mfma_f32_16x16x32_bf16 v[18:21], v[18:21], v[122:125], 0
	v_mfma_f32_16x16x32_bf16 v[62:65], v[22:25], v[110:113], v[62:65]
	v_mfma_f32_16x16x32_bf16 v[102:105], v[30:33], v[110:113], v[102:105]
	v_mfma_f32_16x16x32_bf16 v[106:109], v[22:25], v[118:121], v[106:109]
	v_mfma_f32_16x16x32_bf16 v[110:113], v[26:29], v[114:117], 0
	v_mfma_f32_16x16x32_bf16 v[18:21], v[22:25], v[126:129], v[18:21]
	v_mfma_f32_16x16x32_bf16 v[22:25], v[26:29], v[122:125], 0
	v_mfma_f32_16x16x32_bf16 v[110:113], v[30:33], v[118:121], v[110:113]
	v_mfma_f32_16x16x32_bf16 v[22:25], v[30:33], v[126:129], v[22:25]
	s_setprio 0
	s_barrier
	s_add_i32 s40, 0, 0x18000
	s_add_i32 s64, 0, 0x1c000
	v_add_u32_e32 v183, s40, v1
	v_add_u32_e32 v186, s64, v1
	ds_read_b128 v[26:29], v183
	ds_read_b128 v[30:33], v183 offset:1024
	ds_read_b128 v[114:117], v183 offset:2048
	ds_read_b128 v[118:121], v183 offset:3072
	ds_read_b128 v[122:125], v186
	ds_read_b128 v[126:129], v186 offset:1024
	ds_read_b128 v[164:167], v186 offset:2048
	ds_read_b128 v[168:171], v186 offset:3072
	s_add_u32 s52, s30, 0x80100
	s_addc_u32 s53, s31, 0
	s_mov_b32 m0, s29
	v_lshl_add_u64 v[218:219], s[52:53], 0, v[130:131]
	ds_read_b128 v[172:175], v146 offset:32768
	ds_read_b128 v[176:179], v146 offset:33792
	ds_read_b128 v[188:191], v146 offset:34816
	ds_read_b128 v[192:195], v146 offset:35840
	ds_read_b128 v[196:199], v146 offset:36864
	ds_read_b128 v[200:203], v146 offset:37888
	ds_read_b128 v[204:207], v146 offset:38912
	ds_read_b128 v[208:211], v146 offset:39936
	global_load_lds_dwordx4 v[218:219], off
	v_lshl_add_u64 v[218:219], s[52:53], 0, v[134:135]
	s_mov_b32 m0, s42
	s_nop 0
	global_load_lds_dwordx4 v[218:219], off
	s_waitcnt vmcnt(8)
	s_waitcnt lgkmcnt(0)
	s_barrier
	s_setprio 1
	v_mfma_f32_16x16x32_bf16 v[66:69], v[26:29], v[172:175], v[66:69]
	v_mfma_f32_16x16x32_bf16 v[70:73], v[114:117], v[172:175], v[70:73]
	v_mfma_f32_16x16x32_bf16 v[74:77], v[26:29], v[188:191], v[74:77]
	v_mfma_f32_16x16x32_bf16 v[78:81], v[114:117], v[188:191], v[78:81]
	v_mfma_f32_16x16x32_bf16 v[82:85], v[26:29], v[196:199], v[82:85]
	v_mfma_f32_16x16x32_bf16 v[86:89], v[114:117], v[196:199], v[86:89]
	v_mfma_f32_16x16x32_bf16 v[90:93], v[26:29], v[204:207], v[90:93]
	v_mfma_f32_16x16x32_bf16 v[94:97], v[114:117], v[204:207], v[94:97]
	v_mfma_f32_16x16x32_bf16 v[66:69], v[30:33], v[176:179], v[66:69]
	v_mfma_f32_16x16x32_bf16 v[70:73], v[118:121], v[176:179], v[70:73]
	v_mfma_f32_16x16x32_bf16 v[74:77], v[30:33], v[192:195], v[74:77]
	v_mfma_f32_16x16x32_bf16 v[78:81], v[118:121], v[192:195], v[78:81]
	v_mfma_f32_16x16x32_bf16 v[82:85], v[30:33], v[200:203], v[82:85]
	v_mfma_f32_16x16x32_bf16 v[86:89], v[118:121], v[200:203], v[86:89]
	v_mfma_f32_16x16x32_bf16 v[90:93], v[30:33], v[208:211], v[90:93]
	v_mfma_f32_16x16x32_bf16 v[94:97], v[118:121], v[208:211], v[94:97]
	v_mfma_f32_16x16x32_bf16 v[98:101], v[122:125], v[172:175], v[98:101]
	v_mfma_f32_16x16x32_bf16 v[34:37], v[164:167], v[172:175], v[34:37]
	v_mfma_f32_16x16x32_bf16 v[38:41], v[122:125], v[188:191], v[38:41]
	v_mfma_f32_16x16x32_bf16 v[42:45], v[164:167], v[188:191], v[42:45]
	v_mfma_f32_16x16x32_bf16 v[46:49], v[122:125], v[196:199], v[46:49]
	v_mfma_f32_16x16x32_bf16 v[50:53], v[164:167], v[196:199], v[50:53]
	v_mfma_f32_16x16x32_bf16 v[54:57], v[122:125], v[204:207], v[54:57]
	v_mfma_f32_16x16x32_bf16 v[58:61], v[164:167], v[204:207], v[58:61]
	v_mfma_f32_16x16x32_bf16 v[98:101], v[126:129], v[176:179], v[98:101]
	v_mfma_f32_16x16x32_bf16 v[34:37], v[168:171], v[176:179], v[34:37]
	v_mfma_f32_16x16x32_bf16 v[38:41], v[126:129], v[192:195], v[38:41]
	v_mfma_f32_16x16x32_bf16 v[42:45], v[168:171], v[192:195], v[42:45]
	v_mfma_f32_16x16x32_bf16 v[46:49], v[126:129], v[200:203], v[46:49]
	v_mfma_f32_16x16x32_bf16 v[50:53], v[168:171], v[200:203], v[50:53]
	v_mfma_f32_16x16x32_bf16 v[54:57], v[126:129], v[208:211], v[54:57]
	v_mfma_f32_16x16x32_bf16 v[58:61], v[168:171], v[208:211], v[58:61]
	s_setprio 0
	s_barrier
; #define PG8_STAGE(bufoff, gbase, voff) do { _Pragma("unroll") for (int _i = 0; _i < 2; ++_i) \
;         __builtin_amdgcn_global_load_lds((const unsigned*)((const char*)(gbase) + (voff)[_i]), (LAS unsigned*)(lds + (bufoff) + ldsw + _i * 8192), 16, 0, 0); } while (0)
; #define PG8_LDA(dst, b, h) do { _Pragma("unroll") for (int m = 0; m < 4; ++m) _Pragma("unroll") for (int k = 0; k < 2; ++k) dst[m][k] = *(const LAS bf16x8*)(lds + PG8_SA(b, h) + aoff + m * 2048 + k * 1024); } while (0)
; #define PG8_LDB(dst, b, h) do { _Pragma("unroll") for (int n = 0; n < 2; ++n) _Pragma("unroll") for (int k = 0; k < 2; ++k) dst[n][k] = *(const LAS bf16x8*)(lds + PG8_SB(b, h) + boff + n * 2048 + k * 1024); } while (0)
; #define PG8_MMA(ai, bj, At, Bt) do { __builtin_amdgcn_s_setprio(1); _Pragma("unroll") for (int m = 0; m < 4; ++m) _Pragma("unroll") for (int n = 0; n < 2; ++n) _Pragma("unroll") for (int k = 0; k < 2; ++k) \
;         acc[ai][bj][m][n] = __builtin_amdgcn_mfma_f32_16x16x32_bf16(Bt[n][k], At[m][k], acc[ai][bj][m][n], 0, 0, 0); __builtin_amdgcn_s_setprio(0); } while (0)
; #define PG8_WAIT_V(n) asm volatile("s_waitcnt vmcnt(" #n ")" ::: "memory")
; #define PG8_BAR __builtin_amdgcn_s_barrier()
; template <class Epi>
; __device__ __forceinline__ void gemm_phase(LAS unsigned char* lds, const Gemm g, const StaticOrder& S, const Epi& E) {
;     ...
;             PG8_LDB(B0, 0, 0); PG8_LDB(B1, 0, 1); PG8_SCHED; PG8_LDA(At, 0, 0); PG8_STAGE(PG8_SA(1, 1), a1 + hstepA, voffA);
;             PG8_WAIT_V(8); PG8_WAIT_L(0); PG8_BAR; PG8_MMA(0, 0, At, B0); PG8_MMA(0, 1, At, B1); PG8_BAR; PG8_SCHED;
;             PG8_LDA(At, 0, 1); PG8_STAGE(PG8_SB(0, 0), b2, voffB); PG8_STAGE(PG8_SB(0, 1), b2 + hstepB, voffB); PG8_STAGE(PG8_SA(0, 0), a2, voffA);
;             PG8_WAIT_V(8); PG8_WAIT_L(0); PG8_BAR; PG8_MMA(1, 0, At, B0); PG8_MMA(1, 1, At, B1); PG8_BAR; PG8_SCHED;
;             PG8_LDB(B0, 1, 0); PG8_LDB(B1, 1, 1); PG8_SCHED; PG8_LDA(At, 1, 0); PG8_STAGE(PG8_SA(0, 1), a2 + hstepA, voffA);
;             PG8_WAIT_V(8); PG8_WAIT_L(0); PG8_BAR; PG8_MMA(0, 0, At, B0); PG8_MMA(0, 1, At, B1); PG8_BAR; PG8_SCHED;
;             PG8_LDA(At, 1, 1); PG8_STAGE(PG8_SB(1, 0), b3, voffB); PG8_STAGE(PG8_SB(1, 1), b3 + hstepB, voffB); PG8_STAGE(PG8_SA(1, 0), a3, voffA);
;             PG8_WAIT_V(8); PG8_WAIT_L(0); PG8_BAR; PG8_MMA(1, 0, At, B0); PG8_MMA(1, 1, At, B1); PG8_BAR; PG8_SCHED;
	s_add_i32 s52, s40, s11
	s_mov_b64 vcc, 0x180
	s_add_i32 s40, s52, 0x2000
	v_lshl_add_u64 v[184:185], v[184:185], 0, vcc
	s_mov_b32 m0, s52
	s_add_u32 s62, s34, 0x10180
	ds_read_b128 v[172:175], v146 offset:49152
	ds_read_b128 v[176:179], v146 offset:50176
	ds_read_b128 v[188:191], v146 offset:51200
	ds_read_b128 v[192:195], v146 offset:52224
	ds_read_b128 v[196:199], v146 offset:53248
	ds_read_b128 v[200:203], v146 offset:54272
	ds_read_b128 v[204:207], v146 offset:55296
	ds_read_b128 v[208:211], v146 offset:56320
	global_load_lds_dwordx4 v[184:185], off
	v_lshl_add_u64 v[184:185], v[212:213], 0, vcc
	s_mov_b32 m0, s40
	s_addc_u32 s63, s35, 0
	s_add_i32 s34, s64, s11
	global_load_lds_dwordx4 v[184:185], off
	v_lshl_add_u64 v[184:185], s[62:63], 0, v[132:133]
	s_mov_b32 m0, s34
	s_add_i32 s35, s34, 0x2000
	global_load_lds_dwordx4 v[184:185], off
	v_lshl_add_u64 v[184:185], s[62:63], 0, v[136:137]
	s_mov_b32 m0, s35
	s_nop 0
	global_load_lds_dwordx4 v[184:185], off
	v_lshl_add_u64 v[184:185], v[214:215], 0, vcc
	s_mov_b32 m0, s68
	s_nop 0
	global_load_lds_dwordx4 v[184:185], off
	v_lshl_add_u64 v[184:185], v[216:217], 0, vcc
	s_mov_b32 m0, s69
	s_nop 0
	global_load_lds_dwordx4 v[184:185], off
	s_waitcnt vmcnt(8)
	s_waitcnt lgkmcnt(0)
	s_barrier
	s_setprio 1
	v_mfma_f32_16x16x32_bf16 v[2:5], v[26:29], v[204:207], v[2:5]
	v_mfma_f32_16x16x32_bf16 v[6:9], v[114:117], v[204:207], v[6:9]
	v_mfma_f32_16x16x32_bf16 v[138:141], v[26:29], v[172:175], v[138:141]
	v_mfma_f32_16x16x32_bf16 v[142:145], v[114:117], v[172:175], v[142:145]
	v_mfma_f32_16x16x32_bf16 v[148:151], v[26:29], v[188:191], v[148:151]
	v_mfma_f32_16x16x32_bf16 v[152:155], v[114:117], v[188:191], v[152:155]
	v_mfma_f32_16x16x32_bf16 v[156:159], v[26:29], v[196:199], v[156:159]
	v_mfma_f32_16x16x32_bf16 v[160:163], v[114:117], v[196:199], v[160:163]
	v_mfma_f32_16x16x32_bf16 v[2:5], v[30:33], v[208:211], v[2:5]
	v_mfma_f32_16x16x32_bf16 v[6:9], v[118:121], v[208:211], v[6:9]
	v_mfma_f32_16x16x32_bf16 v[138:141], v[30:33], v[176:179], v[138:141]
	v_mfma_f32_16x16x32_bf16 v[142:145], v[118:121], v[176:179], v[142:145]
	v_mfma_f32_16x16x32_bf16 v[148:151], v[30:33], v[192:195], v[148:151]
	v_mfma_f32_16x16x32_bf16 v[152:155], v[118:121], v[192:195], v[152:155]
	v_mfma_f32_16x16x32_bf16 v[156:159], v[30:33], v[200:203], v[156:159]
	v_mfma_f32_16x16x32_bf16 v[160:163], v[118:121], v[200:203], v[160:163]
	v_mfma_f32_16x16x32_bf16 v[10:13], v[122:125], v[172:175], v[10:13]
	v_mfma_f32_16x16x32_bf16 v[14:17], v[164:167], v[172:175], v[14:17]
	v_mfma_f32_16x16x32_bf16 v[26:29], v[122:125], v[188:191], v[62:65]
	v_mfma_f32_16x16x32_bf16 v[30:33], v[164:167], v[188:191], v[102:105]
	v_mfma_f32_16x16x32_bf16 v[62:65], v[122:125], v[196:199], v[106:109]
	v_mfma_f32_16x16x32_bf16 v[102:105], v[164:167], v[196:199], v[110:113]
	v_mfma_f32_16x16x32_bf16 v[18:21], v[122:125], v[204:207], v[18:21]
	v_mfma_f32_16x16x32_bf16 v[22:25], v[164:167], v[204:207], v[22:25]
	v_mfma_f32_16x16x32_bf16 v[10:13], v[126:129], v[176:179], v[10:13]
	v_mfma_f32_16x16x32_bf16 v[14:17], v[168:171], v[176:179], v[14:17]
	v_mfma_f32_16x16x32_bf16 v[26:29], v[126:129], v[192:195], v[26:29]
	v_mfma_f32_16x16x32_bf16 v[30:33], v[168:171], v[192:195], v[30:33]
	v_mfma_f32_16x16x32_bf16 v[62:65], v[126:129], v[200:203], v[62:65]
	v_mfma_f32_16x16x32_bf16 v[102:105], v[168:171], v[200:203], v[102:105]
	v_mfma_f32_16x16x32_bf16 v[18:21], v[126:129], v[208:211], v[18:21]
	v_mfma_f32_16x16x32_bf16 v[22:25], v[168:171], v[208:211], v[22:25]
	s_setprio 0
	s_barrier
	ds_read_b128 v[106:109], v147
	ds_read_b128 v[110:113], v147 offset:1024
	ds_read_b128 v[114:117], v147 offset:2048
	ds_read_b128 v[118:121], v147 offset:3072
	ds_read_b128 v[122:125], v181
	ds_read_b128 v[126:129], v181 offset:1024
	ds_read_b128 v[164:167], v181 offset:2048
	ds_read_b128 v[168:171], v181 offset:3072
	s_add_u32 s30, s30, 0x80180
	s_addc_u32 s31, s31, 0
	s_mov_b32 m0, s41
	v_lshl_add_u64 v[184:185], s[30:31], 0, v[130:131]
	ds_read_b128 v[172:175], v146
	ds_read_b128 v[176:179], v146 offset:1024
	ds_read_b128 v[188:191], v146 offset:2048
	ds_read_b128 v[192:195], v146 offset:3072
	ds_read_b128 v[196:199], v146 offset:4096
	ds_read_b128 v[200:203], v146 offset:5120
	ds_read_b128 v[204:207], v146 offset:6144
	ds_read_b128 v[208:211], v146 offset:7168
	global_load_lds_dwordx4 v[184:185], off
	v_lshl_add_u64 v[184:185], s[30:31], 0, v[134:135]
	s_mov_b32 m0, s1
	s_nop 0
	global_load_lds_dwordx4 v[184:185], off
	s_waitcnt vmcnt(8)
	s_waitcnt lgkmcnt(0)
	s_barrier
; #define PG8_STAGE(bufoff, gbase, voff) do { _Pragma("unroll") for (int _i = 0; _i < 2; ++_i) \
;         __builtin_amdgcn_global_load_lds((const unsigned*)((const char*)(gbase) + (voff)[_i]), (LAS unsigned*)(lds + (bufoff) + ldsw + _i * 8192), 16, 0, 0); } while (0)
; #define PG8_LDA(dst, b, h) do { _Pragma("unroll") for (int m = 0; m < 4; ++m) _Pragma("unroll") for (int k = 0; k < 2; ++k) dst[m][k] = *(const LAS bf16x8*)(lds + PG8_SA(b, h) + aoff + m * 2048 + k * 1024); } while (0)
; #define PG8_MMA(ai, bj, At, Bt) do { __builtin_amdgcn_s_setprio(1); _Pragma("unroll") for (int m = 0; m < 4; ++m) _Pragma("unroll") for (int n = 0; n < 2; ++n) _Pragma("unroll") for (int k = 0; k < 2; ++k) \
;         acc[ai][bj][m][n] = __builtin_amdgcn_mfma_f32_16x16x32_bf16(Bt[n][k], At[m][k], acc[ai][bj][m][n], 0, 0, 0); __builtin_amdgcn_s_setprio(0); } while (0)
; #define PG8_WAIT_V(n) asm volatile("s_waitcnt vmcnt(" #n ")" ::: "memory")
; #define PG8_WAIT_L(n) asm volatile("s_waitcnt lgkmcnt(" #n ")" ::: "memory")
; #define PG8_BAR __builtin_amdgcn_s_barrier()
; #define PG8_SCHED __builtin_amdgcn_sched_barrier(0)
; template <class Epi>
; __device__ __forceinline__ void gemm_phase(LAS unsigned char* lds, const Gemm g, const StaticOrder& S, const Epi& E) {
;     ...
;             PG8_WAIT_V(8); PG8_WAIT_L(0); PG8_BAR; PG8_MMA(0, 0, At, B0); PG8_MMA(0, 1, At, B1); PG8_BAR; PG8_SCHED;
;             PG8_LDA(At, 0, 1); PG8_STAGE(PG8_SB(0, 0), b2, voffB); PG8_STAGE(PG8_SB(0, 1), b2 + hstepB, voffB); PG8_STAGE(PG8_SA(0, 0), a2, voffA);
;             PG8_WAIT_V(8); PG8_WAIT_L(0); PG8_BAR; PG8_MMA(1, 0, At, B0); PG8_MMA(1, 1, At, B1); PG8_BAR; PG8_SCHED;
	s_setprio 1
	v_mfma_f32_16x16x32_bf16 v[90:93], v[106:109], v[204:207], v[90:93]
	v_mfma_f32_16x16x32_bf16 v[66:69], v[106:109], v[172:175], v[66:69]
	v_mfma_f32_16x16x32_bf16 v[70:73], v[114:117], v[172:175], v[70:73]
	v_mfma_f32_16x16x32_bf16 v[74:77], v[106:109], v[188:191], v[74:77]
	v_mfma_f32_16x16x32_bf16 v[78:81], v[114:117], v[188:191], v[78:81]
	v_mfma_f32_16x16x32_bf16 v[82:85], v[106:109], v[196:199], v[82:85]
	v_mfma_f32_16x16x32_bf16 v[86:89], v[114:117], v[196:199], v[86:89]
	v_mfma_f32_16x16x32_bf16 v[212:215], v[110:113], v[208:211], v[90:93]
	v_mfma_f32_16x16x32_bf16 v[90:93], v[114:117], v[204:207], v[94:97]
	v_mfma_f32_16x16x32_bf16 v[66:69], v[110:113], v[176:179], v[66:69]
	v_mfma_f32_16x16x32_bf16 v[70:73], v[118:121], v[176:179], v[70:73]
	v_mfma_f32_16x16x32_bf16 v[74:77], v[110:113], v[192:195], v[74:77]
	v_mfma_f32_16x16x32_bf16 v[78:81], v[118:121], v[192:195], v[78:81]
	v_mfma_f32_16x16x32_bf16 v[82:85], v[110:113], v[200:203], v[82:85]
	v_mfma_f32_16x16x32_bf16 v[86:89], v[118:121], v[200:203], v[86:89]
	v_mfma_f32_16x16x32_bf16 v[94:97], v[118:121], v[208:211], v[90:93]
	v_mfma_f32_16x16x32_bf16 v[90:93], v[122:125], v[172:175], v[98:101]
	v_mfma_f32_16x16x32_bf16 v[34:37], v[164:167], v[172:175], v[34:37]
	v_mfma_f32_16x16x32_bf16 v[38:41], v[122:125], v[188:191], v[38:41]
	v_mfma_f32_16x16x32_bf16 v[42:45], v[164:167], v[188:191], v[42:45]
	v_mfma_f32_16x16x32_bf16 v[46:49], v[122:125], v[196:199], v[46:49]
	v_mfma_f32_16x16x32_bf16 v[50:53], v[164:167], v[196:199], v[50:53]
	v_mfma_f32_16x16x32_bf16 v[54:57], v[122:125], v[204:207], v[54:57]
	v_mfma_f32_16x16x32_bf16 v[58:61], v[164:167], v[204:207], v[58:61]
	v_mfma_f32_16x16x32_bf16 v[98:101], v[126:129], v[176:179], v[90:93]
	v_mfma_f32_16x16x32_bf16 v[34:37], v[168:171], v[176:179], v[34:37]
	v_mfma_f32_16x16x32_bf16 v[38:41], v[126:129], v[192:195], v[38:41]
	v_mfma_f32_16x16x32_bf16 v[42:45], v[168:171], v[192:195], v[42:45]
	v_mfma_f32_16x16x32_bf16 v[46:49], v[126:129], v[200:203], v[46:49]
	v_mfma_f32_16x16x32_bf16 v[50:53], v[168:171], v[200:203], v[50:53]
	v_mfma_f32_16x16x32_bf16 v[54:57], v[126:129], v[208:211], v[54:57]
	v_mfma_f32_16x16x32_bf16 v[58:61], v[168:171], v[208:211], v[58:61]
	s_setprio 0
	s_barrier
	s_mov_b32 m0, s33
	v_lshl_add_u64 v[184:185], s[6:7], 0, v[132:133]
	s_add_u32 s30, s6, 0x10000
	ds_read_b128 v[90:93], v146 offset:16384
	ds_read_b128 v[172:175], v146 offset:17408
	ds_read_b128 v[176:179], v146 offset:18432
	ds_read_b128 v[188:191], v146 offset:19456
	ds_read_b128 v[192:195], v146 offset:20480
	ds_read_b128 v[196:199], v146 offset:21504
	ds_read_b128 v[200:203], v146 offset:22528
	ds_read_b128 v[204:207], v146 offset:23552
	global_load_lds_dwordx4 v[184:185], off
	v_lshl_add_u64 v[244:245], s[6:7], 0, v[136:137]
	s_mov_b32 m0, s3
	s_addc_u32 s31, s7, 0
	global_load_lds_dwordx4 v[244:245], off
	v_lshl_add_u64 v[208:209], s[30:31], 0, v[132:133]
	s_mov_b32 m0, s21
	v_lshl_add_u64 v[246:247], s[24:25], 0, v[130:131]
	global_load_lds_dwordx4 v[208:209], off
	v_lshl_add_u64 v[208:209], s[30:31], 0, v[136:137]
	s_mov_b32 m0, s23
	v_lshl_add_u64 v[248:249], s[24:25], 0, v[134:135]
	global_load_lds_dwordx4 v[208:209], off
	s_mov_b32 m0, s14
	s_nop 0
	global_load_lds_dwordx4 v[246:247], off
	s_mov_b32 m0, s15
	s_nop 0
	global_load_lds_dwordx4 v[248:249], off
	s_waitcnt vmcnt(8)
	s_waitcnt lgkmcnt(0)
	s_barrier
	s_setprio 1
	v_mfma_f32_16x16x32_bf16 v[2:5], v[106:109], v[200:203], v[2:5]
	v_mfma_f32_16x16x32_bf16 v[6:9], v[114:117], v[200:203], v[6:9]
	v_mfma_f32_16x16x32_bf16 v[138:141], v[106:109], v[90:93], v[138:141]
	v_mfma_f32_16x16x32_bf16 v[142:145], v[114:117], v[90:93], v[142:145]
	v_mfma_f32_16x16x32_bf16 v[148:151], v[106:109], v[176:179], v[148:151]
	v_mfma_f32_16x16x32_bf16 v[152:155], v[114:117], v[176:179], v[152:155]
	v_mfma_f32_16x16x32_bf16 v[156:159], v[106:109], v[192:195], v[156:159]
	v_mfma_f32_16x16x32_bf16 v[160:163], v[114:117], v[192:195], v[160:163]
	v_mfma_f32_16x16x32_bf16 v[2:5], v[110:113], v[204:207], v[2:5]
	v_mfma_f32_16x16x32_bf16 v[6:9], v[118:121], v[204:207], v[6:9]
	v_mfma_f32_16x16x32_bf16 v[138:141], v[110:113], v[172:175], v[138:141]
	v_mfma_f32_16x16x32_bf16 v[142:145], v[118:121], v[172:175], v[142:145]
	v_mfma_f32_16x16x32_bf16 v[148:151], v[110:113], v[188:191], v[148:151]
	v_mfma_f32_16x16x32_bf16 v[152:155], v[118:121], v[188:191], v[152:155]
	v_mfma_f32_16x16x32_bf16 v[156:159], v[110:113], v[196:199], v[156:159]
	v_mfma_f32_16x16x32_bf16 v[160:163], v[118:121], v[196:199], v[160:163]
	v_mfma_f32_16x16x32_bf16 v[10:13], v[122:125], v[90:93], v[10:13]
	v_mfma_f32_16x16x32_bf16 v[208:211], v[126:129], v[172:175], v[10:13]
	v_mfma_f32_16x16x32_bf16 v[10:13], v[164:167], v[90:93], v[14:17]
	v_mfma_f32_16x16x32_bf16 v[14:17], v[168:171], v[172:175], v[10:13]
	v_mfma_f32_16x16x32_bf16 v[10:13], v[122:125], v[176:179], v[26:29]
	v_mfma_f32_16x16x32_bf16 v[172:175], v[126:129], v[188:191], v[10:13]
	v_mfma_f32_16x16x32_bf16 v[10:13], v[164:167], v[176:179], v[30:33]
	v_mfma_f32_16x16x32_bf16 v[30:33], v[168:171], v[188:191], v[10:13]
	v_mfma_f32_16x16x32_bf16 v[10:13], v[122:125], v[192:195], v[62:65]
	v_mfma_f32_16x16x32_bf16 v[176:179], v[126:129], v[196:199], v[10:13]
	v_mfma_f32_16x16x32_bf16 v[10:13], v[164:167], v[192:195], v[102:105]
	v_mfma_f32_16x16x32_bf16 v[188:191], v[168:171], v[196:199], v[10:13]
	v_mfma_f32_16x16x32_bf16 v[10:13], v[122:125], v[200:203], v[18:21]
	v_mfma_f32_16x16x32_bf16 v[192:195], v[126:129], v[204:207], v[10:13]
	v_mfma_f32_16x16x32_bf16 v[10:13], v[164:167], v[200:203], v[22:25]
	v_mfma_f32_16x16x32_bf16 v[164:167], v[168:171], v[204:207], v[10:13]
	s_setprio 0
	s_barrier
; #define PG8_STAGE(bufoff, gbase, voff) do { _Pragma("unroll") for (int _i = 0; _i < 2; ++_i) \
;         __builtin_amdgcn_global_load_lds((const unsigned*)((const char*)(gbase) + (voff)[_i]), (LAS unsigned*)(lds + (bufoff) + ldsw + _i * 8192), 16, 0, 0); } while (0)
; #define PG8_LDA(dst, b, h) do { _Pragma("unroll") for (int m = 0; m < 4; ++m) _Pragma("unroll") for (int k = 0; k < 2; ++k) dst[m][k] = *(const LAS bf16x8*)(lds + PG8_SA(b, h) + aoff + m * 2048 + k * 1024); } while (0)
; #define PG8_LDB(dst, b, h) do { _Pragma("unroll") for (int n = 0; n < 2; ++n) _Pragma("unroll") for (int k = 0; k < 2; ++k) dst[n][k] = *(const LAS bf16x8*)(lds + PG8_SB(b, h) + boff + n * 2048 + k * 1024); } while (0)
; #define PG8_MMA(ai, bj, At, Bt) do { __builtin_amdgcn_s_setprio(1); _Pragma("unroll") for (int m = 0; m < 4; ++m) _Pragma("unroll") for (int n = 0; n < 2; ++n) _Pragma("unroll") for (int k = 0; k < 2; ++k) \
;         acc[ai][bj][m][n] = __builtin_amdgcn_mfma_f32_16x16x32_bf16(Bt[n][k], At[m][k], acc[ai][bj][m][n], 0, 0, 0); __builtin_amdgcn_s_setprio(0); } while (0)
; #define PG8_WAIT_V(n) asm volatile("s_waitcnt vmcnt(" #n ")" ::: "memory")
; #define PG8_WAIT_L(n) asm volatile("s_waitcnt lgkmcnt(" #n ")" ::: "memory")
; #define PG8_BAR __builtin_amdgcn_s_barrier()
; #define PG8_SCHED __builtin_amdgcn_sched_barrier(0)
; template <class Epi>
; __device__ __forceinline__ void gemm_phase(LAS unsigned char* lds, const Gemm g, const StaticOrder& S, const Epi& E) {
;     ...
;             PG8_LDB(B0, 1, 0); PG8_LDB(B1, 1, 1); PG8_SCHED; PG8_LDA(At, 1, 0); PG8_STAGE(PG8_SA(0, 1), a2 + hstepA, voffA);
;             PG8_WAIT_V(8); PG8_WAIT_L(0); PG8_BAR; PG8_MMA(0, 0, At, B0); PG8_MMA(0, 1, At, B1); PG8_BAR; PG8_SCHED;
;             PG8_LDA(At, 1, 1); PG8_STAGE(PG8_SB(1, 0), b3, voffB); PG8_STAGE(PG8_SB(1, 1), b3 + hstepB, voffB); PG8_STAGE(PG8_SA(1, 0), a3, voffA);
;             PG8_WAIT_V(8); PG8_WAIT_L(0); PG8_BAR; PG8_MMA(1, 0, At, B0); PG8_MMA(1, 1, At, B1); PG8_BAR; PG8_SCHED;
;         }
;         if (wr == 0) PG8_BAR;
	s_nop 4
	ds_read_b128 v[10:13], v183
	ds_read_b128 v[18:21], v183 offset:1024
	ds_read_b128 v[62:65], v183 offset:2048
	ds_read_b128 v[168:171], v183 offset:3072
	ds_read_b128 v[196:199], v186
	ds_read_b128 v[200:203], v186 offset:1024
	ds_read_b128 v[204:207], v186 offset:2048
	ds_read_b128 v[216:219], v186 offset:3072
	s_add_u32 s30, s24, 0x80000
	s_addc_u32 s31, s25, 0
	s_mov_b32 m0, s29
	v_lshl_add_u64 v[90:91], s[30:31], 0, v[130:131]
	ds_read_b128 v[22:25], v146 offset:32768
	ds_read_b128 v[26:29], v146 offset:33792
	ds_read_b128 v[220:223], v146 offset:34816
	ds_read_b128 v[224:227], v146 offset:35840
	ds_read_b128 v[228:231], v146 offset:36864
	ds_read_b128 v[232:235], v146 offset:37888
	ds_read_b128 v[236:239], v146 offset:38912
	ds_read_b128 v[240:243], v146 offset:39936
	global_load_lds_dwordx4 v[90:91], off
	v_lshl_add_u64 v[90:91], s[30:31], 0, v[134:135]
	s_mov_b32 m0, s42
	s_nop 0
	global_load_lds_dwordx4 v[90:91], off
	s_waitcnt vmcnt(8)
	s_waitcnt lgkmcnt(0)
	s_barrier
	s_setprio 1
	v_mfma_f32_16x16x32_bf16 v[66:69], v[10:13], v[22:25], v[66:69]
	v_mfma_f32_16x16x32_bf16 v[126:129], v[18:21], v[26:29], v[66:69]
	v_mfma_f32_16x16x32_bf16 v[66:69], v[62:65], v[22:25], v[70:73]
	v_mfma_f32_16x16x32_bf16 v[118:121], v[168:171], v[26:29], v[66:69]
	v_mfma_f32_16x16x32_bf16 v[66:69], v[10:13], v[220:223], v[74:77]
	v_mfma_f32_16x16x32_bf16 v[106:109], v[18:21], v[224:227], v[66:69]
	v_mfma_f32_16x16x32_bf16 v[66:69], v[62:65], v[220:223], v[78:81]
	v_mfma_f32_16x16x32_bf16 v[102:105], v[168:171], v[224:227], v[66:69]
	v_mfma_f32_16x16x32_bf16 v[66:69], v[10:13], v[228:231], v[82:85]
	v_mfma_f32_16x16x32_bf16 v[90:93], v[18:21], v[232:235], v[66:69]
	v_mfma_f32_16x16x32_bf16 v[66:69], v[62:65], v[228:231], v[86:89]
	v_mfma_f32_16x16x32_bf16 v[86:89], v[168:171], v[232:235], v[66:69]
	v_mfma_f32_16x16x32_bf16 v[66:69], v[10:13], v[236:239], v[212:215]
	v_mfma_f32_16x16x32_bf16 v[74:77], v[18:21], v[240:243], v[66:69]
	v_mfma_f32_16x16x32_bf16 v[66:69], v[62:65], v[236:239], v[94:97]
	v_mfma_f32_16x16x32_bf16 v[70:73], v[168:171], v[240:243], v[66:69]
	v_mfma_f32_16x16x32_bf16 v[66:69], v[196:199], v[22:25], v[98:101]
	v_mfma_f32_16x16x32_bf16 v[22:25], v[204:207], v[22:25], v[34:37]
	v_mfma_f32_16x16x32_bf16 v[114:117], v[216:219], v[26:29], v[22:25]
	v_mfma_f32_16x16x32_bf16 v[22:25], v[196:199], v[220:223], v[38:41]
	v_mfma_f32_16x16x32_bf16 v[110:113], v[200:203], v[224:227], v[22:25]
	v_mfma_f32_16x16x32_bf16 v[22:25], v[204:207], v[220:223], v[42:45]
	v_mfma_f32_16x16x32_bf16 v[98:101], v[216:219], v[224:227], v[22:25]
	v_mfma_f32_16x16x32_bf16 v[22:25], v[196:199], v[228:231], v[46:49]
	v_mfma_f32_16x16x32_bf16 v[94:97], v[200:203], v[232:235], v[22:25]
	v_mfma_f32_16x16x32_bf16 v[22:25], v[204:207], v[228:231], v[50:53]
	v_mfma_f32_16x16x32_bf16 v[82:85], v[216:219], v[232:235], v[22:25]
	v_mfma_f32_16x16x32_bf16 v[22:25], v[196:199], v[236:239], v[54:57]
	v_mfma_f32_16x16x32_bf16 v[78:81], v[200:203], v[240:243], v[22:25]
	v_mfma_f32_16x16x32_bf16 v[22:25], v[204:207], v[236:239], v[58:61]
	v_mfma_f32_16x16x32_bf16 v[122:125], v[200:203], v[26:29], v[66:69]
	v_mfma_f32_16x16x32_bf16 v[66:69], v[216:219], v[240:243], v[22:25]
	s_setprio 0
	s_barrier
	s_mov_b32 m0, s52
	s_nop 2
	v_lshl_add_u64 v[22:23], v[184:185], 0, s[84:85]
	s_add_u32 s6, s6, 0x10080
	ds_read_b128 v[34:37], v146 offset:49152
	ds_read_b128 v[46:49], v146 offset:50176
	ds_read_b128 v[212:215], v146 offset:51200
	ds_read_b128 v[220:223], v146 offset:52224
	ds_read_b128 v[224:227], v146 offset:53248
	ds_read_b128 v[228:231], v146 offset:54272
	ds_read_b128 v[232:235], v146 offset:55296
	ds_read_b128 v[236:239], v146 offset:56320
	global_load_lds_dwordx4 v[22:23], off
	v_lshl_add_u64 v[22:23], v[244:245], 0, s[84:85]
	s_mov_b32 m0, s40
	s_addc_u32 s7, s7, 0
	global_load_lds_dwordx4 v[22:23], off
	v_lshl_add_u64 v[22:23], s[6:7], 0, v[132:133]
	s_mov_b32 m0, s34
	s_nop 0
	global_load_lds_dwordx4 v[22:23], off
	v_lshl_add_u64 v[22:23], s[6:7], 0, v[136:137]
	s_mov_b32 m0, s35
	s_nop 0
	global_load_lds_dwordx4 v[22:23], off
	v_lshl_add_u64 v[22:23], v[246:247], 0, s[84:85]
	s_mov_b32 m0, s68
	s_nop 0
	global_load_lds_dwordx4 v[22:23], off
	v_lshl_add_u64 v[22:23], v[248:249], 0, s[84:85]
	s_mov_b32 m0, s69
	s_nop 0
	global_load_lds_dwordx4 v[22:23], off
	s_waitcnt vmcnt(8)
	s_waitcnt lgkmcnt(0)
	s_barrier
	s_setprio 1
	v_mfma_f32_16x16x32_bf16 v[22:25], v[10:13], v[34:37], v[138:141]
	v_mfma_f32_16x16x32_bf16 v[58:61], v[18:21], v[46:49], v[22:25]
	v_mfma_f32_16x16x32_bf16 v[22:25], v[62:65], v[34:37], v[142:145]
	v_mfma_f32_16x16x32_bf16 v[54:57], v[168:171], v[46:49], v[22:25]
	v_mfma_f32_16x16x32_bf16 v[22:25], v[10:13], v[212:215], v[148:151]
	v_mfma_f32_16x16x32_bf16 v[42:45], v[18:21], v[220:223], v[22:25]
	v_mfma_f32_16x16x32_bf16 v[22:25], v[62:65], v[212:215], v[152:155]
	v_mfma_f32_16x16x32_bf16 v[38:41], v[168:171], v[220:223], v[22:25]
	v_mfma_f32_16x16x32_bf16 v[22:25], v[10:13], v[224:227], v[156:159]
	v_mfma_f32_16x16x32_bf16 v[2:5], v[10:13], v[232:235], v[2:5]
	v_mfma_f32_16x16x32_bf16 v[26:29], v[18:21], v[228:231], v[22:25]
	v_mfma_f32_16x16x32_bf16 v[22:25], v[62:65], v[224:227], v[160:163]
	v_mfma_f32_16x16x32_bf16 v[10:13], v[18:21], v[236:239], v[2:5]
	v_mfma_f32_16x16x32_bf16 v[2:5], v[62:65], v[232:235], v[6:9]
	v_mfma_f32_16x16x32_bf16 v[22:25], v[168:171], v[228:231], v[22:25]
	v_mfma_f32_16x16x32_bf16 v[6:9], v[168:171], v[236:239], v[2:5]
	v_mfma_f32_16x16x32_bf16 v[2:5], v[196:199], v[34:37], v[208:211]
	v_mfma_f32_16x16x32_bf16 v[62:65], v[200:203], v[46:49], v[2:5]
	v_mfma_f32_16x16x32_bf16 v[2:5], v[204:207], v[34:37], v[14:17]
	v_mfma_f32_16x16x32_bf16 v[50:53], v[216:219], v[46:49], v[2:5]
	v_mfma_f32_16x16x32_bf16 v[2:5], v[196:199], v[212:215], v[172:175]
	v_mfma_f32_16x16x32_bf16 v[46:49], v[200:203], v[220:223], v[2:5]
	v_mfma_f32_16x16x32_bf16 v[2:5], v[204:207], v[212:215], v[30:33]
	v_mfma_f32_16x16x32_bf16 v[34:37], v[216:219], v[220:223], v[2:5]
	v_mfma_f32_16x16x32_bf16 v[2:5], v[196:199], v[224:227], v[176:179]
	v_mfma_f32_16x16x32_bf16 v[30:33], v[200:203], v[228:231], v[2:5]
	v_mfma_f32_16x16x32_bf16 v[2:5], v[204:207], v[224:227], v[188:191]
	v_mfma_f32_16x16x32_bf16 v[18:21], v[216:219], v[228:231], v[2:5]
	v_mfma_f32_16x16x32_bf16 v[2:5], v[196:199], v[232:235], v[192:195]
	v_mfma_f32_16x16x32_bf16 v[14:17], v[200:203], v[236:239], v[2:5]
	v_mfma_f32_16x16x32_bf16 v[2:5], v[204:207], v[232:235], v[164:167]
	v_mfma_f32_16x16x32_bf16 v[2:5], v[216:219], v[236:239], v[2:5]
	s_setprio 0
	s_barrier
	s_andn2_b64 vcc, exec, s[16:17]
	s_cbranch_vccnz .LBB0_684
	s_barrier

; #define PG8_STAGE(bufoff, gbase, voff) do { _Pragma("unroll") for (int _i = 0; _i < 2; ++_i) \
;         __builtin_amdgcn_global_load_lds((const unsigned*)((const char*)(gbase) + (voff)[_i]), (LAS unsigned*)(lds + (bufoff) + ldsw + _i * 8192), 16, 0, 0); } while (0)
; #define PG8_LDA(dst, b, h) do { _Pragma("unroll") for (int m = 0; m < 4; ++m) _Pragma("unroll") for (int k = 0; k < 2; ++k) dst[m][k] = *(const LAS bf16x8*)(lds + PG8_SA(b, h) + aoff + m * 2048 + k * 1024); } while (0)
; #define PG8_LDB(dst, b, h) do { _Pragma("unroll") for (int n = 0; n < 2; ++n) _Pragma("unroll") for (int k = 0; k < 2; ++k) dst[n][k] = *(const LAS bf16x8*)(lds + PG8_SB(b, h) + boff + n * 2048 + k * 1024); } while (0)
; #define PG8_MMA(ai, bj, At, Bt) do { __builtin_amdgcn_s_setprio(1); _Pragma("unroll") for (int m = 0; m < 4; ++m) _Pragma("unroll") for (int n = 0; n < 2; ++n) _Pragma("unroll") for (int k = 0; k < 2; ++k) \
;         acc[ai][bj][m][n] = __builtin_amdgcn_mfma_f32_16x16x32_bf16(Bt[n][k], At[m][k], acc[ai][bj][m][n], 0, 0, 0); __builtin_amdgcn_s_setprio(0); } while (0)
; #define PG8_WAIT_V(n) asm volatile("s_waitcnt vmcnt(" #n ")" ::: "memory")
; #define PG8_WAIT_L(n) asm volatile("s_waitcnt lgkmcnt(" #n ")" ::: "memory")
; #define PG8_BAR __builtin_amdgcn_s_barrier()
; #define PG8_SCHED __builtin_amdgcn_sched_barrier(0)
; template <class Epi>
; __device__ __forceinline__ void gemm_phase(LAS unsigned char* lds, const Gemm g, const StaticOrder& S, const Epi& E) {
;     ...
;             const bool last = (t == nt - 2);
;             const char* a1 = cA + (size_t)(t + 1) * kstep;
;             const char* a2 = last ? nA : cA + (size_t)(t + 2) * kstep; const char* b2 = last ? nB : cB + (size_t)(t + 2) * kstep;
;             const char* a3 = a2 + kstep; const char* b3 = b2 + kstep;
;             PG8_LDB(B0, 0, 0); PG8_LDB(B1, 0, 1); PG8_SCHED; PG8_LDA(At, 0, 0); PG8_STAGE(PG8_SA(1, 1), a1 + hstepA, voffA);
;             PG8_WAIT_V(8); PG8_WAIT_L(0); PG8_BAR; PG8_MMA(0, 0, At, B0); PG8_MMA(0, 1, At, B1); PG8_BAR; PG8_SCHED;
;             PG8_LDA(At, 0, 1); PG8_STAGE(PG8_SB(0, 0), b2, voffB); PG8_STAGE(PG8_SB(0, 1), b2 + hstepB, voffB); PG8_STAGE(PG8_SA(0, 0), a2, voffA);
;             PG8_WAIT_V(8); PG8_WAIT_L(0); PG8_BAR; PG8_MMA(1, 0, At, B0); PG8_MMA(1, 1, At, B1); PG8_BAR; PG8_SCHED;
.LBB0_1010:
	s_add_u32 s14, s26, 0xfff80080
	s_addc_u32 s15, s27, -1
	s_add_i32 s41, 0, 0x10000
	s_cmp_eq_u32 s52, 28
	s_cselect_b32 s29, s1, s15
	s_cselect_b32 s28, s3, s14
	s_cselect_b32 s15, s7, s40
	s_cselect_b32 s14, s17, s19
	s_add_i32 s53, 0, 0x14000
	v_add_u32_e32 v142, s41, v1
	v_add_u32_e32 v158, s53, v1
	ds_read_b128 v[130:133], v142
	ds_read_b128 v[134:137], v142 offset:1024
	ds_read_b128 v[138:141], v142 offset:2048
	ds_read_b128 v[142:145], v142 offset:3072
	ds_read_b128 v[146:149], v158
	ds_read_b128 v[150:153], v158 offset:1024
	ds_read_b128 v[154:157], v158 offset:2048
	ds_read_b128 v[158:161], v158 offset:3072
	v_lshl_add_u64 v[178:179], s[26:27], 0, v[196:197]
	s_add_i32 m0, s25, 0xc000
	ds_read_b128 v[162:165], v181
	ds_read_b128 v[166:169], v181 offset:1024
	ds_read_b128 v[170:173], v181 offset:2048
	ds_read_b128 v[174:177], v181 offset:3072
	ds_read_b128 v[200:203], v181 offset:4096
	ds_read_b128 v[204:207], v181 offset:5120
	ds_read_b128 v[208:211], v181 offset:6144
	ds_read_b128 v[212:215], v181 offset:7168
	global_load_lds_dwordx4 v[178:179], off
	v_lshl_add_u64 v[178:179], s[26:27], 0, v[198:199]
	s_add_i32 m0, s25, 0xe000
	s_nop 0
	global_load_lds_dwordx4 v[178:179], off
	s_waitcnt vmcnt(8)
	s_waitcnt lgkmcnt(0)
	s_barrier
	s_setprio 1
	v_mfma_f32_16x16x32_bf16 v[126:129], v[130:133], v[162:165], v[126:129]
	v_mfma_f32_16x16x32_bf16 v[122:125], v[138:141], v[162:165], v[122:125]
	v_mfma_f32_16x16x32_bf16 v[110:113], v[130:133], v[170:173], v[110:113]
	v_mfma_f32_16x16x32_bf16 v[106:109], v[138:141], v[170:173], v[106:109]
	v_mfma_f32_16x16x32_bf16 v[94:97], v[130:133], v[200:203], v[94:97]
	v_mfma_f32_16x16x32_bf16 v[90:93], v[138:141], v[200:203], v[90:93]
	v_mfma_f32_16x16x32_bf16 v[82:85], v[130:133], v[208:211], v[82:85]
	v_mfma_f32_16x16x32_bf16 v[74:77], v[138:141], v[208:211], v[74:77]
	v_mfma_f32_16x16x32_bf16 v[126:129], v[134:137], v[166:169], v[126:129]
	v_mfma_f32_16x16x32_bf16 v[122:125], v[142:145], v[166:169], v[122:125]
	v_mfma_f32_16x16x32_bf16 v[110:113], v[134:137], v[174:177], v[110:113]
	v_mfma_f32_16x16x32_bf16 v[106:109], v[142:145], v[174:177], v[106:109]
	v_mfma_f32_16x16x32_bf16 v[94:97], v[134:137], v[204:207], v[94:97]
	v_mfma_f32_16x16x32_bf16 v[90:93], v[142:145], v[204:207], v[90:93]
	v_mfma_f32_16x16x32_bf16 v[82:85], v[134:137], v[212:215], v[82:85]
	v_mfma_f32_16x16x32_bf16 v[74:77], v[142:145], v[212:215], v[74:77]
	v_mfma_f32_16x16x32_bf16 v[118:121], v[146:149], v[162:165], v[118:121]
	v_mfma_f32_16x16x32_bf16 v[114:117], v[154:157], v[162:165], v[114:117]
	v_mfma_f32_16x16x32_bf16 v[102:105], v[146:149], v[170:173], v[102:105]
	v_mfma_f32_16x16x32_bf16 v[98:101], v[154:157], v[170:173], v[98:101]
	v_mfma_f32_16x16x32_bf16 v[86:89], v[146:149], v[200:203], v[86:89]
	v_mfma_f32_16x16x32_bf16 v[78:81], v[154:157], v[200:203], v[78:81]
	v_mfma_f32_16x16x32_bf16 v[70:73], v[146:149], v[208:211], v[70:73]
	v_mfma_f32_16x16x32_bf16 v[66:69], v[154:157], v[208:211], v[66:69]
	v_mfma_f32_16x16x32_bf16 v[118:121], v[150:153], v[166:169], v[118:121]
	v_mfma_f32_16x16x32_bf16 v[114:117], v[158:161], v[166:169], v[114:117]
	v_mfma_f32_16x16x32_bf16 v[102:105], v[150:153], v[174:177], v[102:105]
	v_mfma_f32_16x16x32_bf16 v[98:101], v[158:161], v[174:177], v[98:101]
	v_mfma_f32_16x16x32_bf16 v[86:89], v[150:153], v[204:207], v[86:89]
	v_mfma_f32_16x16x32_bf16 v[78:81], v[158:161], v[204:207], v[78:81]
	v_mfma_f32_16x16x32_bf16 v[70:73], v[150:153], v[212:215], v[70:73]
	v_mfma_f32_16x16x32_bf16 v[66:69], v[158:161], v[212:215], v[66:69]
	s_setprio 0
	s_barrier
	s_add_i32 s41, s41, s30
	v_lshl_add_u64 v[178:179], s[14:15], 0, v[190:191]
	s_mov_b32 m0, s41
	ds_read_b128 v[162:165], v181 offset:16384
	ds_read_b128 v[166:169], v181 offset:17408
	ds_read_b128 v[170:173], v181 offset:18432
	ds_read_b128 v[174:177], v181 offset:19456
	ds_read_b128 v[200:203], v181 offset:20480
	ds_read_b128 v[204:207], v181 offset:21504
	ds_read_b128 v[208:211], v181 offset:22528
	ds_read_b128 v[212:215], v181 offset:23552
	global_load_lds_dwordx4 v[178:179], off
	s_add_i32 m0, s41, 0x2000
	s_add_u32 s62, s14, 0x80000
	v_lshl_add_u64 v[184:185], s[14:15], 0, v[194:195]
	s_addc_u32 s63, s15, 0
	s_add_i32 s41, s53, s30
	global_load_lds_dwordx4 v[184:185], off
	v_lshl_add_u64 v[216:217], s[62:63], 0, v[190:191]
	s_mov_b32 m0, s41
	v_lshl_add_u64 v[218:219], s[28:29], 0, v[192:193]
	global_load_lds_dwordx4 v[216:217], off
	v_lshl_add_u64 v[216:217], s[62:63], 0, v[194:195]
	s_add_i32 m0, s41, 0x2000
	s_nop 0
	global_load_lds_dwordx4 v[216:217], off
	v_lshl_add_u64 v[216:217], s[28:29], 0, v[188:189]
	s_mov_b32 m0, s25
	s_nop 0
	global_load_lds_dwordx4 v[216:217], off
	s_mov_b32 m0, s31
	s_nop 0
	global_load_lds_dwordx4 v[218:219], off
	s_waitcnt vmcnt(8)
	s_waitcnt lgkmcnt(0)
	s_barrier
; #define PG8_STAGE(bufoff, gbase, voff) do { _Pragma("unroll") for (int _i = 0; _i < 2; ++_i) \
;         __builtin_amdgcn_global_load_lds((const unsigned*)((const char*)(gbase) + (voff)[_i]), (LAS unsigned*)(lds + (bufoff) + ldsw + _i * 8192), 16, 0, 0); } while (0)
; #define PG8_LDA(dst, b, h) do { _Pragma("unroll") for (int m = 0; m < 4; ++m) _Pragma("unroll") for (int k = 0; k < 2; ++k) dst[m][k] = *(const LAS bf16x8*)(lds + PG8_SA(b, h) + aoff + m * 2048 + k * 1024); } while (0)
; #define PG8_LDB(dst, b, h) do { _Pragma("unroll") for (int n = 0; n < 2; ++n) _Pragma("unroll") for (int k = 0; k < 2; ++k) dst[n][k] = *(const LAS bf16x8*)(lds + PG8_SB(b, h) + boff + n * 2048 + k * 1024); } while (0)
; #define PG8_MMA(ai, bj, At, Bt) do { __builtin_amdgcn_s_setprio(1); _Pragma("unroll") for (int m = 0; m < 4; ++m) _Pragma("unroll") for (int n = 0; n < 2; ++n) _Pragma("unroll") for (int k = 0; k < 2; ++k) \
;         acc[ai][bj][m][n] = __builtin_amdgcn_mfma_f32_16x16x32_bf16(Bt[n][k], At[m][k], acc[ai][bj][m][n], 0, 0, 0); __builtin_amdgcn_s_setprio(0); } while (0)
; #define PG8_WAIT_V(n) asm volatile("s_waitcnt vmcnt(" #n ")" ::: "memory")
; #define PG8_WAIT_L(n) asm volatile("s_waitcnt lgkmcnt(" #n ")" ::: "memory")
; #define PG8_BAR __builtin_amdgcn_s_barrier()
; #define PG8_SCHED __builtin_amdgcn_sched_barrier(0)
; template <class Epi>
; __device__ __forceinline__ void gemm_phase(LAS unsigned char* lds, const Gemm g, const StaticOrder& S, const Epi& E) {
;     ...
;             PG8_WAIT_V(8); PG8_WAIT_L(0); PG8_BAR; PG8_MMA(1, 0, At, B0); PG8_MMA(1, 1, At, B1); PG8_BAR; PG8_SCHED;
;             PG8_LDB(B0, 1, 0); PG8_LDB(B1, 1, 1); PG8_SCHED; PG8_LDA(At, 1, 0); PG8_STAGE(PG8_SA(0, 1), a2 + hstepA, voffA);
;             PG8_WAIT_V(8); PG8_WAIT_L(0); PG8_BAR; PG8_MMA(0, 0, At, B0); PG8_MMA(0, 1, At, B1); PG8_BAR; PG8_SCHED;
	s_setprio 1
	v_mfma_f32_16x16x32_bf16 v[62:65], v[130:133], v[162:165], v[62:65]
	v_mfma_f32_16x16x32_bf16 v[58:61], v[138:141], v[162:165], v[58:61]
	v_mfma_f32_16x16x32_bf16 v[50:53], v[130:133], v[170:173], v[50:53]
	v_mfma_f32_16x16x32_bf16 v[42:45], v[138:141], v[170:173], v[42:45]
	v_mfma_f32_16x16x32_bf16 v[30:33], v[130:133], v[200:203], v[30:33]
	v_mfma_f32_16x16x32_bf16 v[26:29], v[138:141], v[200:203], v[26:29]
	v_mfma_f32_16x16x32_bf16 v[18:21], v[130:133], v[208:211], v[18:21]
	v_mfma_f32_16x16x32_bf16 v[10:13], v[138:141], v[208:211], v[10:13]
	v_mfma_f32_16x16x32_bf16 v[62:65], v[134:137], v[166:169], v[62:65]
	v_mfma_f32_16x16x32_bf16 v[58:61], v[142:145], v[166:169], v[58:61]
	v_mfma_f32_16x16x32_bf16 v[50:53], v[134:137], v[174:177], v[50:53]
	v_mfma_f32_16x16x32_bf16 v[42:45], v[142:145], v[174:177], v[42:45]
	v_mfma_f32_16x16x32_bf16 v[30:33], v[134:137], v[204:207], v[30:33]
	v_mfma_f32_16x16x32_bf16 v[26:29], v[142:145], v[204:207], v[26:29]
	v_mfma_f32_16x16x32_bf16 v[18:21], v[134:137], v[212:215], v[18:21]
	v_mfma_f32_16x16x32_bf16 v[10:13], v[142:145], v[212:215], v[10:13]
	v_mfma_f32_16x16x32_bf16 v[54:57], v[146:149], v[162:165], v[54:57]
	v_mfma_f32_16x16x32_bf16 v[46:49], v[154:157], v[162:165], v[46:49]
	v_mfma_f32_16x16x32_bf16 v[38:41], v[146:149], v[170:173], v[38:41]
	v_mfma_f32_16x16x32_bf16 v[34:37], v[154:157], v[170:173], v[34:37]
	v_mfma_f32_16x16x32_bf16 v[22:25], v[146:149], v[200:203], v[22:25]
	v_mfma_f32_16x16x32_bf16 v[14:17], v[154:157], v[200:203], v[14:17]
	v_mfma_f32_16x16x32_bf16 v[6:9], v[146:149], v[208:211], v[6:9]
	v_mfma_f32_16x16x32_bf16 v[2:5], v[154:157], v[208:211], v[2:5]
	v_mfma_f32_16x16x32_bf16 v[54:57], v[150:153], v[166:169], v[54:57]
	v_mfma_f32_16x16x32_bf16 v[46:49], v[158:161], v[166:169], v[46:49]
	v_mfma_f32_16x16x32_bf16 v[38:41], v[150:153], v[174:177], v[38:41]
	v_mfma_f32_16x16x32_bf16 v[34:37], v[158:161], v[174:177], v[34:37]
	v_mfma_f32_16x16x32_bf16 v[22:25], v[150:153], v[204:207], v[22:25]
	v_mfma_f32_16x16x32_bf16 v[14:17], v[158:161], v[204:207], v[14:17]
	v_mfma_f32_16x16x32_bf16 v[6:9], v[150:153], v[212:215], v[6:9]
	v_mfma_f32_16x16x32_bf16 v[2:5], v[158:161], v[212:215], v[2:5]
	s_setprio 0
	s_barrier
	s_add_i32 s41, 0, 0x18000
	s_add_i32 s53, 0, 0x1c000
	v_add_u32_e32 v142, s41, v1
	v_add_u32_e32 v158, s53, v1
	ds_read_b128 v[130:133], v142
	ds_read_b128 v[134:137], v142 offset:1024
	ds_read_b128 v[138:141], v142 offset:2048
	ds_read_b128 v[142:145], v142 offset:3072
	ds_read_b128 v[146:149], v158
	ds_read_b128 v[150:153], v158 offset:1024
	ds_read_b128 v[154:157], v158 offset:2048
	ds_read_b128 v[158:161], v158 offset:3072
	s_add_u32 s28, s28, 0x80000
	s_addc_u32 s29, s29, 0
	s_mov_b32 m0, s33
	v_lshl_add_u64 v[220:221], s[28:29], 0, v[188:189]
	ds_read_b128 v[162:165], v181 offset:32768
	ds_read_b128 v[166:169], v181 offset:33792
	ds_read_b128 v[170:173], v181 offset:34816
	ds_read_b128 v[174:177], v181 offset:35840
	ds_read_b128 v[200:203], v181 offset:36864
	ds_read_b128 v[204:207], v181 offset:37888
	ds_read_b128 v[208:211], v181 offset:38912
	ds_read_b128 v[212:215], v181 offset:39936
	global_load_lds_dwordx4 v[220:221], off
	v_lshl_add_u64 v[220:221], s[28:29], 0, v[192:193]
	s_mov_b32 m0, s34
	s_nop 0
	global_load_lds_dwordx4 v[220:221], off
	s_waitcnt vmcnt(8)
	s_waitcnt lgkmcnt(0)
	s_barrier
	s_setprio 1
	v_mfma_f32_16x16x32_bf16 v[126:129], v[130:133], v[162:165], v[126:129]
	v_mfma_f32_16x16x32_bf16 v[122:125], v[138:141], v[162:165], v[122:125]
	v_mfma_f32_16x16x32_bf16 v[110:113], v[130:133], v[170:173], v[110:113]
	v_mfma_f32_16x16x32_bf16 v[106:109], v[138:141], v[170:173], v[106:109]
	v_mfma_f32_16x16x32_bf16 v[94:97], v[130:133], v[200:203], v[94:97]
	v_mfma_f32_16x16x32_bf16 v[90:93], v[138:141], v[200:203], v[90:93]
	v_mfma_f32_16x16x32_bf16 v[82:85], v[130:133], v[208:211], v[82:85]
	v_mfma_f32_16x16x32_bf16 v[74:77], v[138:141], v[208:211], v[74:77]
	v_mfma_f32_16x16x32_bf16 v[126:129], v[134:137], v[166:169], v[126:129]
	v_mfma_f32_16x16x32_bf16 v[122:125], v[142:145], v[166:169], v[122:125]
	v_mfma_f32_16x16x32_bf16 v[110:113], v[134:137], v[174:177], v[110:113]
	v_mfma_f32_16x16x32_bf16 v[106:109], v[142:145], v[174:177], v[106:109]
	v_mfma_f32_16x16x32_bf16 v[94:97], v[134:137], v[204:207], v[94:97]
	v_mfma_f32_16x16x32_bf16 v[90:93], v[142:145], v[204:207], v[90:93]
	v_mfma_f32_16x16x32_bf16 v[82:85], v[134:137], v[212:215], v[82:85]
	v_mfma_f32_16x16x32_bf16 v[74:77], v[142:145], v[212:215], v[74:77]
	v_mfma_f32_16x16x32_bf16 v[118:121], v[146:149], v[162:165], v[118:121]
	v_mfma_f32_16x16x32_bf16 v[114:117], v[154:157], v[162:165], v[114:117]
	v_mfma_f32_16x16x32_bf16 v[102:105], v[146:149], v[170:173], v[102:105]
	v_mfma_f32_16x16x32_bf16 v[98:101], v[154:157], v[170:173], v[98:101]
	v_mfma_f32_16x16x32_bf16 v[86:89], v[146:149], v[200:203], v[86:89]
	v_mfma_f32_16x16x32_bf16 v[78:81], v[154:157], v[200:203], v[78:81]
	v_mfma_f32_16x16x32_bf16 v[70:73], v[146:149], v[208:211], v[70:73]
	v_mfma_f32_16x16x32_bf16 v[66:69], v[154:157], v[208:211], v[66:69]
	v_mfma_f32_16x16x32_bf16 v[118:121], v[150:153], v[166:169], v[118:121]
	v_mfma_f32_16x16x32_bf16 v[114:117], v[158:161], v[166:169], v[114:117]
	v_mfma_f32_16x16x32_bf16 v[102:105], v[150:153], v[174:177], v[102:105]
	v_mfma_f32_16x16x32_bf16 v[98:101], v[158:161], v[174:177], v[98:101]
	v_mfma_f32_16x16x32_bf16 v[86:89], v[150:153], v[204:207], v[86:89]
	v_mfma_f32_16x16x32_bf16 v[78:81], v[158:161], v[204:207], v[78:81]
	v_mfma_f32_16x16x32_bf16 v[70:73], v[150:153], v[212:215], v[70:73]
	v_mfma_f32_16x16x32_bf16 v[66:69], v[158:161], v[212:215], v[66:69]
	s_setprio 0
	s_barrier
; #define PG8_STAGE(bufoff, gbase, voff) do { _Pragma("unroll") for (int _i = 0; _i < 2; ++_i) \
;         __builtin_amdgcn_global_load_lds((const unsigned*)((const char*)(gbase) + (voff)[_i]), (LAS unsigned*)(lds + (bufoff) + ldsw + _i * 8192), 16, 0, 0); } while (0)
; #define PG8_LDA(dst, b, h) do { _Pragma("unroll") for (int m = 0; m < 4; ++m) _Pragma("unroll") for (int k = 0; k < 2; ++k) dst[m][k] = *(const LAS bf16x8*)(lds + PG8_SA(b, h) + aoff + m * 2048 + k * 1024); } while (0)
; #define PG8_MMA(ai, bj, At, Bt) do { __builtin_amdgcn_s_setprio(1); _Pragma("unroll") for (int m = 0; m < 4; ++m) _Pragma("unroll") for (int n = 0; n < 2; ++n) _Pragma("unroll") for (int k = 0; k < 2; ++k) \
;         acc[ai][bj][m][n] = __builtin_amdgcn_mfma_f32_16x16x32_bf16(Bt[n][k], At[m][k], acc[ai][bj][m][n], 0, 0, 0); __builtin_amdgcn_s_setprio(0); } while (0)
; #define PG8_WAIT_V(n) asm volatile("s_waitcnt vmcnt(" #n ")" ::: "memory")
; #define PG8_WAIT_L(n) asm volatile("s_waitcnt lgkmcnt(" #n ")" ::: "memory")
; #define PG8_BAR __builtin_amdgcn_s_barrier()
; #define PG8_SCHED __builtin_amdgcn_sched_barrier(0)
; template <class Epi>
; __device__ __forceinline__ void gemm_phase(LAS unsigned char* lds, const Gemm g, const StaticOrder& S, const Epi& E) {
;     ...
;             PG8_LDA(At, 1, 1); PG8_STAGE(PG8_SB(1, 0), b3, voffB); PG8_STAGE(PG8_SB(1, 1), b3 + hstepB, voffB); PG8_STAGE(PG8_SA(1, 0), a3, voffA);
;             PG8_WAIT_V(8); PG8_WAIT_L(0); PG8_BAR; PG8_MMA(1, 0, At, B0); PG8_MMA(1, 1, At, B1); PG8_BAR; PG8_SCHED;
;         }
	s_add_i32 s28, s41, s30
	v_lshl_add_u64 v[178:179], v[178:179], 0, s[84:85]
	s_mov_b32 m0, s28
	ds_read_b128 v[162:165], v181 offset:49152
	ds_read_b128 v[166:169], v181 offset:50176
	ds_read_b128 v[170:173], v181 offset:51200
	ds_read_b128 v[174:177], v181 offset:52224
	ds_read_b128 v[200:203], v181 offset:53248
	ds_read_b128 v[204:207], v181 offset:54272
	ds_read_b128 v[208:211], v181 offset:55296
	ds_read_b128 v[212:215], v181 offset:56320
	global_load_lds_dwordx4 v[178:179], off
	s_add_i32 m0, s28, 0x2000
	s_add_u32 s14, s14, 0x80080
	v_lshl_add_u64 v[178:179], v[184:185], 0, s[84:85]
	s_addc_u32 s15, s15, 0
	s_add_i32 s28, s53, s30
	global_load_lds_dwordx4 v[178:179], off
	v_lshl_add_u64 v[178:179], s[14:15], 0, v[190:191]
	s_mov_b32 m0, s28
	s_nop 0
	global_load_lds_dwordx4 v[178:179], off
	v_lshl_add_u64 v[178:179], s[14:15], 0, v[194:195]
	s_add_i32 m0, s28, 0x2000
	s_nop 0
	global_load_lds_dwordx4 v[178:179], off
	v_lshl_add_u64 v[178:179], v[216:217], 0, s[84:85]
	s_mov_b32 m0, s44
	s_nop 0
	global_load_lds_dwordx4 v[178:179], off
	v_lshl_add_u64 v[178:179], v[218:219], 0, s[84:85]
	s_mov_b32 m0, s45
	s_nop 0
	global_load_lds_dwordx4 v[178:179], off
	s_waitcnt vmcnt(8)
	s_waitcnt lgkmcnt(0)
	s_barrier
	s_setprio 1
	v_mfma_f32_16x16x32_bf16 v[62:65], v[130:133], v[162:165], v[62:65]
	v_mfma_f32_16x16x32_bf16 v[58:61], v[138:141], v[162:165], v[58:61]
	v_mfma_f32_16x16x32_bf16 v[50:53], v[130:133], v[170:173], v[50:53]
	v_mfma_f32_16x16x32_bf16 v[42:45], v[138:141], v[170:173], v[42:45]
	v_mfma_f32_16x16x32_bf16 v[30:33], v[130:133], v[200:203], v[30:33]
	v_mfma_f32_16x16x32_bf16 v[26:29], v[138:141], v[200:203], v[26:29]
	v_mfma_f32_16x16x32_bf16 v[18:21], v[130:133], v[208:211], v[18:21]
	v_mfma_f32_16x16x32_bf16 v[10:13], v[138:141], v[208:211], v[10:13]
	v_mfma_f32_16x16x32_bf16 v[62:65], v[134:137], v[166:169], v[62:65]
	v_mfma_f32_16x16x32_bf16 v[58:61], v[142:145], v[166:169], v[58:61]
	v_mfma_f32_16x16x32_bf16 v[50:53], v[134:137], v[174:177], v[50:53]
	v_mfma_f32_16x16x32_bf16 v[42:45], v[142:145], v[174:177], v[42:45]
	v_mfma_f32_16x16x32_bf16 v[30:33], v[134:137], v[204:207], v[30:33]
	v_mfma_f32_16x16x32_bf16 v[26:29], v[142:145], v[204:207], v[26:29]
	v_mfma_f32_16x16x32_bf16 v[18:21], v[134:137], v[212:215], v[18:21]
	v_mfma_f32_16x16x32_bf16 v[10:13], v[142:145], v[212:215], v[10:13]
	v_mfma_f32_16x16x32_bf16 v[54:57], v[146:149], v[162:165], v[54:57]
	v_mfma_f32_16x16x32_bf16 v[46:49], v[154:157], v[162:165], v[46:49]
	v_mfma_f32_16x16x32_bf16 v[38:41], v[146:149], v[170:173], v[38:41]
	v_mfma_f32_16x16x32_bf16 v[34:37], v[154:157], v[170:173], v[34:37]
	v_mfma_f32_16x16x32_bf16 v[22:25], v[146:149], v[200:203], v[22:25]
	v_mfma_f32_16x16x32_bf16 v[14:17], v[154:157], v[200:203], v[14:17]
	v_mfma_f32_16x16x32_bf16 v[6:9], v[146:149], v[208:211], v[6:9]
	v_mfma_f32_16x16x32_bf16 v[2:5], v[154:157], v[208:211], v[2:5]
	v_mfma_f32_16x16x32_bf16 v[54:57], v[150:153], v[166:169], v[54:57]
	v_mfma_f32_16x16x32_bf16 v[46:49], v[158:161], v[166:169], v[46:49]
	v_mfma_f32_16x16x32_bf16 v[38:41], v[150:153], v[174:177], v[38:41]
	v_mfma_f32_16x16x32_bf16 v[34:37], v[158:161], v[174:177], v[34:37]
	v_mfma_f32_16x16x32_bf16 v[22:25], v[150:153], v[204:207], v[22:25]
	v_mfma_f32_16x16x32_bf16 v[14:17], v[158:161], v[204:207], v[14:17]
	v_mfma_f32_16x16x32_bf16 v[6:9], v[150:153], v[212:215], v[6:9]
	v_mfma_f32_16x16x32_bf16 v[2:5], v[158:161], v[212:215], v[2:5]
	s_setprio 0
	s_barrier
	s_add_i32 s52, s52, 2
	s_add_u32 s26, s26, 0x100
	s_addc_u32 s27, s27, 0
	s_add_u32 s19, s19, 0x100
	s_addc_u32 s40, s40, 0
	s_cmp_gt_u32 s52, 29
	s_cbranch_scc0 .LBB0_1010
	s_cmp_ge_u32 s74, 16
	s_cbranch_scc1 .Lwpf_a
	s_lshl_b32 s100, s74, 9
	v_add_u32_e32 v130, s100, v246
	v_lshrrev_b32_e32 v131, 2, v130
	v_and_b32_e32 v130, 3, v130
	v_lshlrev_b32_e32 v130, 7, v130
	v_lshl_add_u32 v130, v131, 12, v130
	s_add_u32 s100, s88, 0x1800000
	s_addc_u32 s101, s89, 0
	s_mov_b32 m0, 0x21000
	s_nop 0
	global_load_lds_dword v130, s[100:101]

; #define PG8_STAGE(bufoff, gbase, voff) do { _Pragma("unroll") for (int _i = 0; _i < 2; ++_i) \
;         __builtin_amdgcn_global_load_lds((const unsigned*)((const char*)(gbase) + (voff)[_i]), (LAS unsigned*)(lds + (bufoff) + ldsw + _i * 8192), 16, 0, 0); } while (0)
; #define PG8_LDA(dst, b, h) do { _Pragma("unroll") for (int m = 0; m < 4; ++m) _Pragma("unroll") for (int k = 0; k < 2; ++k) dst[m][k] = *(const LAS bf16x8*)(lds + PG8_SA(b, h) + aoff + m * 2048 + k * 1024); } while (0)
; #define PG8_LDB(dst, b, h) do { _Pragma("unroll") for (int n = 0; n < 2; ++n) _Pragma("unroll") for (int k = 0; k < 2; ++k) dst[n][k] = *(const LAS bf16x8*)(lds + PG8_SB(b, h) + boff + n * 2048 + k * 1024); } while (0)
; #define PG8_MMA(ai, bj, At, Bt) do { __builtin_amdgcn_s_setprio(1); _Pragma("unroll") for (int m = 0; m < 4; ++m) _Pragma("unroll") for (int n = 0; n < 2; ++n) _Pragma("unroll") for (int k = 0; k < 2; ++k) \
;         acc[ai][bj][m][n] = __builtin_amdgcn_mfma_f32_16x16x32_bf16(Bt[n][k], At[m][k], acc[ai][bj][m][n], 0, 0, 0); __builtin_amdgcn_s_setprio(0); } while (0)
; #define PG8_WAIT_V(n) asm volatile("s_waitcnt vmcnt(" #n ")" ::: "memory")
; #define PG8_WAIT_L(n) asm volatile("s_waitcnt lgkmcnt(" #n ")" ::: "memory")
; #define PG8_BAR __builtin_amdgcn_s_barrier()
; #define PG8_SCHED __builtin_amdgcn_sched_barrier(0)
; template <class Epi>
; __device__ __forceinline__ void gemm_phase(LAS unsigned char* lds, const Gemm g, const StaticOrder& S, const Epi& E) {
;     ...
;             const bool last = (t == nt - 2);
;             const char* a1 = cA + (size_t)(t + 1) * kstep;
;             const char* a2 = last ? nA : cA + (size_t)(t + 2) * kstep; const char* b2 = last ? nB : cB + (size_t)(t + 2) * kstep;
;             const char* a3 = a2 + kstep; const char* b3 = b2 + kstep;
;             PG8_LDB(B0, 0, 0); PG8_LDB(B1, 0, 1); PG8_SCHED; PG8_LDA(At, 0, 0); PG8_STAGE(PG8_SA(1, 1), a1 + hstepA, voffA);
;             PG8_WAIT_V(8); PG8_WAIT_L(0); PG8_BAR; PG8_MMA(0, 0, At, B0); PG8_MMA(0, 1, At, B1); PG8_BAR; PG8_SCHED;
;             PG8_LDA(At, 0, 1); PG8_STAGE(PG8_SB(0, 0), b2, voffB); PG8_STAGE(PG8_SB(0, 1), b2 + hstepB, voffB); PG8_STAGE(PG8_SA(0, 0), a2, voffA);
;             PG8_WAIT_V(8); PG8_WAIT_L(0); PG8_BAR; PG8_MMA(1, 0, At, B0); PG8_MMA(1, 1, At, B1); PG8_BAR; PG8_SCHED;
.LBB0_1107:
	s_add_u32 s34, vcc_lo, 0xfff80080
	s_addc_u32 s35, vcc_hi, -1
	s_add_i32 s76, 0, 0x10000
	s_cmp_eq_u32 s41, 28
	s_cselect_b32 s69, s3, s35
	s_cselect_b32 s68, s7, s34
	s_cselect_b32 s35, s13, s87
	s_cselect_b32 s34, s40, s65
	s_add_i32 s78, 0, 0x14000
	v_add_u32_e32 v142, s76, v1
	v_add_u32_e32 v163, s78, v1
	ds_read_b128 v[130:133], v142
	ds_read_b128 v[134:137], v142 offset:1024
	ds_read_b128 v[138:141], v142 offset:2048
	ds_read_b128 v[142:145], v142 offset:3072
	ds_read_b128 v[158:161], v163
	ds_read_b128 v[164:167], v163 offset:1024
	ds_read_b128 v[168:171], v163 offset:2048
	ds_read_b128 v[172:175], v163 offset:3072
	v_lshl_add_u64 v[184:185], vcc, 0, v[154:155]
	s_add_i32 m0, s70, 0xc000
	ds_read_b128 v[176:179], v162
	ds_read_b128 v[188:191], v162 offset:1024
	ds_read_b128 v[192:195], v162 offset:2048
	ds_read_b128 v[196:199], v162 offset:3072
	ds_read_b128 v[200:203], v162 offset:4096
	ds_read_b128 v[204:207], v162 offset:5120
	ds_read_b128 v[208:211], v162 offset:6144
	ds_read_b128 v[212:215], v162 offset:7168
	global_load_lds_dwordx4 v[184:185], off
	v_lshl_add_u64 v[184:185], vcc, 0, v[156:157]
	s_add_i32 m0, s70, 0xe000
	s_nop 0
	global_load_lds_dwordx4 v[184:185], off
	s_waitcnt vmcnt(8)
	s_waitcnt lgkmcnt(0)
	s_barrier
	s_setprio 1
	v_mfma_f32_16x16x32_bf16 v[126:129], v[130:133], v[176:179], v[126:129]
	v_mfma_f32_16x16x32_bf16 v[122:125], v[138:141], v[176:179], v[122:125]
	v_mfma_f32_16x16x32_bf16 v[114:117], v[130:133], v[192:195], v[114:117]
	v_mfma_f32_16x16x32_bf16 v[106:109], v[138:141], v[192:195], v[106:109]
	v_mfma_f32_16x16x32_bf16 v[98:101], v[130:133], v[200:203], v[98:101]
	v_mfma_f32_16x16x32_bf16 v[90:93], v[138:141], v[200:203], v[90:93]
	v_mfma_f32_16x16x32_bf16 v[82:85], v[130:133], v[208:211], v[82:85]
	v_mfma_f32_16x16x32_bf16 v[74:77], v[138:141], v[208:211], v[74:77]
	v_mfma_f32_16x16x32_bf16 v[126:129], v[134:137], v[188:191], v[126:129]
	v_mfma_f32_16x16x32_bf16 v[122:125], v[142:145], v[188:191], v[122:125]
	v_mfma_f32_16x16x32_bf16 v[114:117], v[134:137], v[196:199], v[114:117]
	v_mfma_f32_16x16x32_bf16 v[106:109], v[142:145], v[196:199], v[106:109]
	v_mfma_f32_16x16x32_bf16 v[98:101], v[134:137], v[204:207], v[98:101]
	v_mfma_f32_16x16x32_bf16 v[90:93], v[142:145], v[204:207], v[90:93]
	v_mfma_f32_16x16x32_bf16 v[82:85], v[134:137], v[212:215], v[82:85]
	v_mfma_f32_16x16x32_bf16 v[74:77], v[142:145], v[212:215], v[74:77]
	v_mfma_f32_16x16x32_bf16 v[118:121], v[158:161], v[176:179], v[118:121]
	v_mfma_f32_16x16x32_bf16 v[110:113], v[168:171], v[176:179], v[110:113]
	v_mfma_f32_16x16x32_bf16 v[102:105], v[158:161], v[192:195], v[102:105]
	v_mfma_f32_16x16x32_bf16 v[94:97], v[168:171], v[192:195], v[94:97]
	v_mfma_f32_16x16x32_bf16 v[86:89], v[158:161], v[200:203], v[86:89]
	v_mfma_f32_16x16x32_bf16 v[78:81], v[168:171], v[200:203], v[78:81]
	v_mfma_f32_16x16x32_bf16 v[70:73], v[158:161], v[208:211], v[70:73]
	v_mfma_f32_16x16x32_bf16 v[66:69], v[168:171], v[208:211], v[66:69]
	v_mfma_f32_16x16x32_bf16 v[118:121], v[164:167], v[188:191], v[118:121]
	v_mfma_f32_16x16x32_bf16 v[110:113], v[172:175], v[188:191], v[110:113]
	v_mfma_f32_16x16x32_bf16 v[102:105], v[164:167], v[196:199], v[102:105]
	v_mfma_f32_16x16x32_bf16 v[94:97], v[172:175], v[196:199], v[94:97]
	v_mfma_f32_16x16x32_bf16 v[86:89], v[164:167], v[204:207], v[86:89]
	v_mfma_f32_16x16x32_bf16 v[78:81], v[172:175], v[204:207], v[78:81]
	v_mfma_f32_16x16x32_bf16 v[70:73], v[164:167], v[212:215], v[70:73]
	v_mfma_f32_16x16x32_bf16 v[66:69], v[172:175], v[212:215], v[66:69]
	s_setprio 0
	s_barrier
	s_add_i32 s76, s76, s42
	v_lshl_add_u64 v[184:185], s[34:35], 0, v[148:149]
	s_mov_b32 m0, s76
	ds_read_b128 v[176:179], v162 offset:16384
	ds_read_b128 v[188:191], v162 offset:17408
	ds_read_b128 v[192:195], v162 offset:18432
	ds_read_b128 v[196:199], v162 offset:19456
	ds_read_b128 v[200:203], v162 offset:20480
	ds_read_b128 v[204:207], v162 offset:21504
	ds_read_b128 v[208:211], v162 offset:22528
	ds_read_b128 v[212:215], v162 offset:23552
	global_load_lds_dwordx4 v[184:185], off
	s_add_i32 m0, s76, 0x2000
	s_add_u32 s76, s34, 0x80000
	v_lshl_add_u64 v[216:217], s[34:35], 0, v[152:153]
	s_addc_u32 s77, s35, 0
	s_add_i32 s78, s78, s42
	global_load_lds_dwordx4 v[216:217], off
	v_lshl_add_u64 v[218:219], s[76:77], 0, v[148:149]
	s_mov_b32 m0, s78
	v_lshl_add_u64 v[220:221], s[68:69], 0, v[150:151]
	global_load_lds_dwordx4 v[218:219], off
	v_lshl_add_u64 v[218:219], s[76:77], 0, v[152:153]
	s_add_i32 m0, s78, 0x2000
	s_nop 0
	global_load_lds_dwordx4 v[218:219], off
	v_lshl_add_u64 v[218:219], s[68:69], 0, v[146:147]
	s_mov_b32 m0, s70
	s_nop 0
	global_load_lds_dwordx4 v[218:219], off
	s_mov_b32 m0, s91
	s_nop 0
	global_load_lds_dwordx4 v[220:221], off
	s_waitcnt vmcnt(8)
	s_waitcnt lgkmcnt(0)
	s_barrier
; #define PG8_STAGE(bufoff, gbase, voff) do { _Pragma("unroll") for (int _i = 0; _i < 2; ++_i) \
;         __builtin_amdgcn_global_load_lds((const unsigned*)((const char*)(gbase) + (voff)[_i]), (LAS unsigned*)(lds + (bufoff) + ldsw + _i * 8192), 16, 0, 0); } while (0)
; #define PG8_LDA(dst, b, h) do { _Pragma("unroll") for (int m = 0; m < 4; ++m) _Pragma("unroll") for (int k = 0; k < 2; ++k) dst[m][k] = *(const LAS bf16x8*)(lds + PG8_SA(b, h) + aoff + m * 2048 + k * 1024); } while (0)
; #define PG8_LDB(dst, b, h) do { _Pragma("unroll") for (int n = 0; n < 2; ++n) _Pragma("unroll") for (int k = 0; k < 2; ++k) dst[n][k] = *(const LAS bf16x8*)(lds + PG8_SB(b, h) + boff + n * 2048 + k * 1024); } while (0)
; #define PG8_MMA(ai, bj, At, Bt) do { __builtin_amdgcn_s_setprio(1); _Pragma("unroll") for (int m = 0; m < 4; ++m) _Pragma("unroll") for (int n = 0; n < 2; ++n) _Pragma("unroll") for (int k = 0; k < 2; ++k) \
;         acc[ai][bj][m][n] = __builtin_amdgcn_mfma_f32_16x16x32_bf16(Bt[n][k], At[m][k], acc[ai][bj][m][n], 0, 0, 0); __builtin_amdgcn_s_setprio(0); } while (0)
; #define PG8_WAIT_V(n) asm volatile("s_waitcnt vmcnt(" #n ")" ::: "memory")
; #define PG8_WAIT_L(n) asm volatile("s_waitcnt lgkmcnt(" #n ")" ::: "memory")
; #define PG8_BAR __builtin_amdgcn_s_barrier()
; #define PG8_SCHED __builtin_amdgcn_sched_barrier(0)
; template <class Epi>
; __device__ __forceinline__ void gemm_phase(LAS unsigned char* lds, const Gemm g, const StaticOrder& S, const Epi& E) {
;     ...
;             PG8_WAIT_V(8); PG8_WAIT_L(0); PG8_BAR; PG8_MMA(1, 0, At, B0); PG8_MMA(1, 1, At, B1); PG8_BAR; PG8_SCHED;
;             PG8_LDB(B0, 1, 0); PG8_LDB(B1, 1, 1); PG8_SCHED; PG8_LDA(At, 1, 0); PG8_STAGE(PG8_SA(0, 1), a2 + hstepA, voffA);
;             PG8_WAIT_V(8); PG8_WAIT_L(0); PG8_BAR; PG8_MMA(0, 0, At, B0); PG8_MMA(0, 1, At, B1); PG8_BAR; PG8_SCHED;
	s_setprio 1
	v_mfma_f32_16x16x32_bf16 v[62:65], v[130:133], v[176:179], v[62:65]
	v_mfma_f32_16x16x32_bf16 v[58:61], v[138:141], v[176:179], v[58:61]
	v_mfma_f32_16x16x32_bf16 v[54:57], v[130:133], v[192:195], v[54:57]
	v_mfma_f32_16x16x32_bf16 v[46:49], v[138:141], v[192:195], v[46:49]
	v_mfma_f32_16x16x32_bf16 v[38:41], v[130:133], v[200:203], v[38:41]
	v_mfma_f32_16x16x32_bf16 v[30:33], v[138:141], v[200:203], v[30:33]
	v_mfma_f32_16x16x32_bf16 v[22:25], v[130:133], v[208:211], v[22:25]
	v_mfma_f32_16x16x32_bf16 v[14:17], v[138:141], v[208:211], v[14:17]
	v_mfma_f32_16x16x32_bf16 v[62:65], v[134:137], v[188:191], v[62:65]
	v_mfma_f32_16x16x32_bf16 v[58:61], v[142:145], v[188:191], v[58:61]
	v_mfma_f32_16x16x32_bf16 v[54:57], v[134:137], v[196:199], v[54:57]
	v_mfma_f32_16x16x32_bf16 v[46:49], v[142:145], v[196:199], v[46:49]
	v_mfma_f32_16x16x32_bf16 v[38:41], v[134:137], v[204:207], v[38:41]
	v_mfma_f32_16x16x32_bf16 v[30:33], v[142:145], v[204:207], v[30:33]
	v_mfma_f32_16x16x32_bf16 v[22:25], v[134:137], v[212:215], v[22:25]
	v_mfma_f32_16x16x32_bf16 v[14:17], v[142:145], v[212:215], v[14:17]
	v_mfma_f32_16x16x32_bf16 v[50:53], v[158:161], v[176:179], v[50:53]
	v_mfma_f32_16x16x32_bf16 v[42:45], v[168:171], v[176:179], v[42:45]
	v_mfma_f32_16x16x32_bf16 v[34:37], v[158:161], v[192:195], v[34:37]
	v_mfma_f32_16x16x32_bf16 v[26:29], v[168:171], v[192:195], v[26:29]
	v_mfma_f32_16x16x32_bf16 v[18:21], v[158:161], v[200:203], v[18:21]
	v_mfma_f32_16x16x32_bf16 v[10:13], v[168:171], v[200:203], v[10:13]
	v_mfma_f32_16x16x32_bf16 v[6:9], v[158:161], v[208:211], v[6:9]
	v_mfma_f32_16x16x32_bf16 v[2:5], v[168:171], v[208:211], v[2:5]
	v_mfma_f32_16x16x32_bf16 v[50:53], v[164:167], v[188:191], v[50:53]
	v_mfma_f32_16x16x32_bf16 v[42:45], v[172:175], v[188:191], v[42:45]
	v_mfma_f32_16x16x32_bf16 v[34:37], v[164:167], v[196:199], v[34:37]
	v_mfma_f32_16x16x32_bf16 v[26:29], v[172:175], v[196:199], v[26:29]
	v_mfma_f32_16x16x32_bf16 v[18:21], v[164:167], v[204:207], v[18:21]
	v_mfma_f32_16x16x32_bf16 v[10:13], v[172:175], v[204:207], v[10:13]
	v_mfma_f32_16x16x32_bf16 v[6:9], v[164:167], v[212:215], v[6:9]
	v_mfma_f32_16x16x32_bf16 v[2:5], v[172:175], v[212:215], v[2:5]
	s_setprio 0
	s_barrier
	s_add_i32 s76, 0, 0x18000
	s_add_i32 s77, 0, 0x1c000
	v_add_u32_e32 v142, s76, v1
	v_add_u32_e32 v163, s77, v1
	ds_read_b128 v[130:133], v142
	ds_read_b128 v[134:137], v142 offset:1024
	ds_read_b128 v[138:141], v142 offset:2048
	ds_read_b128 v[142:145], v142 offset:3072
	ds_read_b128 v[158:161], v163
	ds_read_b128 v[164:167], v163 offset:1024
	ds_read_b128 v[168:171], v163 offset:2048
	ds_read_b128 v[172:175], v163 offset:3072
	s_add_u32 s68, s68, 0x80000
	s_addc_u32 s69, s69, 0
	s_mov_b32 m0, s62
	v_lshl_add_u64 v[222:223], s[68:69], 0, v[146:147]
	ds_read_b128 v[176:179], v162 offset:32768
	ds_read_b128 v[188:191], v162 offset:33792
	ds_read_b128 v[192:195], v162 offset:34816
	ds_read_b128 v[196:199], v162 offset:35840
	ds_read_b128 v[200:203], v162 offset:36864
	ds_read_b128 v[204:207], v162 offset:37888
	ds_read_b128 v[208:211], v162 offset:38912
	ds_read_b128 v[212:215], v162 offset:39936
	global_load_lds_dwordx4 v[222:223], off
	v_lshl_add_u64 v[222:223], s[68:69], 0, v[150:151]
	s_mov_b32 m0, s63
	s_nop 0
	global_load_lds_dwordx4 v[222:223], off
	s_waitcnt vmcnt(8)
	s_waitcnt lgkmcnt(0)
	s_barrier
	s_setprio 1
	v_mfma_f32_16x16x32_bf16 v[126:129], v[130:133], v[176:179], v[126:129]
	v_mfma_f32_16x16x32_bf16 v[122:125], v[138:141], v[176:179], v[122:125]
	v_mfma_f32_16x16x32_bf16 v[114:117], v[130:133], v[192:195], v[114:117]
	v_mfma_f32_16x16x32_bf16 v[106:109], v[138:141], v[192:195], v[106:109]
	v_mfma_f32_16x16x32_bf16 v[98:101], v[130:133], v[200:203], v[98:101]
	v_mfma_f32_16x16x32_bf16 v[90:93], v[138:141], v[200:203], v[90:93]
	v_mfma_f32_16x16x32_bf16 v[82:85], v[130:133], v[208:211], v[82:85]
	v_mfma_f32_16x16x32_bf16 v[74:77], v[138:141], v[208:211], v[74:77]
	v_mfma_f32_16x16x32_bf16 v[126:129], v[134:137], v[188:191], v[126:129]
	v_mfma_f32_16x16x32_bf16 v[122:125], v[142:145], v[188:191], v[122:125]
	v_mfma_f32_16x16x32_bf16 v[114:117], v[134:137], v[196:199], v[114:117]
	v_mfma_f32_16x16x32_bf16 v[106:109], v[142:145], v[196:199], v[106:109]
	v_mfma_f32_16x16x32_bf16 v[98:101], v[134:137], v[204:207], v[98:101]
	v_mfma_f32_16x16x32_bf16 v[90:93], v[142:145], v[204:207], v[90:93]
	v_mfma_f32_16x16x32_bf16 v[82:85], v[134:137], v[212:215], v[82:85]
	v_mfma_f32_16x16x32_bf16 v[74:77], v[142:145], v[212:215], v[74:77]
	v_mfma_f32_16x16x32_bf16 v[118:121], v[158:161], v[176:179], v[118:121]
	v_mfma_f32_16x16x32_bf16 v[110:113], v[168:171], v[176:179], v[110:113]
	v_mfma_f32_16x16x32_bf16 v[102:105], v[158:161], v[192:195], v[102:105]
	v_mfma_f32_16x16x32_bf16 v[94:97], v[168:171], v[192:195], v[94:97]
	v_mfma_f32_16x16x32_bf16 v[86:89], v[158:161], v[200:203], v[86:89]
	v_mfma_f32_16x16x32_bf16 v[78:81], v[168:171], v[200:203], v[78:81]
	v_mfma_f32_16x16x32_bf16 v[70:73], v[158:161], v[208:211], v[70:73]
	v_mfma_f32_16x16x32_bf16 v[66:69], v[168:171], v[208:211], v[66:69]
	v_mfma_f32_16x16x32_bf16 v[118:121], v[164:167], v[188:191], v[118:121]
	v_mfma_f32_16x16x32_bf16 v[110:113], v[172:175], v[188:191], v[110:113]
	v_mfma_f32_16x16x32_bf16 v[102:105], v[164:167], v[196:199], v[102:105]
	v_mfma_f32_16x16x32_bf16 v[94:97], v[172:175], v[196:199], v[94:97]
	v_mfma_f32_16x16x32_bf16 v[86:89], v[164:167], v[204:207], v[86:89]
	v_mfma_f32_16x16x32_bf16 v[78:81], v[172:175], v[204:207], v[78:81]
	v_mfma_f32_16x16x32_bf16 v[70:73], v[164:167], v[212:215], v[70:73]
	v_mfma_f32_16x16x32_bf16 v[66:69], v[172:175], v[212:215], v[66:69]
	s_setprio 0
	s_barrier
; #define PG8_STAGE(bufoff, gbase, voff) do { _Pragma("unroll") for (int _i = 0; _i < 2; ++_i) \
;         __builtin_amdgcn_global_load_lds((const unsigned*)((const char*)(gbase) + (voff)[_i]), (LAS unsigned*)(lds + (bufoff) + ldsw + _i * 8192), 16, 0, 0); } while (0)
; #define PG8_LDA(dst, b, h) do { _Pragma("unroll") for (int m = 0; m < 4; ++m) _Pragma("unroll") for (int k = 0; k < 2; ++k) dst[m][k] = *(const LAS bf16x8*)(lds + PG8_SA(b, h) + aoff + m * 2048 + k * 1024); } while (0)
; #define PG8_MMA(ai, bj, At, Bt) do { __builtin_amdgcn_s_setprio(1); _Pragma("unroll") for (int m = 0; m < 4; ++m) _Pragma("unroll") for (int n = 0; n < 2; ++n) _Pragma("unroll") for (int k = 0; k < 2; ++k) \
;         acc[ai][bj][m][n] = __builtin_amdgcn_mfma_f32_16x16x32_bf16(Bt[n][k], At[m][k], acc[ai][bj][m][n], 0, 0, 0); __builtin_amdgcn_s_setprio(0); } while (0)
; #define PG8_WAIT_V(n) asm volatile("s_waitcnt vmcnt(" #n ")" ::: "memory")
; #define PG8_WAIT_L(n) asm volatile("s_waitcnt lgkmcnt(" #n ")" ::: "memory")
; #define PG8_BAR __builtin_amdgcn_s_barrier()
; #define PG8_SCHED __builtin_amdgcn_sched_barrier(0)
; template <class Epi>
; __device__ __forceinline__ void gemm_phase(LAS unsigned char* lds, const Gemm g, const StaticOrder& S, const Epi& E) {
;     ...
;             PG8_LDA(At, 1, 1); PG8_STAGE(PG8_SB(1, 0), b3, voffB); PG8_STAGE(PG8_SB(1, 1), b3 + hstepB, voffB); PG8_STAGE(PG8_SA(1, 0), a3, voffA);
;             PG8_WAIT_V(8); PG8_WAIT_L(0); PG8_BAR; PG8_MMA(1, 0, At, B0); PG8_MMA(1, 1, At, B1); PG8_BAR; PG8_SCHED;
;         }
;         if (wr == 0) PG8_BAR;
	s_add_i32 s68, s76, s42
	v_lshl_add_u64 v[184:185], v[184:185], 0, s[84:85]
	s_mov_b32 m0, s68
	ds_read_b128 v[176:179], v162 offset:49152
	ds_read_b128 v[188:191], v162 offset:50176
	ds_read_b128 v[192:195], v162 offset:51200
	ds_read_b128 v[196:199], v162 offset:52224
	ds_read_b128 v[200:203], v162 offset:53248
	ds_read_b128 v[204:207], v162 offset:54272
	ds_read_b128 v[208:211], v162 offset:55296
	ds_read_b128 v[212:215], v162 offset:56320
	global_load_lds_dwordx4 v[184:185], off
	s_add_i32 m0, s68, 0x2000
	s_add_u32 s34, s34, 0x80080
	v_lshl_add_u64 v[184:185], v[216:217], 0, s[84:85]
	s_addc_u32 s35, s35, 0
	s_add_i32 s68, s77, s42
	global_load_lds_dwordx4 v[184:185], off
	v_lshl_add_u64 v[184:185], s[34:35], 0, v[148:149]
	s_mov_b32 m0, s68
	s_nop 0
	global_load_lds_dwordx4 v[184:185], off
	v_lshl_add_u64 v[184:185], s[34:35], 0, v[152:153]
	s_add_i32 m0, s68, 0x2000
	s_nop 0
	global_load_lds_dwordx4 v[184:185], off
	v_lshl_add_u64 v[184:185], v[218:219], 0, s[84:85]
	s_mov_b32 m0, s94
	s_nop 0
	global_load_lds_dwordx4 v[184:185], off
	v_lshl_add_u64 v[184:185], v[220:221], 0, s[84:85]
	s_mov_b32 m0, s95
	s_nop 0
	global_load_lds_dwordx4 v[184:185], off
	s_waitcnt vmcnt(8)
	s_waitcnt lgkmcnt(0)
	s_barrier
	s_setprio 1
	v_mfma_f32_16x16x32_bf16 v[62:65], v[130:133], v[176:179], v[62:65]
	v_mfma_f32_16x16x32_bf16 v[58:61], v[138:141], v[176:179], v[58:61]
	v_mfma_f32_16x16x32_bf16 v[54:57], v[130:133], v[192:195], v[54:57]
	v_mfma_f32_16x16x32_bf16 v[46:49], v[138:141], v[192:195], v[46:49]
	v_mfma_f32_16x16x32_bf16 v[38:41], v[130:133], v[200:203], v[38:41]
	v_mfma_f32_16x16x32_bf16 v[30:33], v[138:141], v[200:203], v[30:33]
	v_mfma_f32_16x16x32_bf16 v[22:25], v[130:133], v[208:211], v[22:25]
	v_mfma_f32_16x16x32_bf16 v[14:17], v[138:141], v[208:211], v[14:17]
	v_mfma_f32_16x16x32_bf16 v[62:65], v[134:137], v[188:191], v[62:65]
	v_mfma_f32_16x16x32_bf16 v[58:61], v[142:145], v[188:191], v[58:61]
	v_mfma_f32_16x16x32_bf16 v[54:57], v[134:137], v[196:199], v[54:57]
	v_mfma_f32_16x16x32_bf16 v[46:49], v[142:145], v[196:199], v[46:49]
	v_mfma_f32_16x16x32_bf16 v[38:41], v[134:137], v[204:207], v[38:41]
	v_mfma_f32_16x16x32_bf16 v[30:33], v[142:145], v[204:207], v[30:33]
	v_mfma_f32_16x16x32_bf16 v[22:25], v[134:137], v[212:215], v[22:25]
	v_mfma_f32_16x16x32_bf16 v[14:17], v[142:145], v[212:215], v[14:17]
	v_mfma_f32_16x16x32_bf16 v[50:53], v[158:161], v[176:179], v[50:53]
	v_mfma_f32_16x16x32_bf16 v[42:45], v[168:171], v[176:179], v[42:45]
	v_mfma_f32_16x16x32_bf16 v[34:37], v[158:161], v[192:195], v[34:37]
	v_mfma_f32_16x16x32_bf16 v[26:29], v[168:171], v[192:195], v[26:29]
	v_mfma_f32_16x16x32_bf16 v[18:21], v[158:161], v[200:203], v[18:21]
	v_mfma_f32_16x16x32_bf16 v[10:13], v[168:171], v[200:203], v[10:13]
	v_mfma_f32_16x16x32_bf16 v[6:9], v[158:161], v[208:211], v[6:9]
	v_mfma_f32_16x16x32_bf16 v[2:5], v[168:171], v[208:211], v[2:5]
	v_mfma_f32_16x16x32_bf16 v[50:53], v[164:167], v[188:191], v[50:53]
	v_mfma_f32_16x16x32_bf16 v[42:45], v[172:175], v[188:191], v[42:45]
	v_mfma_f32_16x16x32_bf16 v[34:37], v[164:167], v[196:199], v[34:37]
	v_mfma_f32_16x16x32_bf16 v[26:29], v[172:175], v[196:199], v[26:29]
	v_mfma_f32_16x16x32_bf16 v[18:21], v[164:167], v[204:207], v[18:21]
	v_mfma_f32_16x16x32_bf16 v[10:13], v[172:175], v[204:207], v[10:13]
	v_mfma_f32_16x16x32_bf16 v[6:9], v[164:167], v[212:215], v[6:9]
	v_mfma_f32_16x16x32_bf16 v[2:5], v[172:175], v[212:215], v[2:5]
	s_setprio 0
	s_barrier
	s_add_i32 s41, s41, 2
	s_add_u32 vcc_lo, vcc_lo, 0x100
	s_addc_u32 vcc_hi, vcc_hi, 0
	s_add_u32 s65, s65, 0x100
	s_addc_u32 s87, s87, 0
	s_cmp_gt_u32 s41, 29
	s_cbranch_scc0 .LBB0_1107
	s_and_b64 vcc, exec, s[10:11]
	s_cbranch_vccz .LBB0_1110
	s_barrier

; #define PG8_STAGE(bufoff, gbase, voff) do { _Pragma("unroll") for (int _i = 0; _i < 2; ++_i) \
;         __builtin_amdgcn_global_load_lds((const unsigned*)((const char*)(gbase) + (voff)[_i]), (LAS unsigned*)(lds + (bufoff) + ldsw + _i * 8192), 16, 0, 0); } while (0)
; #define PG8_LDA(dst, b, h) do { _Pragma("unroll") for (int m = 0; m < 4; ++m) _Pragma("unroll") for (int k = 0; k < 2; ++k) dst[m][k] = *(const LAS bf16x8*)(lds + PG8_SA(b, h) + aoff + m * 2048 + k * 1024); } while (0)
; #define PG8_LDB(dst, b, h) do { _Pragma("unroll") for (int n = 0; n < 2; ++n) _Pragma("unroll") for (int k = 0; k < 2; ++k) dst[n][k] = *(const LAS bf16x8*)(lds + PG8_SB(b, h) + boff + n * 2048 + k * 1024); } while (0)
; #define PG8_MMA(ai, bj, At, Bt) do { __builtin_amdgcn_s_setprio(1); _Pragma("unroll") for (int m = 0; m < 4; ++m) _Pragma("unroll") for (int n = 0; n < 2; ++n) _Pragma("unroll") for (int k = 0; k < 2; ++k) \
;         acc[ai][bj][m][n] = __builtin_amdgcn_mfma_f32_16x16x32_bf16(Bt[n][k], At[m][k], acc[ai][bj][m][n], 0, 0, 0); __builtin_amdgcn_s_setprio(0); } while (0)
; #define PG8_WAIT_V(n) asm volatile("s_waitcnt vmcnt(" #n ")" ::: "memory")
; #define PG8_WAIT_L(n) asm volatile("s_waitcnt lgkmcnt(" #n ")" ::: "memory")
; #define PG8_BAR __builtin_amdgcn_s_barrier()
; #define PG8_SCHED __builtin_amdgcn_sched_barrier(0)
; template <class Epi>
; __device__ __forceinline__ void gemm_phase(LAS unsigned char* lds, const Gemm g, const StaticOrder& S, const Epi& E) {
;     ...
;             const bool last = (t == nt - 2);
;             const char* a1 = cA + (size_t)(t + 1) * kstep;
;             const char* a2 = last ? nA : cA + (size_t)(t + 2) * kstep; const char* b2 = last ? nB : cB + (size_t)(t + 2) * kstep;
;             const char* a3 = a2 + kstep; const char* b3 = b2 + kstep;
;             PG8_LDB(B0, 0, 0); PG8_LDB(B1, 0, 1); PG8_SCHED; PG8_LDA(At, 0, 0); PG8_STAGE(PG8_SA(1, 1), a1 + hstepA, voffA);
;             PG8_WAIT_V(8); PG8_WAIT_L(0); PG8_BAR; PG8_MMA(0, 0, At, B0); PG8_MMA(0, 1, At, B1); PG8_BAR; PG8_SCHED;
;             PG8_LDA(At, 0, 1); PG8_STAGE(PG8_SB(0, 0), b2, voffB); PG8_STAGE(PG8_SB(0, 1), b2 + hstepB, voffB); PG8_STAGE(PG8_SA(0, 0), a2, voffA);
;             PG8_WAIT_V(8); PG8_WAIT_L(0); PG8_BAR; PG8_MMA(1, 0, At, B0); PG8_MMA(1, 1, At, B1); PG8_BAR; PG8_SCHED;
.LBB0_1324:
	s_add_u32 s14, s24, 0xfff80080
	s_addc_u32 s15, s25, -1
	s_add_i32 s53, 0, 0x10000
	s_cmp_eq_u32 s41, 28
	s_cselect_b32 s27, s3, s15
	s_cselect_b32 s26, s7, s14
	s_cselect_b32 s15, s13, s52
	s_cselect_b32 s14, s17, s40
	s_add_i32 s69, 0, 0x14000
	v_add_u32_e32 v142, s53, v1
	v_add_u32_e32 v158, s69, v1
	ds_read_b128 v[130:133], v142
	ds_read_b128 v[134:137], v142 offset:1024
	ds_read_b128 v[138:141], v142 offset:2048
	ds_read_b128 v[142:145], v142 offset:3072
	ds_read_b128 v[146:149], v158
	ds_read_b128 v[150:153], v158 offset:1024
	ds_read_b128 v[154:157], v158 offset:2048
	ds_read_b128 v[158:161], v158 offset:3072
	v_lshl_add_u64 v[178:179], s[24:25], 0, v[170:171]
	s_add_i32 m0, s23, 0xc000
	ds_read_b128 v[162:165], v181
	ds_read_b128 v[174:177], v181 offset:1024
	ds_read_b128 v[188:191], v181 offset:2048
	ds_read_b128 v[192:195], v181 offset:3072
	ds_read_b128 v[196:199], v181 offset:4096
	ds_read_b128 v[200:203], v181 offset:5120
	ds_read_b128 v[204:207], v181 offset:6144
	ds_read_b128 v[208:211], v181 offset:7168
	global_load_lds_dwordx4 v[178:179], off
	v_lshl_add_u64 v[178:179], s[24:25], 0, v[172:173]
	s_add_i32 m0, s23, 0xe000
	s_nop 0
	global_load_lds_dwordx4 v[178:179], off
	s_waitcnt vmcnt(8)
	s_waitcnt lgkmcnt(0)
	s_barrier
	s_setprio 1
	v_mfma_f32_16x16x32_bf16 v[122:125], v[130:133], v[162:165], v[122:125]
	v_mfma_f32_16x16x32_bf16 v[118:121], v[138:141], v[162:165], v[118:121]
	v_mfma_f32_16x16x32_bf16 v[110:113], v[130:133], v[188:191], v[110:113]
	v_mfma_f32_16x16x32_bf16 v[102:105], v[138:141], v[188:191], v[102:105]
	v_mfma_f32_16x16x32_bf16 v[94:97], v[130:133], v[196:199], v[94:97]
	v_mfma_f32_16x16x32_bf16 v[86:89], v[138:141], v[196:199], v[86:89]
	v_mfma_f32_16x16x32_bf16 v[78:81], v[130:133], v[204:207], v[78:81]
	v_mfma_f32_16x16x32_bf16 v[70:73], v[138:141], v[204:207], v[70:73]
	v_mfma_f32_16x16x32_bf16 v[122:125], v[134:137], v[174:177], v[122:125]
	v_mfma_f32_16x16x32_bf16 v[118:121], v[142:145], v[174:177], v[118:121]
	v_mfma_f32_16x16x32_bf16 v[110:113], v[134:137], v[192:195], v[110:113]
	v_mfma_f32_16x16x32_bf16 v[102:105], v[142:145], v[192:195], v[102:105]
	v_mfma_f32_16x16x32_bf16 v[94:97], v[134:137], v[200:203], v[94:97]
	v_mfma_f32_16x16x32_bf16 v[86:89], v[142:145], v[200:203], v[86:89]
	v_mfma_f32_16x16x32_bf16 v[78:81], v[134:137], v[208:211], v[78:81]
	v_mfma_f32_16x16x32_bf16 v[70:73], v[142:145], v[208:211], v[70:73]
	v_mfma_f32_16x16x32_bf16 v[126:129], v[146:149], v[162:165], v[126:129]
	v_mfma_f32_16x16x32_bf16 v[114:117], v[154:157], v[162:165], v[114:117]
	v_mfma_f32_16x16x32_bf16 v[106:109], v[146:149], v[188:191], v[106:109]
	v_mfma_f32_16x16x32_bf16 v[98:101], v[154:157], v[188:191], v[98:101]
	v_mfma_f32_16x16x32_bf16 v[90:93], v[146:149], v[196:199], v[90:93]
	v_mfma_f32_16x16x32_bf16 v[82:85], v[154:157], v[196:199], v[82:85]
	v_mfma_f32_16x16x32_bf16 v[74:77], v[146:149], v[204:207], v[74:77]
	v_mfma_f32_16x16x32_bf16 v[66:69], v[154:157], v[204:207], v[66:69]
	v_mfma_f32_16x16x32_bf16 v[126:129], v[150:153], v[174:177], v[126:129]
	v_mfma_f32_16x16x32_bf16 v[114:117], v[158:161], v[174:177], v[114:117]
	v_mfma_f32_16x16x32_bf16 v[106:109], v[150:153], v[192:195], v[106:109]
	v_mfma_f32_16x16x32_bf16 v[98:101], v[158:161], v[192:195], v[98:101]
	v_mfma_f32_16x16x32_bf16 v[90:93], v[150:153], v[200:203], v[90:93]
	v_mfma_f32_16x16x32_bf16 v[82:85], v[158:161], v[200:203], v[82:85]
	v_mfma_f32_16x16x32_bf16 v[74:77], v[150:153], v[208:211], v[74:77]
	v_mfma_f32_16x16x32_bf16 v[66:69], v[158:161], v[208:211], v[66:69]
	s_setprio 0
	s_barrier
	s_add_i32 s53, s53, s28
	v_lshl_add_u64 v[178:179], s[14:15], 0, v[166:167]
	s_mov_b32 m0, s53
	ds_read_b128 v[162:165], v181 offset:16384
	ds_read_b128 v[174:177], v181 offset:17408
	ds_read_b128 v[188:191], v181 offset:18432
	ds_read_b128 v[192:195], v181 offset:19456
	ds_read_b128 v[196:199], v181 offset:20480
	ds_read_b128 v[200:203], v181 offset:21504
	ds_read_b128 v[204:207], v181 offset:22528
	ds_read_b128 v[208:211], v181 offset:23552
	global_load_lds_dwordx4 v[178:179], off
	s_add_i32 m0, s53, 0x2000
	s_add_u32 s64, s14, 0x80000
	v_lshl_add_u64 v[184:185], s[14:15], 0, v[168:169]
	s_addc_u32 s65, s15, 0
	s_add_i32 s53, s69, s28
	global_load_lds_dwordx4 v[184:185], off
	v_lshl_add_u64 v[212:213], s[64:65], 0, v[166:167]
	s_mov_b32 m0, s53
	v_lshl_add_u64 v[214:215], s[26:27], 0, v[168:169]
	global_load_lds_dwordx4 v[212:213], off
	v_lshl_add_u64 v[212:213], s[64:65], 0, v[168:169]
	s_add_i32 m0, s53, 0x2000
	s_nop 0
	global_load_lds_dwordx4 v[212:213], off
	v_lshl_add_u64 v[212:213], s[26:27], 0, v[166:167]
	s_mov_b32 m0, s23
	s_nop 0
	global_load_lds_dwordx4 v[212:213], off
	s_mov_b32 m0, s29
	s_nop 0
	global_load_lds_dwordx4 v[214:215], off
	s_waitcnt vmcnt(8)
	s_waitcnt lgkmcnt(0)
	s_barrier
; #define PG8_STAGE(bufoff, gbase, voff) do { _Pragma("unroll") for (int _i = 0; _i < 2; ++_i) \
;         __builtin_amdgcn_global_load_lds((const unsigned*)((const char*)(gbase) + (voff)[_i]), (LAS unsigned*)(lds + (bufoff) + ldsw + _i * 8192), 16, 0, 0); } while (0)
; #define PG8_LDA(dst, b, h) do { _Pragma("unroll") for (int m = 0; m < 4; ++m) _Pragma("unroll") for (int k = 0; k < 2; ++k) dst[m][k] = *(const LAS bf16x8*)(lds + PG8_SA(b, h) + aoff + m * 2048 + k * 1024); } while (0)
; #define PG8_LDB(dst, b, h) do { _Pragma("unroll") for (int n = 0; n < 2; ++n) _Pragma("unroll") for (int k = 0; k < 2; ++k) dst[n][k] = *(const LAS bf16x8*)(lds + PG8_SB(b, h) + boff + n * 2048 + k * 1024); } while (0)
; #define PG8_MMA(ai, bj, At, Bt) do { __builtin_amdgcn_s_setprio(1); _Pragma("unroll") for (int m = 0; m < 4; ++m) _Pragma("unroll") for (int n = 0; n < 2; ++n) _Pragma("unroll") for (int k = 0; k < 2; ++k) \
;         acc[ai][bj][m][n] = __builtin_amdgcn_mfma_f32_16x16x32_bf16(Bt[n][k], At[m][k], acc[ai][bj][m][n], 0, 0, 0); __builtin_amdgcn_s_setprio(0); } while (0)
; #define PG8_WAIT_V(n) asm volatile("s_waitcnt vmcnt(" #n ")" ::: "memory")
; #define PG8_WAIT_L(n) asm volatile("s_waitcnt lgkmcnt(" #n ")" ::: "memory")
; #define PG8_BAR __builtin_amdgcn_s_barrier()
; #define PG8_SCHED __builtin_amdgcn_sched_barrier(0)
; template <class Epi>
; __device__ __forceinline__ void gemm_phase(LAS unsigned char* lds, const Gemm g, const StaticOrder& S, const Epi& E) {
;     ...
;             PG8_WAIT_V(8); PG8_WAIT_L(0); PG8_BAR; PG8_MMA(1, 0, At, B0); PG8_MMA(1, 1, At, B1); PG8_BAR; PG8_SCHED;
;             PG8_LDB(B0, 1, 0); PG8_LDB(B1, 1, 1); PG8_SCHED; PG8_LDA(At, 1, 0); PG8_STAGE(PG8_SA(0, 1), a2 + hstepA, voffA);
;             PG8_WAIT_V(8); PG8_WAIT_L(0); PG8_BAR; PG8_MMA(0, 0, At, B0); PG8_MMA(0, 1, At, B1); PG8_BAR; PG8_SCHED;
	s_setprio 1
	v_mfma_f32_16x16x32_bf16 v[62:65], v[130:133], v[162:165], v[62:65]
	v_mfma_f32_16x16x32_bf16 v[54:57], v[138:141], v[162:165], v[54:57]
	v_mfma_f32_16x16x32_bf16 v[46:49], v[130:133], v[188:191], v[46:49]
	v_mfma_f32_16x16x32_bf16 v[38:41], v[138:141], v[188:191], v[38:41]
	v_mfma_f32_16x16x32_bf16 v[30:33], v[130:133], v[196:199], v[30:33]
	v_mfma_f32_16x16x32_bf16 v[22:25], v[138:141], v[196:199], v[22:25]
	v_mfma_f32_16x16x32_bf16 v[14:17], v[130:133], v[204:207], v[14:17]
	v_mfma_f32_16x16x32_bf16 v[6:9], v[138:141], v[204:207], v[6:9]
	v_mfma_f32_16x16x32_bf16 v[62:65], v[134:137], v[174:177], v[62:65]
	v_mfma_f32_16x16x32_bf16 v[54:57], v[142:145], v[174:177], v[54:57]
	v_mfma_f32_16x16x32_bf16 v[46:49], v[134:137], v[192:195], v[46:49]
	v_mfma_f32_16x16x32_bf16 v[38:41], v[142:145], v[192:195], v[38:41]
	v_mfma_f32_16x16x32_bf16 v[30:33], v[134:137], v[200:203], v[30:33]
	v_mfma_f32_16x16x32_bf16 v[22:25], v[142:145], v[200:203], v[22:25]
	v_mfma_f32_16x16x32_bf16 v[14:17], v[134:137], v[208:211], v[14:17]
	v_mfma_f32_16x16x32_bf16 v[6:9], v[142:145], v[208:211], v[6:9]
	v_mfma_f32_16x16x32_bf16 v[58:61], v[146:149], v[162:165], v[58:61]
	v_mfma_f32_16x16x32_bf16 v[50:53], v[154:157], v[162:165], v[50:53]
	v_mfma_f32_16x16x32_bf16 v[42:45], v[146:149], v[188:191], v[42:45]
	v_mfma_f32_16x16x32_bf16 v[34:37], v[154:157], v[188:191], v[34:37]
	v_mfma_f32_16x16x32_bf16 v[26:29], v[146:149], v[196:199], v[26:29]
	v_mfma_f32_16x16x32_bf16 v[18:21], v[154:157], v[196:199], v[18:21]
	v_mfma_f32_16x16x32_bf16 v[10:13], v[146:149], v[204:207], v[10:13]
	v_mfma_f32_16x16x32_bf16 v[2:5], v[154:157], v[204:207], v[2:5]
	v_mfma_f32_16x16x32_bf16 v[58:61], v[150:153], v[174:177], v[58:61]
	v_mfma_f32_16x16x32_bf16 v[50:53], v[158:161], v[174:177], v[50:53]
	v_mfma_f32_16x16x32_bf16 v[42:45], v[150:153], v[192:195], v[42:45]
	v_mfma_f32_16x16x32_bf16 v[34:37], v[158:161], v[192:195], v[34:37]
	v_mfma_f32_16x16x32_bf16 v[26:29], v[150:153], v[200:203], v[26:29]
	v_mfma_f32_16x16x32_bf16 v[18:21], v[158:161], v[200:203], v[18:21]
	v_mfma_f32_16x16x32_bf16 v[10:13], v[150:153], v[208:211], v[10:13]
	v_mfma_f32_16x16x32_bf16 v[2:5], v[158:161], v[208:211], v[2:5]
	s_setprio 0
	s_barrier
	s_add_i32 s53, 0, 0x18000
	s_add_i32 s64, 0, 0x1c000
	v_add_u32_e32 v142, s53, v1
	v_add_u32_e32 v158, s64, v1
	ds_read_b128 v[130:133], v142
	ds_read_b128 v[134:137], v142 offset:1024
	ds_read_b128 v[138:141], v142 offset:2048
	ds_read_b128 v[142:145], v142 offset:3072
	ds_read_b128 v[146:149], v158
	ds_read_b128 v[150:153], v158 offset:1024
	ds_read_b128 v[154:157], v158 offset:2048
	ds_read_b128 v[158:161], v158 offset:3072
	s_add_u32 s26, s26, 0x80000
	s_addc_u32 s27, s27, 0
	s_mov_b32 m0, s30
	v_lshl_add_u64 v[216:217], s[26:27], 0, v[166:167]
	ds_read_b128 v[162:165], v181 offset:32768
	ds_read_b128 v[174:177], v181 offset:33792
	ds_read_b128 v[188:191], v181 offset:34816
	ds_read_b128 v[192:195], v181 offset:35840
	ds_read_b128 v[196:199], v181 offset:36864
	ds_read_b128 v[200:203], v181 offset:37888
	ds_read_b128 v[204:207], v181 offset:38912
	ds_read_b128 v[208:211], v181 offset:39936
	global_load_lds_dwordx4 v[216:217], off
	v_lshl_add_u64 v[216:217], s[26:27], 0, v[168:169]
	s_mov_b32 m0, s31
	s_nop 0
	global_load_lds_dwordx4 v[216:217], off
	s_waitcnt vmcnt(8)
	s_waitcnt lgkmcnt(0)
	s_barrier
	s_setprio 1
	v_mfma_f32_16x16x32_bf16 v[122:125], v[130:133], v[162:165], v[122:125]
	v_mfma_f32_16x16x32_bf16 v[118:121], v[138:141], v[162:165], v[118:121]
	v_mfma_f32_16x16x32_bf16 v[110:113], v[130:133], v[188:191], v[110:113]
	v_mfma_f32_16x16x32_bf16 v[102:105], v[138:141], v[188:191], v[102:105]
	v_mfma_f32_16x16x32_bf16 v[94:97], v[130:133], v[196:199], v[94:97]
	v_mfma_f32_16x16x32_bf16 v[86:89], v[138:141], v[196:199], v[86:89]
	v_mfma_f32_16x16x32_bf16 v[78:81], v[130:133], v[204:207], v[78:81]
	v_mfma_f32_16x16x32_bf16 v[70:73], v[138:141], v[204:207], v[70:73]
	v_mfma_f32_16x16x32_bf16 v[122:125], v[134:137], v[174:177], v[122:125]
	v_mfma_f32_16x16x32_bf16 v[118:121], v[142:145], v[174:177], v[118:121]
	v_mfma_f32_16x16x32_bf16 v[110:113], v[134:137], v[192:195], v[110:113]
	v_mfma_f32_16x16x32_bf16 v[102:105], v[142:145], v[192:195], v[102:105]
	v_mfma_f32_16x16x32_bf16 v[94:97], v[134:137], v[200:203], v[94:97]
	v_mfma_f32_16x16x32_bf16 v[86:89], v[142:145], v[200:203], v[86:89]
	v_mfma_f32_16x16x32_bf16 v[78:81], v[134:137], v[208:211], v[78:81]
	v_mfma_f32_16x16x32_bf16 v[70:73], v[142:145], v[208:211], v[70:73]
	v_mfma_f32_16x16x32_bf16 v[126:129], v[146:149], v[162:165], v[126:129]
	v_mfma_f32_16x16x32_bf16 v[114:117], v[154:157], v[162:165], v[114:117]
	v_mfma_f32_16x16x32_bf16 v[106:109], v[146:149], v[188:191], v[106:109]
	v_mfma_f32_16x16x32_bf16 v[98:101], v[154:157], v[188:191], v[98:101]
	v_mfma_f32_16x16x32_bf16 v[90:93], v[146:149], v[196:199], v[90:93]
	v_mfma_f32_16x16x32_bf16 v[82:85], v[154:157], v[196:199], v[82:85]
	v_mfma_f32_16x16x32_bf16 v[74:77], v[146:149], v[204:207], v[74:77]
	v_mfma_f32_16x16x32_bf16 v[66:69], v[154:157], v[204:207], v[66:69]
	v_mfma_f32_16x16x32_bf16 v[126:129], v[150:153], v[174:177], v[126:129]
	v_mfma_f32_16x16x32_bf16 v[114:117], v[158:161], v[174:177], v[114:117]
	v_mfma_f32_16x16x32_bf16 v[106:109], v[150:153], v[192:195], v[106:109]
	v_mfma_f32_16x16x32_bf16 v[98:101], v[158:161], v[192:195], v[98:101]
	v_mfma_f32_16x16x32_bf16 v[90:93], v[150:153], v[200:203], v[90:93]
	v_mfma_f32_16x16x32_bf16 v[82:85], v[158:161], v[200:203], v[82:85]
	v_mfma_f32_16x16x32_bf16 v[74:77], v[150:153], v[208:211], v[74:77]
	v_mfma_f32_16x16x32_bf16 v[66:69], v[158:161], v[208:211], v[66:69]
	s_setprio 0
	s_barrier
; #define PG8_STAGE(bufoff, gbase, voff) do { _Pragma("unroll") for (int _i = 0; _i < 2; ++_i) \
;         __builtin_amdgcn_global_load_lds((const unsigned*)((const char*)(gbase) + (voff)[_i]), (LAS unsigned*)(lds + (bufoff) + ldsw + _i * 8192), 16, 0, 0); } while (0)
; #define PG8_LDA(dst, b, h) do { _Pragma("unroll") for (int m = 0; m < 4; ++m) _Pragma("unroll") for (int k = 0; k < 2; ++k) dst[m][k] = *(const LAS bf16x8*)(lds + PG8_SA(b, h) + aoff + m * 2048 + k * 1024); } while (0)
; #define PG8_MMA(ai, bj, At, Bt) do { __builtin_amdgcn_s_setprio(1); _Pragma("unroll") for (int m = 0; m < 4; ++m) _Pragma("unroll") for (int n = 0; n < 2; ++n) _Pragma("unroll") for (int k = 0; k < 2; ++k) \
;         acc[ai][bj][m][n] = __builtin_amdgcn_mfma_f32_16x16x32_bf16(Bt[n][k], At[m][k], acc[ai][bj][m][n], 0, 0, 0); __builtin_amdgcn_s_setprio(0); } while (0)
; #define PG8_WAIT_V(n) asm volatile("s_waitcnt vmcnt(" #n ")" ::: "memory")
; #define PG8_WAIT_L(n) asm volatile("s_waitcnt lgkmcnt(" #n ")" ::: "memory")
; #define PG8_BAR __builtin_amdgcn_s_barrier()
; #define PG8_SCHED __builtin_amdgcn_sched_barrier(0)
; template <class Epi>
; __device__ __forceinline__ void gemm_phase(LAS unsigned char* lds, const Gemm g, const StaticOrder& S, const Epi& E) {
;     ...
;             PG8_LDA(At, 1, 1); PG8_STAGE(PG8_SB(1, 0), b3, voffB); PG8_STAGE(PG8_SB(1, 1), b3 + hstepB, voffB); PG8_STAGE(PG8_SA(1, 0), a3, voffA);
;             PG8_WAIT_V(8); PG8_WAIT_L(0); PG8_BAR; PG8_MMA(1, 0, At, B0); PG8_MMA(1, 1, At, B1); PG8_BAR; PG8_SCHED;
;         }
	s_add_i32 s26, s53, s28
	v_lshl_add_u64 v[178:179], v[178:179], 0, s[84:85]
	s_mov_b32 m0, s26
	ds_read_b128 v[162:165], v181 offset:49152
	ds_read_b128 v[174:177], v181 offset:50176
	ds_read_b128 v[188:191], v181 offset:51200
	ds_read_b128 v[192:195], v181 offset:52224
	ds_read_b128 v[196:199], v181 offset:53248
	ds_read_b128 v[200:203], v181 offset:54272
	ds_read_b128 v[204:207], v181 offset:55296
	ds_read_b128 v[208:211], v181 offset:56320
	global_load_lds_dwordx4 v[178:179], off
	s_add_i32 m0, s26, 0x2000
	s_add_u32 s14, s14, 0x80080
	v_lshl_add_u64 v[178:179], v[184:185], 0, s[84:85]
	s_addc_u32 s15, s15, 0
	s_add_i32 s26, s64, s28
	global_load_lds_dwordx4 v[178:179], off
	v_lshl_add_u64 v[178:179], s[14:15], 0, v[166:167]
	s_mov_b32 m0, s26
	s_nop 0
	global_load_lds_dwordx4 v[178:179], off
	v_lshl_add_u64 v[178:179], s[14:15], 0, v[168:169]
	s_add_i32 m0, s26, 0x2000
	s_nop 0
	global_load_lds_dwordx4 v[178:179], off
	v_lshl_add_u64 v[178:179], v[212:213], 0, s[84:85]
	s_mov_b32 m0, s35
	s_nop 0
	global_load_lds_dwordx4 v[178:179], off
	v_lshl_add_u64 v[178:179], v[214:215], 0, s[84:85]
	s_mov_b32 m0, s42
	s_nop 0
	global_load_lds_dwordx4 v[178:179], off
	s_waitcnt vmcnt(8)
	s_waitcnt lgkmcnt(0)
	s_barrier
	s_setprio 1
	v_mfma_f32_16x16x32_bf16 v[62:65], v[130:133], v[162:165], v[62:65]
	v_mfma_f32_16x16x32_bf16 v[54:57], v[138:141], v[162:165], v[54:57]
	v_mfma_f32_16x16x32_bf16 v[46:49], v[130:133], v[188:191], v[46:49]
	v_mfma_f32_16x16x32_bf16 v[38:41], v[138:141], v[188:191], v[38:41]
	v_mfma_f32_16x16x32_bf16 v[30:33], v[130:133], v[196:199], v[30:33]
	v_mfma_f32_16x16x32_bf16 v[22:25], v[138:141], v[196:199], v[22:25]
	v_mfma_f32_16x16x32_bf16 v[14:17], v[130:133], v[204:207], v[14:17]
	v_mfma_f32_16x16x32_bf16 v[6:9], v[138:141], v[204:207], v[6:9]
	v_mfma_f32_16x16x32_bf16 v[62:65], v[134:137], v[174:177], v[62:65]
	v_mfma_f32_16x16x32_bf16 v[54:57], v[142:145], v[174:177], v[54:57]
	v_mfma_f32_16x16x32_bf16 v[46:49], v[134:137], v[192:195], v[46:49]
	v_mfma_f32_16x16x32_bf16 v[38:41], v[142:145], v[192:195], v[38:41]
	v_mfma_f32_16x16x32_bf16 v[30:33], v[134:137], v[200:203], v[30:33]
	v_mfma_f32_16x16x32_bf16 v[22:25], v[142:145], v[200:203], v[22:25]
	v_mfma_f32_16x16x32_bf16 v[14:17], v[134:137], v[208:211], v[14:17]
	v_mfma_f32_16x16x32_bf16 v[6:9], v[142:145], v[208:211], v[6:9]
	v_mfma_f32_16x16x32_bf16 v[58:61], v[146:149], v[162:165], v[58:61]
	v_mfma_f32_16x16x32_bf16 v[50:53], v[154:157], v[162:165], v[50:53]
	v_mfma_f32_16x16x32_bf16 v[42:45], v[146:149], v[188:191], v[42:45]
	v_mfma_f32_16x16x32_bf16 v[34:37], v[154:157], v[188:191], v[34:37]
	v_mfma_f32_16x16x32_bf16 v[26:29], v[146:149], v[196:199], v[26:29]
	v_mfma_f32_16x16x32_bf16 v[18:21], v[154:157], v[196:199], v[18:21]
	v_mfma_f32_16x16x32_bf16 v[10:13], v[146:149], v[204:207], v[10:13]
	v_mfma_f32_16x16x32_bf16 v[2:5], v[154:157], v[204:207], v[2:5]
	v_mfma_f32_16x16x32_bf16 v[58:61], v[150:153], v[174:177], v[58:61]
	v_mfma_f32_16x16x32_bf16 v[50:53], v[158:161], v[174:177], v[50:53]
	v_mfma_f32_16x16x32_bf16 v[42:45], v[150:153], v[192:195], v[42:45]
	v_mfma_f32_16x16x32_bf16 v[34:37], v[158:161], v[192:195], v[34:37]
	v_mfma_f32_16x16x32_bf16 v[26:29], v[150:153], v[200:203], v[26:29]
	v_mfma_f32_16x16x32_bf16 v[18:21], v[158:161], v[200:203], v[18:21]
	v_mfma_f32_16x16x32_bf16 v[10:13], v[150:153], v[208:211], v[10:13]
	v_mfma_f32_16x16x32_bf16 v[2:5], v[158:161], v[208:211], v[2:5]
	s_setprio 0
	s_barrier
	s_add_i32 s41, s41, 2
	s_add_u32 s24, s24, 0x100
	s_addc_u32 s25, s25, 0
	s_add_u32 s40, s40, 0x100
	s_addc_u32 s52, s52, 0
	s_cmp_gt_u32 s41, 29
	s_cbranch_scc0 .LBB0_1324
	s_cmp_ge_u32 s74, 16
	s_cbranch_scc1 .Lwpf_b
	s_lshl_b32 s100, s74, 9
	v_add_u32_e32 v130, s100, v246
	v_lshrrev_b32_e32 v131, 2, v130
	v_and_b32_e32 v130, 3, v130
	v_lshlrev_b32_e32 v130, 7, v130
	v_lshl_add_u32 v130, v131, 12, v130
	s_add_u32 s100, s88, 0x1800000
	s_addc_u32 s101, s89, 0
	s_mov_b32 m0, 0x21000
	s_nop 0
	global_load_lds_dword v130, s[100:101]

; #define PG8_STAGE(bufoff, gbase, voff) do { _Pragma("unroll") for (int _i = 0; _i < 2; ++_i) \
;         __builtin_amdgcn_global_load_lds((const unsigned*)((const char*)(gbase) + (voff)[_i]), (LAS unsigned*)(lds + (bufoff) + ldsw + _i * 8192), 16, 0, 0); } while (0)
; #define PG8_LDA(dst, b, h) do { _Pragma("unroll") for (int m = 0; m < 4; ++m) _Pragma("unroll") for (int k = 0; k < 2; ++k) dst[m][k] = *(const LAS bf16x8*)(lds + PG8_SA(b, h) + aoff + m * 2048 + k * 1024); } while (0)
; #define PG8_LDB(dst, b, h) do { _Pragma("unroll") for (int n = 0; n < 2; ++n) _Pragma("unroll") for (int k = 0; k < 2; ++k) dst[n][k] = *(const LAS bf16x8*)(lds + PG8_SB(b, h) + boff + n * 2048 + k * 1024); } while (0)
; #define PG8_MMA(ai, bj, At, Bt) do { __builtin_amdgcn_s_setprio(1); _Pragma("unroll") for (int m = 0; m < 4; ++m) _Pragma("unroll") for (int n = 0; n < 2; ++n) _Pragma("unroll") for (int k = 0; k < 2; ++k) \
;         acc[ai][bj][m][n] = __builtin_amdgcn_mfma_f32_16x16x32_bf16(Bt[n][k], At[m][k], acc[ai][bj][m][n], 0, 0, 0); __builtin_amdgcn_s_setprio(0); } while (0)
; #define PG8_WAIT_V(n) asm volatile("s_waitcnt vmcnt(" #n ")" ::: "memory")
; #define PG8_WAIT_L(n) asm volatile("s_waitcnt lgkmcnt(" #n ")" ::: "memory")
; #define PG8_BAR __builtin_amdgcn_s_barrier()
; #define PG8_SCHED __builtin_amdgcn_sched_barrier(0)
; template <class Epi>
; __device__ __forceinline__ void gemm_phase(LAS unsigned char* lds, const Gemm g, const StaticOrder& S, const Epi& E) {
;     ...
;             const bool last = (t == nt - 2);
;             const char* a1 = cA + (size_t)(t + 1) * kstep;
;             const char* a2 = last ? nA : cA + (size_t)(t + 2) * kstep; const char* b2 = last ? nB : cB + (size_t)(t + 2) * kstep;
;             const char* a3 = a2 + kstep; const char* b3 = b2 + kstep;
;             PG8_LDB(B0, 0, 0); PG8_LDB(B1, 0, 1); PG8_SCHED; PG8_LDA(At, 0, 0); PG8_STAGE(PG8_SA(1, 1), a1 + hstepA, voffA);
;             PG8_WAIT_V(8); PG8_WAIT_L(0); PG8_BAR; PG8_MMA(0, 0, At, B0); PG8_MMA(0, 1, At, B1); PG8_BAR; PG8_SCHED;
;             PG8_LDA(At, 0, 1); PG8_STAGE(PG8_SB(0, 0), b2, voffB); PG8_STAGE(PG8_SB(0, 1), b2 + hstepB, voffB); PG8_STAGE(PG8_SA(0, 0), a2, voffA);
;             PG8_WAIT_V(8); PG8_WAIT_L(0); PG8_BAR; PG8_MMA(1, 0, At, B0); PG8_MMA(1, 1, At, B1); PG8_BAR; PG8_SCHED;
.LBB0_1412:
	s_add_u32 s14, s22, 0xfff80080
	s_addc_u32 s15, s23, -1
	s_add_i32 s41, 0, 0x10000
	s_cmp_eq_u32 s64, 28
	s_cselect_b32 s25, s3, s15
	s_cselect_b32 s24, s7, s14
	s_cselect_b32 s15, s13, s63
	s_cselect_b32 s14, s17, s40
	s_add_i32 s65, 0, 0x14000
	v_add_u32_e32 v142, s41, v1
	v_add_u32_e32 v163, s65, v1
	ds_read_b128 v[130:133], v142
	ds_read_b128 v[134:137], v142 offset:1024
	ds_read_b128 v[138:141], v142 offset:2048
	ds_read_b128 v[142:145], v142 offset:3072
	ds_read_b128 v[158:161], v163
	ds_read_b128 v[164:167], v163 offset:1024
	ds_read_b128 v[168:171], v163 offset:2048
	ds_read_b128 v[172:175], v163 offset:3072
	v_lshl_add_u64 v[184:185], s[22:23], 0, v[154:155]
	s_add_i32 m0, s30, 0xc000
	ds_read_b128 v[176:179], v162
	ds_read_b128 v[188:191], v162 offset:1024
	ds_read_b128 v[192:195], v162 offset:2048
	ds_read_b128 v[196:199], v162 offset:3072
	ds_read_b128 v[200:203], v162 offset:4096
	ds_read_b128 v[204:207], v162 offset:5120
	ds_read_b128 v[208:211], v162 offset:6144
	ds_read_b128 v[212:215], v162 offset:7168
	global_load_lds_dwordx4 v[184:185], off
	v_lshl_add_u64 v[184:185], s[22:23], 0, v[156:157]
	s_add_i32 m0, s30, 0xe000
	s_nop 0
	global_load_lds_dwordx4 v[184:185], off
	s_waitcnt vmcnt(8)
	s_waitcnt lgkmcnt(0)
	s_barrier
	s_setprio 1
	v_mfma_f32_16x16x32_bf16 v[126:129], v[130:133], v[176:179], v[126:129]
	v_mfma_f32_16x16x32_bf16 v[122:125], v[138:141], v[176:179], v[122:125]
	v_mfma_f32_16x16x32_bf16 v[118:121], v[130:133], v[192:195], v[118:121]
	v_mfma_f32_16x16x32_bf16 v[110:113], v[138:141], v[192:195], v[110:113]
	v_mfma_f32_16x16x32_bf16 v[102:105], v[130:133], v[200:203], v[102:105]
	v_mfma_f32_16x16x32_bf16 v[94:97], v[138:141], v[200:203], v[94:97]
	v_mfma_f32_16x16x32_bf16 v[86:89], v[130:133], v[208:211], v[86:89]
	v_mfma_f32_16x16x32_bf16 v[78:81], v[138:141], v[208:211], v[78:81]
	v_mfma_f32_16x16x32_bf16 v[126:129], v[134:137], v[188:191], v[126:129]
	v_mfma_f32_16x16x32_bf16 v[122:125], v[142:145], v[188:191], v[122:125]
	v_mfma_f32_16x16x32_bf16 v[118:121], v[134:137], v[196:199], v[118:121]
	v_mfma_f32_16x16x32_bf16 v[110:113], v[142:145], v[196:199], v[110:113]
	v_mfma_f32_16x16x32_bf16 v[102:105], v[134:137], v[204:207], v[102:105]
	v_mfma_f32_16x16x32_bf16 v[94:97], v[142:145], v[204:207], v[94:97]
	v_mfma_f32_16x16x32_bf16 v[86:89], v[134:137], v[212:215], v[86:89]
	v_mfma_f32_16x16x32_bf16 v[78:81], v[142:145], v[212:215], v[78:81]
	v_mfma_f32_16x16x32_bf16 v[114:117], v[158:161], v[176:179], v[114:117]
	v_mfma_f32_16x16x32_bf16 v[106:109], v[168:171], v[176:179], v[106:109]
	v_mfma_f32_16x16x32_bf16 v[98:101], v[158:161], v[192:195], v[98:101]
	v_mfma_f32_16x16x32_bf16 v[90:93], v[168:171], v[192:195], v[90:93]
	v_mfma_f32_16x16x32_bf16 v[82:85], v[158:161], v[200:203], v[82:85]
	v_mfma_f32_16x16x32_bf16 v[74:77], v[168:171], v[200:203], v[74:77]
	v_mfma_f32_16x16x32_bf16 v[70:73], v[158:161], v[208:211], v[70:73]
	v_mfma_f32_16x16x32_bf16 v[66:69], v[168:171], v[208:211], v[66:69]
	v_mfma_f32_16x16x32_bf16 v[114:117], v[164:167], v[188:191], v[114:117]
	v_mfma_f32_16x16x32_bf16 v[106:109], v[172:175], v[188:191], v[106:109]
	v_mfma_f32_16x16x32_bf16 v[98:101], v[164:167], v[196:199], v[98:101]
	v_mfma_f32_16x16x32_bf16 v[90:93], v[172:175], v[196:199], v[90:93]
	v_mfma_f32_16x16x32_bf16 v[82:85], v[164:167], v[204:207], v[82:85]
	v_mfma_f32_16x16x32_bf16 v[74:77], v[172:175], v[204:207], v[74:77]
	v_mfma_f32_16x16x32_bf16 v[70:73], v[164:167], v[212:215], v[70:73]
	v_mfma_f32_16x16x32_bf16 v[66:69], v[172:175], v[212:215], v[66:69]
	s_setprio 0
	s_barrier
	s_add_i32 s41, s41, s28
	v_lshl_add_u64 v[184:185], s[14:15], 0, v[150:151]
	s_mov_b32 m0, s41
	ds_read_b128 v[176:179], v162 offset:16384
	ds_read_b128 v[188:191], v162 offset:17408
	ds_read_b128 v[192:195], v162 offset:18432
	ds_read_b128 v[196:199], v162 offset:19456
	ds_read_b128 v[200:203], v162 offset:20480
	ds_read_b128 v[204:207], v162 offset:21504
	ds_read_b128 v[208:211], v162 offset:22528
	ds_read_b128 v[212:215], v162 offset:23552
	global_load_lds_dwordx4 v[184:185], off
	s_add_i32 m0, s41, 0x2000
	s_add_u32 s68, s14, 0x80000
	v_lshl_add_u64 v[216:217], s[14:15], 0, v[146:147]
	s_addc_u32 s69, s15, 0
	s_add_i32 s41, s65, s28
	global_load_lds_dwordx4 v[216:217], off
	v_lshl_add_u64 v[218:219], s[68:69], 0, v[150:151]
	s_mov_b32 m0, s41
	v_lshl_add_u64 v[220:221], s[24:25], 0, v[148:149]
	global_load_lds_dwordx4 v[218:219], off
	v_lshl_add_u64 v[218:219], s[68:69], 0, v[146:147]
	s_add_i32 m0, s41, 0x2000
	s_nop 0
	global_load_lds_dwordx4 v[218:219], off
	v_lshl_add_u64 v[218:219], s[24:25], 0, v[152:153]
	s_mov_b32 m0, s30
	s_nop 0
	global_load_lds_dwordx4 v[218:219], off
	s_mov_b32 m0, s31
	s_nop 0
	global_load_lds_dwordx4 v[220:221], off
	s_waitcnt vmcnt(8)
	s_waitcnt lgkmcnt(0)
	s_barrier
; #define PG8_STAGE(bufoff, gbase, voff) do { _Pragma("unroll") for (int _i = 0; _i < 2; ++_i) \
;         __builtin_amdgcn_global_load_lds((const unsigned*)((const char*)(gbase) + (voff)[_i]), (LAS unsigned*)(lds + (bufoff) + ldsw + _i * 8192), 16, 0, 0); } while (0)
; #define PG8_LDA(dst, b, h) do { _Pragma("unroll") for (int m = 0; m < 4; ++m) _Pragma("unroll") for (int k = 0; k < 2; ++k) dst[m][k] = *(const LAS bf16x8*)(lds + PG8_SA(b, h) + aoff + m * 2048 + k * 1024); } while (0)
; #define PG8_LDB(dst, b, h) do { _Pragma("unroll") for (int n = 0; n < 2; ++n) _Pragma("unroll") for (int k = 0; k < 2; ++k) dst[n][k] = *(const LAS bf16x8*)(lds + PG8_SB(b, h) + boff + n * 2048 + k * 1024); } while (0)
; #define PG8_MMA(ai, bj, At, Bt) do { __builtin_amdgcn_s_setprio(1); _Pragma("unroll") for (int m = 0; m < 4; ++m) _Pragma("unroll") for (int n = 0; n < 2; ++n) _Pragma("unroll") for (int k = 0; k < 2; ++k) \
;         acc[ai][bj][m][n] = __builtin_amdgcn_mfma_f32_16x16x32_bf16(Bt[n][k], At[m][k], acc[ai][bj][m][n], 0, 0, 0); __builtin_amdgcn_s_setprio(0); } while (0)
; #define PG8_WAIT_V(n) asm volatile("s_waitcnt vmcnt(" #n ")" ::: "memory")
; #define PG8_WAIT_L(n) asm volatile("s_waitcnt lgkmcnt(" #n ")" ::: "memory")
; #define PG8_BAR __builtin_amdgcn_s_barrier()
; #define PG8_SCHED __builtin_amdgcn_sched_barrier(0)
; template <class Epi>
; __device__ __forceinline__ void gemm_phase(LAS unsigned char* lds, const Gemm g, const StaticOrder& S, const Epi& E) {
;     ...
;             PG8_WAIT_V(8); PG8_WAIT_L(0); PG8_BAR; PG8_MMA(1, 0, At, B0); PG8_MMA(1, 1, At, B1); PG8_BAR; PG8_SCHED;
;             PG8_LDB(B0, 1, 0); PG8_LDB(B1, 1, 1); PG8_SCHED; PG8_LDA(At, 1, 0); PG8_STAGE(PG8_SA(0, 1), a2 + hstepA, voffA);
;             PG8_WAIT_V(8); PG8_WAIT_L(0); PG8_BAR; PG8_MMA(0, 0, At, B0); PG8_MMA(0, 1, At, B1); PG8_BAR; PG8_SCHED;
	s_setprio 1
	v_mfma_f32_16x16x32_bf16 v[62:65], v[130:133], v[176:179], v[62:65]
	v_mfma_f32_16x16x32_bf16 v[58:61], v[138:141], v[176:179], v[58:61]
	v_mfma_f32_16x16x32_bf16 v[54:57], v[130:133], v[192:195], v[54:57]
	v_mfma_f32_16x16x32_bf16 v[46:49], v[138:141], v[192:195], v[46:49]
	v_mfma_f32_16x16x32_bf16 v[38:41], v[130:133], v[200:203], v[38:41]
	v_mfma_f32_16x16x32_bf16 v[30:33], v[138:141], v[200:203], v[30:33]
	v_mfma_f32_16x16x32_bf16 v[22:25], v[130:133], v[208:211], v[22:25]
	v_mfma_f32_16x16x32_bf16 v[14:17], v[138:141], v[208:211], v[14:17]
	v_mfma_f32_16x16x32_bf16 v[62:65], v[134:137], v[188:191], v[62:65]
	v_mfma_f32_16x16x32_bf16 v[58:61], v[142:145], v[188:191], v[58:61]
	v_mfma_f32_16x16x32_bf16 v[54:57], v[134:137], v[196:199], v[54:57]
	v_mfma_f32_16x16x32_bf16 v[46:49], v[142:145], v[196:199], v[46:49]
	v_mfma_f32_16x16x32_bf16 v[38:41], v[134:137], v[204:207], v[38:41]
	v_mfma_f32_16x16x32_bf16 v[30:33], v[142:145], v[204:207], v[30:33]
	v_mfma_f32_16x16x32_bf16 v[22:25], v[134:137], v[212:215], v[22:25]
	v_mfma_f32_16x16x32_bf16 v[14:17], v[142:145], v[212:215], v[14:17]
	v_mfma_f32_16x16x32_bf16 v[50:53], v[158:161], v[176:179], v[50:53]
	v_mfma_f32_16x16x32_bf16 v[42:45], v[168:171], v[176:179], v[42:45]
	v_mfma_f32_16x16x32_bf16 v[34:37], v[158:161], v[192:195], v[34:37]
	v_mfma_f32_16x16x32_bf16 v[26:29], v[168:171], v[192:195], v[26:29]
	v_mfma_f32_16x16x32_bf16 v[18:21], v[158:161], v[200:203], v[18:21]
	v_mfma_f32_16x16x32_bf16 v[10:13], v[168:171], v[200:203], v[10:13]
	v_mfma_f32_16x16x32_bf16 v[6:9], v[158:161], v[208:211], v[6:9]
	v_mfma_f32_16x16x32_bf16 v[2:5], v[168:171], v[208:211], v[2:5]
	v_mfma_f32_16x16x32_bf16 v[50:53], v[164:167], v[188:191], v[50:53]
	v_mfma_f32_16x16x32_bf16 v[42:45], v[172:175], v[188:191], v[42:45]
	v_mfma_f32_16x16x32_bf16 v[34:37], v[164:167], v[196:199], v[34:37]
	v_mfma_f32_16x16x32_bf16 v[26:29], v[172:175], v[196:199], v[26:29]
	v_mfma_f32_16x16x32_bf16 v[18:21], v[164:167], v[204:207], v[18:21]
	v_mfma_f32_16x16x32_bf16 v[10:13], v[172:175], v[204:207], v[10:13]
	v_mfma_f32_16x16x32_bf16 v[6:9], v[164:167], v[212:215], v[6:9]
	v_mfma_f32_16x16x32_bf16 v[2:5], v[172:175], v[212:215], v[2:5]
	s_setprio 0
	s_barrier
	s_add_i32 s41, 0, 0x18000
	s_add_i32 s65, 0, 0x1c000
	v_add_u32_e32 v142, s41, v1
	v_add_u32_e32 v163, s65, v1
	ds_read_b128 v[130:133], v142
	ds_read_b128 v[134:137], v142 offset:1024
	ds_read_b128 v[138:141], v142 offset:2048
	ds_read_b128 v[142:145], v142 offset:3072
	ds_read_b128 v[158:161], v163
	ds_read_b128 v[164:167], v163 offset:1024
	ds_read_b128 v[168:171], v163 offset:2048
	ds_read_b128 v[172:175], v163 offset:3072
	s_add_u32 s24, s24, 0x80000
	s_addc_u32 s25, s25, 0
	s_mov_b32 m0, s33
	v_lshl_add_u64 v[222:223], s[24:25], 0, v[152:153]
	ds_read_b128 v[176:179], v162 offset:32768
	ds_read_b128 v[188:191], v162 offset:33792
	ds_read_b128 v[192:195], v162 offset:34816
	ds_read_b128 v[196:199], v162 offset:35840
	ds_read_b128 v[200:203], v162 offset:36864
	ds_read_b128 v[204:207], v162 offset:37888
	ds_read_b128 v[208:211], v162 offset:38912
	ds_read_b128 v[212:215], v162 offset:39936
	global_load_lds_dwordx4 v[222:223], off
	v_lshl_add_u64 v[222:223], s[24:25], 0, v[148:149]
	s_mov_b32 m0, s34
	s_nop 0
	global_load_lds_dwordx4 v[222:223], off
	s_waitcnt vmcnt(8)
	s_waitcnt lgkmcnt(0)
	s_barrier
	s_setprio 1
	v_mfma_f32_16x16x32_bf16 v[126:129], v[130:133], v[176:179], v[126:129]
	v_mfma_f32_16x16x32_bf16 v[122:125], v[138:141], v[176:179], v[122:125]
	v_mfma_f32_16x16x32_bf16 v[118:121], v[130:133], v[192:195], v[118:121]
	v_mfma_f32_16x16x32_bf16 v[110:113], v[138:141], v[192:195], v[110:113]
	v_mfma_f32_16x16x32_bf16 v[102:105], v[130:133], v[200:203], v[102:105]
	v_mfma_f32_16x16x32_bf16 v[94:97], v[138:141], v[200:203], v[94:97]
	v_mfma_f32_16x16x32_bf16 v[86:89], v[130:133], v[208:211], v[86:89]
	v_mfma_f32_16x16x32_bf16 v[78:81], v[138:141], v[208:211], v[78:81]
	v_mfma_f32_16x16x32_bf16 v[126:129], v[134:137], v[188:191], v[126:129]
	v_mfma_f32_16x16x32_bf16 v[122:125], v[142:145], v[188:191], v[122:125]
	v_mfma_f32_16x16x32_bf16 v[118:121], v[134:137], v[196:199], v[118:121]
	v_mfma_f32_16x16x32_bf16 v[110:113], v[142:145], v[196:199], v[110:113]
	v_mfma_f32_16x16x32_bf16 v[102:105], v[134:137], v[204:207], v[102:105]
	v_mfma_f32_16x16x32_bf16 v[94:97], v[142:145], v[204:207], v[94:97]
	v_mfma_f32_16x16x32_bf16 v[86:89], v[134:137], v[212:215], v[86:89]
	v_mfma_f32_16x16x32_bf16 v[78:81], v[142:145], v[212:215], v[78:81]
	v_mfma_f32_16x16x32_bf16 v[114:117], v[158:161], v[176:179], v[114:117]
	v_mfma_f32_16x16x32_bf16 v[106:109], v[168:171], v[176:179], v[106:109]
	v_mfma_f32_16x16x32_bf16 v[98:101], v[158:161], v[192:195], v[98:101]
	v_mfma_f32_16x16x32_bf16 v[90:93], v[168:171], v[192:195], v[90:93]
	v_mfma_f32_16x16x32_bf16 v[82:85], v[158:161], v[200:203], v[82:85]
	v_mfma_f32_16x16x32_bf16 v[74:77], v[168:171], v[200:203], v[74:77]
	v_mfma_f32_16x16x32_bf16 v[70:73], v[158:161], v[208:211], v[70:73]
	v_mfma_f32_16x16x32_bf16 v[66:69], v[168:171], v[208:211], v[66:69]
	v_mfma_f32_16x16x32_bf16 v[114:117], v[164:167], v[188:191], v[114:117]
	v_mfma_f32_16x16x32_bf16 v[106:109], v[172:175], v[188:191], v[106:109]
	v_mfma_f32_16x16x32_bf16 v[98:101], v[164:167], v[196:199], v[98:101]
	v_mfma_f32_16x16x32_bf16 v[90:93], v[172:175], v[196:199], v[90:93]
	v_mfma_f32_16x16x32_bf16 v[82:85], v[164:167], v[204:207], v[82:85]
	v_mfma_f32_16x16x32_bf16 v[74:77], v[172:175], v[204:207], v[74:77]
	v_mfma_f32_16x16x32_bf16 v[70:73], v[164:167], v[212:215], v[70:73]
	v_mfma_f32_16x16x32_bf16 v[66:69], v[172:175], v[212:215], v[66:69]
	s_setprio 0
	s_barrier
; #define PG8_STAGE(bufoff, gbase, voff) do { _Pragma("unroll") for (int _i = 0; _i < 2; ++_i) \
;         __builtin_amdgcn_global_load_lds((const unsigned*)((const char*)(gbase) + (voff)[_i]), (LAS unsigned*)(lds + (bufoff) + ldsw + _i * 8192), 16, 0, 0); } while (0)
; #define PG8_LDA(dst, b, h) do { _Pragma("unroll") for (int m = 0; m < 4; ++m) _Pragma("unroll") for (int k = 0; k < 2; ++k) dst[m][k] = *(const LAS bf16x8*)(lds + PG8_SA(b, h) + aoff + m * 2048 + k * 1024); } while (0)
; #define PG8_MMA(ai, bj, At, Bt) do { __builtin_amdgcn_s_setprio(1); _Pragma("unroll") for (int m = 0; m < 4; ++m) _Pragma("unroll") for (int n = 0; n < 2; ++n) _Pragma("unroll") for (int k = 0; k < 2; ++k) \
;         acc[ai][bj][m][n] = __builtin_amdgcn_mfma_f32_16x16x32_bf16(Bt[n][k], At[m][k], acc[ai][bj][m][n], 0, 0, 0); __builtin_amdgcn_s_setprio(0); } while (0)
; #define PG8_WAIT_V(n) asm volatile("s_waitcnt vmcnt(" #n ")" ::: "memory")
; #define PG8_WAIT_L(n) asm volatile("s_waitcnt lgkmcnt(" #n ")" ::: "memory")
; #define PG8_BAR __builtin_amdgcn_s_barrier()
; #define PG8_SCHED __builtin_amdgcn_sched_barrier(0)
; template <class Epi>
; __device__ __forceinline__ void gemm_phase(LAS unsigned char* lds, const Gemm g, const StaticOrder& S, const Epi& E) {
;     ...
;             PG8_LDA(At, 1, 1); PG8_STAGE(PG8_SB(1, 0), b3, voffB); PG8_STAGE(PG8_SB(1, 1), b3 + hstepB, voffB); PG8_STAGE(PG8_SA(1, 0), a3, voffA);
;             PG8_WAIT_V(8); PG8_WAIT_L(0); PG8_BAR; PG8_MMA(1, 0, At, B0); PG8_MMA(1, 1, At, B1); PG8_BAR; PG8_SCHED;
;         }
;         if (wr == 0) PG8_BAR;
	s_add_i32 s24, s41, s28
	v_lshl_add_u64 v[184:185], v[184:185], 0, s[84:85]
	s_mov_b32 m0, s24
	ds_read_b128 v[176:179], v162 offset:49152
	ds_read_b128 v[188:191], v162 offset:50176
	ds_read_b128 v[192:195], v162 offset:51200
	ds_read_b128 v[196:199], v162 offset:52224
	ds_read_b128 v[200:203], v162 offset:53248
	ds_read_b128 v[204:207], v162 offset:54272
	ds_read_b128 v[208:211], v162 offset:55296
	ds_read_b128 v[212:215], v162 offset:56320
	global_load_lds_dwordx4 v[184:185], off
	s_add_i32 m0, s24, 0x2000
	s_add_u32 s14, s14, 0x80080
	v_lshl_add_u64 v[184:185], v[216:217], 0, s[84:85]
	s_addc_u32 s15, s15, 0
	s_add_i32 s24, s65, s28
	global_load_lds_dwordx4 v[184:185], off
	v_lshl_add_u64 v[184:185], s[14:15], 0, v[150:151]
	s_mov_b32 m0, s24
	s_nop 0
	global_load_lds_dwordx4 v[184:185], off
	v_lshl_add_u64 v[184:185], s[14:15], 0, v[146:147]
	s_add_i32 m0, s24, 0x2000
	s_nop 0
	global_load_lds_dwordx4 v[184:185], off
	v_lshl_add_u64 v[184:185], v[218:219], 0, s[84:85]
	s_mov_b32 m0, s44
	s_nop 0
	global_load_lds_dwordx4 v[184:185], off
	v_lshl_add_u64 v[184:185], v[220:221], 0, s[84:85]
	s_mov_b32 m0, s45
	s_nop 0
	global_load_lds_dwordx4 v[184:185], off
	s_waitcnt vmcnt(8)
	s_waitcnt lgkmcnt(0)
	s_barrier
	s_setprio 1
	v_mfma_f32_16x16x32_bf16 v[62:65], v[130:133], v[176:179], v[62:65]
	v_mfma_f32_16x16x32_bf16 v[58:61], v[138:141], v[176:179], v[58:61]
	v_mfma_f32_16x16x32_bf16 v[54:57], v[130:133], v[192:195], v[54:57]
	v_mfma_f32_16x16x32_bf16 v[46:49], v[138:141], v[192:195], v[46:49]
	v_mfma_f32_16x16x32_bf16 v[38:41], v[130:133], v[200:203], v[38:41]
	v_mfma_f32_16x16x32_bf16 v[30:33], v[138:141], v[200:203], v[30:33]
	v_mfma_f32_16x16x32_bf16 v[22:25], v[130:133], v[208:211], v[22:25]
	v_mfma_f32_16x16x32_bf16 v[14:17], v[138:141], v[208:211], v[14:17]
	v_mfma_f32_16x16x32_bf16 v[62:65], v[134:137], v[188:191], v[62:65]
	v_mfma_f32_16x16x32_bf16 v[58:61], v[142:145], v[188:191], v[58:61]
	v_mfma_f32_16x16x32_bf16 v[54:57], v[134:137], v[196:199], v[54:57]
	v_mfma_f32_16x16x32_bf16 v[46:49], v[142:145], v[196:199], v[46:49]
	v_mfma_f32_16x16x32_bf16 v[38:41], v[134:137], v[204:207], v[38:41]
	v_mfma_f32_16x16x32_bf16 v[30:33], v[142:145], v[204:207], v[30:33]
	v_mfma_f32_16x16x32_bf16 v[22:25], v[134:137], v[212:215], v[22:25]
	v_mfma_f32_16x16x32_bf16 v[14:17], v[142:145], v[212:215], v[14:17]
	v_mfma_f32_16x16x32_bf16 v[50:53], v[158:161], v[176:179], v[50:53]
	v_mfma_f32_16x16x32_bf16 v[42:45], v[168:171], v[176:179], v[42:45]
	v_mfma_f32_16x16x32_bf16 v[34:37], v[158:161], v[192:195], v[34:37]
	v_mfma_f32_16x16x32_bf16 v[26:29], v[168:171], v[192:195], v[26:29]
	v_mfma_f32_16x16x32_bf16 v[18:21], v[158:161], v[200:203], v[18:21]
	v_mfma_f32_16x16x32_bf16 v[10:13], v[168:171], v[200:203], v[10:13]
	v_mfma_f32_16x16x32_bf16 v[6:9], v[158:161], v[208:211], v[6:9]
	v_mfma_f32_16x16x32_bf16 v[2:5], v[168:171], v[208:211], v[2:5]
	v_mfma_f32_16x16x32_bf16 v[50:53], v[164:167], v[188:191], v[50:53]
	v_mfma_f32_16x16x32_bf16 v[42:45], v[172:175], v[188:191], v[42:45]
	v_mfma_f32_16x16x32_bf16 v[34:37], v[164:167], v[196:199], v[34:37]
	v_mfma_f32_16x16x32_bf16 v[26:29], v[172:175], v[196:199], v[26:29]
	v_mfma_f32_16x16x32_bf16 v[18:21], v[164:167], v[204:207], v[18:21]
	v_mfma_f32_16x16x32_bf16 v[10:13], v[172:175], v[204:207], v[10:13]
	v_mfma_f32_16x16x32_bf16 v[6:9], v[164:167], v[212:215], v[6:9]
	v_mfma_f32_16x16x32_bf16 v[2:5], v[172:175], v[212:215], v[2:5]
	s_setprio 0
	s_barrier
	s_add_i32 s64, s64, 2
	s_add_u32 s22, s22, 0x100
	s_addc_u32 s23, s23, 0
	s_add_u32 s40, s40, 0x100
	s_addc_u32 s63, s63, 0
	s_cmp_gt_u32 s64, 29
	s_cbranch_scc0 .LBB0_1412
	s_and_b64 vcc, exec, s[10:11]
	s_cbranch_vccz .LBB0_1415
	s_barrier

; #define PG8_STAGE(bufoff, gbase, voff) do { _Pragma("unroll") for (int _i = 0; _i < 2; ++_i) \
;         __builtin_amdgcn_global_load_lds((const unsigned*)((const char*)(gbase) + (voff)[_i]), (LAS unsigned*)(lds + (bufoff) + ldsw + _i * 8192), 16, 0, 0); } while (0)
; #define PG8_LDA(dst, b, h) do { _Pragma("unroll") for (int m = 0; m < 4; ++m) _Pragma("unroll") for (int k = 0; k < 2; ++k) dst[m][k] = *(const LAS bf16x8*)(lds + PG8_SA(b, h) + aoff + m * 2048 + k * 1024); } while (0)
; #define PG8_LDB(dst, b, h) do { _Pragma("unroll") for (int n = 0; n < 2; ++n) _Pragma("unroll") for (int k = 0; k < 2; ++k) dst[n][k] = *(const LAS bf16x8*)(lds + PG8_SB(b, h) + boff + n * 2048 + k * 1024); } while (0)
; #define PG8_MMA(ai, bj, At, Bt) do { __builtin_amdgcn_s_setprio(1); _Pragma("unroll") for (int m = 0; m < 4; ++m) _Pragma("unroll") for (int n = 0; n < 2; ++n) _Pragma("unroll") for (int k = 0; k < 2; ++k) \
;         acc[ai][bj][m][n] = __builtin_amdgcn_mfma_f32_16x16x32_bf16(Bt[n][k], At[m][k], acc[ai][bj][m][n], 0, 0, 0); __builtin_amdgcn_s_setprio(0); } while (0)
; #define PG8_WAIT_V(n) asm volatile("s_waitcnt vmcnt(" #n ")" ::: "memory")
; #define PG8_WAIT_L(n) asm volatile("s_waitcnt lgkmcnt(" #n ")" ::: "memory")
; #define PG8_BAR __builtin_amdgcn_s_barrier()
; #define PG8_SCHED __builtin_amdgcn_sched_barrier(0)
; template <class Epi>
; __device__ __forceinline__ void gemm_phase(LAS unsigned char* lds, const Gemm g, const StaticOrder& S, const Epi& E) {
;     ...
;             const bool last = (t == nt - 2);
;             const char* a1 = cA + (size_t)(t + 1) * kstep;
;             const char* a2 = last ? nA : cA + (size_t)(t + 2) * kstep; const char* b2 = last ? nB : cB + (size_t)(t + 2) * kstep;
;             const char* a3 = a2 + kstep; const char* b3 = b2 + kstep;
;             PG8_LDB(B0, 0, 0); PG8_LDB(B1, 0, 1); PG8_SCHED; PG8_LDA(At, 0, 0); PG8_STAGE(PG8_SA(1, 1), a1 + hstepA, voffA);
;             PG8_WAIT_V(8); PG8_WAIT_L(0); PG8_BAR; PG8_MMA(0, 0, At, B0); PG8_MMA(0, 1, At, B1); PG8_BAR; PG8_SCHED;
;             PG8_LDA(At, 0, 1); PG8_STAGE(PG8_SB(0, 0), b2, voffB); PG8_STAGE(PG8_SB(0, 1), b2 + hstepB, voffB); PG8_STAGE(PG8_SA(0, 0), a2, voffA);
;             PG8_WAIT_V(8); PG8_WAIT_L(0); PG8_BAR; PG8_MMA(1, 0, At, B0); PG8_MMA(1, 1, At, B1); PG8_BAR; PG8_SCHED;
.LBB0_1440:
	s_add_u32 s41, s20, s14
	s_addc_u32 s44, s21, 0
	s_add_u32 s15, s41, 0x100
	s_addc_u32 s34, s44, 0
	s_and_b64 s[30:31], s[28:29], exec
	s_cselect_b32 s31, s19, s34
	s_cselect_b32 s30, s3, s15
	s_add_u32 s14, s12, s14
	s_addc_u32 s15, s13, 0
	s_add_u32 s34, s14, 0x100
	s_addc_u32 s35, s15, 0
	s_add_i32 s81, 0, 0x10000
	s_and_b64 s[14:15], s[28:29], exec
	s_cselect_b32 s35, s17, s35
	s_cselect_b32 s34, s40, s34
	s_add_i32 s29, 0, 0x14000
	s_add_u32 s68, s41, 0x10080
	s_addc_u32 s69, s44, 0
	s_add_i32 s77, s81, s63
	s_add_i32 m0, s11, 0xc000
	s_add_i32 s83, s11, 0xe000
	s_add_i32 s80, s77, 0x2000
	v_add_u32_e32 v139, s81, v1
	s_add_u32 s44, s34, 0x10000
	ds_read_b128 v[140:143], v139
	ds_read_b128 v[144:147], v139 offset:1024
	ds_read_b128 v[148:151], v139 offset:2048
	ds_read_b128 v[152:155], v139 offset:3072
	v_add_u32_e32 v139, s29, v1
	s_addc_u32 s45, s35, 0
	s_add_i32 s79, s29, s63
	ds_read_b128 v[156:159], v139
	ds_read_b128 v[160:163], v139 offset:1024
	ds_read_b128 v[164:167], v139 offset:2048
	ds_read_b128 v[168:171], v139 offset:3072
	s_add_i32 s78, s79, 0x2000
	s_add_i32 vcc_lo, 0, 0x18000
	s_add_i32 vcc_hi, 0, 0x1c000
	s_add_u32 s14, s30, 0x10000
	s_addc_u32 s15, s31, 0
	s_add_i32 s41, vcc_lo, s63
	s_add_i32 s76, s41, 0x2000
	s_add_u32 s28, s34, 0x10080
	s_addc_u32 s29, s35, 0
	s_add_i32 s81, vcc_hi, s63
	s_add_i32 s82, s81, 0x2000
	v_lshl_add_u64 v[184:185], s[68:69], 0, v[130:131]
	ds_read_b128 v[172:175], v138
	ds_read_b128 v[176:179], v138 offset:1024
	ds_read_b128 v[188:191], v138 offset:2048
	ds_read_b128 v[192:195], v138 offset:3072
	ds_read_b128 v[196:199], v138 offset:4096
	ds_read_b128 v[200:203], v138 offset:5120
	ds_read_b128 v[204:207], v138 offset:6144
	ds_read_b128 v[208:211], v138 offset:7168
	global_load_lds_dwordx4 v[184:185], off
	v_lshl_add_u64 v[184:185], s[68:69], 0, v[134:135]
	s_mov_b32 m0, s83
	s_nop 0
	global_load_lds_dwordx4 v[184:185], off
	s_waitcnt vmcnt(8)
	s_waitcnt lgkmcnt(0)
	s_barrier
	s_setprio 1
	v_mfma_f32_16x16x32_bf16 v[126:129], v[140:143], v[172:175], v[126:129]
	v_mfma_f32_16x16x32_bf16 v[122:125], v[148:151], v[172:175], v[122:125]
	v_mfma_f32_16x16x32_bf16 v[118:121], v[140:143], v[188:191], v[118:121]
	v_mfma_f32_16x16x32_bf16 v[114:117], v[148:151], v[188:191], v[114:117]
	v_mfma_f32_16x16x32_bf16 v[102:105], v[140:143], v[196:199], v[102:105]
	v_mfma_f32_16x16x32_bf16 v[98:101], v[148:151], v[196:199], v[98:101]
	v_mfma_f32_16x16x32_bf16 v[86:89], v[140:143], v[204:207], v[86:89]
	v_mfma_f32_16x16x32_bf16 v[82:85], v[148:151], v[204:207], v[82:85]
	v_mfma_f32_16x16x32_bf16 v[126:129], v[144:147], v[176:179], v[126:129]
	v_mfma_f32_16x16x32_bf16 v[122:125], v[152:155], v[176:179], v[122:125]
	v_mfma_f32_16x16x32_bf16 v[118:121], v[144:147], v[192:195], v[118:121]
	v_mfma_f32_16x16x32_bf16 v[114:117], v[152:155], v[192:195], v[114:117]
	v_mfma_f32_16x16x32_bf16 v[102:105], v[144:147], v[200:203], v[102:105]
	v_mfma_f32_16x16x32_bf16 v[98:101], v[152:155], v[200:203], v[98:101]
	v_mfma_f32_16x16x32_bf16 v[86:89], v[144:147], v[208:211], v[86:89]
	v_mfma_f32_16x16x32_bf16 v[82:85], v[152:155], v[208:211], v[82:85]
	v_mfma_f32_16x16x32_bf16 v[110:113], v[156:159], v[172:175], v[110:113]
	v_mfma_f32_16x16x32_bf16 v[106:109], v[164:167], v[172:175], v[106:109]
	v_mfma_f32_16x16x32_bf16 v[94:97], v[156:159], v[188:191], v[94:97]
	v_mfma_f32_16x16x32_bf16 v[90:93], v[164:167], v[188:191], v[90:93]
	v_mfma_f32_16x16x32_bf16 v[78:81], v[156:159], v[196:199], v[78:81]
	v_mfma_f32_16x16x32_bf16 v[74:77], v[164:167], v[196:199], v[74:77]
	v_mfma_f32_16x16x32_bf16 v[70:73], v[156:159], v[204:207], v[70:73]
	v_mfma_f32_16x16x32_bf16 v[66:69], v[164:167], v[204:207], v[66:69]
	v_mfma_f32_16x16x32_bf16 v[110:113], v[160:163], v[176:179], v[110:113]
	v_mfma_f32_16x16x32_bf16 v[106:109], v[168:171], v[176:179], v[106:109]
	v_mfma_f32_16x16x32_bf16 v[94:97], v[160:163], v[192:195], v[94:97]
	v_mfma_f32_16x16x32_bf16 v[90:93], v[168:171], v[192:195], v[90:93]
	v_mfma_f32_16x16x32_bf16 v[78:81], v[160:163], v[200:203], v[78:81]
	v_mfma_f32_16x16x32_bf16 v[74:77], v[168:171], v[200:203], v[74:77]
	v_mfma_f32_16x16x32_bf16 v[70:73], v[160:163], v[208:211], v[70:73]
	v_mfma_f32_16x16x32_bf16 v[66:69], v[168:171], v[208:211], v[66:69]
	s_setprio 0
	s_barrier
	s_mov_b32 m0, s77
	v_lshl_add_u64 v[184:185], s[34:35], 0, v[132:133]
	ds_read_b128 v[172:175], v138 offset:16384
	ds_read_b128 v[176:179], v138 offset:17408
	ds_read_b128 v[188:191], v138 offset:18432
	ds_read_b128 v[192:195], v138 offset:19456
	ds_read_b128 v[196:199], v138 offset:20480
	ds_read_b128 v[200:203], v138 offset:21504
	ds_read_b128 v[204:207], v138 offset:22528
	ds_read_b128 v[208:211], v138 offset:23552
	global_load_lds_dwordx4 v[184:185], off
	v_lshl_add_u64 v[212:213], s[34:35], 0, v[136:137]
	s_mov_b32 m0, s80
	v_lshl_add_u64 v[214:215], s[44:45], 0, v[132:133]
	global_load_lds_dwordx4 v[212:213], off
	s_mov_b32 m0, s79
	v_lshl_add_u64 v[216:217], s[30:31], 0, v[134:135]
	global_load_lds_dwordx4 v[214:215], off
	v_lshl_add_u64 v[214:215], s[44:45], 0, v[136:137]
	s_mov_b32 m0, s78
	s_nop 0
	global_load_lds_dwordx4 v[214:215], off
	v_lshl_add_u64 v[214:215], s[30:31], 0, v[130:131]
	s_mov_b32 m0, s11
	s_nop 0
	global_load_lds_dwordx4 v[214:215], off
	s_mov_b32 m0, s64
	s_nop 0
	global_load_lds_dwordx4 v[216:217], off
	s_waitcnt vmcnt(8)
	s_waitcnt lgkmcnt(0)
	s_barrier
; #define PG8_STAGE(bufoff, gbase, voff) do { _Pragma("unroll") for (int _i = 0; _i < 2; ++_i) \
;         __builtin_amdgcn_global_load_lds((const unsigned*)((const char*)(gbase) + (voff)[_i]), (LAS unsigned*)(lds + (bufoff) + ldsw + _i * 8192), 16, 0, 0); } while (0)
; #define PG8_LDA(dst, b, h) do { _Pragma("unroll") for (int m = 0; m < 4; ++m) _Pragma("unroll") for (int k = 0; k < 2; ++k) dst[m][k] = *(const LAS bf16x8*)(lds + PG8_SA(b, h) + aoff + m * 2048 + k * 1024); } while (0)
; #define PG8_LDB(dst, b, h) do { _Pragma("unroll") for (int n = 0; n < 2; ++n) _Pragma("unroll") for (int k = 0; k < 2; ++k) dst[n][k] = *(const LAS bf16x8*)(lds + PG8_SB(b, h) + boff + n * 2048 + k * 1024); } while (0)
; #define PG8_MMA(ai, bj, At, Bt) do { __builtin_amdgcn_s_setprio(1); _Pragma("unroll") for (int m = 0; m < 4; ++m) _Pragma("unroll") for (int n = 0; n < 2; ++n) _Pragma("unroll") for (int k = 0; k < 2; ++k) \
;         acc[ai][bj][m][n] = __builtin_amdgcn_mfma_f32_16x16x32_bf16(Bt[n][k], At[m][k], acc[ai][bj][m][n], 0, 0, 0); __builtin_amdgcn_s_setprio(0); } while (0)
; #define PG8_WAIT_V(n) asm volatile("s_waitcnt vmcnt(" #n ")" ::: "memory")
; #define PG8_WAIT_L(n) asm volatile("s_waitcnt lgkmcnt(" #n ")" ::: "memory")
; #define PG8_BAR __builtin_amdgcn_s_barrier()
; #define PG8_SCHED __builtin_amdgcn_sched_barrier(0)
; template <class Epi>
; __device__ __forceinline__ void gemm_phase(LAS unsigned char* lds, const Gemm g, const StaticOrder& S, const Epi& E) {
;     ...
;             PG8_WAIT_V(8); PG8_WAIT_L(0); PG8_BAR; PG8_MMA(1, 0, At, B0); PG8_MMA(1, 1, At, B1); PG8_BAR; PG8_SCHED;
;             PG8_LDB(B0, 1, 0); PG8_LDB(B1, 1, 1); PG8_SCHED; PG8_LDA(At, 1, 0); PG8_STAGE(PG8_SA(0, 1), a2 + hstepA, voffA);
;             PG8_WAIT_V(8); PG8_WAIT_L(0); PG8_BAR; PG8_MMA(0, 0, At, B0); PG8_MMA(0, 1, At, B1); PG8_BAR; PG8_SCHED;
	s_setprio 1
	v_mfma_f32_16x16x32_bf16 v[62:65], v[140:143], v[172:175], v[62:65]
	v_mfma_f32_16x16x32_bf16 v[58:61], v[148:151], v[172:175], v[58:61]
	v_mfma_f32_16x16x32_bf16 v[54:57], v[140:143], v[188:191], v[54:57]
	v_mfma_f32_16x16x32_bf16 v[50:53], v[148:151], v[188:191], v[50:53]
	v_mfma_f32_16x16x32_bf16 v[38:41], v[140:143], v[196:199], v[38:41]
	v_mfma_f32_16x16x32_bf16 v[34:37], v[148:151], v[196:199], v[34:37]
	v_mfma_f32_16x16x32_bf16 v[22:25], v[140:143], v[204:207], v[22:25]
	v_mfma_f32_16x16x32_bf16 v[18:21], v[148:151], v[204:207], v[18:21]
	v_mfma_f32_16x16x32_bf16 v[62:65], v[144:147], v[176:179], v[62:65]
	v_mfma_f32_16x16x32_bf16 v[58:61], v[152:155], v[176:179], v[58:61]
	v_mfma_f32_16x16x32_bf16 v[54:57], v[144:147], v[192:195], v[54:57]
	v_mfma_f32_16x16x32_bf16 v[50:53], v[152:155], v[192:195], v[50:53]
	v_mfma_f32_16x16x32_bf16 v[38:41], v[144:147], v[200:203], v[38:41]
	v_mfma_f32_16x16x32_bf16 v[34:37], v[152:155], v[200:203], v[34:37]
	v_mfma_f32_16x16x32_bf16 v[22:25], v[144:147], v[208:211], v[22:25]
	v_mfma_f32_16x16x32_bf16 v[18:21], v[152:155], v[208:211], v[18:21]
	v_mfma_f32_16x16x32_bf16 v[46:49], v[156:159], v[172:175], v[46:49]
	v_mfma_f32_16x16x32_bf16 v[42:45], v[164:167], v[172:175], v[42:45]
	v_mfma_f32_16x16x32_bf16 v[30:33], v[156:159], v[188:191], v[30:33]
	v_mfma_f32_16x16x32_bf16 v[26:29], v[164:167], v[188:191], v[26:29]
	v_mfma_f32_16x16x32_bf16 v[14:17], v[156:159], v[196:199], v[14:17]
	v_mfma_f32_16x16x32_bf16 v[10:13], v[164:167], v[196:199], v[10:13]
	v_mfma_f32_16x16x32_bf16 v[6:9], v[156:159], v[204:207], v[6:9]
	v_mfma_f32_16x16x32_bf16 v[2:5], v[164:167], v[204:207], v[2:5]
	v_mfma_f32_16x16x32_bf16 v[46:49], v[160:163], v[176:179], v[46:49]
	v_mfma_f32_16x16x32_bf16 v[42:45], v[168:171], v[176:179], v[42:45]
	v_mfma_f32_16x16x32_bf16 v[30:33], v[160:163], v[192:195], v[30:33]
	v_mfma_f32_16x16x32_bf16 v[26:29], v[168:171], v[192:195], v[26:29]
	v_mfma_f32_16x16x32_bf16 v[14:17], v[160:163], v[200:203], v[14:17]
	v_mfma_f32_16x16x32_bf16 v[10:13], v[168:171], v[200:203], v[10:13]
	v_mfma_f32_16x16x32_bf16 v[6:9], v[160:163], v[208:211], v[6:9]
	v_mfma_f32_16x16x32_bf16 v[2:5], v[168:171], v[208:211], v[2:5]
	s_setprio 0
	s_barrier
	v_add_u32_e32 v139, vcc_lo, v1
	ds_read_b128 v[140:143], v139
	ds_read_b128 v[144:147], v139 offset:1024
	ds_read_b128 v[148:151], v139 offset:2048
	ds_read_b128 v[152:155], v139 offset:3072
	v_add_u32_e32 v139, vcc_hi, v1
	ds_read_b128 v[156:159], v139
	ds_read_b128 v[160:163], v139 offset:1024
	ds_read_b128 v[164:167], v139 offset:2048
	ds_read_b128 v[168:171], v139 offset:3072
	s_mov_b32 m0, s65
	v_lshl_add_u64 v[218:219], s[14:15], 0, v[130:131]
	ds_read_b128 v[172:175], v138 offset:32768
	ds_read_b128 v[176:179], v138 offset:33792
	ds_read_b128 v[188:191], v138 offset:34816
	ds_read_b128 v[192:195], v138 offset:35840
	ds_read_b128 v[196:199], v138 offset:36864
	ds_read_b128 v[200:203], v138 offset:37888
	ds_read_b128 v[204:207], v138 offset:38912
	ds_read_b128 v[208:211], v138 offset:39936
	global_load_lds_dwordx4 v[218:219], off
	v_lshl_add_u64 v[218:219], s[14:15], 0, v[134:135]
	s_mov_b32 m0, s70
	s_nop 0
	global_load_lds_dwordx4 v[218:219], off
	s_waitcnt vmcnt(8)
	s_waitcnt lgkmcnt(0)
	s_barrier
	s_setprio 1
	v_mfma_f32_16x16x32_bf16 v[126:129], v[140:143], v[172:175], v[126:129]
	v_mfma_f32_16x16x32_bf16 v[122:125], v[148:151], v[172:175], v[122:125]
	v_mfma_f32_16x16x32_bf16 v[118:121], v[140:143], v[188:191], v[118:121]
	v_mfma_f32_16x16x32_bf16 v[114:117], v[148:151], v[188:191], v[114:117]
	v_mfma_f32_16x16x32_bf16 v[102:105], v[140:143], v[196:199], v[102:105]
	v_mfma_f32_16x16x32_bf16 v[98:101], v[148:151], v[196:199], v[98:101]
	v_mfma_f32_16x16x32_bf16 v[86:89], v[140:143], v[204:207], v[86:89]
	v_mfma_f32_16x16x32_bf16 v[82:85], v[148:151], v[204:207], v[82:85]
	v_mfma_f32_16x16x32_bf16 v[126:129], v[144:147], v[176:179], v[126:129]
	v_mfma_f32_16x16x32_bf16 v[122:125], v[152:155], v[176:179], v[122:125]
	v_mfma_f32_16x16x32_bf16 v[118:121], v[144:147], v[192:195], v[118:121]
	v_mfma_f32_16x16x32_bf16 v[114:117], v[152:155], v[192:195], v[114:117]
	v_mfma_f32_16x16x32_bf16 v[102:105], v[144:147], v[200:203], v[102:105]
	v_mfma_f32_16x16x32_bf16 v[98:101], v[152:155], v[200:203], v[98:101]
	v_mfma_f32_16x16x32_bf16 v[86:89], v[144:147], v[208:211], v[86:89]
	v_mfma_f32_16x16x32_bf16 v[82:85], v[152:155], v[208:211], v[82:85]
	v_mfma_f32_16x16x32_bf16 v[110:113], v[156:159], v[172:175], v[110:113]
	v_mfma_f32_16x16x32_bf16 v[106:109], v[164:167], v[172:175], v[106:109]
	v_mfma_f32_16x16x32_bf16 v[94:97], v[156:159], v[188:191], v[94:97]
	v_mfma_f32_16x16x32_bf16 v[90:93], v[164:167], v[188:191], v[90:93]
	v_mfma_f32_16x16x32_bf16 v[78:81], v[156:159], v[196:199], v[78:81]
	v_mfma_f32_16x16x32_bf16 v[74:77], v[164:167], v[196:199], v[74:77]
	v_mfma_f32_16x16x32_bf16 v[70:73], v[156:159], v[204:207], v[70:73]
	v_mfma_f32_16x16x32_bf16 v[66:69], v[164:167], v[204:207], v[66:69]
	v_mfma_f32_16x16x32_bf16 v[110:113], v[160:163], v[176:179], v[110:113]
	v_mfma_f32_16x16x32_bf16 v[106:109], v[168:171], v[176:179], v[106:109]
	v_mfma_f32_16x16x32_bf16 v[94:97], v[160:163], v[192:195], v[94:97]
	v_mfma_f32_16x16x32_bf16 v[90:93], v[168:171], v[192:195], v[90:93]
	v_mfma_f32_16x16x32_bf16 v[78:81], v[160:163], v[200:203], v[78:81]
	v_mfma_f32_16x16x32_bf16 v[74:77], v[168:171], v[200:203], v[74:77]
	v_mfma_f32_16x16x32_bf16 v[70:73], v[160:163], v[208:211], v[70:73]
	v_mfma_f32_16x16x32_bf16 v[66:69], v[168:171], v[208:211], v[66:69]
	s_setprio 0
	s_barrier
; #define PG8_STAGE(bufoff, gbase, voff) do { _Pragma("unroll") for (int _i = 0; _i < 2; ++_i) \
;         __builtin_amdgcn_global_load_lds((const unsigned*)((const char*)(gbase) + (voff)[_i]), (LAS unsigned*)(lds + (bufoff) + ldsw + _i * 8192), 16, 0, 0); } while (0)
; #define PG8_LDA(dst, b, h) do { _Pragma("unroll") for (int m = 0; m < 4; ++m) _Pragma("unroll") for (int k = 0; k < 2; ++k) dst[m][k] = *(const LAS bf16x8*)(lds + PG8_SA(b, h) + aoff + m * 2048 + k * 1024); } while (0)
; #define PG8_MMA(ai, bj, At, Bt) do { __builtin_amdgcn_s_setprio(1); _Pragma("unroll") for (int m = 0; m < 4; ++m) _Pragma("unroll") for (int n = 0; n < 2; ++n) _Pragma("unroll") for (int k = 0; k < 2; ++k) \
;         acc[ai][bj][m][n] = __builtin_amdgcn_mfma_f32_16x16x32_bf16(Bt[n][k], At[m][k], acc[ai][bj][m][n], 0, 0, 0); __builtin_amdgcn_s_setprio(0); } while (0)
; #define PG8_WAIT_V(n) asm volatile("s_waitcnt vmcnt(" #n ")" ::: "memory")
; #define PG8_WAIT_L(n) asm volatile("s_waitcnt lgkmcnt(" #n ")" ::: "memory")
; #define PG8_BAR __builtin_amdgcn_s_barrier()
; #define PG8_SCHED __builtin_amdgcn_sched_barrier(0)
; template <class Epi>
; __device__ __forceinline__ void gemm_phase(LAS unsigned char* lds, const Gemm g, const StaticOrder& S, const Epi& E) {
;     ...
;             PG8_LDA(At, 1, 1); PG8_STAGE(PG8_SB(1, 0), b3, voffB); PG8_STAGE(PG8_SB(1, 1), b3 + hstepB, voffB); PG8_STAGE(PG8_SA(1, 0), a3, voffA);
;             PG8_WAIT_V(8); PG8_WAIT_L(0); PG8_BAR; PG8_MMA(1, 0, At, B0); PG8_MMA(1, 1, At, B1); PG8_BAR; PG8_SCHED;
;         }
;         if (wr == 0) PG8_BAR;
	s_mov_b32 m0, s41
	v_lshl_add_u64 v[184:185], v[184:185], 0, s[84:85]
	ds_read_b128 v[172:175], v138 offset:49152
	ds_read_b128 v[176:179], v138 offset:50176
	ds_read_b128 v[188:191], v138 offset:51200
	ds_read_b128 v[192:195], v138 offset:52224
	ds_read_b128 v[196:199], v138 offset:53248
	ds_read_b128 v[200:203], v138 offset:54272
	ds_read_b128 v[204:207], v138 offset:55296
	ds_read_b128 v[208:211], v138 offset:56320
	global_load_lds_dwordx4 v[184:185], off
	v_lshl_add_u64 v[184:185], v[212:213], 0, s[84:85]
	s_mov_b32 m0, s76
	s_nop 0
	global_load_lds_dwordx4 v[184:185], off
	v_lshl_add_u64 v[184:185], s[28:29], 0, v[132:133]
	s_mov_b32 m0, s81
	s_nop 0
	global_load_lds_dwordx4 v[184:185], off
	v_lshl_add_u64 v[184:185], s[28:29], 0, v[136:137]
	s_mov_b32 m0, s82
	s_nop 0
	global_load_lds_dwordx4 v[184:185], off
	v_lshl_add_u64 v[184:185], v[214:215], 0, s[84:85]
	s_mov_b32 m0, s86
	s_nop 0
	global_load_lds_dwordx4 v[184:185], off
	v_lshl_add_u64 v[184:185], v[216:217], 0, s[84:85]
	s_mov_b32 m0, s87
	s_nop 0
	global_load_lds_dwordx4 v[184:185], off
	s_waitcnt vmcnt(8)
	s_waitcnt lgkmcnt(0)
	s_barrier
	s_setprio 1
	v_mfma_f32_16x16x32_bf16 v[62:65], v[140:143], v[172:175], v[62:65]
	v_mfma_f32_16x16x32_bf16 v[58:61], v[148:151], v[172:175], v[58:61]
	v_mfma_f32_16x16x32_bf16 v[54:57], v[140:143], v[188:191], v[54:57]
	v_mfma_f32_16x16x32_bf16 v[50:53], v[148:151], v[188:191], v[50:53]
	v_mfma_f32_16x16x32_bf16 v[38:41], v[140:143], v[196:199], v[38:41]
	v_mfma_f32_16x16x32_bf16 v[34:37], v[148:151], v[196:199], v[34:37]
	v_mfma_f32_16x16x32_bf16 v[22:25], v[140:143], v[204:207], v[22:25]
	v_mfma_f32_16x16x32_bf16 v[18:21], v[148:151], v[204:207], v[18:21]
	v_mfma_f32_16x16x32_bf16 v[62:65], v[144:147], v[176:179], v[62:65]
	v_mfma_f32_16x16x32_bf16 v[58:61], v[152:155], v[176:179], v[58:61]
	v_mfma_f32_16x16x32_bf16 v[54:57], v[144:147], v[192:195], v[54:57]
	v_mfma_f32_16x16x32_bf16 v[50:53], v[152:155], v[192:195], v[50:53]
	v_mfma_f32_16x16x32_bf16 v[38:41], v[144:147], v[200:203], v[38:41]
	v_mfma_f32_16x16x32_bf16 v[34:37], v[152:155], v[200:203], v[34:37]
	v_mfma_f32_16x16x32_bf16 v[22:25], v[144:147], v[208:211], v[22:25]
	v_mfma_f32_16x16x32_bf16 v[18:21], v[152:155], v[208:211], v[18:21]
	v_mfma_f32_16x16x32_bf16 v[46:49], v[156:159], v[172:175], v[46:49]
	v_mfma_f32_16x16x32_bf16 v[42:45], v[164:167], v[172:175], v[42:45]
	v_mfma_f32_16x16x32_bf16 v[30:33], v[156:159], v[188:191], v[30:33]
	v_mfma_f32_16x16x32_bf16 v[26:29], v[164:167], v[188:191], v[26:29]
	v_mfma_f32_16x16x32_bf16 v[14:17], v[156:159], v[196:199], v[14:17]
	v_mfma_f32_16x16x32_bf16 v[10:13], v[164:167], v[196:199], v[10:13]
	v_mfma_f32_16x16x32_bf16 v[6:9], v[156:159], v[204:207], v[6:9]
	v_mfma_f32_16x16x32_bf16 v[2:5], v[164:167], v[204:207], v[2:5]
	v_mfma_f32_16x16x32_bf16 v[46:49], v[160:163], v[176:179], v[46:49]
	v_mfma_f32_16x16x32_bf16 v[42:45], v[168:171], v[176:179], v[42:45]
	v_mfma_f32_16x16x32_bf16 v[30:33], v[160:163], v[192:195], v[30:33]
	v_mfma_f32_16x16x32_bf16 v[26:29], v[168:171], v[192:195], v[26:29]
	v_mfma_f32_16x16x32_bf16 v[14:17], v[160:163], v[200:203], v[14:17]
	v_mfma_f32_16x16x32_bf16 v[10:13], v[168:171], v[200:203], v[10:13]
	v_mfma_f32_16x16x32_bf16 v[6:9], v[160:163], v[208:211], v[6:9]
	v_mfma_f32_16x16x32_bf16 v[2:5], v[168:171], v[208:211], v[2:5]
	s_setprio 0
	s_barrier
	s_movk_i32 s14, 0x100
	s_andn2_b64 vcc, exec, s[26:27]
	s_mov_b64 s[28:29], -1
	s_mov_b64 s[26:27], 0
	s_cbranch_vccz .LBB0_1440
	v_readlane_b32 s28, v255, 28
	s_and_b64 vcc, exec, s[8:9]
	v_readlane_b32 s29, v255, 29
	s_cbranch_vccz .LBB0_1443
	s_barrier

; #define PG8_STAGE(bufoff, gbase, voff) do { _Pragma("unroll") for (int _i = 0; _i < 2; ++_i) \
;         __builtin_amdgcn_global_load_lds((const unsigned*)((const char*)(gbase) + (voff)[_i]), (LAS unsigned*)(lds + (bufoff) + ldsw + _i * 8192), 16, 0, 0); } while (0)
; #define PG8_LDA(dst, b, h) do { _Pragma("unroll") for (int m = 0; m < 4; ++m) _Pragma("unroll") for (int k = 0; k < 2; ++k) dst[m][k] = *(const LAS bf16x8*)(lds + PG8_SA(b, h) + aoff + m * 2048 + k * 1024); } while (0)
; #define PG8_LDB(dst, b, h) do { _Pragma("unroll") for (int n = 0; n < 2; ++n) _Pragma("unroll") for (int k = 0; k < 2; ++k) dst[n][k] = *(const LAS bf16x8*)(lds + PG8_SB(b, h) + boff + n * 2048 + k * 1024); } while (0)
; #define PG8_MMA(ai, bj, At, Bt) do { __builtin_amdgcn_s_setprio(1); _Pragma("unroll") for (int m = 0; m < 4; ++m) _Pragma("unroll") for (int n = 0; n < 2; ++n) _Pragma("unroll") for (int k = 0; k < 2; ++k) \
;         acc[ai][bj][m][n] = __builtin_amdgcn_mfma_f32_16x16x32_bf16(Bt[n][k], At[m][k], acc[ai][bj][m][n], 0, 0, 0); __builtin_amdgcn_s_setprio(0); } while (0)
; #define PG8_WAIT_V(n) asm volatile("s_waitcnt vmcnt(" #n ")" ::: "memory")
; #define PG8_WAIT_L(n) asm volatile("s_waitcnt lgkmcnt(" #n ")" ::: "memory")
; #define PG8_BAR __builtin_amdgcn_s_barrier()
; #define PG8_SCHED __builtin_amdgcn_sched_barrier(0)
; template <class Epi>
; __device__ __forceinline__ void gemm_phase(LAS unsigned char* lds, const Gemm g, const StaticOrder& S, const Epi& E) {
;     ...
;             const bool last = (t == nt - 2);
;             const char* a1 = cA + (size_t)(t + 1) * kstep;
;             const char* a2 = last ? nA : cA + (size_t)(t + 2) * kstep; const char* b2 = last ? nB : cB + (size_t)(t + 2) * kstep;
;             const char* a3 = a2 + kstep; const char* b3 = b2 + kstep;
;             PG8_LDB(B0, 0, 0); PG8_LDB(B1, 0, 1); PG8_SCHED; PG8_LDA(At, 0, 0); PG8_STAGE(PG8_SA(1, 1), a1 + hstepA, voffA);
;             PG8_WAIT_V(8); PG8_WAIT_L(0); PG8_BAR; PG8_MMA(0, 0, At, B0); PG8_MMA(0, 1, At, B1); PG8_BAR; PG8_SCHED;
;             PG8_LDA(At, 0, 1); PG8_STAGE(PG8_SB(0, 0), b2, voffB); PG8_STAGE(PG8_SB(0, 1), b2 + hstepB, voffB); PG8_STAGE(PG8_SA(0, 0), a2, voffA);
;             PG8_WAIT_V(8); PG8_WAIT_L(0); PG8_BAR; PG8_MMA(1, 0, At, B0); PG8_MMA(1, 1, At, B1); PG8_BAR; PG8_SCHED;
.LBB0_2035:
	s_add_u32 s14, s24, 0xfff80080
	s_addc_u32 s15, s25, -1
	s_add_i32 s41, 0, 0x10000
	s_cmp_eq_u32 s52, 28
	s_cselect_b32 s27, s1, s15
	s_cselect_b32 s26, s3, s14
	s_cselect_b32 s15, s7, s40
	s_cselect_b32 s14, s13, s17
	s_add_i32 s53, 0, 0x14000
	v_add_u32_e32 v142, s41, v1
	v_add_u32_e32 v158, s53, v1
	ds_read_b128 v[130:133], v142
	ds_read_b128 v[134:137], v142 offset:1024
	ds_read_b128 v[138:141], v142 offset:2048
	ds_read_b128 v[142:145], v142 offset:3072
	ds_read_b128 v[146:149], v158
	ds_read_b128 v[150:153], v158 offset:1024
	ds_read_b128 v[154:157], v158 offset:2048
	ds_read_b128 v[158:161], v158 offset:3072
	v_lshl_add_u64 v[178:179], s[24:25], 0, v[196:197]
	s_add_i32 m0, s23, 0xc000
	ds_read_b128 v[162:165], v181
	ds_read_b128 v[166:169], v181 offset:1024
	ds_read_b128 v[170:173], v181 offset:2048
	ds_read_b128 v[174:177], v181 offset:3072
	ds_read_b128 v[200:203], v181 offset:4096
	ds_read_b128 v[204:207], v181 offset:5120
	ds_read_b128 v[208:211], v181 offset:6144
	ds_read_b128 v[212:215], v181 offset:7168
	global_load_lds_dwordx4 v[178:179], off
	v_lshl_add_u64 v[178:179], s[24:25], 0, v[198:199]
	s_add_i32 m0, s23, 0xe000
	s_nop 0
	global_load_lds_dwordx4 v[178:179], off
	s_waitcnt vmcnt(8)
	s_waitcnt lgkmcnt(0)
	s_barrier
	s_setprio 1
	v_mfma_f32_16x16x32_bf16 v[126:129], v[130:133], v[162:165], v[126:129]
	v_mfma_f32_16x16x32_bf16 v[122:125], v[138:141], v[162:165], v[122:125]
	v_mfma_f32_16x16x32_bf16 v[110:113], v[130:133], v[170:173], v[110:113]
	v_mfma_f32_16x16x32_bf16 v[106:109], v[138:141], v[170:173], v[106:109]
	v_mfma_f32_16x16x32_bf16 v[94:97], v[130:133], v[200:203], v[94:97]
	v_mfma_f32_16x16x32_bf16 v[90:93], v[138:141], v[200:203], v[90:93]
	v_mfma_f32_16x16x32_bf16 v[82:85], v[130:133], v[208:211], v[82:85]
	v_mfma_f32_16x16x32_bf16 v[74:77], v[138:141], v[208:211], v[74:77]
	v_mfma_f32_16x16x32_bf16 v[126:129], v[134:137], v[166:169], v[126:129]
	v_mfma_f32_16x16x32_bf16 v[122:125], v[142:145], v[166:169], v[122:125]
	v_mfma_f32_16x16x32_bf16 v[110:113], v[134:137], v[174:177], v[110:113]
	v_mfma_f32_16x16x32_bf16 v[106:109], v[142:145], v[174:177], v[106:109]
	v_mfma_f32_16x16x32_bf16 v[94:97], v[134:137], v[204:207], v[94:97]
	v_mfma_f32_16x16x32_bf16 v[90:93], v[142:145], v[204:207], v[90:93]
	v_mfma_f32_16x16x32_bf16 v[82:85], v[134:137], v[212:215], v[82:85]
	v_mfma_f32_16x16x32_bf16 v[74:77], v[142:145], v[212:215], v[74:77]
	v_mfma_f32_16x16x32_bf16 v[118:121], v[146:149], v[162:165], v[118:121]
	v_mfma_f32_16x16x32_bf16 v[114:117], v[154:157], v[162:165], v[114:117]
	v_mfma_f32_16x16x32_bf16 v[102:105], v[146:149], v[170:173], v[102:105]
	v_mfma_f32_16x16x32_bf16 v[98:101], v[154:157], v[170:173], v[98:101]
	v_mfma_f32_16x16x32_bf16 v[86:89], v[146:149], v[200:203], v[86:89]
	v_mfma_f32_16x16x32_bf16 v[78:81], v[154:157], v[200:203], v[78:81]
	v_mfma_f32_16x16x32_bf16 v[70:73], v[146:149], v[208:211], v[70:73]
	v_mfma_f32_16x16x32_bf16 v[66:69], v[154:157], v[208:211], v[66:69]
	v_mfma_f32_16x16x32_bf16 v[118:121], v[150:153], v[166:169], v[118:121]
	v_mfma_f32_16x16x32_bf16 v[114:117], v[158:161], v[166:169], v[114:117]
	v_mfma_f32_16x16x32_bf16 v[102:105], v[150:153], v[174:177], v[102:105]
	v_mfma_f32_16x16x32_bf16 v[98:101], v[158:161], v[174:177], v[98:101]
	v_mfma_f32_16x16x32_bf16 v[86:89], v[150:153], v[204:207], v[86:89]
	v_mfma_f32_16x16x32_bf16 v[78:81], v[158:161], v[204:207], v[78:81]
	v_mfma_f32_16x16x32_bf16 v[70:73], v[150:153], v[212:215], v[70:73]
	v_mfma_f32_16x16x32_bf16 v[66:69], v[158:161], v[212:215], v[66:69]
	s_setprio 0
	s_barrier
	s_add_i32 s41, s41, s30
	v_lshl_add_u64 v[178:179], s[14:15], 0, v[190:191]
	s_mov_b32 m0, s41
	ds_read_b128 v[162:165], v181 offset:16384
	ds_read_b128 v[166:169], v181 offset:17408
	ds_read_b128 v[170:173], v181 offset:18432
	ds_read_b128 v[174:177], v181 offset:19456
	ds_read_b128 v[200:203], v181 offset:20480
	ds_read_b128 v[204:207], v181 offset:21504
	ds_read_b128 v[208:211], v181 offset:22528
	ds_read_b128 v[212:215], v181 offset:23552
	global_load_lds_dwordx4 v[178:179], off
	s_add_i32 m0, s41, 0x2000
	s_add_u32 s62, s14, 0x80000
	v_lshl_add_u64 v[184:185], s[14:15], 0, v[194:195]
	s_addc_u32 s63, s15, 0
	s_add_i32 s41, s53, s30
	global_load_lds_dwordx4 v[184:185], off
	v_lshl_add_u64 v[216:217], s[62:63], 0, v[190:191]
	s_mov_b32 m0, s41
	v_lshl_add_u64 v[218:219], s[26:27], 0, v[192:193]
	global_load_lds_dwordx4 v[216:217], off
	v_lshl_add_u64 v[216:217], s[62:63], 0, v[194:195]
	s_add_i32 m0, s41, 0x2000
	s_nop 0
	global_load_lds_dwordx4 v[216:217], off
	v_lshl_add_u64 v[216:217], s[26:27], 0, v[188:189]
	s_mov_b32 m0, s23
	s_nop 0
	global_load_lds_dwordx4 v[216:217], off
	s_mov_b32 m0, s34
	s_nop 0
	global_load_lds_dwordx4 v[218:219], off
	s_waitcnt vmcnt(8)
	s_waitcnt lgkmcnt(0)
	s_barrier
; #define PG8_STAGE(bufoff, gbase, voff) do { _Pragma("unroll") for (int _i = 0; _i < 2; ++_i) \
;         __builtin_amdgcn_global_load_lds((const unsigned*)((const char*)(gbase) + (voff)[_i]), (LAS unsigned*)(lds + (bufoff) + ldsw + _i * 8192), 16, 0, 0); } while (0)
; #define PG8_LDA(dst, b, h) do { _Pragma("unroll") for (int m = 0; m < 4; ++m) _Pragma("unroll") for (int k = 0; k < 2; ++k) dst[m][k] = *(const LAS bf16x8*)(lds + PG8_SA(b, h) + aoff + m * 2048 + k * 1024); } while (0)
; #define PG8_LDB(dst, b, h) do { _Pragma("unroll") for (int n = 0; n < 2; ++n) _Pragma("unroll") for (int k = 0; k < 2; ++k) dst[n][k] = *(const LAS bf16x8*)(lds + PG8_SB(b, h) + boff + n * 2048 + k * 1024); } while (0)
; #define PG8_MMA(ai, bj, At, Bt) do { __builtin_amdgcn_s_setprio(1); _Pragma("unroll") for (int m = 0; m < 4; ++m) _Pragma("unroll") for (int n = 0; n < 2; ++n) _Pragma("unroll") for (int k = 0; k < 2; ++k) \
;         acc[ai][bj][m][n] = __builtin_amdgcn_mfma_f32_16x16x32_bf16(Bt[n][k], At[m][k], acc[ai][bj][m][n], 0, 0, 0); __builtin_amdgcn_s_setprio(0); } while (0)
; #define PG8_WAIT_V(n) asm volatile("s_waitcnt vmcnt(" #n ")" ::: "memory")
; #define PG8_WAIT_L(n) asm volatile("s_waitcnt lgkmcnt(" #n ")" ::: "memory")
; #define PG8_BAR __builtin_amdgcn_s_barrier()
; #define PG8_SCHED __builtin_amdgcn_sched_barrier(0)
; template <class Epi>
; __device__ __forceinline__ void gemm_phase(LAS unsigned char* lds, const Gemm g, const StaticOrder& S, const Epi& E) {
;     ...
;             PG8_WAIT_V(8); PG8_WAIT_L(0); PG8_BAR; PG8_MMA(1, 0, At, B0); PG8_MMA(1, 1, At, B1); PG8_BAR; PG8_SCHED;
;             PG8_LDB(B0, 1, 0); PG8_LDB(B1, 1, 1); PG8_SCHED; PG8_LDA(At, 1, 0); PG8_STAGE(PG8_SA(0, 1), a2 + hstepA, voffA);
;             PG8_WAIT_V(8); PG8_WAIT_L(0); PG8_BAR; PG8_MMA(0, 0, At, B0); PG8_MMA(0, 1, At, B1); PG8_BAR; PG8_SCHED;
	s_setprio 1
	v_mfma_f32_16x16x32_bf16 v[62:65], v[130:133], v[162:165], v[62:65]
	v_mfma_f32_16x16x32_bf16 v[58:61], v[138:141], v[162:165], v[58:61]
	v_mfma_f32_16x16x32_bf16 v[50:53], v[130:133], v[170:173], v[50:53]
	v_mfma_f32_16x16x32_bf16 v[42:45], v[138:141], v[170:173], v[42:45]
	v_mfma_f32_16x16x32_bf16 v[30:33], v[130:133], v[200:203], v[30:33]
	v_mfma_f32_16x16x32_bf16 v[26:29], v[138:141], v[200:203], v[26:29]
	v_mfma_f32_16x16x32_bf16 v[18:21], v[130:133], v[208:211], v[18:21]
	v_mfma_f32_16x16x32_bf16 v[10:13], v[138:141], v[208:211], v[10:13]
	v_mfma_f32_16x16x32_bf16 v[62:65], v[134:137], v[166:169], v[62:65]
	v_mfma_f32_16x16x32_bf16 v[58:61], v[142:145], v[166:169], v[58:61]
	v_mfma_f32_16x16x32_bf16 v[50:53], v[134:137], v[174:177], v[50:53]
	v_mfma_f32_16x16x32_bf16 v[42:45], v[142:145], v[174:177], v[42:45]
	v_mfma_f32_16x16x32_bf16 v[30:33], v[134:137], v[204:207], v[30:33]
	v_mfma_f32_16x16x32_bf16 v[26:29], v[142:145], v[204:207], v[26:29]
	v_mfma_f32_16x16x32_bf16 v[18:21], v[134:137], v[212:215], v[18:21]
	v_mfma_f32_16x16x32_bf16 v[10:13], v[142:145], v[212:215], v[10:13]
	v_mfma_f32_16x16x32_bf16 v[54:57], v[146:149], v[162:165], v[54:57]
	v_mfma_f32_16x16x32_bf16 v[46:49], v[154:157], v[162:165], v[46:49]
	v_mfma_f32_16x16x32_bf16 v[38:41], v[146:149], v[170:173], v[38:41]
	v_mfma_f32_16x16x32_bf16 v[34:37], v[154:157], v[170:173], v[34:37]
	v_mfma_f32_16x16x32_bf16 v[22:25], v[146:149], v[200:203], v[22:25]
	v_mfma_f32_16x16x32_bf16 v[14:17], v[154:157], v[200:203], v[14:17]
	v_mfma_f32_16x16x32_bf16 v[6:9], v[146:149], v[208:211], v[6:9]
	v_mfma_f32_16x16x32_bf16 v[2:5], v[154:157], v[208:211], v[2:5]
	v_mfma_f32_16x16x32_bf16 v[54:57], v[150:153], v[166:169], v[54:57]
	v_mfma_f32_16x16x32_bf16 v[46:49], v[158:161], v[166:169], v[46:49]
	v_mfma_f32_16x16x32_bf16 v[38:41], v[150:153], v[174:177], v[38:41]
	v_mfma_f32_16x16x32_bf16 v[34:37], v[158:161], v[174:177], v[34:37]
	v_mfma_f32_16x16x32_bf16 v[22:25], v[150:153], v[204:207], v[22:25]
	v_mfma_f32_16x16x32_bf16 v[14:17], v[158:161], v[204:207], v[14:17]
	v_mfma_f32_16x16x32_bf16 v[6:9], v[150:153], v[212:215], v[6:9]
	v_mfma_f32_16x16x32_bf16 v[2:5], v[158:161], v[212:215], v[2:5]
	s_setprio 0
	s_barrier
	s_add_i32 s41, 0, 0x18000
	s_add_i32 s53, 0, 0x1c000
	v_add_u32_e32 v142, s41, v1
	v_add_u32_e32 v158, s53, v1
	ds_read_b128 v[130:133], v142
	ds_read_b128 v[134:137], v142 offset:1024
	ds_read_b128 v[138:141], v142 offset:2048
	ds_read_b128 v[142:145], v142 offset:3072
	ds_read_b128 v[146:149], v158
	ds_read_b128 v[150:153], v158 offset:1024
	ds_read_b128 v[154:157], v158 offset:2048
	ds_read_b128 v[158:161], v158 offset:3072
	s_add_u32 s26, s26, 0x80000
	s_addc_u32 s27, s27, 0
	s_mov_b32 m0, s35
	v_lshl_add_u64 v[220:221], s[26:27], 0, v[188:189]
	ds_read_b128 v[162:165], v181 offset:32768
	ds_read_b128 v[166:169], v181 offset:33792
	ds_read_b128 v[170:173], v181 offset:34816
	ds_read_b128 v[174:177], v181 offset:35840
	ds_read_b128 v[200:203], v181 offset:36864
	ds_read_b128 v[204:207], v181 offset:37888
	ds_read_b128 v[208:211], v181 offset:38912
	ds_read_b128 v[212:215], v181 offset:39936
	global_load_lds_dwordx4 v[220:221], off
	v_lshl_add_u64 v[220:221], s[26:27], 0, v[192:193]
	s_mov_b32 m0, s42
	s_nop 0
	global_load_lds_dwordx4 v[220:221], off
	s_waitcnt vmcnt(8)
	s_waitcnt lgkmcnt(0)
	s_barrier
	s_setprio 1
	v_mfma_f32_16x16x32_bf16 v[126:129], v[130:133], v[162:165], v[126:129]
	v_mfma_f32_16x16x32_bf16 v[122:125], v[138:141], v[162:165], v[122:125]
	v_mfma_f32_16x16x32_bf16 v[110:113], v[130:133], v[170:173], v[110:113]
	v_mfma_f32_16x16x32_bf16 v[106:109], v[138:141], v[170:173], v[106:109]
	v_mfma_f32_16x16x32_bf16 v[94:97], v[130:133], v[200:203], v[94:97]
	v_mfma_f32_16x16x32_bf16 v[90:93], v[138:141], v[200:203], v[90:93]
	v_mfma_f32_16x16x32_bf16 v[82:85], v[130:133], v[208:211], v[82:85]
	v_mfma_f32_16x16x32_bf16 v[74:77], v[138:141], v[208:211], v[74:77]
	v_mfma_f32_16x16x32_bf16 v[126:129], v[134:137], v[166:169], v[126:129]
	v_mfma_f32_16x16x32_bf16 v[122:125], v[142:145], v[166:169], v[122:125]
	v_mfma_f32_16x16x32_bf16 v[110:113], v[134:137], v[174:177], v[110:113]
	v_mfma_f32_16x16x32_bf16 v[106:109], v[142:145], v[174:177], v[106:109]
	v_mfma_f32_16x16x32_bf16 v[94:97], v[134:137], v[204:207], v[94:97]
	v_mfma_f32_16x16x32_bf16 v[90:93], v[142:145], v[204:207], v[90:93]
	v_mfma_f32_16x16x32_bf16 v[82:85], v[134:137], v[212:215], v[82:85]
	v_mfma_f32_16x16x32_bf16 v[74:77], v[142:145], v[212:215], v[74:77]
	v_mfma_f32_16x16x32_bf16 v[118:121], v[146:149], v[162:165], v[118:121]
	v_mfma_f32_16x16x32_bf16 v[114:117], v[154:157], v[162:165], v[114:117]
	v_mfma_f32_16x16x32_bf16 v[102:105], v[146:149], v[170:173], v[102:105]
	v_mfma_f32_16x16x32_bf16 v[98:101], v[154:157], v[170:173], v[98:101]
	v_mfma_f32_16x16x32_bf16 v[86:89], v[146:149], v[200:203], v[86:89]
	v_mfma_f32_16x16x32_bf16 v[78:81], v[154:157], v[200:203], v[78:81]
	v_mfma_f32_16x16x32_bf16 v[70:73], v[146:149], v[208:211], v[70:73]
	v_mfma_f32_16x16x32_bf16 v[66:69], v[154:157], v[208:211], v[66:69]
	v_mfma_f32_16x16x32_bf16 v[118:121], v[150:153], v[166:169], v[118:121]
	v_mfma_f32_16x16x32_bf16 v[114:117], v[158:161], v[166:169], v[114:117]
	v_mfma_f32_16x16x32_bf16 v[102:105], v[150:153], v[174:177], v[102:105]
	v_mfma_f32_16x16x32_bf16 v[98:101], v[158:161], v[174:177], v[98:101]
	v_mfma_f32_16x16x32_bf16 v[86:89], v[150:153], v[204:207], v[86:89]
	v_mfma_f32_16x16x32_bf16 v[78:81], v[158:161], v[204:207], v[78:81]
	v_mfma_f32_16x16x32_bf16 v[70:73], v[150:153], v[212:215], v[70:73]
	v_mfma_f32_16x16x32_bf16 v[66:69], v[158:161], v[212:215], v[66:69]
	s_setprio 0
	s_barrier
; #define PG8_STAGE(bufoff, gbase, voff) do { _Pragma("unroll") for (int _i = 0; _i < 2; ++_i) \
;         __builtin_amdgcn_global_load_lds((const unsigned*)((const char*)(gbase) + (voff)[_i]), (LAS unsigned*)(lds + (bufoff) + ldsw + _i * 8192), 16, 0, 0); } while (0)
; #define PG8_LDA(dst, b, h) do { _Pragma("unroll") for (int m = 0; m < 4; ++m) _Pragma("unroll") for (int k = 0; k < 2; ++k) dst[m][k] = *(const LAS bf16x8*)(lds + PG8_SA(b, h) + aoff + m * 2048 + k * 1024); } while (0)
; #define PG8_MMA(ai, bj, At, Bt) do { __builtin_amdgcn_s_setprio(1); _Pragma("unroll") for (int m = 0; m < 4; ++m) _Pragma("unroll") for (int n = 0; n < 2; ++n) _Pragma("unroll") for (int k = 0; k < 2; ++k) \
;         acc[ai][bj][m][n] = __builtin_amdgcn_mfma_f32_16x16x32_bf16(Bt[n][k], At[m][k], acc[ai][bj][m][n], 0, 0, 0); __builtin_amdgcn_s_setprio(0); } while (0)
; #define PG8_WAIT_V(n) asm volatile("s_waitcnt vmcnt(" #n ")" ::: "memory")
; #define PG8_WAIT_L(n) asm volatile("s_waitcnt lgkmcnt(" #n ")" ::: "memory")
; #define PG8_BAR __builtin_amdgcn_s_barrier()
; #define PG8_SCHED __builtin_amdgcn_sched_barrier(0)
; template <class Epi>
; __device__ __forceinline__ void gemm_phase(LAS unsigned char* lds, const Gemm g, const StaticOrder& S, const Epi& E) {
;     ...
;             PG8_LDA(At, 1, 1); PG8_STAGE(PG8_SB(1, 0), b3, voffB); PG8_STAGE(PG8_SB(1, 1), b3 + hstepB, voffB); PG8_STAGE(PG8_SA(1, 0), a3, voffA);
;             PG8_WAIT_V(8); PG8_WAIT_L(0); PG8_BAR; PG8_MMA(1, 0, At, B0); PG8_MMA(1, 1, At, B1); PG8_BAR; PG8_SCHED;
;         }
	s_add_i32 s26, s41, s30
	v_lshl_add_u64 v[178:179], v[178:179], 0, s[84:85]
	s_mov_b32 m0, s26
	ds_read_b128 v[162:165], v181 offset:49152
	ds_read_b128 v[166:169], v181 offset:50176
	ds_read_b128 v[170:173], v181 offset:51200
	ds_read_b128 v[174:177], v181 offset:52224
	ds_read_b128 v[200:203], v181 offset:53248
	ds_read_b128 v[204:207], v181 offset:54272
	ds_read_b128 v[208:211], v181 offset:55296
	ds_read_b128 v[212:215], v181 offset:56320
	global_load_lds_dwordx4 v[178:179], off
	s_add_i32 m0, s26, 0x2000
	s_add_u32 s14, s14, 0x80080
	v_lshl_add_u64 v[178:179], v[184:185], 0, s[84:85]
	s_addc_u32 s15, s15, 0
	s_add_i32 s26, s53, s30
	global_load_lds_dwordx4 v[178:179], off
	v_lshl_add_u64 v[178:179], s[14:15], 0, v[190:191]
	s_mov_b32 m0, s26
	s_nop 0
	global_load_lds_dwordx4 v[178:179], off
	v_lshl_add_u64 v[178:179], s[14:15], 0, v[194:195]
	s_add_i32 m0, s26, 0x2000
	s_nop 0
	global_load_lds_dwordx4 v[178:179], off
	v_lshl_add_u64 v[178:179], v[216:217], 0, s[84:85]
	s_mov_b32 m0, s68
	s_nop 0
	global_load_lds_dwordx4 v[178:179], off
	v_lshl_add_u64 v[178:179], v[218:219], 0, s[84:85]
	s_mov_b32 m0, s69
	s_nop 0
	global_load_lds_dwordx4 v[178:179], off
	s_waitcnt vmcnt(8)
	s_waitcnt lgkmcnt(0)
	s_barrier
	s_setprio 1
	v_mfma_f32_16x16x32_bf16 v[62:65], v[130:133], v[162:165], v[62:65]
	v_mfma_f32_16x16x32_bf16 v[58:61], v[138:141], v[162:165], v[58:61]
	v_mfma_f32_16x16x32_bf16 v[50:53], v[130:133], v[170:173], v[50:53]
	v_mfma_f32_16x16x32_bf16 v[42:45], v[138:141], v[170:173], v[42:45]
	v_mfma_f32_16x16x32_bf16 v[30:33], v[130:133], v[200:203], v[30:33]
	v_mfma_f32_16x16x32_bf16 v[26:29], v[138:141], v[200:203], v[26:29]
	v_mfma_f32_16x16x32_bf16 v[18:21], v[130:133], v[208:211], v[18:21]
	v_mfma_f32_16x16x32_bf16 v[10:13], v[138:141], v[208:211], v[10:13]
	v_mfma_f32_16x16x32_bf16 v[62:65], v[134:137], v[166:169], v[62:65]
	v_mfma_f32_16x16x32_bf16 v[58:61], v[142:145], v[166:169], v[58:61]
	v_mfma_f32_16x16x32_bf16 v[50:53], v[134:137], v[174:177], v[50:53]
	v_mfma_f32_16x16x32_bf16 v[42:45], v[142:145], v[174:177], v[42:45]
	v_mfma_f32_16x16x32_bf16 v[30:33], v[134:137], v[204:207], v[30:33]
	v_mfma_f32_16x16x32_bf16 v[26:29], v[142:145], v[204:207], v[26:29]
	v_mfma_f32_16x16x32_bf16 v[18:21], v[134:137], v[212:215], v[18:21]
	v_mfma_f32_16x16x32_bf16 v[10:13], v[142:145], v[212:215], v[10:13]
	v_mfma_f32_16x16x32_bf16 v[54:57], v[146:149], v[162:165], v[54:57]
	v_mfma_f32_16x16x32_bf16 v[46:49], v[154:157], v[162:165], v[46:49]
	v_mfma_f32_16x16x32_bf16 v[38:41], v[146:149], v[170:173], v[38:41]
	v_mfma_f32_16x16x32_bf16 v[34:37], v[154:157], v[170:173], v[34:37]
	v_mfma_f32_16x16x32_bf16 v[22:25], v[146:149], v[200:203], v[22:25]
	v_mfma_f32_16x16x32_bf16 v[14:17], v[154:157], v[200:203], v[14:17]
	v_mfma_f32_16x16x32_bf16 v[6:9], v[146:149], v[208:211], v[6:9]
	v_mfma_f32_16x16x32_bf16 v[2:5], v[154:157], v[208:211], v[2:5]
	v_mfma_f32_16x16x32_bf16 v[54:57], v[150:153], v[166:169], v[54:57]
	v_mfma_f32_16x16x32_bf16 v[46:49], v[158:161], v[166:169], v[46:49]
	v_mfma_f32_16x16x32_bf16 v[38:41], v[150:153], v[174:177], v[38:41]
	v_mfma_f32_16x16x32_bf16 v[34:37], v[158:161], v[174:177], v[34:37]
	v_mfma_f32_16x16x32_bf16 v[22:25], v[150:153], v[204:207], v[22:25]
	v_mfma_f32_16x16x32_bf16 v[14:17], v[158:161], v[204:207], v[14:17]
	v_mfma_f32_16x16x32_bf16 v[6:9], v[150:153], v[212:215], v[6:9]
	v_mfma_f32_16x16x32_bf16 v[2:5], v[158:161], v[212:215], v[2:5]
	s_setprio 0
	s_barrier
	s_add_i32 s52, s52, 2
	s_add_u32 s24, s24, 0x100
	s_addc_u32 s25, s25, 0
	s_add_u32 s17, s17, 0x100
	s_addc_u32 s40, s40, 0
	s_cmp_gt_u32 s52, 29
	s_cbranch_scc0 .LBB0_2035
	s_cmp_ge_u32 s74, 16
	s_cbranch_scc1 .Lwpf_c
	s_lshl_b32 s100, s74, 9
	v_add_u32_e32 v130, s100, v246
	v_lshrrev_b32_e32 v131, 2, v130
	v_and_b32_e32 v130, 3, v130
	v_lshlrev_b32_e32 v130, 7, v130
	v_lshl_add_u32 v130, v131, 12, v130
	s_add_u32 s100, s88, 0x1800000
	s_addc_u32 s101, s89, 0
	s_mov_b32 m0, 0x21000
	s_nop 0
	global_load_lds_dword v130, s[100:101]

; #define PG8_STAGE(bufoff, gbase, voff) do { _Pragma("unroll") for (int _i = 0; _i < 2; ++_i) \
;         __builtin_amdgcn_global_load_lds((const unsigned*)((const char*)(gbase) + (voff)[_i]), (LAS unsigned*)(lds + (bufoff) + ldsw + _i * 8192), 16, 0, 0); } while (0)
; #define PG8_LDA(dst, b, h) do { _Pragma("unroll") for (int m = 0; m < 4; ++m) _Pragma("unroll") for (int k = 0; k < 2; ++k) dst[m][k] = *(const LAS bf16x8*)(lds + PG8_SA(b, h) + aoff + m * 2048 + k * 1024); } while (0)
; #define PG8_LDB(dst, b, h) do { _Pragma("unroll") for (int n = 0; n < 2; ++n) _Pragma("unroll") for (int k = 0; k < 2; ++k) dst[n][k] = *(const LAS bf16x8*)(lds + PG8_SB(b, h) + boff + n * 2048 + k * 1024); } while (0)
; #define PG8_MMA(ai, bj, At, Bt) do { __builtin_amdgcn_s_setprio(1); _Pragma("unroll") for (int m = 0; m < 4; ++m) _Pragma("unroll") for (int n = 0; n < 2; ++n) _Pragma("unroll") for (int k = 0; k < 2; ++k) \
;         acc[ai][bj][m][n] = __builtin_amdgcn_mfma_f32_16x16x32_bf16(Bt[n][k], At[m][k], acc[ai][bj][m][n], 0, 0, 0); __builtin_amdgcn_s_setprio(0); } while (0)
; #define PG8_WAIT_V(n) asm volatile("s_waitcnt vmcnt(" #n ")" ::: "memory")
; #define PG8_WAIT_L(n) asm volatile("s_waitcnt lgkmcnt(" #n ")" ::: "memory")
; #define PG8_BAR __builtin_amdgcn_s_barrier()
; #define PG8_SCHED __builtin_amdgcn_sched_barrier(0)
; template <class Epi>
; __device__ __forceinline__ void gemm_phase(LAS unsigned char* lds, const Gemm g, const StaticOrder& S, const Epi& E) {
;     ...
;             const bool last = (t == nt - 2);
;             const char* a1 = cA + (size_t)(t + 1) * kstep;
;             const char* a2 = last ? nA : cA + (size_t)(t + 2) * kstep; const char* b2 = last ? nB : cB + (size_t)(t + 2) * kstep;
;             const char* a3 = a2 + kstep; const char* b3 = b2 + kstep;
;             PG8_LDB(B0, 0, 0); PG8_LDB(B1, 0, 1); PG8_SCHED; PG8_LDA(At, 0, 0); PG8_STAGE(PG8_SA(1, 1), a1 + hstepA, voffA);
;             PG8_WAIT_V(8); PG8_WAIT_L(0); PG8_BAR; PG8_MMA(0, 0, At, B0); PG8_MMA(0, 1, At, B1); PG8_BAR; PG8_SCHED;
;             PG8_LDA(At, 0, 1); PG8_STAGE(PG8_SB(0, 0), b2, voffB); PG8_STAGE(PG8_SB(0, 1), b2 + hstepB, voffB); PG8_STAGE(PG8_SA(0, 0), a2, voffA);
;             PG8_WAIT_V(8); PG8_WAIT_L(0); PG8_BAR; PG8_MMA(1, 0, At, B0); PG8_MMA(1, 1, At, B1); PG8_BAR; PG8_SCHED;
.LBB0_2130:
	s_add_u32 s14, s20, 0xfff80080
	s_addc_u32 s15, s21, -1
	s_add_i32 s62, 0, 0x10000
	s_cmp_eq_u32 s41, 28
	s_cselect_b32 s23, s3, s15
	s_cselect_b32 s22, s11, s14
	v_add_u32_e32 v142, s62, v1
	s_cselect_b32 s15, s9, s53
	s_cselect_b32 s14, s40, s52
	s_add_i32 s64, 0, 0x14000
	ds_read_b128 v[146:149], v142
	ds_read_b128 v[150:153], v142 offset:1024
	ds_read_b128 v[154:157], v142 offset:2048
	ds_read_b128 v[158:161], v142 offset:3072
	v_add_u32_e32 v142, s64, v1
	ds_read_b128 v[162:165], v142
	ds_read_b128 v[166:169], v142 offset:1024
	ds_read_b128 v[170:173], v142 offset:2048
	ds_read_b128 v[174:177], v142 offset:3072
	v_lshl_add_u64 v[142:143], s[20:21], 0, v[138:139]
	s_add_i32 m0, s19, 0xc000
	ds_read_b128 v[188:191], v144
	ds_read_b128 v[192:195], v144 offset:1024
	ds_read_b128 v[196:199], v144 offset:2048
	ds_read_b128 v[200:203], v144 offset:3072
	ds_read_b128 v[204:207], v144 offset:4096
	ds_read_b128 v[208:211], v144 offset:5120
	ds_read_b128 v[212:215], v144 offset:6144
	ds_read_b128 v[216:219], v144 offset:7168
	global_load_lds_dwordx4 v[142:143], off
	v_lshl_add_u64 v[142:143], s[20:21], 0, v[140:141]
	s_add_i32 m0, s19, 0xe000
	s_nop 0
	global_load_lds_dwordx4 v[142:143], off
	s_waitcnt vmcnt(8)
	s_waitcnt lgkmcnt(0)
	s_barrier
	s_setprio 1
	v_mfma_f32_16x16x32_bf16 v[126:129], v[146:149], v[188:191], v[126:129]
	v_mfma_f32_16x16x32_bf16 v[122:125], v[154:157], v[188:191], v[122:125]
	v_mfma_f32_16x16x32_bf16 v[110:113], v[146:149], v[196:199], v[110:113]
	v_mfma_f32_16x16x32_bf16 v[106:109], v[154:157], v[196:199], v[106:109]
	v_mfma_f32_16x16x32_bf16 v[94:97], v[146:149], v[204:207], v[94:97]
	v_mfma_f32_16x16x32_bf16 v[90:93], v[154:157], v[204:207], v[90:93]
	v_mfma_f32_16x16x32_bf16 v[78:81], v[146:149], v[212:215], v[78:81]
	v_mfma_f32_16x16x32_bf16 v[74:77], v[154:157], v[212:215], v[74:77]
	v_mfma_f32_16x16x32_bf16 v[126:129], v[150:153], v[192:195], v[126:129]
	v_mfma_f32_16x16x32_bf16 v[122:125], v[158:161], v[192:195], v[122:125]
	v_mfma_f32_16x16x32_bf16 v[110:113], v[150:153], v[200:203], v[110:113]
	v_mfma_f32_16x16x32_bf16 v[106:109], v[158:161], v[200:203], v[106:109]
	v_mfma_f32_16x16x32_bf16 v[94:97], v[150:153], v[208:211], v[94:97]
	v_mfma_f32_16x16x32_bf16 v[90:93], v[158:161], v[208:211], v[90:93]
	v_mfma_f32_16x16x32_bf16 v[78:81], v[150:153], v[216:219], v[78:81]
	v_mfma_f32_16x16x32_bf16 v[74:77], v[158:161], v[216:219], v[74:77]
	v_mfma_f32_16x16x32_bf16 v[118:121], v[162:165], v[188:191], v[118:121]
	v_mfma_f32_16x16x32_bf16 v[114:117], v[170:173], v[188:191], v[114:117]
	v_mfma_f32_16x16x32_bf16 v[102:105], v[162:165], v[196:199], v[102:105]
	v_mfma_f32_16x16x32_bf16 v[98:101], v[170:173], v[196:199], v[98:101]
	v_mfma_f32_16x16x32_bf16 v[86:89], v[162:165], v[204:207], v[86:89]
	v_mfma_f32_16x16x32_bf16 v[82:85], v[170:173], v[204:207], v[82:85]
	v_mfma_f32_16x16x32_bf16 v[70:73], v[162:165], v[212:215], v[70:73]
	v_mfma_f32_16x16x32_bf16 v[66:69], v[170:173], v[212:215], v[66:69]
	v_mfma_f32_16x16x32_bf16 v[118:121], v[166:169], v[192:195], v[118:121]
	v_mfma_f32_16x16x32_bf16 v[114:117], v[174:177], v[192:195], v[114:117]
	v_mfma_f32_16x16x32_bf16 v[102:105], v[166:169], v[200:203], v[102:105]
	v_mfma_f32_16x16x32_bf16 v[98:101], v[174:177], v[200:203], v[98:101]
	v_mfma_f32_16x16x32_bf16 v[86:89], v[166:169], v[208:211], v[86:89]
	v_mfma_f32_16x16x32_bf16 v[82:85], v[174:177], v[208:211], v[82:85]
	v_mfma_f32_16x16x32_bf16 v[70:73], v[166:169], v[216:219], v[70:73]
	v_mfma_f32_16x16x32_bf16 v[66:69], v[174:177], v[216:219], v[66:69]
	s_setprio 0
	s_barrier
	s_add_i32 s62, s62, s27
	v_lshl_add_u64 v[142:143], s[14:15], 0, v[132:133]
	s_mov_b32 m0, s62
	ds_read_b128 v[188:191], v144 offset:16384
	ds_read_b128 v[192:195], v144 offset:17408
	ds_read_b128 v[196:199], v144 offset:18432
	ds_read_b128 v[200:203], v144 offset:19456
	ds_read_b128 v[204:207], v144 offset:20480
	ds_read_b128 v[208:211], v144 offset:21504
	ds_read_b128 v[212:215], v144 offset:22528
	ds_read_b128 v[216:219], v144 offset:23552
	global_load_lds_dwordx4 v[142:143], off
	s_add_i32 m0, s62, 0x2000
	s_add_u32 s62, s14, 0x80000
	v_lshl_add_u64 v[178:179], s[14:15], 0, v[136:137]
	s_addc_u32 s63, s15, 0
	s_add_i32 s64, s64, s27
	global_load_lds_dwordx4 v[178:179], off
	v_lshl_add_u64 v[184:185], s[62:63], 0, v[132:133]
	s_mov_b32 m0, s64
	v_lshl_add_u64 v[220:221], s[22:23], 0, v[134:135]
	global_load_lds_dwordx4 v[184:185], off
	v_lshl_add_u64 v[184:185], s[62:63], 0, v[136:137]
	s_add_i32 m0, s64, 0x2000
	s_nop 0
	global_load_lds_dwordx4 v[184:185], off
	v_lshl_add_u64 v[184:185], s[22:23], 0, v[130:131]
	s_mov_b32 m0, s19
	s_nop 0
	global_load_lds_dwordx4 v[184:185], off
	s_mov_b32 m0, s28
	s_nop 0
	global_load_lds_dwordx4 v[220:221], off
	s_waitcnt vmcnt(8)
	s_waitcnt lgkmcnt(0)
	s_barrier
; #define PG8_STAGE(bufoff, gbase, voff) do { _Pragma("unroll") for (int _i = 0; _i < 2; ++_i) \
;         __builtin_amdgcn_global_load_lds((const unsigned*)((const char*)(gbase) + (voff)[_i]), (LAS unsigned*)(lds + (bufoff) + ldsw + _i * 8192), 16, 0, 0); } while (0)
; #define PG8_LDA(dst, b, h) do { _Pragma("unroll") for (int m = 0; m < 4; ++m) _Pragma("unroll") for (int k = 0; k < 2; ++k) dst[m][k] = *(const LAS bf16x8*)(lds + PG8_SA(b, h) + aoff + m * 2048 + k * 1024); } while (0)
; #define PG8_LDB(dst, b, h) do { _Pragma("unroll") for (int n = 0; n < 2; ++n) _Pragma("unroll") for (int k = 0; k < 2; ++k) dst[n][k] = *(const LAS bf16x8*)(lds + PG8_SB(b, h) + boff + n * 2048 + k * 1024); } while (0)
; #define PG8_MMA(ai, bj, At, Bt) do { __builtin_amdgcn_s_setprio(1); _Pragma("unroll") for (int m = 0; m < 4; ++m) _Pragma("unroll") for (int n = 0; n < 2; ++n) _Pragma("unroll") for (int k = 0; k < 2; ++k) \
;         acc[ai][bj][m][n] = __builtin_amdgcn_mfma_f32_16x16x32_bf16(Bt[n][k], At[m][k], acc[ai][bj][m][n], 0, 0, 0); __builtin_amdgcn_s_setprio(0); } while (0)
; #define PG8_WAIT_V(n) asm volatile("s_waitcnt vmcnt(" #n ")" ::: "memory")
; #define PG8_WAIT_L(n) asm volatile("s_waitcnt lgkmcnt(" #n ")" ::: "memory")
; #define PG8_BAR __builtin_amdgcn_s_barrier()
; #define PG8_SCHED __builtin_amdgcn_sched_barrier(0)
; template <class Epi>
; __device__ __forceinline__ void gemm_phase(LAS unsigned char* lds, const Gemm g, const StaticOrder& S, const Epi& E) {
;     ...
;             PG8_WAIT_V(8); PG8_WAIT_L(0); PG8_BAR; PG8_MMA(1, 0, At, B0); PG8_MMA(1, 1, At, B1); PG8_BAR; PG8_SCHED;
;             PG8_LDB(B0, 1, 0); PG8_LDB(B1, 1, 1); PG8_SCHED; PG8_LDA(At, 1, 0); PG8_STAGE(PG8_SA(0, 1), a2 + hstepA, voffA);
;             PG8_WAIT_V(8); PG8_WAIT_L(0); PG8_BAR; PG8_MMA(0, 0, At, B0); PG8_MMA(0, 1, At, B1); PG8_BAR; PG8_SCHED;
	s_setprio 1
	v_mfma_f32_16x16x32_bf16 v[62:65], v[146:149], v[188:191], v[62:65]
	v_mfma_f32_16x16x32_bf16 v[58:61], v[154:157], v[188:191], v[58:61]
	v_mfma_f32_16x16x32_bf16 v[46:49], v[146:149], v[196:199], v[46:49]
	v_mfma_f32_16x16x32_bf16 v[42:45], v[154:157], v[196:199], v[42:45]
	v_mfma_f32_16x16x32_bf16 v[30:33], v[146:149], v[204:207], v[30:33]
	v_mfma_f32_16x16x32_bf16 v[26:29], v[154:157], v[204:207], v[26:29]
	v_mfma_f32_16x16x32_bf16 v[14:17], v[146:149], v[212:215], v[14:17]
	v_mfma_f32_16x16x32_bf16 v[10:13], v[154:157], v[212:215], v[10:13]
	v_mfma_f32_16x16x32_bf16 v[62:65], v[150:153], v[192:195], v[62:65]
	v_mfma_f32_16x16x32_bf16 v[58:61], v[158:161], v[192:195], v[58:61]
	v_mfma_f32_16x16x32_bf16 v[46:49], v[150:153], v[200:203], v[46:49]
	v_mfma_f32_16x16x32_bf16 v[42:45], v[158:161], v[200:203], v[42:45]
	v_mfma_f32_16x16x32_bf16 v[30:33], v[150:153], v[208:211], v[30:33]
	v_mfma_f32_16x16x32_bf16 v[26:29], v[158:161], v[208:211], v[26:29]
	v_mfma_f32_16x16x32_bf16 v[14:17], v[150:153], v[216:219], v[14:17]
	v_mfma_f32_16x16x32_bf16 v[10:13], v[158:161], v[216:219], v[10:13]
	v_mfma_f32_16x16x32_bf16 v[54:57], v[162:165], v[188:191], v[54:57]
	v_mfma_f32_16x16x32_bf16 v[50:53], v[170:173], v[188:191], v[50:53]
	v_mfma_f32_16x16x32_bf16 v[38:41], v[162:165], v[196:199], v[38:41]
	v_mfma_f32_16x16x32_bf16 v[34:37], v[170:173], v[196:199], v[34:37]
	v_mfma_f32_16x16x32_bf16 v[22:25], v[162:165], v[204:207], v[22:25]
	v_mfma_f32_16x16x32_bf16 v[18:21], v[170:173], v[204:207], v[18:21]
	v_mfma_f32_16x16x32_bf16 v[6:9], v[162:165], v[212:215], v[6:9]
	v_mfma_f32_16x16x32_bf16 v[2:5], v[170:173], v[212:215], v[2:5]
	v_mfma_f32_16x16x32_bf16 v[54:57], v[166:169], v[192:195], v[54:57]
	v_mfma_f32_16x16x32_bf16 v[50:53], v[174:177], v[192:195], v[50:53]
	v_mfma_f32_16x16x32_bf16 v[38:41], v[166:169], v[200:203], v[38:41]
	v_mfma_f32_16x16x32_bf16 v[34:37], v[174:177], v[200:203], v[34:37]
	v_mfma_f32_16x16x32_bf16 v[22:25], v[166:169], v[208:211], v[22:25]
	v_mfma_f32_16x16x32_bf16 v[18:21], v[174:177], v[208:211], v[18:21]
	v_mfma_f32_16x16x32_bf16 v[6:9], v[166:169], v[216:219], v[6:9]
	v_mfma_f32_16x16x32_bf16 v[2:5], v[174:177], v[216:219], v[2:5]
	s_setprio 0
	s_barrier
	s_add_i32 s62, 0, 0x18000
	v_add_u32_e32 v145, s62, v1
	s_add_i32 s63, 0, 0x1c000
	ds_read_b128 v[146:149], v145
	ds_read_b128 v[150:153], v145 offset:1024
	ds_read_b128 v[154:157], v145 offset:2048
	ds_read_b128 v[158:161], v145 offset:3072
	v_add_u32_e32 v145, s63, v1
	ds_read_b128 v[162:165], v145
	ds_read_b128 v[166:169], v145 offset:1024
	ds_read_b128 v[170:173], v145 offset:2048
	ds_read_b128 v[174:177], v145 offset:3072
	s_add_u32 s22, s22, 0x80000
	s_addc_u32 s23, s23, 0
	s_mov_b32 m0, s29
	v_lshl_add_u64 v[222:223], s[22:23], 0, v[130:131]
	ds_read_b128 v[188:191], v144 offset:32768
	ds_read_b128 v[192:195], v144 offset:33792
	ds_read_b128 v[196:199], v144 offset:34816
	ds_read_b128 v[200:203], v144 offset:35840
	ds_read_b128 v[204:207], v144 offset:36864
	ds_read_b128 v[208:211], v144 offset:37888
	ds_read_b128 v[212:215], v144 offset:38912
	ds_read_b128 v[216:219], v144 offset:39936
	global_load_lds_dwordx4 v[222:223], off
	v_lshl_add_u64 v[222:223], s[22:23], 0, v[134:135]
	s_mov_b32 m0, s30
	s_nop 0
	global_load_lds_dwordx4 v[222:223], off
	s_waitcnt vmcnt(8)
	s_waitcnt lgkmcnt(0)
	s_barrier
	s_setprio 1
	v_mfma_f32_16x16x32_bf16 v[126:129], v[146:149], v[188:191], v[126:129]
	v_mfma_f32_16x16x32_bf16 v[122:125], v[154:157], v[188:191], v[122:125]
	v_mfma_f32_16x16x32_bf16 v[110:113], v[146:149], v[196:199], v[110:113]
	v_mfma_f32_16x16x32_bf16 v[106:109], v[154:157], v[196:199], v[106:109]
	v_mfma_f32_16x16x32_bf16 v[94:97], v[146:149], v[204:207], v[94:97]
	v_mfma_f32_16x16x32_bf16 v[90:93], v[154:157], v[204:207], v[90:93]
	v_mfma_f32_16x16x32_bf16 v[78:81], v[146:149], v[212:215], v[78:81]
	v_mfma_f32_16x16x32_bf16 v[74:77], v[154:157], v[212:215], v[74:77]
	v_mfma_f32_16x16x32_bf16 v[126:129], v[150:153], v[192:195], v[126:129]
	v_mfma_f32_16x16x32_bf16 v[122:125], v[158:161], v[192:195], v[122:125]
	v_mfma_f32_16x16x32_bf16 v[110:113], v[150:153], v[200:203], v[110:113]
	v_mfma_f32_16x16x32_bf16 v[106:109], v[158:161], v[200:203], v[106:109]
	v_mfma_f32_16x16x32_bf16 v[94:97], v[150:153], v[208:211], v[94:97]
	v_mfma_f32_16x16x32_bf16 v[90:93], v[158:161], v[208:211], v[90:93]
	v_mfma_f32_16x16x32_bf16 v[78:81], v[150:153], v[216:219], v[78:81]
	v_mfma_f32_16x16x32_bf16 v[74:77], v[158:161], v[216:219], v[74:77]
	v_mfma_f32_16x16x32_bf16 v[118:121], v[162:165], v[188:191], v[118:121]
	v_mfma_f32_16x16x32_bf16 v[114:117], v[170:173], v[188:191], v[114:117]
	v_mfma_f32_16x16x32_bf16 v[102:105], v[162:165], v[196:199], v[102:105]
	v_mfma_f32_16x16x32_bf16 v[98:101], v[170:173], v[196:199], v[98:101]
	v_mfma_f32_16x16x32_bf16 v[86:89], v[162:165], v[204:207], v[86:89]
	v_mfma_f32_16x16x32_bf16 v[82:85], v[170:173], v[204:207], v[82:85]
	v_mfma_f32_16x16x32_bf16 v[70:73], v[162:165], v[212:215], v[70:73]
	v_mfma_f32_16x16x32_bf16 v[66:69], v[170:173], v[212:215], v[66:69]
	v_mfma_f32_16x16x32_bf16 v[118:121], v[166:169], v[192:195], v[118:121]
	v_mfma_f32_16x16x32_bf16 v[114:117], v[174:177], v[192:195], v[114:117]
	v_mfma_f32_16x16x32_bf16 v[102:105], v[166:169], v[200:203], v[102:105]
	v_mfma_f32_16x16x32_bf16 v[98:101], v[174:177], v[200:203], v[98:101]
	v_mfma_f32_16x16x32_bf16 v[86:89], v[166:169], v[208:211], v[86:89]
	v_mfma_f32_16x16x32_bf16 v[82:85], v[174:177], v[208:211], v[82:85]
	v_mfma_f32_16x16x32_bf16 v[70:73], v[166:169], v[216:219], v[70:73]
	v_mfma_f32_16x16x32_bf16 v[66:69], v[174:177], v[216:219], v[66:69]
	s_setprio 0
	s_barrier
; #define PG8_STAGE(bufoff, gbase, voff) do { _Pragma("unroll") for (int _i = 0; _i < 2; ++_i) \
;         __builtin_amdgcn_global_load_lds((const unsigned*)((const char*)(gbase) + (voff)[_i]), (LAS unsigned*)(lds + (bufoff) + ldsw + _i * 8192), 16, 0, 0); } while (0)
; #define PG8_LDA(dst, b, h) do { _Pragma("unroll") for (int m = 0; m < 4; ++m) _Pragma("unroll") for (int k = 0; k < 2; ++k) dst[m][k] = *(const LAS bf16x8*)(lds + PG8_SA(b, h) + aoff + m * 2048 + k * 1024); } while (0)
; #define PG8_MMA(ai, bj, At, Bt) do { __builtin_amdgcn_s_setprio(1); _Pragma("unroll") for (int m = 0; m < 4; ++m) _Pragma("unroll") for (int n = 0; n < 2; ++n) _Pragma("unroll") for (int k = 0; k < 2; ++k) \
;         acc[ai][bj][m][n] = __builtin_amdgcn_mfma_f32_16x16x32_bf16(Bt[n][k], At[m][k], acc[ai][bj][m][n], 0, 0, 0); __builtin_amdgcn_s_setprio(0); } while (0)
; #define PG8_WAIT_V(n) asm volatile("s_waitcnt vmcnt(" #n ")" ::: "memory")
; #define PG8_WAIT_L(n) asm volatile("s_waitcnt lgkmcnt(" #n ")" ::: "memory")
; #define PG8_BAR __builtin_amdgcn_s_barrier()
; #define PG8_SCHED __builtin_amdgcn_sched_barrier(0)
; template <class Epi>
; __device__ __forceinline__ void gemm_phase(LAS unsigned char* lds, const Gemm g, const StaticOrder& S, const Epi& E) {
;     ...
;             PG8_LDA(At, 1, 1); PG8_STAGE(PG8_SB(1, 0), b3, voffB); PG8_STAGE(PG8_SB(1, 1), b3 + hstepB, voffB); PG8_STAGE(PG8_SA(1, 0), a3, voffA);
;             PG8_WAIT_V(8); PG8_WAIT_L(0); PG8_BAR; PG8_MMA(1, 0, At, B0); PG8_MMA(1, 1, At, B1); PG8_BAR; PG8_SCHED;
;         }
	s_add_i32 s22, s62, s27
	v_lshl_add_u64 v[142:143], v[142:143], 0, s[84:85]
	s_mov_b32 m0, s22
	ds_read_b128 v[188:191], v144 offset:49152
	ds_read_b128 v[192:195], v144 offset:50176
	ds_read_b128 v[196:199], v144 offset:51200
	ds_read_b128 v[200:203], v144 offset:52224
	ds_read_b128 v[204:207], v144 offset:53248
	ds_read_b128 v[208:211], v144 offset:54272
	ds_read_b128 v[212:215], v144 offset:55296
	ds_read_b128 v[216:219], v144 offset:56320
	global_load_lds_dwordx4 v[142:143], off
	s_add_i32 m0, s22, 0x2000
	s_add_u32 s14, s14, 0x80080
	v_lshl_add_u64 v[142:143], v[178:179], 0, s[84:85]
	s_addc_u32 s15, s15, 0
	s_add_i32 s22, s63, s27
	global_load_lds_dwordx4 v[142:143], off
	v_lshl_add_u64 v[142:143], s[14:15], 0, v[132:133]
	s_mov_b32 m0, s22
	s_nop 0
	global_load_lds_dwordx4 v[142:143], off
	v_lshl_add_u64 v[142:143], s[14:15], 0, v[136:137]
	s_add_i32 m0, s22, 0x2000
	s_nop 0
	global_load_lds_dwordx4 v[142:143], off
	v_lshl_add_u64 v[142:143], v[184:185], 0, s[84:85]
	s_mov_b32 m0, s34
	s_nop 0
	global_load_lds_dwordx4 v[142:143], off
	v_lshl_add_u64 v[142:143], v[220:221], 0, s[84:85]
	s_mov_b32 m0, s35
	s_nop 0
	global_load_lds_dwordx4 v[142:143], off
	s_waitcnt vmcnt(8)
	s_waitcnt lgkmcnt(0)
	s_barrier
	s_setprio 1
	v_mfma_f32_16x16x32_bf16 v[62:65], v[146:149], v[188:191], v[62:65]
	v_mfma_f32_16x16x32_bf16 v[58:61], v[154:157], v[188:191], v[58:61]
	v_mfma_f32_16x16x32_bf16 v[46:49], v[146:149], v[196:199], v[46:49]
	v_mfma_f32_16x16x32_bf16 v[42:45], v[154:157], v[196:199], v[42:45]
	v_mfma_f32_16x16x32_bf16 v[30:33], v[146:149], v[204:207], v[30:33]
	v_mfma_f32_16x16x32_bf16 v[26:29], v[154:157], v[204:207], v[26:29]
	v_mfma_f32_16x16x32_bf16 v[14:17], v[146:149], v[212:215], v[14:17]
	v_mfma_f32_16x16x32_bf16 v[10:13], v[154:157], v[212:215], v[10:13]
	v_mfma_f32_16x16x32_bf16 v[62:65], v[150:153], v[192:195], v[62:65]
	v_mfma_f32_16x16x32_bf16 v[58:61], v[158:161], v[192:195], v[58:61]
	v_mfma_f32_16x16x32_bf16 v[46:49], v[150:153], v[200:203], v[46:49]
	v_mfma_f32_16x16x32_bf16 v[42:45], v[158:161], v[200:203], v[42:45]
	v_mfma_f32_16x16x32_bf16 v[30:33], v[150:153], v[208:211], v[30:33]
	v_mfma_f32_16x16x32_bf16 v[26:29], v[158:161], v[208:211], v[26:29]
	v_mfma_f32_16x16x32_bf16 v[14:17], v[150:153], v[216:219], v[14:17]
	v_mfma_f32_16x16x32_bf16 v[10:13], v[158:161], v[216:219], v[10:13]
	v_mfma_f32_16x16x32_bf16 v[54:57], v[162:165], v[188:191], v[54:57]
	v_mfma_f32_16x16x32_bf16 v[50:53], v[170:173], v[188:191], v[50:53]
	v_mfma_f32_16x16x32_bf16 v[38:41], v[162:165], v[196:199], v[38:41]
	v_mfma_f32_16x16x32_bf16 v[34:37], v[170:173], v[196:199], v[34:37]
	v_mfma_f32_16x16x32_bf16 v[22:25], v[162:165], v[204:207], v[22:25]
	v_mfma_f32_16x16x32_bf16 v[18:21], v[170:173], v[204:207], v[18:21]
	v_mfma_f32_16x16x32_bf16 v[6:9], v[162:165], v[212:215], v[6:9]
	v_mfma_f32_16x16x32_bf16 v[2:5], v[170:173], v[212:215], v[2:5]
	v_mfma_f32_16x16x32_bf16 v[54:57], v[166:169], v[192:195], v[54:57]
	v_mfma_f32_16x16x32_bf16 v[50:53], v[174:177], v[192:195], v[50:53]
	v_mfma_f32_16x16x32_bf16 v[38:41], v[166:169], v[200:203], v[38:41]
	v_mfma_f32_16x16x32_bf16 v[34:37], v[174:177], v[200:203], v[34:37]
	v_mfma_f32_16x16x32_bf16 v[22:25], v[166:169], v[208:211], v[22:25]
	v_mfma_f32_16x16x32_bf16 v[18:21], v[174:177], v[208:211], v[18:21]
	v_mfma_f32_16x16x32_bf16 v[6:9], v[166:169], v[216:219], v[6:9]
	v_mfma_f32_16x16x32_bf16 v[2:5], v[174:177], v[216:219], v[2:5]
	s_setprio 0
	s_barrier
	s_add_i32 s41, s41, 2
	s_add_u32 s20, s20, 0x100
	s_addc_u32 s21, s21, 0
	s_add_u32 s52, s52, 0x100
	s_addc_u32 s53, s53, 0
	s_cmp_gt_u32 s41, 29
	s_cbranch_scc0 .LBB0_2130
	s_cmp_ge_u32 s74, 16
	s_cbranch_scc1 .Lwpf_d
	s_lshl_b32 s100, s74, 9
	v_add_u32_e32 v146, s100, v246
	v_lshrrev_b32_e32 v147, 2, v146
	v_and_b32_e32 v146, 3, v146
	v_lshlrev_b32_e32 v146, 7, v146
	v_lshl_add_u32 v146, v147, 14, v146
	s_add_u32 s100, s88, 0x2000000
	s_addc_u32 s101, s89, 0
	s_mov_b32 m0, 0x21000
	s_nop 0
	global_load_lds_dword v146, s[100:101]

; #define PG8_STAGE(bufoff, gbase, voff) do { _Pragma("unroll") for (int _i = 0; _i < 2; ++_i) \
;         __builtin_amdgcn_global_load_lds((const unsigned*)((const char*)(gbase) + (voff)[_i]), (LAS unsigned*)(lds + (bufoff) + ldsw + _i * 8192), 16, 0, 0); } while (0)
; #define PG8_LDA(dst, b, h) do { _Pragma("unroll") for (int m = 0; m < 4; ++m) _Pragma("unroll") for (int k = 0; k < 2; ++k) dst[m][k] = *(const LAS bf16x8*)(lds + PG8_SA(b, h) + aoff + m * 2048 + k * 1024); } while (0)
; #define PG8_LDB(dst, b, h) do { _Pragma("unroll") for (int n = 0; n < 2; ++n) _Pragma("unroll") for (int k = 0; k < 2; ++k) dst[n][k] = *(const LAS bf16x8*)(lds + PG8_SB(b, h) + boff + n * 2048 + k * 1024); } while (0)
; #define PG8_MMA(ai, bj, At, Bt) do { __builtin_amdgcn_s_setprio(1); _Pragma("unroll") for (int m = 0; m < 4; ++m) _Pragma("unroll") for (int n = 0; n < 2; ++n) _Pragma("unroll") for (int k = 0; k < 2; ++k) \
;         acc[ai][bj][m][n] = __builtin_amdgcn_mfma_f32_16x16x32_bf16(Bt[n][k], At[m][k], acc[ai][bj][m][n], 0, 0, 0); __builtin_amdgcn_s_setprio(0); } while (0)
; #define PG8_WAIT_V(n) asm volatile("s_waitcnt vmcnt(" #n ")" ::: "memory")
; #define PG8_WAIT_L(n) asm volatile("s_waitcnt lgkmcnt(" #n ")" ::: "memory")
; #define PG8_BAR __builtin_amdgcn_s_barrier()
; #define PG8_SCHED __builtin_amdgcn_sched_barrier(0)
; template <class Epi>
; __device__ __forceinline__ void gemm_phase(LAS unsigned char* lds, const Gemm g, const StaticOrder& S, const Epi& E) {
;     ...
;             const bool last = (t == nt - 2);
;             const char* a1 = cA + (size_t)(t + 1) * kstep;
;             const char* a2 = last ? nA : cA + (size_t)(t + 2) * kstep; const char* b2 = last ? nB : cB + (size_t)(t + 2) * kstep;
;             const char* a3 = a2 + kstep; const char* b3 = b2 + kstep;
;             PG8_LDB(B0, 0, 0); PG8_LDB(B1, 0, 1); PG8_SCHED; PG8_LDA(At, 0, 0); PG8_STAGE(PG8_SA(1, 1), a1 + hstepA, voffA);
;             PG8_WAIT_V(8); PG8_WAIT_L(0); PG8_BAR; PG8_MMA(0, 0, At, B0); PG8_MMA(0, 1, At, B1); PG8_BAR; PG8_SCHED;
;             PG8_LDA(At, 0, 1); PG8_STAGE(PG8_SB(0, 0), b2, voffB); PG8_STAGE(PG8_SB(0, 1), b2 + hstepB, voffB); PG8_STAGE(PG8_SA(0, 0), a2, voffA);
;             PG8_WAIT_V(8); PG8_WAIT_L(0); PG8_BAR; PG8_MMA(1, 0, At, B0); PG8_MMA(1, 1, At, B1); PG8_BAR; PG8_SCHED;
.LBB0_2155:
	s_add_u32 s41, s20, s14
	s_addc_u32 s44, s21, 0
	s_add_u32 s15, s41, 0x100
	s_addc_u32 s34, s44, 0
	s_and_b64 s[30:31], s[28:29], exec
	s_cselect_b32 s31, s19, s34
	s_cselect_b32 s30, s3, s15
	s_add_u32 s14, s12, s14
	s_addc_u32 s15, s13, 0
	s_add_u32 s34, s14, 0x100
	s_addc_u32 s35, s15, 0
	s_add_i32 s81, 0, 0x10000
	s_and_b64 s[14:15], s[28:29], exec
	s_cselect_b32 s35, s17, s35
	s_cselect_b32 s34, s40, s34
	s_add_i32 s29, 0, 0x14000
	s_add_u32 s68, s41, 0x10080
	s_addc_u32 s69, s44, 0
	s_add_i32 s80, s81, s63
	s_add_i32 m0, s11, 0xc000
	s_add_i32 s83, s11, 0xe000
	s_add_i32 s77, s80, 0x2000
	v_add_u32_e32 v139, s81, v1
	s_add_u32 s44, s34, 0x10000
	ds_read_b128 v[140:143], v139
	ds_read_b128 v[144:147], v139 offset:1024
	ds_read_b128 v[148:151], v139 offset:2048
	ds_read_b128 v[152:155], v139 offset:3072
	v_add_u32_e32 v139, s29, v1
	s_addc_u32 s45, s35, 0
	s_add_i32 s79, s29, s63
	ds_read_b128 v[156:159], v139
	ds_read_b128 v[160:163], v139 offset:1024
	ds_read_b128 v[164:167], v139 offset:2048
	ds_read_b128 v[168:171], v139 offset:3072
	s_add_i32 s78, s79, 0x2000
	s_add_i32 s76, 0, 0x18000
	s_add_i32 vcc_hi, 0, 0x1c000
	s_add_u32 s14, s30, 0x10000
	s_addc_u32 s15, s31, 0
	s_add_i32 vcc_lo, s76, s63
	s_add_i32 s41, vcc_lo, 0x2000
	s_add_u32 s28, s34, 0x10080
	s_addc_u32 s29, s35, 0
	s_add_i32 s82, vcc_hi, s63
	s_add_i32 s81, s82, 0x2000
	v_lshl_add_u64 v[184:185], s[68:69], 0, v[130:131]
	ds_read_b128 v[172:175], v138
	ds_read_b128 v[176:179], v138 offset:1024
	ds_read_b128 v[188:191], v138 offset:2048
	ds_read_b128 v[192:195], v138 offset:3072
	ds_read_b128 v[196:199], v138 offset:4096
	ds_read_b128 v[200:203], v138 offset:5120
	ds_read_b128 v[204:207], v138 offset:6144
	ds_read_b128 v[208:211], v138 offset:7168
	global_load_lds_dwordx4 v[184:185], off
	v_lshl_add_u64 v[184:185], s[68:69], 0, v[134:135]
	s_mov_b32 m0, s83
	s_nop 0
	global_load_lds_dwordx4 v[184:185], off
	s_waitcnt vmcnt(8)
	s_waitcnt lgkmcnt(0)
	s_barrier
	s_setprio 1
	v_mfma_f32_16x16x32_bf16 v[126:129], v[140:143], v[172:175], v[126:129]
	v_mfma_f32_16x16x32_bf16 v[122:125], v[148:151], v[172:175], v[122:125]
	v_mfma_f32_16x16x32_bf16 v[118:121], v[140:143], v[188:191], v[118:121]
	v_mfma_f32_16x16x32_bf16 v[114:117], v[148:151], v[188:191], v[114:117]
	v_mfma_f32_16x16x32_bf16 v[102:105], v[140:143], v[196:199], v[102:105]
	v_mfma_f32_16x16x32_bf16 v[98:101], v[148:151], v[196:199], v[98:101]
	v_mfma_f32_16x16x32_bf16 v[86:89], v[140:143], v[204:207], v[86:89]
	v_mfma_f32_16x16x32_bf16 v[82:85], v[148:151], v[204:207], v[82:85]
	v_mfma_f32_16x16x32_bf16 v[126:129], v[144:147], v[176:179], v[126:129]
	v_mfma_f32_16x16x32_bf16 v[122:125], v[152:155], v[176:179], v[122:125]
	v_mfma_f32_16x16x32_bf16 v[118:121], v[144:147], v[192:195], v[118:121]
	v_mfma_f32_16x16x32_bf16 v[114:117], v[152:155], v[192:195], v[114:117]
	v_mfma_f32_16x16x32_bf16 v[102:105], v[144:147], v[200:203], v[102:105]
	v_mfma_f32_16x16x32_bf16 v[98:101], v[152:155], v[200:203], v[98:101]
	v_mfma_f32_16x16x32_bf16 v[86:89], v[144:147], v[208:211], v[86:89]
	v_mfma_f32_16x16x32_bf16 v[82:85], v[152:155], v[208:211], v[82:85]
	v_mfma_f32_16x16x32_bf16 v[110:113], v[156:159], v[172:175], v[110:113]
	v_mfma_f32_16x16x32_bf16 v[106:109], v[164:167], v[172:175], v[106:109]
	v_mfma_f32_16x16x32_bf16 v[94:97], v[156:159], v[188:191], v[94:97]
	v_mfma_f32_16x16x32_bf16 v[90:93], v[164:167], v[188:191], v[90:93]
	v_mfma_f32_16x16x32_bf16 v[78:81], v[156:159], v[196:199], v[78:81]
	v_mfma_f32_16x16x32_bf16 v[74:77], v[164:167], v[196:199], v[74:77]
	v_mfma_f32_16x16x32_bf16 v[70:73], v[156:159], v[204:207], v[70:73]
	v_mfma_f32_16x16x32_bf16 v[66:69], v[164:167], v[204:207], v[66:69]
	v_mfma_f32_16x16x32_bf16 v[110:113], v[160:163], v[176:179], v[110:113]
	v_mfma_f32_16x16x32_bf16 v[106:109], v[168:171], v[176:179], v[106:109]
	v_mfma_f32_16x16x32_bf16 v[94:97], v[160:163], v[192:195], v[94:97]
	v_mfma_f32_16x16x32_bf16 v[90:93], v[168:171], v[192:195], v[90:93]
	v_mfma_f32_16x16x32_bf16 v[78:81], v[160:163], v[200:203], v[78:81]
	v_mfma_f32_16x16x32_bf16 v[74:77], v[168:171], v[200:203], v[74:77]
	v_mfma_f32_16x16x32_bf16 v[70:73], v[160:163], v[208:211], v[70:73]
	v_mfma_f32_16x16x32_bf16 v[66:69], v[168:171], v[208:211], v[66:69]
	s_setprio 0
	s_barrier
	s_mov_b32 m0, s80
	v_lshl_add_u64 v[184:185], s[34:35], 0, v[132:133]
	ds_read_b128 v[172:175], v138 offset:16384
	ds_read_b128 v[176:179], v138 offset:17408
	ds_read_b128 v[188:191], v138 offset:18432
	ds_read_b128 v[192:195], v138 offset:19456
	ds_read_b128 v[196:199], v138 offset:20480
	ds_read_b128 v[200:203], v138 offset:21504
	ds_read_b128 v[204:207], v138 offset:22528
	ds_read_b128 v[208:211], v138 offset:23552
	global_load_lds_dwordx4 v[184:185], off
	v_lshl_add_u64 v[212:213], s[34:35], 0, v[136:137]
	s_mov_b32 m0, s77
	v_lshl_add_u64 v[214:215], s[44:45], 0, v[132:133]
	global_load_lds_dwordx4 v[212:213], off
	s_mov_b32 m0, s79
	v_lshl_add_u64 v[216:217], s[30:31], 0, v[134:135]
	global_load_lds_dwordx4 v[214:215], off
	v_lshl_add_u64 v[214:215], s[44:45], 0, v[136:137]
	s_mov_b32 m0, s78
	s_nop 0
	global_load_lds_dwordx4 v[214:215], off
	v_lshl_add_u64 v[214:215], s[30:31], 0, v[130:131]
	s_mov_b32 m0, s11
	s_nop 0
	global_load_lds_dwordx4 v[214:215], off
	s_mov_b32 m0, s64
	s_nop 0
	global_load_lds_dwordx4 v[216:217], off
	s_waitcnt vmcnt(8)
	s_waitcnt lgkmcnt(0)
	s_barrier
; #define PG8_STAGE(bufoff, gbase, voff) do { _Pragma("unroll") for (int _i = 0; _i < 2; ++_i) \
;         __builtin_amdgcn_global_load_lds((const unsigned*)((const char*)(gbase) + (voff)[_i]), (LAS unsigned*)(lds + (bufoff) + ldsw + _i * 8192), 16, 0, 0); } while (0)
; #define PG8_LDA(dst, b, h) do { _Pragma("unroll") for (int m = 0; m < 4; ++m) _Pragma("unroll") for (int k = 0; k < 2; ++k) dst[m][k] = *(const LAS bf16x8*)(lds + PG8_SA(b, h) + aoff + m * 2048 + k * 1024); } while (0)
; #define PG8_LDB(dst, b, h) do { _Pragma("unroll") for (int n = 0; n < 2; ++n) _Pragma("unroll") for (int k = 0; k < 2; ++k) dst[n][k] = *(const LAS bf16x8*)(lds + PG8_SB(b, h) + boff + n * 2048 + k * 1024); } while (0)
; #define PG8_MMA(ai, bj, At, Bt) do { __builtin_amdgcn_s_setprio(1); _Pragma("unroll") for (int m = 0; m < 4; ++m) _Pragma("unroll") for (int n = 0; n < 2; ++n) _Pragma("unroll") for (int k = 0; k < 2; ++k) \
;         acc[ai][bj][m][n] = __builtin_amdgcn_mfma_f32_16x16x32_bf16(Bt[n][k], At[m][k], acc[ai][bj][m][n], 0, 0, 0); __builtin_amdgcn_s_setprio(0); } while (0)
; #define PG8_WAIT_V(n) asm volatile("s_waitcnt vmcnt(" #n ")" ::: "memory")
; #define PG8_WAIT_L(n) asm volatile("s_waitcnt lgkmcnt(" #n ")" ::: "memory")
; #define PG8_BAR __builtin_amdgcn_s_barrier()
; #define PG8_SCHED __builtin_amdgcn_sched_barrier(0)
; template <class Epi>
; __device__ __forceinline__ void gemm_phase(LAS unsigned char* lds, const Gemm g, const StaticOrder& S, const Epi& E) {
;     ...
;             PG8_WAIT_V(8); PG8_WAIT_L(0); PG8_BAR; PG8_MMA(1, 0, At, B0); PG8_MMA(1, 1, At, B1); PG8_BAR; PG8_SCHED;
;             PG8_LDB(B0, 1, 0); PG8_LDB(B1, 1, 1); PG8_SCHED; PG8_LDA(At, 1, 0); PG8_STAGE(PG8_SA(0, 1), a2 + hstepA, voffA);
;             PG8_WAIT_V(8); PG8_WAIT_L(0); PG8_BAR; PG8_MMA(0, 0, At, B0); PG8_MMA(0, 1, At, B1); PG8_BAR; PG8_SCHED;
	s_setprio 1
	v_mfma_f32_16x16x32_bf16 v[62:65], v[140:143], v[172:175], v[62:65]
	v_mfma_f32_16x16x32_bf16 v[58:61], v[148:151], v[172:175], v[58:61]
	v_mfma_f32_16x16x32_bf16 v[54:57], v[140:143], v[188:191], v[54:57]
	v_mfma_f32_16x16x32_bf16 v[50:53], v[148:151], v[188:191], v[50:53]
	v_mfma_f32_16x16x32_bf16 v[38:41], v[140:143], v[196:199], v[38:41]
	v_mfma_f32_16x16x32_bf16 v[34:37], v[148:151], v[196:199], v[34:37]
	v_mfma_f32_16x16x32_bf16 v[22:25], v[140:143], v[204:207], v[22:25]
	v_mfma_f32_16x16x32_bf16 v[18:21], v[148:151], v[204:207], v[18:21]
	v_mfma_f32_16x16x32_bf16 v[62:65], v[144:147], v[176:179], v[62:65]
	v_mfma_f32_16x16x32_bf16 v[58:61], v[152:155], v[176:179], v[58:61]
	v_mfma_f32_16x16x32_bf16 v[54:57], v[144:147], v[192:195], v[54:57]
	v_mfma_f32_16x16x32_bf16 v[50:53], v[152:155], v[192:195], v[50:53]
	v_mfma_f32_16x16x32_bf16 v[38:41], v[144:147], v[200:203], v[38:41]
	v_mfma_f32_16x16x32_bf16 v[34:37], v[152:155], v[200:203], v[34:37]
	v_mfma_f32_16x16x32_bf16 v[22:25], v[144:147], v[208:211], v[22:25]
	v_mfma_f32_16x16x32_bf16 v[18:21], v[152:155], v[208:211], v[18:21]
	v_mfma_f32_16x16x32_bf16 v[46:49], v[156:159], v[172:175], v[46:49]
	v_mfma_f32_16x16x32_bf16 v[42:45], v[164:167], v[172:175], v[42:45]
	v_mfma_f32_16x16x32_bf16 v[30:33], v[156:159], v[188:191], v[30:33]
	v_mfma_f32_16x16x32_bf16 v[26:29], v[164:167], v[188:191], v[26:29]
	v_mfma_f32_16x16x32_bf16 v[14:17], v[156:159], v[196:199], v[14:17]
	v_mfma_f32_16x16x32_bf16 v[10:13], v[164:167], v[196:199], v[10:13]
	v_mfma_f32_16x16x32_bf16 v[6:9], v[156:159], v[204:207], v[6:9]
	v_mfma_f32_16x16x32_bf16 v[2:5], v[164:167], v[204:207], v[2:5]
	v_mfma_f32_16x16x32_bf16 v[46:49], v[160:163], v[176:179], v[46:49]
	v_mfma_f32_16x16x32_bf16 v[42:45], v[168:171], v[176:179], v[42:45]
	v_mfma_f32_16x16x32_bf16 v[30:33], v[160:163], v[192:195], v[30:33]
	v_mfma_f32_16x16x32_bf16 v[26:29], v[168:171], v[192:195], v[26:29]
	v_mfma_f32_16x16x32_bf16 v[14:17], v[160:163], v[200:203], v[14:17]
	v_mfma_f32_16x16x32_bf16 v[10:13], v[168:171], v[200:203], v[10:13]
	v_mfma_f32_16x16x32_bf16 v[6:9], v[160:163], v[208:211], v[6:9]
	v_mfma_f32_16x16x32_bf16 v[2:5], v[168:171], v[208:211], v[2:5]
	s_setprio 0
	s_barrier
	v_add_u32_e32 v139, s76, v1
	ds_read_b128 v[140:143], v139
	ds_read_b128 v[144:147], v139 offset:1024
	ds_read_b128 v[148:151], v139 offset:2048
	ds_read_b128 v[152:155], v139 offset:3072
	v_add_u32_e32 v139, vcc_hi, v1
	ds_read_b128 v[156:159], v139
	ds_read_b128 v[160:163], v139 offset:1024
	ds_read_b128 v[164:167], v139 offset:2048
	ds_read_b128 v[168:171], v139 offset:3072
	s_mov_b32 m0, s65
	v_lshl_add_u64 v[218:219], s[14:15], 0, v[130:131]
	ds_read_b128 v[172:175], v138 offset:32768
	ds_read_b128 v[176:179], v138 offset:33792
	ds_read_b128 v[188:191], v138 offset:34816
	ds_read_b128 v[192:195], v138 offset:35840
	ds_read_b128 v[196:199], v138 offset:36864
	ds_read_b128 v[200:203], v138 offset:37888
	ds_read_b128 v[204:207], v138 offset:38912
	ds_read_b128 v[208:211], v138 offset:39936
	global_load_lds_dwordx4 v[218:219], off
	v_lshl_add_u64 v[218:219], s[14:15], 0, v[134:135]
	s_mov_b32 m0, s70
	s_nop 0
	global_load_lds_dwordx4 v[218:219], off
	s_waitcnt vmcnt(8)
	s_waitcnt lgkmcnt(0)
	s_barrier
	s_setprio 1
	v_mfma_f32_16x16x32_bf16 v[126:129], v[140:143], v[172:175], v[126:129]
	v_mfma_f32_16x16x32_bf16 v[122:125], v[148:151], v[172:175], v[122:125]
	v_mfma_f32_16x16x32_bf16 v[118:121], v[140:143], v[188:191], v[118:121]
	v_mfma_f32_16x16x32_bf16 v[114:117], v[148:151], v[188:191], v[114:117]
	v_mfma_f32_16x16x32_bf16 v[102:105], v[140:143], v[196:199], v[102:105]
	v_mfma_f32_16x16x32_bf16 v[98:101], v[148:151], v[196:199], v[98:101]
	v_mfma_f32_16x16x32_bf16 v[86:89], v[140:143], v[204:207], v[86:89]
	v_mfma_f32_16x16x32_bf16 v[82:85], v[148:151], v[204:207], v[82:85]
	v_mfma_f32_16x16x32_bf16 v[126:129], v[144:147], v[176:179], v[126:129]
	v_mfma_f32_16x16x32_bf16 v[122:125], v[152:155], v[176:179], v[122:125]
	v_mfma_f32_16x16x32_bf16 v[118:121], v[144:147], v[192:195], v[118:121]
	v_mfma_f32_16x16x32_bf16 v[114:117], v[152:155], v[192:195], v[114:117]
	v_mfma_f32_16x16x32_bf16 v[102:105], v[144:147], v[200:203], v[102:105]
	v_mfma_f32_16x16x32_bf16 v[98:101], v[152:155], v[200:203], v[98:101]
	v_mfma_f32_16x16x32_bf16 v[86:89], v[144:147], v[208:211], v[86:89]
	v_mfma_f32_16x16x32_bf16 v[82:85], v[152:155], v[208:211], v[82:85]
	v_mfma_f32_16x16x32_bf16 v[110:113], v[156:159], v[172:175], v[110:113]
	v_mfma_f32_16x16x32_bf16 v[106:109], v[164:167], v[172:175], v[106:109]
	v_mfma_f32_16x16x32_bf16 v[94:97], v[156:159], v[188:191], v[94:97]
	v_mfma_f32_16x16x32_bf16 v[90:93], v[164:167], v[188:191], v[90:93]
	v_mfma_f32_16x16x32_bf16 v[78:81], v[156:159], v[196:199], v[78:81]
	v_mfma_f32_16x16x32_bf16 v[74:77], v[164:167], v[196:199], v[74:77]
	v_mfma_f32_16x16x32_bf16 v[70:73], v[156:159], v[204:207], v[70:73]
	v_mfma_f32_16x16x32_bf16 v[66:69], v[164:167], v[204:207], v[66:69]
	v_mfma_f32_16x16x32_bf16 v[110:113], v[160:163], v[176:179], v[110:113]
	v_mfma_f32_16x16x32_bf16 v[106:109], v[168:171], v[176:179], v[106:109]
	v_mfma_f32_16x16x32_bf16 v[94:97], v[160:163], v[192:195], v[94:97]
	v_mfma_f32_16x16x32_bf16 v[90:93], v[168:171], v[192:195], v[90:93]
	v_mfma_f32_16x16x32_bf16 v[78:81], v[160:163], v[200:203], v[78:81]
	v_mfma_f32_16x16x32_bf16 v[74:77], v[168:171], v[200:203], v[74:77]
	v_mfma_f32_16x16x32_bf16 v[70:73], v[160:163], v[208:211], v[70:73]
	v_mfma_f32_16x16x32_bf16 v[66:69], v[168:171], v[208:211], v[66:69]
	s_setprio 0
	s_barrier
; #define PG8_STAGE(bufoff, gbase, voff) do { _Pragma("unroll") for (int _i = 0; _i < 2; ++_i) \
;         __builtin_amdgcn_global_load_lds((const unsigned*)((const char*)(gbase) + (voff)[_i]), (LAS unsigned*)(lds + (bufoff) + ldsw + _i * 8192), 16, 0, 0); } while (0)
; #define PG8_LDA(dst, b, h) do { _Pragma("unroll") for (int m = 0; m < 4; ++m) _Pragma("unroll") for (int k = 0; k < 2; ++k) dst[m][k] = *(const LAS bf16x8*)(lds + PG8_SA(b, h) + aoff + m * 2048 + k * 1024); } while (0)
; #define PG8_MMA(ai, bj, At, Bt) do { __builtin_amdgcn_s_setprio(1); _Pragma("unroll") for (int m = 0; m < 4; ++m) _Pragma("unroll") for (int n = 0; n < 2; ++n) _Pragma("unroll") for (int k = 0; k < 2; ++k) \
;         acc[ai][bj][m][n] = __builtin_amdgcn_mfma_f32_16x16x32_bf16(Bt[n][k], At[m][k], acc[ai][bj][m][n], 0, 0, 0); __builtin_amdgcn_s_setprio(0); } while (0)
; #define PG8_WAIT_V(n) asm volatile("s_waitcnt vmcnt(" #n ")" ::: "memory")
; #define PG8_WAIT_L(n) asm volatile("s_waitcnt lgkmcnt(" #n ")" ::: "memory")
; #define PG8_BAR __builtin_amdgcn_s_barrier()
; #define PG8_SCHED __builtin_amdgcn_sched_barrier(0)
; template <class Epi>
; __device__ __forceinline__ void gemm_phase(LAS unsigned char* lds, const Gemm g, const StaticOrder& S, const Epi& E) {
;     ...
;             PG8_LDA(At, 1, 1); PG8_STAGE(PG8_SB(1, 0), b3, voffB); PG8_STAGE(PG8_SB(1, 1), b3 + hstepB, voffB); PG8_STAGE(PG8_SA(1, 0), a3, voffA);
;             PG8_WAIT_V(8); PG8_WAIT_L(0); PG8_BAR; PG8_MMA(1, 0, At, B0); PG8_MMA(1, 1, At, B1); PG8_BAR; PG8_SCHED;
;         }
;         if (wr == 0) PG8_BAR;
	s_mov_b32 m0, vcc_lo
	v_lshl_add_u64 v[184:185], v[184:185], 0, s[84:85]
	ds_read_b128 v[172:175], v138 offset:49152
	ds_read_b128 v[176:179], v138 offset:50176
	ds_read_b128 v[188:191], v138 offset:51200
	ds_read_b128 v[192:195], v138 offset:52224
	ds_read_b128 v[196:199], v138 offset:53248
	ds_read_b128 v[200:203], v138 offset:54272
	ds_read_b128 v[204:207], v138 offset:55296
	ds_read_b128 v[208:211], v138 offset:56320
	global_load_lds_dwordx4 v[184:185], off
	v_lshl_add_u64 v[184:185], v[212:213], 0, s[84:85]
	s_mov_b32 m0, s41
	s_nop 0
	global_load_lds_dwordx4 v[184:185], off
	v_lshl_add_u64 v[184:185], s[28:29], 0, v[132:133]
	s_mov_b32 m0, s82
	s_nop 0
	global_load_lds_dwordx4 v[184:185], off
	v_lshl_add_u64 v[184:185], s[28:29], 0, v[136:137]
	s_mov_b32 m0, s81
	s_nop 0
	global_load_lds_dwordx4 v[184:185], off
	v_lshl_add_u64 v[184:185], v[214:215], 0, s[84:85]
	s_mov_b32 m0, s86
	s_nop 0
	global_load_lds_dwordx4 v[184:185], off
	v_lshl_add_u64 v[184:185], v[216:217], 0, s[84:85]
	s_mov_b32 m0, s87
	s_nop 0
	global_load_lds_dwordx4 v[184:185], off
	s_waitcnt vmcnt(8)
	s_waitcnt lgkmcnt(0)
	s_barrier
	s_setprio 1
	v_mfma_f32_16x16x32_bf16 v[62:65], v[140:143], v[172:175], v[62:65]
	v_mfma_f32_16x16x32_bf16 v[58:61], v[148:151], v[172:175], v[58:61]
	v_mfma_f32_16x16x32_bf16 v[54:57], v[140:143], v[188:191], v[54:57]
	v_mfma_f32_16x16x32_bf16 v[50:53], v[148:151], v[188:191], v[50:53]
	v_mfma_f32_16x16x32_bf16 v[38:41], v[140:143], v[196:199], v[38:41]
	v_mfma_f32_16x16x32_bf16 v[34:37], v[148:151], v[196:199], v[34:37]
	v_mfma_f32_16x16x32_bf16 v[22:25], v[140:143], v[204:207], v[22:25]
	v_mfma_f32_16x16x32_bf16 v[18:21], v[148:151], v[204:207], v[18:21]
	v_mfma_f32_16x16x32_bf16 v[62:65], v[144:147], v[176:179], v[62:65]
	v_mfma_f32_16x16x32_bf16 v[58:61], v[152:155], v[176:179], v[58:61]
	v_mfma_f32_16x16x32_bf16 v[54:57], v[144:147], v[192:195], v[54:57]
	v_mfma_f32_16x16x32_bf16 v[50:53], v[152:155], v[192:195], v[50:53]
	v_mfma_f32_16x16x32_bf16 v[38:41], v[144:147], v[200:203], v[38:41]
	v_mfma_f32_16x16x32_bf16 v[34:37], v[152:155], v[200:203], v[34:37]
	v_mfma_f32_16x16x32_bf16 v[22:25], v[144:147], v[208:211], v[22:25]
	v_mfma_f32_16x16x32_bf16 v[18:21], v[152:155], v[208:211], v[18:21]
	v_mfma_f32_16x16x32_bf16 v[46:49], v[156:159], v[172:175], v[46:49]
	v_mfma_f32_16x16x32_bf16 v[42:45], v[164:167], v[172:175], v[42:45]
	v_mfma_f32_16x16x32_bf16 v[30:33], v[156:159], v[188:191], v[30:33]
	v_mfma_f32_16x16x32_bf16 v[26:29], v[164:167], v[188:191], v[26:29]
	v_mfma_f32_16x16x32_bf16 v[14:17], v[156:159], v[196:199], v[14:17]
	v_mfma_f32_16x16x32_bf16 v[10:13], v[164:167], v[196:199], v[10:13]
	v_mfma_f32_16x16x32_bf16 v[6:9], v[156:159], v[204:207], v[6:9]
	v_mfma_f32_16x16x32_bf16 v[2:5], v[164:167], v[204:207], v[2:5]
	v_mfma_f32_16x16x32_bf16 v[46:49], v[160:163], v[176:179], v[46:49]
	v_mfma_f32_16x16x32_bf16 v[42:45], v[168:171], v[176:179], v[42:45]
	v_mfma_f32_16x16x32_bf16 v[30:33], v[160:163], v[192:195], v[30:33]
	v_mfma_f32_16x16x32_bf16 v[26:29], v[168:171], v[192:195], v[26:29]
	v_mfma_f32_16x16x32_bf16 v[14:17], v[160:163], v[200:203], v[14:17]
	v_mfma_f32_16x16x32_bf16 v[10:13], v[168:171], v[200:203], v[10:13]
	v_mfma_f32_16x16x32_bf16 v[6:9], v[160:163], v[208:211], v[6:9]
	v_mfma_f32_16x16x32_bf16 v[2:5], v[168:171], v[208:211], v[2:5]
	s_setprio 0
	s_barrier
	s_movk_i32 s14, 0x100
	s_andn2_b64 vcc, exec, s[26:27]
	s_mov_b64 s[28:29], -1
	s_mov_b64 s[26:27], 0
	s_cbranch_vccz .LBB0_2155
	v_readlane_b32 s28, v255, 28
	s_and_b64 vcc, exec, s[8:9]
	v_readlane_b32 s29, v255, 29
	s_cbranch_vccz .LBB0_2158
	s_barrier

; #define PG8_STAGE(bufoff, gbase, voff) do { _Pragma("unroll") for (int _i = 0; _i < 2; ++_i) \
;         __builtin_amdgcn_global_load_lds((const unsigned*)((const char*)(gbase) + (voff)[_i]), (LAS unsigned*)(lds + (bufoff) + ldsw + _i * 8192), 16, 0, 0); } while (0)
; #define PG8_LDA(dst, b, h) do { _Pragma("unroll") for (int m = 0; m < 4; ++m) _Pragma("unroll") for (int k = 0; k < 2; ++k) dst[m][k] = *(const LAS bf16x8*)(lds + PG8_SA(b, h) + aoff + m * 2048 + k * 1024); } while (0)
; #define PG8_LDB(dst, b, h) do { _Pragma("unroll") for (int n = 0; n < 2; ++n) _Pragma("unroll") for (int k = 0; k < 2; ++k) dst[n][k] = *(const LAS bf16x8*)(lds + PG8_SB(b, h) + boff + n * 2048 + k * 1024); } while (0)
; #define PG8_MMA(ai, bj, At, Bt) do { __builtin_amdgcn_s_setprio(1); _Pragma("unroll") for (int m = 0; m < 4; ++m) _Pragma("unroll") for (int n = 0; n < 2; ++n) _Pragma("unroll") for (int k = 0; k < 2; ++k) \
;         acc[ai][bj][m][n] = __builtin_amdgcn_mfma_f32_16x16x32_bf16(Bt[n][k], At[m][k], acc[ai][bj][m][n], 0, 0, 0); __builtin_amdgcn_s_setprio(0); } while (0)
; #define PG8_WAIT_V(n) asm volatile("s_waitcnt vmcnt(" #n ")" ::: "memory")
; #define PG8_WAIT_L(n) asm volatile("s_waitcnt lgkmcnt(" #n ")" ::: "memory")
; #define PG8_BAR __builtin_amdgcn_s_barrier()
; #define PG8_SCHED __builtin_amdgcn_sched_barrier(0)
; template <class Epi>
; __device__ __forceinline__ void gemm_phase(LAS unsigned char* lds, const Gemm g, const StaticOrder& S, const Epi& E) {
;     ...
;             const bool last = (t == nt - 2);
;             const char* a1 = cA + (size_t)(t + 1) * kstep;
;             const char* a2 = last ? nA : cA + (size_t)(t + 2) * kstep; const char* b2 = last ? nB : cB + (size_t)(t + 2) * kstep;
;             const char* a3 = a2 + kstep; const char* b3 = b2 + kstep;
;             PG8_LDB(B0, 0, 0); PG8_LDB(B1, 0, 1); PG8_SCHED; PG8_LDA(At, 0, 0); PG8_STAGE(PG8_SA(1, 1), a1 + hstepA, voffA);
;             PG8_WAIT_V(8); PG8_WAIT_L(0); PG8_BAR; PG8_MMA(0, 0, At, B0); PG8_MMA(0, 1, At, B1); PG8_BAR; PG8_SCHED;
;             PG8_LDA(At, 0, 1); PG8_STAGE(PG8_SB(0, 0), b2, voffB); PG8_STAGE(PG8_SB(0, 1), b2 + hstepB, voffB); PG8_STAGE(PG8_SA(0, 0), a2, voffA);
;             PG8_WAIT_V(8); PG8_WAIT_L(0); PG8_BAR; PG8_MMA(1, 0, At, B0); PG8_MMA(1, 1, At, B1); PG8_BAR; PG8_SCHED;
.LBB0_2233:
	s_add_u32 s14, s24, 0xffe00080
	s_addc_u32 s15, s25, -1
	s_add_i32 s52, 0, 0x10000
	s_cmpk_eq_i32 s41, 0x7c
	s_cselect_b32 s27, s1, s15
	s_cselect_b32 s26, s3, s14
	s_cselect_b32 s15, s9, s40
	s_cselect_b32 s14, s17, s19
	s_add_i32 s62, 0, 0x14000
	v_add_u32_e32 v142, s52, v1
	v_add_u32_e32 v167, s62, v1
	ds_read_b128 v[130:133], v142
	ds_read_b128 v[134:137], v142 offset:1024
	ds_read_b128 v[138:141], v142 offset:2048
	ds_read_b128 v[142:145], v142 offset:3072
	ds_read_b128 v[146:149], v167
	ds_read_b128 v[162:165], v167 offset:1024
	ds_read_b128 v[168:171], v167 offset:2048
	ds_read_b128 v[172:175], v167 offset:3072
	v_lshl_add_u64 v[184:185], s[24:25], 0, v[158:159]
	s_add_i32 m0, s31, 0xc000
	ds_read_b128 v[176:179], v166
	ds_read_b128 v[188:191], v166 offset:1024
	ds_read_b128 v[192:195], v166 offset:2048
	ds_read_b128 v[196:199], v166 offset:3072
	ds_read_b128 v[200:203], v166 offset:4096
	ds_read_b128 v[204:207], v166 offset:5120
	ds_read_b128 v[208:211], v166 offset:6144
	ds_read_b128 v[212:215], v166 offset:7168
	global_load_lds_dwordx4 v[184:185], off
	v_lshl_add_u64 v[184:185], s[24:25], 0, v[160:161]
	s_add_i32 m0, s31, 0xe000
	s_nop 0
	global_load_lds_dwordx4 v[184:185], off
	s_waitcnt vmcnt(8)
	s_waitcnt lgkmcnt(0)
	s_barrier
	s_setprio 1
	v_mfma_f32_16x16x32_bf16 v[126:129], v[130:133], v[176:179], v[126:129]
	v_mfma_f32_16x16x32_bf16 v[122:125], v[138:141], v[176:179], v[122:125]
	v_mfma_f32_16x16x32_bf16 v[118:121], v[130:133], v[192:195], v[118:121]
	v_mfma_f32_16x16x32_bf16 v[114:117], v[138:141], v[192:195], v[114:117]
	v_mfma_f32_16x16x32_bf16 v[94:97], v[130:133], v[200:203], v[94:97]
	v_mfma_f32_16x16x32_bf16 v[90:93], v[138:141], v[200:203], v[90:93]
	v_mfma_f32_16x16x32_bf16 v[82:85], v[130:133], v[208:211], v[82:85]
	v_mfma_f32_16x16x32_bf16 v[74:77], v[138:141], v[208:211], v[74:77]
	v_mfma_f32_16x16x32_bf16 v[126:129], v[134:137], v[188:191], v[126:129]
	v_mfma_f32_16x16x32_bf16 v[122:125], v[142:145], v[188:191], v[122:125]
	v_mfma_f32_16x16x32_bf16 v[118:121], v[134:137], v[196:199], v[118:121]
	v_mfma_f32_16x16x32_bf16 v[114:117], v[142:145], v[196:199], v[114:117]
	v_mfma_f32_16x16x32_bf16 v[94:97], v[134:137], v[204:207], v[94:97]
	v_mfma_f32_16x16x32_bf16 v[90:93], v[142:145], v[204:207], v[90:93]
	v_mfma_f32_16x16x32_bf16 v[82:85], v[134:137], v[212:215], v[82:85]
	v_mfma_f32_16x16x32_bf16 v[74:77], v[142:145], v[212:215], v[74:77]
	v_mfma_f32_16x16x32_bf16 v[110:113], v[146:149], v[176:179], v[110:113]
	v_mfma_f32_16x16x32_bf16 v[106:109], v[168:171], v[176:179], v[106:109]
	v_mfma_f32_16x16x32_bf16 v[102:105], v[146:149], v[192:195], v[102:105]
	v_mfma_f32_16x16x32_bf16 v[98:101], v[168:171], v[192:195], v[98:101]
	v_mfma_f32_16x16x32_bf16 v[86:89], v[146:149], v[200:203], v[86:89]
	v_mfma_f32_16x16x32_bf16 v[78:81], v[168:171], v[200:203], v[78:81]
	v_mfma_f32_16x16x32_bf16 v[70:73], v[146:149], v[208:211], v[70:73]
	v_mfma_f32_16x16x32_bf16 v[66:69], v[168:171], v[208:211], v[66:69]
	v_mfma_f32_16x16x32_bf16 v[110:113], v[162:165], v[188:191], v[110:113]
	v_mfma_f32_16x16x32_bf16 v[106:109], v[172:175], v[188:191], v[106:109]
	v_mfma_f32_16x16x32_bf16 v[102:105], v[162:165], v[196:199], v[102:105]
	v_mfma_f32_16x16x32_bf16 v[98:101], v[172:175], v[196:199], v[98:101]
	v_mfma_f32_16x16x32_bf16 v[86:89], v[162:165], v[204:207], v[86:89]
	v_mfma_f32_16x16x32_bf16 v[78:81], v[172:175], v[204:207], v[78:81]
	v_mfma_f32_16x16x32_bf16 v[70:73], v[162:165], v[212:215], v[70:73]
	v_mfma_f32_16x16x32_bf16 v[66:69], v[172:175], v[212:215], v[66:69]
	s_setprio 0
	s_barrier
	s_add_i32 s52, s52, s30
	v_lshl_add_u64 v[184:185], s[14:15], 0, v[152:153]
	s_mov_b32 m0, s52
	ds_read_b128 v[176:179], v166 offset:16384
	ds_read_b128 v[188:191], v166 offset:17408
	ds_read_b128 v[192:195], v166 offset:18432
	ds_read_b128 v[196:199], v166 offset:19456
	ds_read_b128 v[200:203], v166 offset:20480
	ds_read_b128 v[204:207], v166 offset:21504
	ds_read_b128 v[208:211], v166 offset:22528
	ds_read_b128 v[212:215], v166 offset:23552
	global_load_lds_dwordx4 v[184:185], off
	s_add_i32 m0, s52, 0x2000
	s_add_u32 s52, s14, 0x200000
	v_lshl_add_u64 v[216:217], s[14:15], 0, v[156:157]
	s_addc_u32 s53, s15, 0
	s_add_i32 s62, s62, s30
	global_load_lds_dwordx4 v[216:217], off
	v_lshl_add_u64 v[218:219], s[52:53], 0, v[152:153]
	s_mov_b32 m0, s62
	v_lshl_add_u64 v[220:221], s[26:27], 0, v[154:155]
	global_load_lds_dwordx4 v[218:219], off
	v_lshl_add_u64 v[218:219], s[52:53], 0, v[156:157]
	s_add_i32 m0, s62, 0x2000
	s_nop 0
	global_load_lds_dwordx4 v[218:219], off
	v_lshl_add_u64 v[218:219], s[26:27], 0, v[150:151]
	s_mov_b32 m0, s31
	s_nop 0
	global_load_lds_dwordx4 v[218:219], off
	s_mov_b32 m0, s34
	s_nop 0
	global_load_lds_dwordx4 v[220:221], off
	s_waitcnt vmcnt(8)
	s_waitcnt lgkmcnt(0)
	s_barrier
; #define PG8_STAGE(bufoff, gbase, voff) do { _Pragma("unroll") for (int _i = 0; _i < 2; ++_i) \
;         __builtin_amdgcn_global_load_lds((const unsigned*)((const char*)(gbase) + (voff)[_i]), (LAS unsigned*)(lds + (bufoff) + ldsw + _i * 8192), 16, 0, 0); } while (0)
; #define PG8_LDA(dst, b, h) do { _Pragma("unroll") for (int m = 0; m < 4; ++m) _Pragma("unroll") for (int k = 0; k < 2; ++k) dst[m][k] = *(const LAS bf16x8*)(lds + PG8_SA(b, h) + aoff + m * 2048 + k * 1024); } while (0)
; #define PG8_LDB(dst, b, h) do { _Pragma("unroll") for (int n = 0; n < 2; ++n) _Pragma("unroll") for (int k = 0; k < 2; ++k) dst[n][k] = *(const LAS bf16x8*)(lds + PG8_SB(b, h) + boff + n * 2048 + k * 1024); } while (0)
; #define PG8_MMA(ai, bj, At, Bt) do { __builtin_amdgcn_s_setprio(1); _Pragma("unroll") for (int m = 0; m < 4; ++m) _Pragma("unroll") for (int n = 0; n < 2; ++n) _Pragma("unroll") for (int k = 0; k < 2; ++k) \
;         acc[ai][bj][m][n] = __builtin_amdgcn_mfma_f32_16x16x32_bf16(Bt[n][k], At[m][k], acc[ai][bj][m][n], 0, 0, 0); __builtin_amdgcn_s_setprio(0); } while (0)
; #define PG8_WAIT_V(n) asm volatile("s_waitcnt vmcnt(" #n ")" ::: "memory")
; #define PG8_WAIT_L(n) asm volatile("s_waitcnt lgkmcnt(" #n ")" ::: "memory")
; #define PG8_BAR __builtin_amdgcn_s_barrier()
; #define PG8_SCHED __builtin_amdgcn_sched_barrier(0)
; template <class Epi>
; __device__ __forceinline__ void gemm_phase(LAS unsigned char* lds, const Gemm g, const StaticOrder& S, const Epi& E) {
;     ...
;             PG8_WAIT_V(8); PG8_WAIT_L(0); PG8_BAR; PG8_MMA(1, 0, At, B0); PG8_MMA(1, 1, At, B1); PG8_BAR; PG8_SCHED;
;             PG8_LDB(B0, 1, 0); PG8_LDB(B1, 1, 1); PG8_SCHED; PG8_LDA(At, 1, 0); PG8_STAGE(PG8_SA(0, 1), a2 + hstepA, voffA);
;             PG8_WAIT_V(8); PG8_WAIT_L(0); PG8_BAR; PG8_MMA(0, 0, At, B0); PG8_MMA(0, 1, At, B1); PG8_BAR; PG8_SCHED;
	s_setprio 1
	v_mfma_f32_16x16x32_bf16 v[62:65], v[130:133], v[176:179], v[62:65]
	v_mfma_f32_16x16x32_bf16 v[58:61], v[138:141], v[176:179], v[58:61]
	v_mfma_f32_16x16x32_bf16 v[50:53], v[130:133], v[192:195], v[50:53]
	v_mfma_f32_16x16x32_bf16 v[42:45], v[138:141], v[192:195], v[42:45]
	v_mfma_f32_16x16x32_bf16 v[30:33], v[130:133], v[200:203], v[30:33]
	v_mfma_f32_16x16x32_bf16 v[26:29], v[138:141], v[200:203], v[26:29]
	v_mfma_f32_16x16x32_bf16 v[18:21], v[130:133], v[208:211], v[18:21]
	v_mfma_f32_16x16x32_bf16 v[10:13], v[138:141], v[208:211], v[10:13]
	v_mfma_f32_16x16x32_bf16 v[62:65], v[134:137], v[188:191], v[62:65]
	v_mfma_f32_16x16x32_bf16 v[58:61], v[142:145], v[188:191], v[58:61]
	v_mfma_f32_16x16x32_bf16 v[50:53], v[134:137], v[196:199], v[50:53]
	v_mfma_f32_16x16x32_bf16 v[42:45], v[142:145], v[196:199], v[42:45]
	v_mfma_f32_16x16x32_bf16 v[30:33], v[134:137], v[204:207], v[30:33]
	v_mfma_f32_16x16x32_bf16 v[26:29], v[142:145], v[204:207], v[26:29]
	v_mfma_f32_16x16x32_bf16 v[18:21], v[134:137], v[212:215], v[18:21]
	v_mfma_f32_16x16x32_bf16 v[10:13], v[142:145], v[212:215], v[10:13]
	v_mfma_f32_16x16x32_bf16 v[54:57], v[146:149], v[176:179], v[54:57]
	v_mfma_f32_16x16x32_bf16 v[46:49], v[168:171], v[176:179], v[46:49]
	v_mfma_f32_16x16x32_bf16 v[38:41], v[146:149], v[192:195], v[38:41]
	v_mfma_f32_16x16x32_bf16 v[34:37], v[168:171], v[192:195], v[34:37]
	v_mfma_f32_16x16x32_bf16 v[22:25], v[146:149], v[200:203], v[22:25]
	v_mfma_f32_16x16x32_bf16 v[14:17], v[168:171], v[200:203], v[14:17]
	v_mfma_f32_16x16x32_bf16 v[6:9], v[146:149], v[208:211], v[6:9]
	v_mfma_f32_16x16x32_bf16 v[2:5], v[168:171], v[208:211], v[2:5]
	v_mfma_f32_16x16x32_bf16 v[54:57], v[162:165], v[188:191], v[54:57]
	v_mfma_f32_16x16x32_bf16 v[46:49], v[172:175], v[188:191], v[46:49]
	v_mfma_f32_16x16x32_bf16 v[38:41], v[162:165], v[196:199], v[38:41]
	v_mfma_f32_16x16x32_bf16 v[34:37], v[172:175], v[196:199], v[34:37]
	v_mfma_f32_16x16x32_bf16 v[22:25], v[162:165], v[204:207], v[22:25]
	v_mfma_f32_16x16x32_bf16 v[14:17], v[172:175], v[204:207], v[14:17]
	v_mfma_f32_16x16x32_bf16 v[6:9], v[162:165], v[212:215], v[6:9]
	v_mfma_f32_16x16x32_bf16 v[2:5], v[172:175], v[212:215], v[2:5]
	s_setprio 0
	s_barrier
	s_add_i32 s52, 0, 0x18000
	s_add_i32 s53, 0, 0x1c000
	v_add_u32_e32 v142, s52, v1
	v_add_u32_e32 v167, s53, v1
	ds_read_b128 v[130:133], v142
	ds_read_b128 v[134:137], v142 offset:1024
	ds_read_b128 v[138:141], v142 offset:2048
	ds_read_b128 v[142:145], v142 offset:3072
	ds_read_b128 v[146:149], v167
	ds_read_b128 v[162:165], v167 offset:1024
	ds_read_b128 v[168:171], v167 offset:2048
	ds_read_b128 v[172:175], v167 offset:3072
	s_add_u32 s26, s26, 0x200000
	s_addc_u32 s27, s27, 0
	s_mov_b32 m0, s35
	v_lshl_add_u64 v[222:223], s[26:27], 0, v[150:151]
	ds_read_b128 v[176:179], v166 offset:32768
	ds_read_b128 v[188:191], v166 offset:33792
	ds_read_b128 v[192:195], v166 offset:34816
	ds_read_b128 v[196:199], v166 offset:35840
	ds_read_b128 v[200:203], v166 offset:36864
	ds_read_b128 v[204:207], v166 offset:37888
	ds_read_b128 v[208:211], v166 offset:38912
	ds_read_b128 v[212:215], v166 offset:39936
	global_load_lds_dwordx4 v[222:223], off
	v_lshl_add_u64 v[222:223], s[26:27], 0, v[154:155]
	s_mov_b32 m0, s42
	s_nop 0
	global_load_lds_dwordx4 v[222:223], off
	s_waitcnt vmcnt(8)
	s_waitcnt lgkmcnt(0)
	s_barrier
	s_setprio 1
	v_mfma_f32_16x16x32_bf16 v[126:129], v[130:133], v[176:179], v[126:129]
	v_mfma_f32_16x16x32_bf16 v[122:125], v[138:141], v[176:179], v[122:125]
	v_mfma_f32_16x16x32_bf16 v[118:121], v[130:133], v[192:195], v[118:121]
	v_mfma_f32_16x16x32_bf16 v[114:117], v[138:141], v[192:195], v[114:117]
	v_mfma_f32_16x16x32_bf16 v[94:97], v[130:133], v[200:203], v[94:97]
	v_mfma_f32_16x16x32_bf16 v[90:93], v[138:141], v[200:203], v[90:93]
	v_mfma_f32_16x16x32_bf16 v[82:85], v[130:133], v[208:211], v[82:85]
	v_mfma_f32_16x16x32_bf16 v[74:77], v[138:141], v[208:211], v[74:77]
	v_mfma_f32_16x16x32_bf16 v[126:129], v[134:137], v[188:191], v[126:129]
	v_mfma_f32_16x16x32_bf16 v[122:125], v[142:145], v[188:191], v[122:125]
	v_mfma_f32_16x16x32_bf16 v[118:121], v[134:137], v[196:199], v[118:121]
	v_mfma_f32_16x16x32_bf16 v[114:117], v[142:145], v[196:199], v[114:117]
	v_mfma_f32_16x16x32_bf16 v[94:97], v[134:137], v[204:207], v[94:97]
	v_mfma_f32_16x16x32_bf16 v[90:93], v[142:145], v[204:207], v[90:93]
	v_mfma_f32_16x16x32_bf16 v[82:85], v[134:137], v[212:215], v[82:85]
	v_mfma_f32_16x16x32_bf16 v[74:77], v[142:145], v[212:215], v[74:77]
	v_mfma_f32_16x16x32_bf16 v[110:113], v[146:149], v[176:179], v[110:113]
	v_mfma_f32_16x16x32_bf16 v[106:109], v[168:171], v[176:179], v[106:109]
	v_mfma_f32_16x16x32_bf16 v[102:105], v[146:149], v[192:195], v[102:105]
	v_mfma_f32_16x16x32_bf16 v[98:101], v[168:171], v[192:195], v[98:101]
	v_mfma_f32_16x16x32_bf16 v[86:89], v[146:149], v[200:203], v[86:89]
	v_mfma_f32_16x16x32_bf16 v[78:81], v[168:171], v[200:203], v[78:81]
	v_mfma_f32_16x16x32_bf16 v[70:73], v[146:149], v[208:211], v[70:73]
	v_mfma_f32_16x16x32_bf16 v[66:69], v[168:171], v[208:211], v[66:69]
	v_mfma_f32_16x16x32_bf16 v[110:113], v[162:165], v[188:191], v[110:113]
	v_mfma_f32_16x16x32_bf16 v[106:109], v[172:175], v[188:191], v[106:109]
	v_mfma_f32_16x16x32_bf16 v[102:105], v[162:165], v[196:199], v[102:105]
	v_mfma_f32_16x16x32_bf16 v[98:101], v[172:175], v[196:199], v[98:101]
	v_mfma_f32_16x16x32_bf16 v[86:89], v[162:165], v[204:207], v[86:89]
	v_mfma_f32_16x16x32_bf16 v[78:81], v[172:175], v[204:207], v[78:81]
	v_mfma_f32_16x16x32_bf16 v[70:73], v[162:165], v[212:215], v[70:73]
	v_mfma_f32_16x16x32_bf16 v[66:69], v[172:175], v[212:215], v[66:69]
	s_setprio 0
	s_barrier
; #define PG8_STAGE(bufoff, gbase, voff) do { _Pragma("unroll") for (int _i = 0; _i < 2; ++_i) \
;         __builtin_amdgcn_global_load_lds((const unsigned*)((const char*)(gbase) + (voff)[_i]), (LAS unsigned*)(lds + (bufoff) + ldsw + _i * 8192), 16, 0, 0); } while (0)
; #define PG8_LDA(dst, b, h) do { _Pragma("unroll") for (int m = 0; m < 4; ++m) _Pragma("unroll") for (int k = 0; k < 2; ++k) dst[m][k] = *(const LAS bf16x8*)(lds + PG8_SA(b, h) + aoff + m * 2048 + k * 1024); } while (0)
; #define PG8_MMA(ai, bj, At, Bt) do { __builtin_amdgcn_s_setprio(1); _Pragma("unroll") for (int m = 0; m < 4; ++m) _Pragma("unroll") for (int n = 0; n < 2; ++n) _Pragma("unroll") for (int k = 0; k < 2; ++k) \
;         acc[ai][bj][m][n] = __builtin_amdgcn_mfma_f32_16x16x32_bf16(Bt[n][k], At[m][k], acc[ai][bj][m][n], 0, 0, 0); __builtin_amdgcn_s_setprio(0); } while (0)
; #define PG8_WAIT_V(n) asm volatile("s_waitcnt vmcnt(" #n ")" ::: "memory")
; #define PG8_WAIT_L(n) asm volatile("s_waitcnt lgkmcnt(" #n ")" ::: "memory")
; #define PG8_BAR __builtin_amdgcn_s_barrier()
; #define PG8_SCHED __builtin_amdgcn_sched_barrier(0)
; template <class Epi>
; __device__ __forceinline__ void gemm_phase(LAS unsigned char* lds, const Gemm g, const StaticOrder& S, const Epi& E) {
;     ...
;             PG8_LDA(At, 1, 1); PG8_STAGE(PG8_SB(1, 0), b3, voffB); PG8_STAGE(PG8_SB(1, 1), b3 + hstepB, voffB); PG8_STAGE(PG8_SA(1, 0), a3, voffA);
;             PG8_WAIT_V(8); PG8_WAIT_L(0); PG8_BAR; PG8_MMA(1, 0, At, B0); PG8_MMA(1, 1, At, B1); PG8_BAR; PG8_SCHED;
;         }
	s_add_i32 s26, s52, s30
	v_lshl_add_u64 v[184:185], v[184:185], 0, s[84:85]
	s_mov_b32 m0, s26
	ds_read_b128 v[176:179], v166 offset:49152
	ds_read_b128 v[188:191], v166 offset:50176
	ds_read_b128 v[192:195], v166 offset:51200
	ds_read_b128 v[196:199], v166 offset:52224
	ds_read_b128 v[200:203], v166 offset:53248
	ds_read_b128 v[204:207], v166 offset:54272
	ds_read_b128 v[208:211], v166 offset:55296
	ds_read_b128 v[212:215], v166 offset:56320
	global_load_lds_dwordx4 v[184:185], off
	s_add_i32 m0, s26, 0x2000
	s_add_u32 s14, s14, 0x200080
	v_lshl_add_u64 v[184:185], v[216:217], 0, s[84:85]
	s_addc_u32 s15, s15, 0
	s_add_i32 s26, s53, s30
	global_load_lds_dwordx4 v[184:185], off
	v_lshl_add_u64 v[184:185], s[14:15], 0, v[152:153]
	s_mov_b32 m0, s26
	s_nop 0
	global_load_lds_dwordx4 v[184:185], off
	v_lshl_add_u64 v[184:185], s[14:15], 0, v[156:157]
	s_add_i32 m0, s26, 0x2000
	s_nop 0
	global_load_lds_dwordx4 v[184:185], off
	v_lshl_add_u64 v[184:185], v[218:219], 0, s[84:85]
	s_mov_b32 m0, s68
	s_nop 0
	global_load_lds_dwordx4 v[184:185], off
	v_lshl_add_u64 v[184:185], v[220:221], 0, s[84:85]
	s_mov_b32 m0, s69
	s_nop 0
	global_load_lds_dwordx4 v[184:185], off
	s_waitcnt vmcnt(8)
	s_waitcnt lgkmcnt(0)
	s_barrier
	s_setprio 1
	v_mfma_f32_16x16x32_bf16 v[62:65], v[130:133], v[176:179], v[62:65]
	v_mfma_f32_16x16x32_bf16 v[58:61], v[138:141], v[176:179], v[58:61]
	v_mfma_f32_16x16x32_bf16 v[50:53], v[130:133], v[192:195], v[50:53]
	v_mfma_f32_16x16x32_bf16 v[42:45], v[138:141], v[192:195], v[42:45]
	v_mfma_f32_16x16x32_bf16 v[30:33], v[130:133], v[200:203], v[30:33]
	v_mfma_f32_16x16x32_bf16 v[26:29], v[138:141], v[200:203], v[26:29]
	v_mfma_f32_16x16x32_bf16 v[18:21], v[130:133], v[208:211], v[18:21]
	v_mfma_f32_16x16x32_bf16 v[10:13], v[138:141], v[208:211], v[10:13]
	v_mfma_f32_16x16x32_bf16 v[62:65], v[134:137], v[188:191], v[62:65]
	v_mfma_f32_16x16x32_bf16 v[58:61], v[142:145], v[188:191], v[58:61]
	v_mfma_f32_16x16x32_bf16 v[50:53], v[134:137], v[196:199], v[50:53]
	v_mfma_f32_16x16x32_bf16 v[42:45], v[142:145], v[196:199], v[42:45]
	v_mfma_f32_16x16x32_bf16 v[30:33], v[134:137], v[204:207], v[30:33]
	v_mfma_f32_16x16x32_bf16 v[26:29], v[142:145], v[204:207], v[26:29]
	v_mfma_f32_16x16x32_bf16 v[18:21], v[134:137], v[212:215], v[18:21]
	v_mfma_f32_16x16x32_bf16 v[10:13], v[142:145], v[212:215], v[10:13]
	v_mfma_f32_16x16x32_bf16 v[54:57], v[146:149], v[176:179], v[54:57]
	v_mfma_f32_16x16x32_bf16 v[46:49], v[168:171], v[176:179], v[46:49]
	v_mfma_f32_16x16x32_bf16 v[38:41], v[146:149], v[192:195], v[38:41]
	v_mfma_f32_16x16x32_bf16 v[34:37], v[168:171], v[192:195], v[34:37]
	v_mfma_f32_16x16x32_bf16 v[22:25], v[146:149], v[200:203], v[22:25]
	v_mfma_f32_16x16x32_bf16 v[14:17], v[168:171], v[200:203], v[14:17]
	v_mfma_f32_16x16x32_bf16 v[6:9], v[146:149], v[208:211], v[6:9]
	v_mfma_f32_16x16x32_bf16 v[2:5], v[168:171], v[208:211], v[2:5]
	v_mfma_f32_16x16x32_bf16 v[54:57], v[162:165], v[188:191], v[54:57]
	v_mfma_f32_16x16x32_bf16 v[46:49], v[172:175], v[188:191], v[46:49]
	v_mfma_f32_16x16x32_bf16 v[38:41], v[162:165], v[196:199], v[38:41]
	v_mfma_f32_16x16x32_bf16 v[34:37], v[172:175], v[196:199], v[34:37]
	v_mfma_f32_16x16x32_bf16 v[22:25], v[162:165], v[204:207], v[22:25]
	v_mfma_f32_16x16x32_bf16 v[14:17], v[172:175], v[204:207], v[14:17]
	v_mfma_f32_16x16x32_bf16 v[6:9], v[162:165], v[212:215], v[6:9]
	v_mfma_f32_16x16x32_bf16 v[2:5], v[172:175], v[212:215], v[2:5]
	s_setprio 0
	s_barrier
	s_add_i32 s41, s41, 2
	s_add_u32 s24, s24, 0x100
	s_addc_u32 s25, s25, 0
	s_add_u32 s19, s19, 0x100
	s_addc_u32 s40, s40, 0
	s_cmpk_gt_u32 s41, 0x7d
	s_cbranch_scc0 .LBB0_2233
	s_cmp_ge_u32 s74, 16
	s_cbranch_scc1 .Lwpf_e
	s_lshl_b32 s100, s74, 9
	v_add_u32_e32 v130, s100, v246
	v_lshrrev_b32_e32 v131, 2, v130
	v_and_b32_e32 v130, 3, v130
	v_lshlrev_b32_e32 v130, 7, v130
	v_lshl_add_u32 v130, v131, 12, v130
	s_add_u32 s100, s88, 0x4000000
	s_addc_u32 s101, s89, 0
	s_mov_b32 m0, 0x21000
	s_nop 0
	global_load_lds_dword v130, s[100:101]

; #define PG8_STAGE(bufoff, gbase, voff) do { _Pragma("unroll") for (int _i = 0; _i < 2; ++_i) \
;         __builtin_amdgcn_global_load_lds((const unsigned*)((const char*)(gbase) + (voff)[_i]), (LAS unsigned*)(lds + (bufoff) + ldsw + _i * 8192), 16, 0, 0); } while (0)
; #define PG8_LDA(dst, b, h) do { _Pragma("unroll") for (int m = 0; m < 4; ++m) _Pragma("unroll") for (int k = 0; k < 2; ++k) dst[m][k] = *(const LAS bf16x8*)(lds + PG8_SA(b, h) + aoff + m * 2048 + k * 1024); } while (0)
; #define PG8_LDB(dst, b, h) do { _Pragma("unroll") for (int n = 0; n < 2; ++n) _Pragma("unroll") for (int k = 0; k < 2; ++k) dst[n][k] = *(const LAS bf16x8*)(lds + PG8_SB(b, h) + boff + n * 2048 + k * 1024); } while (0)
; #define PG8_MMA(ai, bj, At, Bt) do { __builtin_amdgcn_s_setprio(1); _Pragma("unroll") for (int m = 0; m < 4; ++m) _Pragma("unroll") for (int n = 0; n < 2; ++n) _Pragma("unroll") for (int k = 0; k < 2; ++k) \
;         acc[ai][bj][m][n] = __builtin_amdgcn_mfma_f32_16x16x32_bf16(Bt[n][k], At[m][k], acc[ai][bj][m][n], 0, 0, 0); __builtin_amdgcn_s_setprio(0); } while (0)
; #define PG8_WAIT_V(n) asm volatile("s_waitcnt vmcnt(" #n ")" ::: "memory")
; #define PG8_WAIT_L(n) asm volatile("s_waitcnt lgkmcnt(" #n ")" ::: "memory")
; #define PG8_BAR __builtin_amdgcn_s_barrier()
; #define PG8_SCHED __builtin_amdgcn_sched_barrier(0)
; template <class Epi>
; __device__ __forceinline__ void gemm_phase(LAS unsigned char* lds, const Gemm g, const StaticOrder& S, const Epi& E) {
;     ...
;             const bool last = (t == nt - 2);
;             const char* a1 = cA + (size_t)(t + 1) * kstep;
;             const char* a2 = last ? nA : cA + (size_t)(t + 2) * kstep; const char* b2 = last ? nB : cB + (size_t)(t + 2) * kstep;
;             const char* a3 = a2 + kstep; const char* b3 = b2 + kstep;
;             PG8_LDB(B0, 0, 0); PG8_LDB(B1, 0, 1); PG8_SCHED; PG8_LDA(At, 0, 0); PG8_STAGE(PG8_SA(1, 1), a1 + hstepA, voffA);
;             PG8_WAIT_V(8); PG8_WAIT_L(0); PG8_BAR; PG8_MMA(0, 0, At, B0); PG8_MMA(0, 1, At, B1); PG8_BAR; PG8_SCHED;
;             PG8_LDA(At, 0, 1); PG8_STAGE(PG8_SB(0, 0), b2, voffB); PG8_STAGE(PG8_SB(0, 1), b2 + hstepB, voffB); PG8_STAGE(PG8_SA(0, 0), a2, voffA);
;             PG8_WAIT_V(8); PG8_WAIT_L(0); PG8_BAR; PG8_MMA(1, 0, At, B0); PG8_MMA(1, 1, At, B1); PG8_BAR; PG8_SCHED;
.LBB0_2332:
	s_add_u32 s14, s24, 0xfff80080
	s_addc_u32 s15, s25, -1
	s_add_i32 s41, 0, 0x10000
	s_cmp_eq_u32 s40, 28
	s_cselect_b32 s27, s1, s15
	s_cselect_b32 s26, s3, s14
	s_cselect_b32 s15, s9, s33
	s_cselect_b32 s14, s17, s19
	s_add_i32 s62, 0, 0x14000
	v_add_u32_e32 v142, s41, v1
	v_add_u32_e32 v170, s62, v1
	ds_read_b128 v[130:133], v142
	ds_read_b128 v[134:137], v142 offset:1024
	ds_read_b128 v[138:141], v142 offset:2048
	ds_read_b128 v[142:145], v142 offset:3072
	ds_read_b128 v[146:149], v170
	ds_read_b128 v[150:153], v170 offset:1024
	ds_read_b128 v[166:169], v170 offset:2048
	ds_read_b128 v[170:173], v170 offset:3072
	v_lshl_add_u64 v[178:179], s[24:25], 0, v[162:163]
	s_add_i32 m0, s35, 0xc000
	ds_read_b128 v[174:177], v181
	ds_read_b128 v[188:191], v181 offset:1024
	ds_read_b128 v[192:195], v181 offset:2048
	ds_read_b128 v[196:199], v181 offset:3072
	ds_read_b128 v[200:203], v181 offset:4096
	ds_read_b128 v[204:207], v181 offset:5120
	ds_read_b128 v[208:211], v181 offset:6144
	ds_read_b128 v[212:215], v181 offset:7168
	global_load_lds_dwordx4 v[178:179], off
	v_lshl_add_u64 v[178:179], s[24:25], 0, v[164:165]
	s_add_i32 m0, s35, 0xe000
	s_nop 0
	global_load_lds_dwordx4 v[178:179], off
	s_waitcnt vmcnt(8)
	s_waitcnt lgkmcnt(0)
	s_barrier
	s_setprio 1
	v_mfma_f32_16x16x32_bf16 v[126:129], v[130:133], v[174:177], v[126:129]
	v_mfma_f32_16x16x32_bf16 v[122:125], v[138:141], v[174:177], v[122:125]
	v_mfma_f32_16x16x32_bf16 v[118:121], v[130:133], v[192:195], v[118:121]
	v_mfma_f32_16x16x32_bf16 v[114:117], v[138:141], v[192:195], v[114:117]
	v_mfma_f32_16x16x32_bf16 v[102:105], v[130:133], v[200:203], v[102:105]
	v_mfma_f32_16x16x32_bf16 v[98:101], v[138:141], v[200:203], v[98:101]
	v_mfma_f32_16x16x32_bf16 v[86:89], v[130:133], v[208:211], v[86:89]
	v_mfma_f32_16x16x32_bf16 v[82:85], v[138:141], v[208:211], v[82:85]
	v_mfma_f32_16x16x32_bf16 v[126:129], v[134:137], v[188:191], v[126:129]
	v_mfma_f32_16x16x32_bf16 v[122:125], v[142:145], v[188:191], v[122:125]
	v_mfma_f32_16x16x32_bf16 v[118:121], v[134:137], v[196:199], v[118:121]
	v_mfma_f32_16x16x32_bf16 v[114:117], v[142:145], v[196:199], v[114:117]
	v_mfma_f32_16x16x32_bf16 v[102:105], v[134:137], v[204:207], v[102:105]
	v_mfma_f32_16x16x32_bf16 v[98:101], v[142:145], v[204:207], v[98:101]
	v_mfma_f32_16x16x32_bf16 v[86:89], v[134:137], v[212:215], v[86:89]
	v_mfma_f32_16x16x32_bf16 v[82:85], v[142:145], v[212:215], v[82:85]
	v_mfma_f32_16x16x32_bf16 v[110:113], v[146:149], v[174:177], v[110:113]
	v_mfma_f32_16x16x32_bf16 v[106:109], v[166:169], v[174:177], v[106:109]
	v_mfma_f32_16x16x32_bf16 v[94:97], v[146:149], v[192:195], v[94:97]
	v_mfma_f32_16x16x32_bf16 v[90:93], v[166:169], v[192:195], v[90:93]
	v_mfma_f32_16x16x32_bf16 v[78:81], v[146:149], v[200:203], v[78:81]
	v_mfma_f32_16x16x32_bf16 v[74:77], v[166:169], v[200:203], v[74:77]
	v_mfma_f32_16x16x32_bf16 v[70:73], v[146:149], v[208:211], v[70:73]
	v_mfma_f32_16x16x32_bf16 v[66:69], v[166:169], v[208:211], v[66:69]
	v_mfma_f32_16x16x32_bf16 v[110:113], v[150:153], v[188:191], v[110:113]
	v_mfma_f32_16x16x32_bf16 v[106:109], v[170:173], v[188:191], v[106:109]
	v_mfma_f32_16x16x32_bf16 v[94:97], v[150:153], v[196:199], v[94:97]
	v_mfma_f32_16x16x32_bf16 v[90:93], v[170:173], v[196:199], v[90:93]
	v_mfma_f32_16x16x32_bf16 v[78:81], v[150:153], v[204:207], v[78:81]
	v_mfma_f32_16x16x32_bf16 v[74:77], v[170:173], v[204:207], v[74:77]
	v_mfma_f32_16x16x32_bf16 v[70:73], v[150:153], v[212:215], v[70:73]
	v_mfma_f32_16x16x32_bf16 v[66:69], v[170:173], v[212:215], v[66:69]
	s_setprio 0
	s_barrier
	s_add_i32 s41, s41, s34
	v_lshl_add_u64 v[178:179], s[14:15], 0, v[156:157]
	s_mov_b32 m0, s41
	ds_read_b128 v[174:177], v181 offset:16384
	ds_read_b128 v[188:191], v181 offset:17408
	ds_read_b128 v[192:195], v181 offset:18432
	ds_read_b128 v[196:199], v181 offset:19456
	ds_read_b128 v[200:203], v181 offset:20480
	ds_read_b128 v[204:207], v181 offset:21504
	ds_read_b128 v[208:211], v181 offset:22528
	ds_read_b128 v[212:215], v181 offset:23552
	global_load_lds_dwordx4 v[178:179], off
	s_add_i32 m0, s41, 0x2000
	s_add_u32 s52, s14, 0x80000
	v_lshl_add_u64 v[184:185], s[14:15], 0, v[160:161]
	s_addc_u32 s53, s15, 0
	s_add_i32 s41, s62, s34
	global_load_lds_dwordx4 v[184:185], off
	v_lshl_add_u64 v[216:217], s[52:53], 0, v[156:157]
	s_mov_b32 m0, s41
	v_lshl_add_u64 v[218:219], s[26:27], 0, v[158:159]
	global_load_lds_dwordx4 v[216:217], off
	v_lshl_add_u64 v[216:217], s[52:53], 0, v[160:161]
	s_add_i32 m0, s41, 0x2000
	s_nop 0
	global_load_lds_dwordx4 v[216:217], off
	v_lshl_add_u64 v[216:217], s[26:27], 0, v[154:155]
	s_mov_b32 m0, s35
	s_nop 0
	global_load_lds_dwordx4 v[216:217], off
	s_mov_b32 m0, s42
	s_nop 0
	global_load_lds_dwordx4 v[218:219], off
	s_waitcnt vmcnt(8)
	s_waitcnt lgkmcnt(0)
	s_barrier
; #define PG8_STAGE(bufoff, gbase, voff) do { _Pragma("unroll") for (int _i = 0; _i < 2; ++_i) \
;         __builtin_amdgcn_global_load_lds((const unsigned*)((const char*)(gbase) + (voff)[_i]), (LAS unsigned*)(lds + (bufoff) + ldsw + _i * 8192), 16, 0, 0); } while (0)
; #define PG8_LDA(dst, b, h) do { _Pragma("unroll") for (int m = 0; m < 4; ++m) _Pragma("unroll") for (int k = 0; k < 2; ++k) dst[m][k] = *(const LAS bf16x8*)(lds + PG8_SA(b, h) + aoff + m * 2048 + k * 1024); } while (0)
; #define PG8_LDB(dst, b, h) do { _Pragma("unroll") for (int n = 0; n < 2; ++n) _Pragma("unroll") for (int k = 0; k < 2; ++k) dst[n][k] = *(const LAS bf16x8*)(lds + PG8_SB(b, h) + boff + n * 2048 + k * 1024); } while (0)
; #define PG8_MMA(ai, bj, At, Bt) do { __builtin_amdgcn_s_setprio(1); _Pragma("unroll") for (int m = 0; m < 4; ++m) _Pragma("unroll") for (int n = 0; n < 2; ++n) _Pragma("unroll") for (int k = 0; k < 2; ++k) \
;         acc[ai][bj][m][n] = __builtin_amdgcn_mfma_f32_16x16x32_bf16(Bt[n][k], At[m][k], acc[ai][bj][m][n], 0, 0, 0); __builtin_amdgcn_s_setprio(0); } while (0)
; #define PG8_WAIT_V(n) asm volatile("s_waitcnt vmcnt(" #n ")" ::: "memory")
; #define PG8_WAIT_L(n) asm volatile("s_waitcnt lgkmcnt(" #n ")" ::: "memory")
; #define PG8_BAR __builtin_amdgcn_s_barrier()
; #define PG8_SCHED __builtin_amdgcn_sched_barrier(0)
; template <class Epi>
; __device__ __forceinline__ void gemm_phase(LAS unsigned char* lds, const Gemm g, const StaticOrder& S, const Epi& E) {
;     ...
;             PG8_WAIT_V(8); PG8_WAIT_L(0); PG8_BAR; PG8_MMA(1, 0, At, B0); PG8_MMA(1, 1, At, B1); PG8_BAR; PG8_SCHED;
;             PG8_LDB(B0, 1, 0); PG8_LDB(B1, 1, 1); PG8_SCHED; PG8_LDA(At, 1, 0); PG8_STAGE(PG8_SA(0, 1), a2 + hstepA, voffA);
;             PG8_WAIT_V(8); PG8_WAIT_L(0); PG8_BAR; PG8_MMA(0, 0, At, B0); PG8_MMA(0, 1, At, B1); PG8_BAR; PG8_SCHED;
	s_setprio 1
	v_mfma_f32_16x16x32_bf16 v[62:65], v[130:133], v[174:177], v[62:65]
	v_mfma_f32_16x16x32_bf16 v[58:61], v[138:141], v[174:177], v[58:61]
	v_mfma_f32_16x16x32_bf16 v[54:57], v[130:133], v[192:195], v[54:57]
	v_mfma_f32_16x16x32_bf16 v[50:53], v[138:141], v[192:195], v[50:53]
	v_mfma_f32_16x16x32_bf16 v[46:49], v[130:133], v[200:203], v[46:49]
	v_mfma_f32_16x16x32_bf16 v[38:41], v[138:141], v[200:203], v[38:41]
	v_mfma_f32_16x16x32_bf16 v[30:33], v[130:133], v[208:211], v[30:33]
	v_mfma_f32_16x16x32_bf16 v[22:25], v[138:141], v[208:211], v[22:25]
	v_mfma_f32_16x16x32_bf16 v[62:65], v[134:137], v[188:191], v[62:65]
	v_mfma_f32_16x16x32_bf16 v[58:61], v[142:145], v[188:191], v[58:61]
	v_mfma_f32_16x16x32_bf16 v[54:57], v[134:137], v[196:199], v[54:57]
	v_mfma_f32_16x16x32_bf16 v[50:53], v[142:145], v[196:199], v[50:53]
	v_mfma_f32_16x16x32_bf16 v[46:49], v[134:137], v[204:207], v[46:49]
	v_mfma_f32_16x16x32_bf16 v[38:41], v[142:145], v[204:207], v[38:41]
	v_mfma_f32_16x16x32_bf16 v[30:33], v[134:137], v[212:215], v[30:33]
	v_mfma_f32_16x16x32_bf16 v[22:25], v[142:145], v[212:215], v[22:25]
	v_mfma_f32_16x16x32_bf16 v[42:45], v[146:149], v[174:177], v[42:45]
	v_mfma_f32_16x16x32_bf16 v[34:37], v[166:169], v[174:177], v[34:37]
	v_mfma_f32_16x16x32_bf16 v[26:29], v[146:149], v[192:195], v[26:29]
	v_mfma_f32_16x16x32_bf16 v[18:21], v[166:169], v[192:195], v[18:21]
	v_mfma_f32_16x16x32_bf16 v[14:17], v[146:149], v[200:203], v[14:17]
	v_mfma_f32_16x16x32_bf16 v[10:13], v[166:169], v[200:203], v[10:13]
	v_mfma_f32_16x16x32_bf16 v[6:9], v[146:149], v[208:211], v[6:9]
	v_mfma_f32_16x16x32_bf16 v[2:5], v[166:169], v[208:211], v[2:5]
	v_mfma_f32_16x16x32_bf16 v[42:45], v[150:153], v[188:191], v[42:45]
	v_mfma_f32_16x16x32_bf16 v[34:37], v[170:173], v[188:191], v[34:37]
	v_mfma_f32_16x16x32_bf16 v[26:29], v[150:153], v[196:199], v[26:29]
	v_mfma_f32_16x16x32_bf16 v[18:21], v[170:173], v[196:199], v[18:21]
	v_mfma_f32_16x16x32_bf16 v[14:17], v[150:153], v[204:207], v[14:17]
	v_mfma_f32_16x16x32_bf16 v[10:13], v[170:173], v[204:207], v[10:13]
	v_mfma_f32_16x16x32_bf16 v[6:9], v[150:153], v[212:215], v[6:9]
	v_mfma_f32_16x16x32_bf16 v[2:5], v[170:173], v[212:215], v[2:5]
	s_setprio 0
	s_barrier
	s_add_i32 s41, 0, 0x18000
	s_add_i32 s52, 0, 0x1c000
	v_add_u32_e32 v142, s41, v1
	v_add_u32_e32 v170, s52, v1
	ds_read_b128 v[130:133], v142
	ds_read_b128 v[134:137], v142 offset:1024
	ds_read_b128 v[138:141], v142 offset:2048
	ds_read_b128 v[142:145], v142 offset:3072
	ds_read_b128 v[146:149], v170
	ds_read_b128 v[150:153], v170 offset:1024
	ds_read_b128 v[166:169], v170 offset:2048
	ds_read_b128 v[170:173], v170 offset:3072
	s_add_u32 s26, s26, 0x80000
	s_addc_u32 s27, s27, 0
	s_mov_b32 m0, s44
	v_lshl_add_u64 v[220:221], s[26:27], 0, v[154:155]
	ds_read_b128 v[174:177], v181 offset:32768
	ds_read_b128 v[188:191], v181 offset:33792
	ds_read_b128 v[192:195], v181 offset:34816
	ds_read_b128 v[196:199], v181 offset:35840
	ds_read_b128 v[200:203], v181 offset:36864
	ds_read_b128 v[204:207], v181 offset:37888
	ds_read_b128 v[208:211], v181 offset:38912
	ds_read_b128 v[212:215], v181 offset:39936
	global_load_lds_dwordx4 v[220:221], off
	v_lshl_add_u64 v[220:221], s[26:27], 0, v[158:159]
	s_mov_b32 m0, s45
	s_nop 0
	global_load_lds_dwordx4 v[220:221], off
	s_waitcnt vmcnt(8)
	s_waitcnt lgkmcnt(0)
	s_barrier
	s_setprio 1
	v_mfma_f32_16x16x32_bf16 v[126:129], v[130:133], v[174:177], v[126:129]
	v_mfma_f32_16x16x32_bf16 v[122:125], v[138:141], v[174:177], v[122:125]
	v_mfma_f32_16x16x32_bf16 v[118:121], v[130:133], v[192:195], v[118:121]
	v_mfma_f32_16x16x32_bf16 v[114:117], v[138:141], v[192:195], v[114:117]
	v_mfma_f32_16x16x32_bf16 v[102:105], v[130:133], v[200:203], v[102:105]
	v_mfma_f32_16x16x32_bf16 v[98:101], v[138:141], v[200:203], v[98:101]
	v_mfma_f32_16x16x32_bf16 v[86:89], v[130:133], v[208:211], v[86:89]
	v_mfma_f32_16x16x32_bf16 v[82:85], v[138:141], v[208:211], v[82:85]
	v_mfma_f32_16x16x32_bf16 v[126:129], v[134:137], v[188:191], v[126:129]
	v_mfma_f32_16x16x32_bf16 v[122:125], v[142:145], v[188:191], v[122:125]
	v_mfma_f32_16x16x32_bf16 v[118:121], v[134:137], v[196:199], v[118:121]
	v_mfma_f32_16x16x32_bf16 v[114:117], v[142:145], v[196:199], v[114:117]
	v_mfma_f32_16x16x32_bf16 v[102:105], v[134:137], v[204:207], v[102:105]
	v_mfma_f32_16x16x32_bf16 v[98:101], v[142:145], v[204:207], v[98:101]
	v_mfma_f32_16x16x32_bf16 v[86:89], v[134:137], v[212:215], v[86:89]
	v_mfma_f32_16x16x32_bf16 v[82:85], v[142:145], v[212:215], v[82:85]
	v_mfma_f32_16x16x32_bf16 v[110:113], v[146:149], v[174:177], v[110:113]
	v_mfma_f32_16x16x32_bf16 v[106:109], v[166:169], v[174:177], v[106:109]
	v_mfma_f32_16x16x32_bf16 v[94:97], v[146:149], v[192:195], v[94:97]
	v_mfma_f32_16x16x32_bf16 v[90:93], v[166:169], v[192:195], v[90:93]
	v_mfma_f32_16x16x32_bf16 v[78:81], v[146:149], v[200:203], v[78:81]
	v_mfma_f32_16x16x32_bf16 v[74:77], v[166:169], v[200:203], v[74:77]
	v_mfma_f32_16x16x32_bf16 v[70:73], v[146:149], v[208:211], v[70:73]
	v_mfma_f32_16x16x32_bf16 v[66:69], v[166:169], v[208:211], v[66:69]
	v_mfma_f32_16x16x32_bf16 v[110:113], v[150:153], v[188:191], v[110:113]
	v_mfma_f32_16x16x32_bf16 v[106:109], v[170:173], v[188:191], v[106:109]
	v_mfma_f32_16x16x32_bf16 v[94:97], v[150:153], v[196:199], v[94:97]
	v_mfma_f32_16x16x32_bf16 v[90:93], v[170:173], v[196:199], v[90:93]
	v_mfma_f32_16x16x32_bf16 v[78:81], v[150:153], v[204:207], v[78:81]
	v_mfma_f32_16x16x32_bf16 v[74:77], v[170:173], v[204:207], v[74:77]
	v_mfma_f32_16x16x32_bf16 v[70:73], v[150:153], v[212:215], v[70:73]
	v_mfma_f32_16x16x32_bf16 v[66:69], v[170:173], v[212:215], v[66:69]
	s_setprio 0
	s_barrier
; #define PG8_STAGE(bufoff, gbase, voff) do { _Pragma("unroll") for (int _i = 0; _i < 2; ++_i) \
;         __builtin_amdgcn_global_load_lds((const unsigned*)((const char*)(gbase) + (voff)[_i]), (LAS unsigned*)(lds + (bufoff) + ldsw + _i * 8192), 16, 0, 0); } while (0)
; #define PG8_LDA(dst, b, h) do { _Pragma("unroll") for (int m = 0; m < 4; ++m) _Pragma("unroll") for (int k = 0; k < 2; ++k) dst[m][k] = *(const LAS bf16x8*)(lds + PG8_SA(b, h) + aoff + m * 2048 + k * 1024); } while (0)
; #define PG8_MMA(ai, bj, At, Bt) do { __builtin_amdgcn_s_setprio(1); _Pragma("unroll") for (int m = 0; m < 4; ++m) _Pragma("unroll") for (int n = 0; n < 2; ++n) _Pragma("unroll") for (int k = 0; k < 2; ++k) \
;         acc[ai][bj][m][n] = __builtin_amdgcn_mfma_f32_16x16x32_bf16(Bt[n][k], At[m][k], acc[ai][bj][m][n], 0, 0, 0); __builtin_amdgcn_s_setprio(0); } while (0)
; #define PG8_WAIT_V(n) asm volatile("s_waitcnt vmcnt(" #n ")" ::: "memory")
; #define PG8_WAIT_L(n) asm volatile("s_waitcnt lgkmcnt(" #n ")" ::: "memory")
; #define PG8_BAR __builtin_amdgcn_s_barrier()
; #define PG8_SCHED __builtin_amdgcn_sched_barrier(0)
; template <class Epi>
; __device__ __forceinline__ void gemm_phase(LAS unsigned char* lds, const Gemm g, const StaticOrder& S, const Epi& E) {
;     ...
;             PG8_LDA(At, 1, 1); PG8_STAGE(PG8_SB(1, 0), b3, voffB); PG8_STAGE(PG8_SB(1, 1), b3 + hstepB, voffB); PG8_STAGE(PG8_SA(1, 0), a3, voffA);
;             PG8_WAIT_V(8); PG8_WAIT_L(0); PG8_BAR; PG8_MMA(1, 0, At, B0); PG8_MMA(1, 1, At, B1); PG8_BAR; PG8_SCHED;
;         }
	s_add_i32 s26, s41, s34
	v_lshl_add_u64 v[178:179], v[178:179], 0, s[84:85]
	s_mov_b32 m0, s26
	ds_read_b128 v[174:177], v181 offset:49152
	ds_read_b128 v[188:191], v181 offset:50176
	ds_read_b128 v[192:195], v181 offset:51200
	ds_read_b128 v[196:199], v181 offset:52224
	ds_read_b128 v[200:203], v181 offset:53248
	ds_read_b128 v[204:207], v181 offset:54272
	ds_read_b128 v[208:211], v181 offset:55296
	ds_read_b128 v[212:215], v181 offset:56320
	global_load_lds_dwordx4 v[178:179], off
	s_add_i32 m0, s26, 0x2000
	s_add_u32 s14, s14, 0x80080
	v_lshl_add_u64 v[178:179], v[184:185], 0, s[84:85]
	s_addc_u32 s15, s15, 0
	s_add_i32 s26, s52, s34
	global_load_lds_dwordx4 v[178:179], off
	v_lshl_add_u64 v[178:179], s[14:15], 0, v[156:157]
	s_mov_b32 m0, s26
	s_nop 0
	global_load_lds_dwordx4 v[178:179], off
	v_lshl_add_u64 v[178:179], s[14:15], 0, v[160:161]
	s_add_i32 m0, s26, 0x2000
	s_nop 0
	global_load_lds_dwordx4 v[178:179], off
	v_lshl_add_u64 v[178:179], v[216:217], 0, s[84:85]
	s_mov_b32 m0, s86
	s_nop 0
	global_load_lds_dwordx4 v[178:179], off
	v_lshl_add_u64 v[178:179], v[218:219], 0, s[84:85]
	s_mov_b32 m0, s87
	s_nop 0
	global_load_lds_dwordx4 v[178:179], off
	s_waitcnt vmcnt(8)
	s_waitcnt lgkmcnt(0)
	s_barrier
	s_setprio 1
	v_mfma_f32_16x16x32_bf16 v[62:65], v[130:133], v[174:177], v[62:65]
	v_mfma_f32_16x16x32_bf16 v[58:61], v[138:141], v[174:177], v[58:61]
	v_mfma_f32_16x16x32_bf16 v[54:57], v[130:133], v[192:195], v[54:57]
	v_mfma_f32_16x16x32_bf16 v[50:53], v[138:141], v[192:195], v[50:53]
	v_mfma_f32_16x16x32_bf16 v[46:49], v[130:133], v[200:203], v[46:49]
	v_mfma_f32_16x16x32_bf16 v[38:41], v[138:141], v[200:203], v[38:41]
	v_mfma_f32_16x16x32_bf16 v[30:33], v[130:133], v[208:211], v[30:33]
	v_mfma_f32_16x16x32_bf16 v[22:25], v[138:141], v[208:211], v[22:25]
	v_mfma_f32_16x16x32_bf16 v[62:65], v[134:137], v[188:191], v[62:65]
	v_mfma_f32_16x16x32_bf16 v[58:61], v[142:145], v[188:191], v[58:61]
	v_mfma_f32_16x16x32_bf16 v[54:57], v[134:137], v[196:199], v[54:57]
	v_mfma_f32_16x16x32_bf16 v[50:53], v[142:145], v[196:199], v[50:53]
	v_mfma_f32_16x16x32_bf16 v[46:49], v[134:137], v[204:207], v[46:49]
	v_mfma_f32_16x16x32_bf16 v[38:41], v[142:145], v[204:207], v[38:41]
	v_mfma_f32_16x16x32_bf16 v[30:33], v[134:137], v[212:215], v[30:33]
	v_mfma_f32_16x16x32_bf16 v[22:25], v[142:145], v[212:215], v[22:25]
	v_mfma_f32_16x16x32_bf16 v[42:45], v[146:149], v[174:177], v[42:45]
	v_mfma_f32_16x16x32_bf16 v[34:37], v[166:169], v[174:177], v[34:37]
	v_mfma_f32_16x16x32_bf16 v[26:29], v[146:149], v[192:195], v[26:29]
	v_mfma_f32_16x16x32_bf16 v[18:21], v[166:169], v[192:195], v[18:21]
	v_mfma_f32_16x16x32_bf16 v[14:17], v[146:149], v[200:203], v[14:17]
	v_mfma_f32_16x16x32_bf16 v[10:13], v[166:169], v[200:203], v[10:13]
	v_mfma_f32_16x16x32_bf16 v[6:9], v[146:149], v[208:211], v[6:9]
	v_mfma_f32_16x16x32_bf16 v[2:5], v[166:169], v[208:211], v[2:5]
	v_mfma_f32_16x16x32_bf16 v[42:45], v[150:153], v[188:191], v[42:45]
	v_mfma_f32_16x16x32_bf16 v[34:37], v[170:173], v[188:191], v[34:37]
	v_mfma_f32_16x16x32_bf16 v[26:29], v[150:153], v[196:199], v[26:29]
	v_mfma_f32_16x16x32_bf16 v[18:21], v[170:173], v[196:199], v[18:21]
	v_mfma_f32_16x16x32_bf16 v[14:17], v[150:153], v[204:207], v[14:17]
	v_mfma_f32_16x16x32_bf16 v[10:13], v[170:173], v[204:207], v[10:13]
	v_mfma_f32_16x16x32_bf16 v[6:9], v[150:153], v[212:215], v[6:9]
	v_mfma_f32_16x16x32_bf16 v[2:5], v[170:173], v[212:215], v[2:5]
	s_setprio 0
	s_barrier
	s_add_i32 s40, s40, 2
	s_add_u32 s24, s24, 0x100
	s_addc_u32 s25, s25, 0
	s_add_u32 s19, s19, 0x100
	s_addc_u32 s33, s33, 0
	s_cmp_gt_u32 s40, 29
	s_cbranch_scc0 .LBB0_2332
	s_cmp_ge_u32 s74, 16
	s_cbranch_scc1 .Lwpf_f
	s_lshl_b32 s100, s74, 9
	v_add_u32_e32 v130, s100, v246
	v_lshrrev_b32_e32 v131, 2, v130
	v_and_b32_e32 v130, 3, v130
	v_lshlrev_b32_e32 v130, 7, v130
	v_lshl_add_u32 v130, v131, 12, v130
	v_readlane_b32 s100, v255, 42
	s_nop 3
	s_mov_b32 s101, 0x16900000
	s_cmp_eq_u32 s100, 1
	s_cselect_b32 s101, 0x15100000, s101
	s_cmp_eq_u32 s100, 0
	s_cselect_b32 s101, 0x13700000, s101
	s_add_u32 s100, s38, s101
	s_addc_u32 s101, s39, 0
	s_mov_b32 m0, 0x21000
	s_nop 0
	global_load_lds_dword v130, s[100:101]

; #define PG8_STAGE(bufoff, gbase, voff) do { _Pragma("unroll") for (int _i = 0; _i < 2; ++_i) \
;         __builtin_amdgcn_global_load_lds((const unsigned*)((const char*)(gbase) + (voff)[_i]), (LAS unsigned*)(lds + (bufoff) + ldsw + _i * 8192), 16, 0, 0); } while (0)
; #define PG8_LDA(dst, b, h) do { _Pragma("unroll") for (int m = 0; m < 4; ++m) _Pragma("unroll") for (int k = 0; k < 2; ++k) dst[m][k] = *(const LAS bf16x8*)(lds + PG8_SA(b, h) + aoff + m * 2048 + k * 1024); } while (0)
; #define PG8_LDB(dst, b, h) do { _Pragma("unroll") for (int n = 0; n < 2; ++n) _Pragma("unroll") for (int k = 0; k < 2; ++k) dst[n][k] = *(const LAS bf16x8*)(lds + PG8_SB(b, h) + boff + n * 2048 + k * 1024); } while (0)
; #define PG8_MMA(ai, bj, At, Bt) do { __builtin_amdgcn_s_setprio(1); _Pragma("unroll") for (int m = 0; m < 4; ++m) _Pragma("unroll") for (int n = 0; n < 2; ++n) _Pragma("unroll") for (int k = 0; k < 2; ++k) \
;         acc[ai][bj][m][n] = __builtin_amdgcn_mfma_f32_16x16x32_bf16(Bt[n][k], At[m][k], acc[ai][bj][m][n], 0, 0, 0); __builtin_amdgcn_s_setprio(0); } while (0)
; #define PG8_WAIT_V(n) asm volatile("s_waitcnt vmcnt(" #n ")" ::: "memory")
; #define PG8_WAIT_L(n) asm volatile("s_waitcnt lgkmcnt(" #n ")" ::: "memory")
; #define PG8_BAR __builtin_amdgcn_s_barrier()
; #define PG8_SCHED __builtin_amdgcn_sched_barrier(0)
; template <class Epi>
; __device__ __forceinline__ void gemm_phase(LAS unsigned char* lds, const Gemm g, const StaticOrder& S, const Epi& E) {
;     ...
;             const bool last = (t == nt - 2);
;             const char* a1 = cA + (size_t)(t + 1) * kstep;
;             const char* a2 = last ? nA : cA + (size_t)(t + 2) * kstep; const char* b2 = last ? nB : cB + (size_t)(t + 2) * kstep;
;             const char* a3 = a2 + kstep; const char* b3 = b2 + kstep;
;             PG8_LDB(B0, 0, 0); PG8_LDB(B1, 0, 1); PG8_SCHED; PG8_LDA(At, 0, 0); PG8_STAGE(PG8_SA(1, 1), a1 + hstepA, voffA);
;             PG8_WAIT_V(8); PG8_WAIT_L(0); PG8_BAR; PG8_MMA(0, 0, At, B0); PG8_MMA(0, 1, At, B1); PG8_BAR; PG8_SCHED;
;             PG8_LDA(At, 0, 1); PG8_STAGE(PG8_SB(0, 0), b2, voffB); PG8_STAGE(PG8_SB(0, 1), b2 + hstepB, voffB); PG8_STAGE(PG8_SA(0, 0), a2, voffA);
;             PG8_WAIT_V(8); PG8_WAIT_L(0); PG8_BAR; PG8_MMA(1, 0, At, B0); PG8_MMA(1, 1, At, B1); PG8_BAR; PG8_SCHED;
.LBB0_2376:
	s_add_u32 s14, s22, 0xfff80080
	s_addc_u32 s15, s23, -1
	s_add_i32 s53, 0, 0x10000
	s_cmp_eq_u32 s41, 28
	s_cselect_b32 s25, s3, s15
	s_cselect_b32 s24, s9, s14
	s_cselect_b32 s15, s13, s52
	s_cselect_b32 s14, s17, s40
	s_add_i32 s64, 0, 0x14000
	v_add_u32_e32 v142, s53, v1
	v_add_u32_e32 v170, s64, v1
	ds_read_b128 v[130:133], v142
	ds_read_b128 v[134:137], v142 offset:1024
	ds_read_b128 v[138:141], v142 offset:2048
	ds_read_b128 v[142:145], v142 offset:3072
	ds_read_b128 v[146:149], v170
	ds_read_b128 v[150:153], v170 offset:1024
	ds_read_b128 v[166:169], v170 offset:2048
	ds_read_b128 v[170:173], v170 offset:3072
	v_lshl_add_u64 v[178:179], s[22:23], 0, v[162:163]
	s_add_i32 m0, s30, 0xc000
	ds_read_b128 v[174:177], v181
	ds_read_b128 v[188:191], v181 offset:1024
	ds_read_b128 v[192:195], v181 offset:2048
	ds_read_b128 v[196:199], v181 offset:3072
	ds_read_b128 v[200:203], v181 offset:4096
	ds_read_b128 v[204:207], v181 offset:5120
	ds_read_b128 v[208:211], v181 offset:6144
	ds_read_b128 v[212:215], v181 offset:7168
	global_load_lds_dwordx4 v[178:179], off
	v_lshl_add_u64 v[178:179], s[22:23], 0, v[164:165]
	s_add_i32 m0, s30, 0xe000
	s_nop 0
	global_load_lds_dwordx4 v[178:179], off
	s_waitcnt vmcnt(8)
	s_waitcnt lgkmcnt(0)
	s_barrier
	s_setprio 1
	v_mfma_f32_16x16x32_bf16 v[126:129], v[130:133], v[174:177], v[126:129]
	v_mfma_f32_16x16x32_bf16 v[122:125], v[138:141], v[174:177], v[122:125]
	v_mfma_f32_16x16x32_bf16 v[118:121], v[130:133], v[192:195], v[118:121]
	v_mfma_f32_16x16x32_bf16 v[114:117], v[138:141], v[192:195], v[114:117]
	v_mfma_f32_16x16x32_bf16 v[102:105], v[130:133], v[200:203], v[102:105]
	v_mfma_f32_16x16x32_bf16 v[98:101], v[138:141], v[200:203], v[98:101]
	v_mfma_f32_16x16x32_bf16 v[86:89], v[130:133], v[208:211], v[86:89]
	v_mfma_f32_16x16x32_bf16 v[82:85], v[138:141], v[208:211], v[82:85]
	v_mfma_f32_16x16x32_bf16 v[126:129], v[134:137], v[188:191], v[126:129]
	v_mfma_f32_16x16x32_bf16 v[122:125], v[142:145], v[188:191], v[122:125]
	v_mfma_f32_16x16x32_bf16 v[118:121], v[134:137], v[196:199], v[118:121]
	v_mfma_f32_16x16x32_bf16 v[114:117], v[142:145], v[196:199], v[114:117]
	v_mfma_f32_16x16x32_bf16 v[102:105], v[134:137], v[204:207], v[102:105]
	v_mfma_f32_16x16x32_bf16 v[98:101], v[142:145], v[204:207], v[98:101]
	v_mfma_f32_16x16x32_bf16 v[86:89], v[134:137], v[212:215], v[86:89]
	v_mfma_f32_16x16x32_bf16 v[82:85], v[142:145], v[212:215], v[82:85]
	v_mfma_f32_16x16x32_bf16 v[110:113], v[146:149], v[174:177], v[110:113]
	v_mfma_f32_16x16x32_bf16 v[106:109], v[166:169], v[174:177], v[106:109]
	v_mfma_f32_16x16x32_bf16 v[94:97], v[146:149], v[192:195], v[94:97]
	v_mfma_f32_16x16x32_bf16 v[90:93], v[166:169], v[192:195], v[90:93]
	v_mfma_f32_16x16x32_bf16 v[78:81], v[146:149], v[200:203], v[78:81]
	v_mfma_f32_16x16x32_bf16 v[74:77], v[166:169], v[200:203], v[74:77]
	v_mfma_f32_16x16x32_bf16 v[70:73], v[146:149], v[208:211], v[70:73]
	v_mfma_f32_16x16x32_bf16 v[66:69], v[166:169], v[208:211], v[66:69]
	v_mfma_f32_16x16x32_bf16 v[110:113], v[150:153], v[188:191], v[110:113]
	v_mfma_f32_16x16x32_bf16 v[106:109], v[170:173], v[188:191], v[106:109]
	v_mfma_f32_16x16x32_bf16 v[94:97], v[150:153], v[196:199], v[94:97]
	v_mfma_f32_16x16x32_bf16 v[90:93], v[170:173], v[196:199], v[90:93]
	v_mfma_f32_16x16x32_bf16 v[78:81], v[150:153], v[204:207], v[78:81]
	v_mfma_f32_16x16x32_bf16 v[74:77], v[170:173], v[204:207], v[74:77]
	v_mfma_f32_16x16x32_bf16 v[70:73], v[150:153], v[212:215], v[70:73]
	v_mfma_f32_16x16x32_bf16 v[66:69], v[170:173], v[212:215], v[66:69]
	s_setprio 0
	s_barrier
	s_add_i32 s53, s53, s27
	v_lshl_add_u64 v[178:179], s[14:15], 0, v[156:157]
	s_mov_b32 m0, s53
	ds_read_b128 v[174:177], v181 offset:16384
	ds_read_b128 v[188:191], v181 offset:17408
	ds_read_b128 v[192:195], v181 offset:18432
	ds_read_b128 v[196:199], v181 offset:19456
	ds_read_b128 v[200:203], v181 offset:20480
	ds_read_b128 v[204:207], v181 offset:21504
	ds_read_b128 v[208:211], v181 offset:22528
	ds_read_b128 v[212:215], v181 offset:23552
	global_load_lds_dwordx4 v[178:179], off
	s_add_i32 m0, s53, 0x2000
	s_add_u32 s62, s14, 0x80000
	v_lshl_add_u64 v[184:185], s[14:15], 0, v[160:161]
	s_addc_u32 s63, s15, 0
	s_add_i32 s53, s64, s27
	global_load_lds_dwordx4 v[184:185], off
	v_lshl_add_u64 v[186:187], s[62:63], 0, v[156:157]
	s_mov_b32 m0, s53
	v_lshl_add_u64 v[216:217], s[24:25], 0, v[158:159]
	global_load_lds_dwordx4 v[186:187], off
	v_lshl_add_u64 v[186:187], s[62:63], 0, v[160:161]
	s_add_i32 m0, s53, 0x2000
	s_nop 0
	global_load_lds_dwordx4 v[186:187], off
	v_lshl_add_u64 v[186:187], s[24:25], 0, v[154:155]
	s_mov_b32 m0, s30
	s_nop 0
	global_load_lds_dwordx4 v[186:187], off
	s_mov_b32 m0, s31
	s_nop 0
	global_load_lds_dwordx4 v[216:217], off
	s_waitcnt vmcnt(8)
	s_waitcnt lgkmcnt(0)
	s_barrier
; #define PG8_STAGE(bufoff, gbase, voff) do { _Pragma("unroll") for (int _i = 0; _i < 2; ++_i) \
;         __builtin_amdgcn_global_load_lds((const unsigned*)((const char*)(gbase) + (voff)[_i]), (LAS unsigned*)(lds + (bufoff) + ldsw + _i * 8192), 16, 0, 0); } while (0)
; #define PG8_LDA(dst, b, h) do { _Pragma("unroll") for (int m = 0; m < 4; ++m) _Pragma("unroll") for (int k = 0; k < 2; ++k) dst[m][k] = *(const LAS bf16x8*)(lds + PG8_SA(b, h) + aoff + m * 2048 + k * 1024); } while (0)
; #define PG8_LDB(dst, b, h) do { _Pragma("unroll") for (int n = 0; n < 2; ++n) _Pragma("unroll") for (int k = 0; k < 2; ++k) dst[n][k] = *(const LAS bf16x8*)(lds + PG8_SB(b, h) + boff + n * 2048 + k * 1024); } while (0)
; #define PG8_MMA(ai, bj, At, Bt) do { __builtin_amdgcn_s_setprio(1); _Pragma("unroll") for (int m = 0; m < 4; ++m) _Pragma("unroll") for (int n = 0; n < 2; ++n) _Pragma("unroll") for (int k = 0; k < 2; ++k) \
;         acc[ai][bj][m][n] = __builtin_amdgcn_mfma_f32_16x16x32_bf16(Bt[n][k], At[m][k], acc[ai][bj][m][n], 0, 0, 0); __builtin_amdgcn_s_setprio(0); } while (0)
; #define PG8_WAIT_V(n) asm volatile("s_waitcnt vmcnt(" #n ")" ::: "memory")
; #define PG8_WAIT_L(n) asm volatile("s_waitcnt lgkmcnt(" #n ")" ::: "memory")
; #define PG8_BAR __builtin_amdgcn_s_barrier()
; #define PG8_SCHED __builtin_amdgcn_sched_barrier(0)
; template <class Epi>
; __device__ __forceinline__ void gemm_phase(LAS unsigned char* lds, const Gemm g, const StaticOrder& S, const Epi& E) {
;     ...
;             PG8_WAIT_V(8); PG8_WAIT_L(0); PG8_BAR; PG8_MMA(1, 0, At, B0); PG8_MMA(1, 1, At, B1); PG8_BAR; PG8_SCHED;
;             PG8_LDB(B0, 1, 0); PG8_LDB(B1, 1, 1); PG8_SCHED; PG8_LDA(At, 1, 0); PG8_STAGE(PG8_SA(0, 1), a2 + hstepA, voffA);
;             PG8_WAIT_V(8); PG8_WAIT_L(0); PG8_BAR; PG8_MMA(0, 0, At, B0); PG8_MMA(0, 1, At, B1); PG8_BAR; PG8_SCHED;
	s_setprio 1
	v_mfma_f32_16x16x32_bf16 v[62:65], v[130:133], v[174:177], v[62:65]
	v_mfma_f32_16x16x32_bf16 v[58:61], v[138:141], v[174:177], v[58:61]
	v_mfma_f32_16x16x32_bf16 v[54:57], v[130:133], v[192:195], v[54:57]
	v_mfma_f32_16x16x32_bf16 v[50:53], v[138:141], v[192:195], v[50:53]
	v_mfma_f32_16x16x32_bf16 v[46:49], v[130:133], v[200:203], v[46:49]
	v_mfma_f32_16x16x32_bf16 v[38:41], v[138:141], v[200:203], v[38:41]
	v_mfma_f32_16x16x32_bf16 v[30:33], v[130:133], v[208:211], v[30:33]
	v_mfma_f32_16x16x32_bf16 v[22:25], v[138:141], v[208:211], v[22:25]
	v_mfma_f32_16x16x32_bf16 v[62:65], v[134:137], v[188:191], v[62:65]
	v_mfma_f32_16x16x32_bf16 v[58:61], v[142:145], v[188:191], v[58:61]
	v_mfma_f32_16x16x32_bf16 v[54:57], v[134:137], v[196:199], v[54:57]
	v_mfma_f32_16x16x32_bf16 v[50:53], v[142:145], v[196:199], v[50:53]
	v_mfma_f32_16x16x32_bf16 v[46:49], v[134:137], v[204:207], v[46:49]
	v_mfma_f32_16x16x32_bf16 v[38:41], v[142:145], v[204:207], v[38:41]
	v_mfma_f32_16x16x32_bf16 v[30:33], v[134:137], v[212:215], v[30:33]
	v_mfma_f32_16x16x32_bf16 v[22:25], v[142:145], v[212:215], v[22:25]
	v_mfma_f32_16x16x32_bf16 v[42:45], v[146:149], v[174:177], v[42:45]
	v_mfma_f32_16x16x32_bf16 v[34:37], v[166:169], v[174:177], v[34:37]
	v_mfma_f32_16x16x32_bf16 v[26:29], v[146:149], v[192:195], v[26:29]
	v_mfma_f32_16x16x32_bf16 v[18:21], v[166:169], v[192:195], v[18:21]
	v_mfma_f32_16x16x32_bf16 v[14:17], v[146:149], v[200:203], v[14:17]
	v_mfma_f32_16x16x32_bf16 v[10:13], v[166:169], v[200:203], v[10:13]
	v_mfma_f32_16x16x32_bf16 v[6:9], v[146:149], v[208:211], v[6:9]
	v_mfma_f32_16x16x32_bf16 v[2:5], v[166:169], v[208:211], v[2:5]
	v_mfma_f32_16x16x32_bf16 v[42:45], v[150:153], v[188:191], v[42:45]
	v_mfma_f32_16x16x32_bf16 v[34:37], v[170:173], v[188:191], v[34:37]
	v_mfma_f32_16x16x32_bf16 v[26:29], v[150:153], v[196:199], v[26:29]
	v_mfma_f32_16x16x32_bf16 v[18:21], v[170:173], v[196:199], v[18:21]
	v_mfma_f32_16x16x32_bf16 v[14:17], v[150:153], v[204:207], v[14:17]
	v_mfma_f32_16x16x32_bf16 v[10:13], v[170:173], v[204:207], v[10:13]
	v_mfma_f32_16x16x32_bf16 v[6:9], v[150:153], v[212:215], v[6:9]
	v_mfma_f32_16x16x32_bf16 v[2:5], v[170:173], v[212:215], v[2:5]
	s_setprio 0
	s_barrier
	s_add_i32 s53, 0, 0x18000
	s_add_i32 s62, 0, 0x1c000
	v_add_u32_e32 v142, s53, v1
	v_add_u32_e32 v170, s62, v1
	ds_read_b128 v[130:133], v142
	ds_read_b128 v[134:137], v142 offset:1024
	ds_read_b128 v[138:141], v142 offset:2048
	ds_read_b128 v[142:145], v142 offset:3072
	ds_read_b128 v[146:149], v170
	ds_read_b128 v[150:153], v170 offset:1024
	ds_read_b128 v[166:169], v170 offset:2048
	ds_read_b128 v[170:173], v170 offset:3072
	s_add_u32 s24, s24, 0x80000
	s_addc_u32 s25, s25, 0
	s_mov_b32 m0, s34
	v_lshl_add_u64 v[218:219], s[24:25], 0, v[154:155]
	ds_read_b128 v[174:177], v181 offset:32768
	ds_read_b128 v[188:191], v181 offset:33792
	ds_read_b128 v[192:195], v181 offset:34816
	ds_read_b128 v[196:199], v181 offset:35840
	ds_read_b128 v[200:203], v181 offset:36864
	ds_read_b128 v[204:207], v181 offset:37888
	ds_read_b128 v[208:211], v181 offset:38912
	ds_read_b128 v[212:215], v181 offset:39936
	global_load_lds_dwordx4 v[218:219], off
	v_lshl_add_u64 v[218:219], s[24:25], 0, v[158:159]
	s_mov_b32 m0, s35
	s_nop 0
	global_load_lds_dwordx4 v[218:219], off
	s_waitcnt vmcnt(8)
	s_waitcnt lgkmcnt(0)
	s_barrier
	s_setprio 1
	v_mfma_f32_16x16x32_bf16 v[126:129], v[130:133], v[174:177], v[126:129]
	v_mfma_f32_16x16x32_bf16 v[122:125], v[138:141], v[174:177], v[122:125]
	v_mfma_f32_16x16x32_bf16 v[118:121], v[130:133], v[192:195], v[118:121]
	v_mfma_f32_16x16x32_bf16 v[114:117], v[138:141], v[192:195], v[114:117]
	v_mfma_f32_16x16x32_bf16 v[102:105], v[130:133], v[200:203], v[102:105]
	v_mfma_f32_16x16x32_bf16 v[98:101], v[138:141], v[200:203], v[98:101]
	v_mfma_f32_16x16x32_bf16 v[86:89], v[130:133], v[208:211], v[86:89]
	v_mfma_f32_16x16x32_bf16 v[82:85], v[138:141], v[208:211], v[82:85]
	v_mfma_f32_16x16x32_bf16 v[126:129], v[134:137], v[188:191], v[126:129]
	v_mfma_f32_16x16x32_bf16 v[122:125], v[142:145], v[188:191], v[122:125]
	v_mfma_f32_16x16x32_bf16 v[118:121], v[134:137], v[196:199], v[118:121]
	v_mfma_f32_16x16x32_bf16 v[114:117], v[142:145], v[196:199], v[114:117]
	v_mfma_f32_16x16x32_bf16 v[102:105], v[134:137], v[204:207], v[102:105]
	v_mfma_f32_16x16x32_bf16 v[98:101], v[142:145], v[204:207], v[98:101]
	v_mfma_f32_16x16x32_bf16 v[86:89], v[134:137], v[212:215], v[86:89]
	v_mfma_f32_16x16x32_bf16 v[82:85], v[142:145], v[212:215], v[82:85]
	v_mfma_f32_16x16x32_bf16 v[110:113], v[146:149], v[174:177], v[110:113]
	v_mfma_f32_16x16x32_bf16 v[106:109], v[166:169], v[174:177], v[106:109]
	v_mfma_f32_16x16x32_bf16 v[94:97], v[146:149], v[192:195], v[94:97]
	v_mfma_f32_16x16x32_bf16 v[90:93], v[166:169], v[192:195], v[90:93]
	v_mfma_f32_16x16x32_bf16 v[78:81], v[146:149], v[200:203], v[78:81]
	v_mfma_f32_16x16x32_bf16 v[74:77], v[166:169], v[200:203], v[74:77]
	v_mfma_f32_16x16x32_bf16 v[70:73], v[146:149], v[208:211], v[70:73]
	v_mfma_f32_16x16x32_bf16 v[66:69], v[166:169], v[208:211], v[66:69]
	v_mfma_f32_16x16x32_bf16 v[110:113], v[150:153], v[188:191], v[110:113]
	v_mfma_f32_16x16x32_bf16 v[106:109], v[170:173], v[188:191], v[106:109]
	v_mfma_f32_16x16x32_bf16 v[94:97], v[150:153], v[196:199], v[94:97]
	v_mfma_f32_16x16x32_bf16 v[90:93], v[170:173], v[196:199], v[90:93]
	v_mfma_f32_16x16x32_bf16 v[78:81], v[150:153], v[204:207], v[78:81]
	v_mfma_f32_16x16x32_bf16 v[74:77], v[170:173], v[204:207], v[74:77]
	v_mfma_f32_16x16x32_bf16 v[70:73], v[150:153], v[212:215], v[70:73]
	v_mfma_f32_16x16x32_bf16 v[66:69], v[170:173], v[212:215], v[66:69]
	s_setprio 0
	s_barrier
; #define PG8_STAGE(bufoff, gbase, voff) do { _Pragma("unroll") for (int _i = 0; _i < 2; ++_i) \
;         __builtin_amdgcn_global_load_lds((const unsigned*)((const char*)(gbase) + (voff)[_i]), (LAS unsigned*)(lds + (bufoff) + ldsw + _i * 8192), 16, 0, 0); } while (0)
; #define PG8_LDA(dst, b, h) do { _Pragma("unroll") for (int m = 0; m < 4; ++m) _Pragma("unroll") for (int k = 0; k < 2; ++k) dst[m][k] = *(const LAS bf16x8*)(lds + PG8_SA(b, h) + aoff + m * 2048 + k * 1024); } while (0)
; #define PG8_MMA(ai, bj, At, Bt) do { __builtin_amdgcn_s_setprio(1); _Pragma("unroll") for (int m = 0; m < 4; ++m) _Pragma("unroll") for (int n = 0; n < 2; ++n) _Pragma("unroll") for (int k = 0; k < 2; ++k) \
;         acc[ai][bj][m][n] = __builtin_amdgcn_mfma_f32_16x16x32_bf16(Bt[n][k], At[m][k], acc[ai][bj][m][n], 0, 0, 0); __builtin_amdgcn_s_setprio(0); } while (0)
; #define PG8_WAIT_V(n) asm volatile("s_waitcnt vmcnt(" #n ")" ::: "memory")
; #define PG8_WAIT_L(n) asm volatile("s_waitcnt lgkmcnt(" #n ")" ::: "memory")
; #define PG8_BAR __builtin_amdgcn_s_barrier()
; #define PG8_SCHED __builtin_amdgcn_sched_barrier(0)
; template <class Epi>
; __device__ __forceinline__ void gemm_phase(LAS unsigned char* lds, const Gemm g, const StaticOrder& S, const Epi& E) {
;     ...
;             PG8_LDA(At, 1, 1); PG8_STAGE(PG8_SB(1, 0), b3, voffB); PG8_STAGE(PG8_SB(1, 1), b3 + hstepB, voffB); PG8_STAGE(PG8_SA(1, 0), a3, voffA);
;             PG8_WAIT_V(8); PG8_WAIT_L(0); PG8_BAR; PG8_MMA(1, 0, At, B0); PG8_MMA(1, 1, At, B1); PG8_BAR; PG8_SCHED;
;         }
;         if (wr == 0) PG8_BAR;
	s_add_i32 s24, s53, s27
	v_lshl_add_u64 v[178:179], v[178:179], 0, s[84:85]
	s_mov_b32 m0, s24
	ds_read_b128 v[174:177], v181 offset:49152
	ds_read_b128 v[188:191], v181 offset:50176
	ds_read_b128 v[192:195], v181 offset:51200
	ds_read_b128 v[196:199], v181 offset:52224
	ds_read_b128 v[200:203], v181 offset:53248
	ds_read_b128 v[204:207], v181 offset:54272
	ds_read_b128 v[208:211], v181 offset:55296
	ds_read_b128 v[212:215], v181 offset:56320
	global_load_lds_dwordx4 v[178:179], off
	s_add_i32 m0, s24, 0x2000
	s_add_u32 s14, s14, 0x80080
	v_lshl_add_u64 v[178:179], v[184:185], 0, s[84:85]
	s_addc_u32 s15, s15, 0
	s_add_i32 s24, s62, s27
	global_load_lds_dwordx4 v[178:179], off
	v_lshl_add_u64 v[178:179], s[14:15], 0, v[156:157]
	s_mov_b32 m0, s24
	s_nop 0
	global_load_lds_dwordx4 v[178:179], off
	v_lshl_add_u64 v[178:179], s[14:15], 0, v[160:161]
	s_add_i32 m0, s24, 0x2000
	s_nop 0
	global_load_lds_dwordx4 v[178:179], off
	v_lshl_add_u64 v[178:179], v[186:187], 0, s[84:85]
	s_mov_b32 m0, s45
	s_nop 0
	global_load_lds_dwordx4 v[178:179], off
	v_lshl_add_u64 v[178:179], v[216:217], 0, s[84:85]
	s_mov_b32 m0, s68
	s_nop 0
	global_load_lds_dwordx4 v[178:179], off
	s_waitcnt vmcnt(8)
	s_waitcnt lgkmcnt(0)
	s_barrier
	s_setprio 1
	v_mfma_f32_16x16x32_bf16 v[62:65], v[130:133], v[174:177], v[62:65]
	v_mfma_f32_16x16x32_bf16 v[58:61], v[138:141], v[174:177], v[58:61]
	v_mfma_f32_16x16x32_bf16 v[54:57], v[130:133], v[192:195], v[54:57]
	v_mfma_f32_16x16x32_bf16 v[50:53], v[138:141], v[192:195], v[50:53]
	v_mfma_f32_16x16x32_bf16 v[46:49], v[130:133], v[200:203], v[46:49]
	v_mfma_f32_16x16x32_bf16 v[38:41], v[138:141], v[200:203], v[38:41]
	v_mfma_f32_16x16x32_bf16 v[30:33], v[130:133], v[208:211], v[30:33]
	v_mfma_f32_16x16x32_bf16 v[22:25], v[138:141], v[208:211], v[22:25]
	v_mfma_f32_16x16x32_bf16 v[62:65], v[134:137], v[188:191], v[62:65]
	v_mfma_f32_16x16x32_bf16 v[58:61], v[142:145], v[188:191], v[58:61]
	v_mfma_f32_16x16x32_bf16 v[54:57], v[134:137], v[196:199], v[54:57]
	v_mfma_f32_16x16x32_bf16 v[50:53], v[142:145], v[196:199], v[50:53]
	v_mfma_f32_16x16x32_bf16 v[46:49], v[134:137], v[204:207], v[46:49]
	v_mfma_f32_16x16x32_bf16 v[38:41], v[142:145], v[204:207], v[38:41]
	v_mfma_f32_16x16x32_bf16 v[30:33], v[134:137], v[212:215], v[30:33]
	v_mfma_f32_16x16x32_bf16 v[22:25], v[142:145], v[212:215], v[22:25]
	v_mfma_f32_16x16x32_bf16 v[42:45], v[146:149], v[174:177], v[42:45]
	v_mfma_f32_16x16x32_bf16 v[34:37], v[166:169], v[174:177], v[34:37]
	v_mfma_f32_16x16x32_bf16 v[26:29], v[146:149], v[192:195], v[26:29]
	v_mfma_f32_16x16x32_bf16 v[18:21], v[166:169], v[192:195], v[18:21]
	v_mfma_f32_16x16x32_bf16 v[14:17], v[146:149], v[200:203], v[14:17]
	v_mfma_f32_16x16x32_bf16 v[10:13], v[166:169], v[200:203], v[10:13]
	v_mfma_f32_16x16x32_bf16 v[6:9], v[146:149], v[208:211], v[6:9]
	v_mfma_f32_16x16x32_bf16 v[2:5], v[166:169], v[208:211], v[2:5]
	v_mfma_f32_16x16x32_bf16 v[42:45], v[150:153], v[188:191], v[42:45]
	v_mfma_f32_16x16x32_bf16 v[34:37], v[170:173], v[188:191], v[34:37]
	v_mfma_f32_16x16x32_bf16 v[26:29], v[150:153], v[196:199], v[26:29]
	v_mfma_f32_16x16x32_bf16 v[18:21], v[170:173], v[196:199], v[18:21]
	v_mfma_f32_16x16x32_bf16 v[14:17], v[150:153], v[204:207], v[14:17]
	v_mfma_f32_16x16x32_bf16 v[10:13], v[170:173], v[204:207], v[10:13]
	v_mfma_f32_16x16x32_bf16 v[6:9], v[150:153], v[212:215], v[6:9]
	v_mfma_f32_16x16x32_bf16 v[2:5], v[170:173], v[212:215], v[2:5]
	s_setprio 0
	s_barrier
	s_add_i32 s41, s41, 2
	s_add_u32 s22, s22, 0x100
	s_addc_u32 s23, s23, 0
	s_add_u32 s40, s40, 0x100
	s_addc_u32 s52, s52, 0
	s_cmp_gt_u32 s41, 29
	s_cbranch_scc0 .LBB0_2376
	v_mov_b64_e32 v[250:251], 0xff
	v_mov_b64_e32 v[252:253], 0x100
	v_mov_b32_e32 v183, 0x7f800000
	s_and_b64 vcc, exec, s[10:11]
	s_cbranch_vccz .LBB0_2379
	s_barrier
